# strategy 4 step (a): one static s_setprio 1 for waves 4-7 (set once after their alignment barrier, kept through the later phases), no per-segment flips in the merged GEMM loops
# baseline (speedup 1.0000x reference)
; __device__ __forceinline__ unsigned cvt_pk_bf16(float lo, float hi) { const f32x2 v = {lo, hi}; const bf16v2_ r = __builtin_convertvector(v, bf16v2_); return __builtin_bit_cast(unsigned, r); }
; #define PG8_BAR __builtin_amdgcn_s_barrier()
; template <class Epi, class Sched>
; __device__ __forceinline__ void gemm_phase(LAS unsigned char* lds, const Gemm g, const Sched& S, const Epi& E) {
;     ...
;     if (wr == 1) PG8_BAR;
;     __device__ __forceinline__ void operator()(const f32x4 (&acc)[2][2][4][2], const Unit& u, int wr, int wc, int ui, int) const {
;     ...
;             for (int m = 0; m < 4; ++m) { const int row = row0 + ai * HALF + m * 16; const float r = r_[ai][m];
; #pragma unroll
;                 for (int bj = 0; bj < 2; ++bj) { const f32x4 v0 = acc[ai][bj][m][0] * r, v1 = acc[ai][bj][m][1] * r;
;                     u32x4 w; w.x = cvt_pk_bf16(v0[0], v0[1]); w.y = cvt_pk_bf16(v0[2], v0[3]); w.z = cvt_pk_bf16(v1[0], v1[1]); w.w = cvt_pk_bf16(v1[2], v1[3]);
;                     bf16_t* p = cmp ? cb + ((size_t)((row / T) * 2 + bj) * T + (row % T)) * 128 + wc * 32 + 8 * fq
;                                     : O + (size_t)row * ldc + col0 + bj * HALF;
;                     *(u32x4*)p = w; } }
.LBB0_346:
	v_mov_b32_e32 v145, v144
	v_mov_b32_e32 v14, v144
	v_mov_b32_e32 v15, v144
	v_pk_mul_f32 v[10:11], v[10:11], v[14:15]
	v_pk_mul_f32 v[8:9], v[8:9], v[144:145]
	v_pk_mul_f32 v[6:7], v[6:7], v[14:15]
	v_pk_mul_f32 v[4:5], v[4:5], v[144:145]
	v_cvt_pk_bf16_f32 v8, v8, v9
	v_cvt_pk_bf16_f32 v9, v10, v11
	v_cvt_pk_bf16_f32 v10, v4, v5
	v_cvt_pk_bf16_f32 v11, v6, v7
	s_and_b64 vcc, exec, s[42:43]
	s_mov_b32 s44, s0
	s_mov_b32 s50, s14
	s_mov_b64 s[20:21], s[4:5]
	s_mov_b64 s[6:7], s[18:19]
	s_mov_b32 s45, s49
	global_store_dwordx4 v[12:13], v[8:11], off
	s_cmpk_lt_u32 s2, 0x100
	s_cbranch_scc1 .Lalign_b_352
	s_barrier
	s_setprio 1

; #define PG8_STAGE(bufoff, gbase, voff) do { _Pragma("unroll") for (int _i = 0; _i < 2; ++_i) \
;         __builtin_amdgcn_global_load_lds((const unsigned*)((const char*)(gbase) + (voff)[_i]), (LAS unsigned*)(lds + (bufoff) + ldsw + _i * 8192), 16, 0, 0); } while (0)
; #define PG8_LDA(dst, b, h) do { _Pragma("unroll") for (int m = 0; m < 4; ++m) _Pragma("unroll") for (int k = 0; k < 2; ++k) dst[m][k] = *(const LAS bf16x8*)(lds + PG8_SA(b, h) + aoff + m * 2048 + k * 1024); } while (0)
; #define PG8_LDB(dst, b, h) do { _Pragma("unroll") for (int n = 0; n < 2; ++n) _Pragma("unroll") for (int k = 0; k < 2; ++k) dst[n][k] = *(const LAS bf16x8*)(lds + PG8_SB(b, h) + boff + n * 2048 + k * 1024); } while (0)
; #define PG8_WAIT_V(n) asm volatile("s_waitcnt vmcnt(" #n ")" ::: "memory")
; #define PG8_WAIT_L(n) asm volatile("s_waitcnt lgkmcnt(" #n ")" ::: "memory")
; #define PG8_BAR __builtin_amdgcn_s_barrier()
; #define PG8_SCHED __builtin_amdgcn_sched_barrier(0)
; template <class Epi, class Sched>
; __device__ __forceinline__ void gemm_phase(LAS unsigned char* lds, const Gemm g, const Sched& S, const Epi& E) {
;     ...
;         const bool has_next = S.next(ui + 1, nxt);
;         const char* nA = has_next ? (const char*)g.A + (size_t)nxt.pm * tstepA : cA; const char* nB = has_next ? (const char*)g.Bt + (size_t)nxt.pn * tstepB : cB;
;         for (int t = 0; t < nt; t += 2) {
;             const bool last = (t == nt - 2);
;             const char* a1 = cA + (size_t)(t + 1) * kstep;
;             const char* a2 = last ? nA : cA + (size_t)(t + 2) * kstep; const char* b2 = last ? nB : cB + (size_t)(t + 2) * kstep;
;             const char* a3 = a2 + kstep; const char* b3 = b2 + kstep;
;             if (last && has_next) S.a_ready(nxt);
;             PG8_LDB(B0, 0, 0); PG8_SCHED; PG8_LDA(At, 0, 0); PG8_STAGE(PG8_SA(1, 1), a1 + hstepA, voffA);
;             PG8_WAIT_L(8); PG8_BAR; PG8_WAIT_L(0); PG8_MMA(0, 0, At, B0); PG8_BAR; PG8_SCHED;
;             PG8_LDB(B1, 0, 1); PG8_STAGE(PG8_SB(0, 0), b2, voffB);
;             PG8_BAR; PG8_WAIT_L(0); PG8_MMA(0, 1, At, B1); PG8_BAR;
;             PG8_LDA(At, 0, 1); PG8_STAGE(PG8_SA(0, 0), a2, voffA);
;             PG8_BAR; PG8_WAIT_L(0); PG8_MMA(1, 0, At, B0); PG8_BAR; PG8_SCHED;
;             PG8_STAGE(PG8_SB(0, 1), b2 + hstepB, voffB);
;             PG8_WAIT_V(6); PG8_BAR; PG8_MMA(1, 1, At, B1); PG8_BAR;
.LBB0_351:
	v_mov_b64_e32 v[4:5], 0xd80
	s_ashr_i32 s15, s14, 31
	v_cmp_lt_i64_e32 vcc, s[4:5], v[4:5]
	s_lshl_b64 s[4:5], s[14:15], 20
	s_add_u32 s18, s88, s4
	s_addc_u32 s19, s89, s5
	s_and_b64 s[4:5], vcc, exec
	s_cselect_b32 s15, s19, s7
	s_cselect_b32 s51, s18, s6
	s_ashr_i32 s1, s0, 31
	s_lshl_b64 s[4:5], s[0:1], 20
	s_add_u32 s4, s28, s4
	s_addc_u32 s5, s29, s5
	s_and_b64 s[24:25], vcc, exec
	s_cselect_b32 s1, s5, s21
	s_cselect_b32 s52, s4, s20
	s_add_u32 s6, s6, 0x80080
	s_addc_u32 s7, s7, 0
	s_add_u32 s53, s20, 0x100
	s_addc_u32 s54, s21, 0
	s_mov_b32 s55, -2
	s_waitcnt lgkmcnt(0)
	s_add_u32 s20, s6, 0xfff80080
	s_addc_u32 s21, s7, -1
	s_add_i32 s56, 0, 0x10000
	v_add_u32_e32 v2, s56, v1
	ds_read_b128 v[144:147], v2
	ds_read_b128 v[150:153], v2 offset:1024
	ds_read_b128 v[154:157], v2 offset:2048
	ds_read_b128 v[158:161], v2 offset:3072
	s_cmp_eq_u32 s55, 28
	s_cselect_b32 s25, s15, s21
	s_cselect_b32 s24, s51, s20
	s_cselect_b32 s21, s1, s54
	s_cselect_b32 s20, s52, s53
	ds_read_b128 v[162:165], v149
	ds_read_b128 v[166:169], v149 offset:1024
	ds_read_b128 v[170:173], v149 offset:2048
	ds_read_b128 v[174:177], v149 offset:3072
	ds_read_b128 v[178:181], v149 offset:4096
	ds_read_b128 v[182:185], v149 offset:5120
	ds_read_b128 v[186:189], v149 offset:6144
	ds_read_b128 v[190:193], v149 offset:7168
	s_add_i32 s58, 0, 0x14000
	v_add_u32_e32 v2, s58, v1
	ds_read_b128 v[194:197], v2
	ds_read_b128 v[198:201], v2 offset:1024
	ds_read_b128 v[202:205], v2 offset:2048
	ds_read_b128 v[206:209], v2 offset:3072
	s_add_i32 m0, s31, 0xc000
	s_nop 0
	global_load_lds_dwordx4 v140, s[6:7]
	s_add_i32 m0, s31, 0xe000
	s_nop 0
	global_load_lds_dwordx4 v142, s[6:7]
	s_waitcnt lgkmcnt(0)
	s_barrier
	v_mfma_f32_16x16x32_bf16 v[128:131], v[144:147], v[162:165], 0
	v_mfma_f32_16x16x32_bf16 v[124:127], v[154:157], v[162:165], 0
	v_mfma_f32_16x16x32_bf16 v[112:115], v[144:147], v[170:173], 0
	v_mfma_f32_16x16x32_bf16 v[108:111], v[154:157], v[170:173], 0
	v_mfma_f32_16x16x32_bf16 v[96:99], v[144:147], v[178:181], 0
	v_mfma_f32_16x16x32_bf16 v[92:95], v[154:157], v[178:181], 0
	v_mfma_f32_16x16x32_bf16 v[80:83], v[144:147], v[186:189], 0
	v_mfma_f32_16x16x32_bf16 v[76:79], v[154:157], v[186:189], 0
	v_mfma_f32_16x16x32_bf16 v[128:131], v[150:153], v[166:169], v[128:131]
	v_mfma_f32_16x16x32_bf16 v[124:127], v[158:161], v[166:169], v[124:127]
	v_mfma_f32_16x16x32_bf16 v[112:115], v[150:153], v[174:177], v[112:115]
	v_mfma_f32_16x16x32_bf16 v[108:111], v[158:161], v[174:177], v[108:111]
	v_mfma_f32_16x16x32_bf16 v[96:99], v[150:153], v[182:185], v[96:99]
	v_mfma_f32_16x16x32_bf16 v[92:95], v[158:161], v[182:185], v[92:95]
	v_mfma_f32_16x16x32_bf16 v[80:83], v[150:153], v[190:193], v[80:83]
	v_mfma_f32_16x16x32_bf16 v[76:79], v[158:161], v[190:193], v[76:79]
	v_mfma_f32_16x16x32_bf16 v[120:123], v[194:197], v[162:165], 0
	v_mfma_f32_16x16x32_bf16 v[116:119], v[202:205], v[162:165], 0
	v_mfma_f32_16x16x32_bf16 v[104:107], v[194:197], v[170:173], 0
	v_mfma_f32_16x16x32_bf16 v[100:103], v[202:205], v[170:173], 0
	v_mfma_f32_16x16x32_bf16 v[88:91], v[194:197], v[178:181], 0
	v_mfma_f32_16x16x32_bf16 v[84:87], v[202:205], v[178:181], 0
	v_mfma_f32_16x16x32_bf16 v[72:75], v[194:197], v[186:189], 0
	v_mfma_f32_16x16x32_bf16 v[68:71], v[202:205], v[186:189], 0
	v_mfma_f32_16x16x32_bf16 v[120:123], v[198:201], v[166:169], v[120:123]
	v_mfma_f32_16x16x32_bf16 v[116:119], v[206:209], v[166:169], v[116:119]
	v_mfma_f32_16x16x32_bf16 v[104:107], v[198:201], v[174:177], v[104:107]
	v_mfma_f32_16x16x32_bf16 v[100:103], v[206:209], v[174:177], v[100:103]
	v_mfma_f32_16x16x32_bf16 v[88:91], v[198:201], v[182:185], v[88:91]
	v_mfma_f32_16x16x32_bf16 v[84:87], v[206:209], v[182:185], v[84:87]
	v_mfma_f32_16x16x32_bf16 v[72:75], v[198:201], v[190:193], v[72:75]
	v_mfma_f32_16x16x32_bf16 v[68:71], v[206:209], v[190:193], v[68:71]
	s_barrier
	ds_read_b128 v[162:165], v149 offset:16384
	ds_read_b128 v[166:169], v149 offset:17408
	ds_read_b128 v[170:173], v149 offset:18432
	ds_read_b128 v[174:177], v149 offset:19456
	ds_read_b128 v[178:181], v149 offset:20480
	ds_read_b128 v[182:185], v149 offset:21504
	ds_read_b128 v[186:189], v149 offset:22528
	ds_read_b128 v[190:193], v149 offset:23552
	s_add_i32 s56, s56, s30
	v_lshl_add_u64 v[210:211], s[20:21], 0, v[136:137]
	s_mov_b32 m0, s56
	s_nop 0
	global_load_lds_dwordx4 v[210:211], off
	v_lshl_add_u64 v[212:213], s[20:21], 0, v[132:133]
	s_add_i32 m0, s56, 0x2000
	s_nop 0
	global_load_lds_dwordx4 v[212:213], off
	s_mov_b32 m0, s31
	v_lshl_add_u64 v[216:217], s[24:25], 0, v[138:139]
	global_load_lds_dwordx4 v[216:217], off
	v_lshl_add_u64 v[218:219], s[24:25], 0, v[134:135]
	s_mov_b32 m0, s35
	s_nop 0
	global_load_lds_dwordx4 v[218:219], off
	s_add_u32 s56, s20, 0x80000
	s_addc_u32 s57, s21, 0
	s_add_i32 s58, s58, s30
	s_mov_b32 m0, s58
	s_nop 0
	global_load_lds_dwordx4 v136, s[56:57]
	s_add_i32 m0, s58, 0x2000
	s_nop 0
	global_load_lds_dwordx4 v132, s[56:57]
	s_waitcnt lgkmcnt(0)
	s_waitcnt vmcnt(6)
	s_barrier
; #define PG8_STAGE(bufoff, gbase, voff) do { _Pragma("unroll") for (int _i = 0; _i < 2; ++_i) \
;         __builtin_amdgcn_global_load_lds((const unsigned*)((const char*)(gbase) + (voff)[_i]), (LAS unsigned*)(lds + (bufoff) + ldsw + _i * 8192), 16, 0, 0); } while (0)
; #define PG8_LDA(dst, b, h) do { _Pragma("unroll") for (int m = 0; m < 4; ++m) _Pragma("unroll") for (int k = 0; k < 2; ++k) dst[m][k] = *(const LAS bf16x8*)(lds + PG8_SA(b, h) + aoff + m * 2048 + k * 1024); } while (0)
; #define PG8_LDB(dst, b, h) do { _Pragma("unroll") for (int n = 0; n < 2; ++n) _Pragma("unroll") for (int k = 0; k < 2; ++k) dst[n][k] = *(const LAS bf16x8*)(lds + PG8_SB(b, h) + boff + n * 2048 + k * 1024); } while (0)
; #define PG8_MMA(ai, bj, At, Bt) do { __builtin_amdgcn_s_setprio(1); _Pragma("unroll") for (int m = 0; m < 4; ++m) _Pragma("unroll") for (int n = 0; n < 2; ++n) _Pragma("unroll") for (int k = 0; k < 2; ++k) \
;         acc[ai][bj][m][n] = __builtin_amdgcn_mfma_f32_16x16x32_bf16(Bt[n][k], At[m][k], acc[ai][bj][m][n], 0, 0, 0); __builtin_amdgcn_s_setprio(0); } while (0)
; #define PG8_WAIT_V(n) asm volatile("s_waitcnt vmcnt(" #n ")" ::: "memory")
; #define PG8_WAIT_L(n) asm volatile("s_waitcnt lgkmcnt(" #n ")" ::: "memory")
; #define PG8_BAR __builtin_amdgcn_s_barrier()
; #define PG8_SCHED __builtin_amdgcn_sched_barrier(0)
; template <class Epi, class Sched>
; __device__ __forceinline__ void gemm_phase(LAS unsigned char* lds, const Gemm g, const Sched& S, const Epi& E) {
;     ...
;             PG8_BAR; PG8_WAIT_L(0); PG8_MMA(0, 1, At, B1); PG8_BAR;
;             PG8_LDA(At, 0, 1); PG8_STAGE(PG8_SA(0, 0), a2, voffA);
;             PG8_BAR; PG8_WAIT_L(0); PG8_MMA(1, 0, At, B0); PG8_BAR; PG8_SCHED;
;             PG8_STAGE(PG8_SB(0, 1), b2 + hstepB, voffB);
;             PG8_WAIT_V(6); PG8_BAR; PG8_MMA(1, 1, At, B1); PG8_BAR;
;             PG8_LDB(B0, 1, 0); PG8_SCHED; PG8_LDA(At, 1, 0); PG8_STAGE(PG8_SA(0, 1), a2 + hstepA, voffA);
;             PG8_WAIT_L(8); PG8_BAR; PG8_WAIT_L(0); PG8_MMA(0, 0, At, B0); PG8_BAR; PG8_SCHED;
;             PG8_LDB(B1, 1, 1); PG8_STAGE(PG8_SB(1, 0), b3, voffB);
;             PG8_BAR; PG8_WAIT_L(0); PG8_MMA(0, 1, At, B1); PG8_BAR;
	v_mfma_f32_16x16x32_bf16 v[64:67], v[144:147], v[162:165], 0
	v_mfma_f32_16x16x32_bf16 v[60:63], v[154:157], v[162:165], 0
	v_mfma_f32_16x16x32_bf16 v[48:51], v[144:147], v[170:173], 0
	v_mfma_f32_16x16x32_bf16 v[44:47], v[154:157], v[170:173], 0
	v_mfma_f32_16x16x32_bf16 v[32:35], v[144:147], v[178:181], 0
	v_mfma_f32_16x16x32_bf16 v[28:31], v[154:157], v[178:181], 0
	v_mfma_f32_16x16x32_bf16 v[16:19], v[144:147], v[186:189], 0
	v_mfma_f32_16x16x32_bf16 v[12:15], v[154:157], v[186:189], 0
	v_mfma_f32_16x16x32_bf16 v[64:67], v[150:153], v[166:169], v[64:67]
	v_mfma_f32_16x16x32_bf16 v[60:63], v[158:161], v[166:169], v[60:63]
	v_mfma_f32_16x16x32_bf16 v[48:51], v[150:153], v[174:177], v[48:51]
	v_mfma_f32_16x16x32_bf16 v[44:47], v[158:161], v[174:177], v[44:47]
	v_mfma_f32_16x16x32_bf16 v[32:35], v[150:153], v[182:185], v[32:35]
	v_mfma_f32_16x16x32_bf16 v[28:31], v[158:161], v[182:185], v[28:31]
	v_mfma_f32_16x16x32_bf16 v[16:19], v[150:153], v[190:193], v[16:19]
	v_mfma_f32_16x16x32_bf16 v[12:15], v[158:161], v[190:193], v[12:15]
	v_mfma_f32_16x16x32_bf16 v[56:59], v[194:197], v[162:165], 0
	v_mfma_f32_16x16x32_bf16 v[52:55], v[202:205], v[162:165], 0
	v_mfma_f32_16x16x32_bf16 v[40:43], v[194:197], v[170:173], 0
	v_mfma_f32_16x16x32_bf16 v[36:39], v[202:205], v[170:173], 0
	v_mfma_f32_16x16x32_bf16 v[24:27], v[194:197], v[178:181], 0
	v_mfma_f32_16x16x32_bf16 v[20:23], v[202:205], v[178:181], 0
	v_mfma_f32_16x16x32_bf16 v[8:11], v[194:197], v[186:189], 0
	v_mfma_f32_16x16x32_bf16 v[4:7], v[202:205], v[186:189], 0
	v_mfma_f32_16x16x32_bf16 v[56:59], v[198:201], v[166:169], v[56:59]
	v_mfma_f32_16x16x32_bf16 v[52:55], v[206:209], v[166:169], v[52:55]
	v_mfma_f32_16x16x32_bf16 v[40:43], v[198:201], v[174:177], v[40:43]
	v_mfma_f32_16x16x32_bf16 v[36:39], v[206:209], v[174:177], v[36:39]
	v_mfma_f32_16x16x32_bf16 v[24:27], v[198:201], v[182:185], v[24:27]
	v_mfma_f32_16x16x32_bf16 v[20:23], v[206:209], v[182:185], v[20:23]
	v_mfma_f32_16x16x32_bf16 v[8:11], v[198:201], v[190:193], v[8:11]
	v_mfma_f32_16x16x32_bf16 v[4:7], v[206:209], v[190:193], v[4:7]
	s_barrier
	s_add_i32 s56, 0, 0x18000
	v_add_u32_e32 v2, s56, v1
	ds_read_b128 v[144:147], v2
	ds_read_b128 v[150:153], v2 offset:1024
	ds_read_b128 v[154:157], v2 offset:2048
	ds_read_b128 v[158:161], v2 offset:3072
	s_add_u32 s24, s24, 0x80000
	s_addc_u32 s25, s25, 0
	ds_read_b128 v[162:165], v149 offset:32768
	ds_read_b128 v[166:169], v149 offset:33792
	ds_read_b128 v[170:173], v149 offset:34816
	ds_read_b128 v[174:177], v149 offset:35840
	ds_read_b128 v[178:181], v149 offset:36864
	ds_read_b128 v[182:185], v149 offset:37888
	ds_read_b128 v[186:189], v149 offset:38912
	ds_read_b128 v[190:193], v149 offset:39936
	s_mov_b32 m0, s36
	s_nop 0
	global_load_lds_dwordx4 v138, s[24:25]
	s_mov_b32 m0, s37
	s_nop 0
	global_load_lds_dwordx4 v134, s[24:25]
	s_add_i32 s24, 0, 0x1c000
	v_add_u32_e32 v2, s24, v1
	ds_read_b128 v[194:197], v2
	ds_read_b128 v[198:201], v2 offset:1024
	ds_read_b128 v[202:205], v2 offset:2048
	ds_read_b128 v[206:209], v2 offset:3072
	s_waitcnt lgkmcnt(0)
	s_barrier
	v_mfma_f32_16x16x32_bf16 v[128:131], v[144:147], v[162:165], v[128:131]
	v_mfma_f32_16x16x32_bf16 v[124:127], v[154:157], v[162:165], v[124:127]
	v_mfma_f32_16x16x32_bf16 v[112:115], v[144:147], v[170:173], v[112:115]
	v_mfma_f32_16x16x32_bf16 v[108:111], v[154:157], v[170:173], v[108:111]
	v_mfma_f32_16x16x32_bf16 v[96:99], v[144:147], v[178:181], v[96:99]
	v_mfma_f32_16x16x32_bf16 v[92:95], v[154:157], v[178:181], v[92:95]
	v_mfma_f32_16x16x32_bf16 v[80:83], v[144:147], v[186:189], v[80:83]
	v_mfma_f32_16x16x32_bf16 v[76:79], v[154:157], v[186:189], v[76:79]
	v_mfma_f32_16x16x32_bf16 v[128:131], v[150:153], v[166:169], v[128:131]
	v_mfma_f32_16x16x32_bf16 v[124:127], v[158:161], v[166:169], v[124:127]
	v_mfma_f32_16x16x32_bf16 v[112:115], v[150:153], v[174:177], v[112:115]
	v_mfma_f32_16x16x32_bf16 v[108:111], v[158:161], v[174:177], v[108:111]
	v_mfma_f32_16x16x32_bf16 v[96:99], v[150:153], v[182:185], v[96:99]
	v_mfma_f32_16x16x32_bf16 v[92:95], v[158:161], v[182:185], v[92:95]
	v_mfma_f32_16x16x32_bf16 v[80:83], v[150:153], v[190:193], v[80:83]
	v_mfma_f32_16x16x32_bf16 v[76:79], v[158:161], v[190:193], v[76:79]
	v_mfma_f32_16x16x32_bf16 v[120:123], v[194:197], v[162:165], v[120:123]
	v_mfma_f32_16x16x32_bf16 v[116:119], v[202:205], v[162:165], v[116:119]
	v_mfma_f32_16x16x32_bf16 v[104:107], v[194:197], v[170:173], v[104:107]
	v_mfma_f32_16x16x32_bf16 v[100:103], v[202:205], v[170:173], v[100:103]
	v_mfma_f32_16x16x32_bf16 v[88:91], v[194:197], v[178:181], v[88:91]
	v_mfma_f32_16x16x32_bf16 v[84:87], v[202:205], v[178:181], v[84:87]
	v_mfma_f32_16x16x32_bf16 v[72:75], v[194:197], v[186:189], v[72:75]
	v_mfma_f32_16x16x32_bf16 v[68:71], v[202:205], v[186:189], v[68:71]
	v_mfma_f32_16x16x32_bf16 v[120:123], v[198:201], v[166:169], v[120:123]
	v_mfma_f32_16x16x32_bf16 v[116:119], v[206:209], v[166:169], v[116:119]
	v_mfma_f32_16x16x32_bf16 v[104:107], v[198:201], v[174:177], v[104:107]
	v_mfma_f32_16x16x32_bf16 v[100:103], v[206:209], v[174:177], v[100:103]
	v_mfma_f32_16x16x32_bf16 v[88:91], v[198:201], v[182:185], v[88:91]
	v_mfma_f32_16x16x32_bf16 v[84:87], v[206:209], v[182:185], v[84:87]
	v_mfma_f32_16x16x32_bf16 v[72:75], v[198:201], v[190:193], v[72:75]
	v_mfma_f32_16x16x32_bf16 v[68:71], v[206:209], v[190:193], v[68:71]
	s_barrier
; #define PG8_STAGE(bufoff, gbase, voff) do { _Pragma("unroll") for (int _i = 0; _i < 2; ++_i) \
;         __builtin_amdgcn_global_load_lds((const unsigned*)((const char*)(gbase) + (voff)[_i]), (LAS unsigned*)(lds + (bufoff) + ldsw + _i * 8192), 16, 0, 0); } while (0)
; #define PG8_LDA(dst, b, h) do { _Pragma("unroll") for (int m = 0; m < 4; ++m) _Pragma("unroll") for (int k = 0; k < 2; ++k) dst[m][k] = *(const LAS bf16x8*)(lds + PG8_SA(b, h) + aoff + m * 2048 + k * 1024); } while (0)
; #define PG8_LDB(dst, b, h) do { _Pragma("unroll") for (int n = 0; n < 2; ++n) _Pragma("unroll") for (int k = 0; k < 2; ++k) dst[n][k] = *(const LAS bf16x8*)(lds + PG8_SB(b, h) + boff + n * 2048 + k * 1024); } while (0)
; #define PG8_MMA(ai, bj, At, Bt) do { __builtin_amdgcn_s_setprio(1); _Pragma("unroll") for (int m = 0; m < 4; ++m) _Pragma("unroll") for (int n = 0; n < 2; ++n) _Pragma("unroll") for (int k = 0; k < 2; ++k) \
;         acc[ai][bj][m][n] = __builtin_amdgcn_mfma_f32_16x16x32_bf16(Bt[n][k], At[m][k], acc[ai][bj][m][n], 0, 0, 0); __builtin_amdgcn_s_setprio(0); } while (0)
; #define PG8_WAIT_V(n) asm volatile("s_waitcnt vmcnt(" #n ")" ::: "memory")
; #define PG8_BAR __builtin_amdgcn_s_barrier()
; template <class Epi, class Sched>
; __device__ __forceinline__ void gemm_phase(LAS unsigned char* lds, const Gemm g, const Sched& S, const Epi& E) {
;     ...
;         for (int t = 0; t < nt; t += 2) {
;             const bool last = (t == nt - 2);
;             const char* a1 = cA + (size_t)(t + 1) * kstep;
;             const char* a2 = last ? nA : cA + (size_t)(t + 2) * kstep; const char* b2 = last ? nB : cB + (size_t)(t + 2) * kstep;
;             const char* a3 = a2 + kstep; const char* b3 = b2 + kstep;
;             if (last && has_next) S.a_ready(nxt);
;             PG8_LDB(B0, 0, 0); PG8_SCHED; PG8_LDA(At, 0, 0); PG8_STAGE(PG8_SA(1, 1), a1 + hstepA, voffA);
;             PG8_WAIT_L(8); PG8_BAR; PG8_WAIT_L(0); PG8_MMA(0, 0, At, B0); PG8_BAR; PG8_SCHED;
;     ...
;             PG8_LDB(B1, 1, 1); PG8_STAGE(PG8_SB(1, 0), b3, voffB);
;             PG8_BAR; PG8_WAIT_L(0); PG8_MMA(0, 1, At, B1); PG8_BAR;
;             PG8_LDA(At, 1, 1); PG8_STAGE(PG8_SA(1, 0), a3, voffA);
;             PG8_BAR; PG8_WAIT_L(0); PG8_MMA(1, 0, At, B0); PG8_BAR; PG8_SCHED;
;             PG8_STAGE(PG8_SB(1, 1), b3 + hstepB, voffB);
;             PG8_WAIT_V(6); PG8_BAR; PG8_MMA(1, 1, At, B1); PG8_BAR;
	ds_read_b128 v[162:165], v149 offset:49152
	ds_read_b128 v[166:169], v149 offset:50176
	ds_read_b128 v[170:173], v149 offset:51200
	ds_read_b128 v[174:177], v149 offset:52224
	ds_read_b128 v[178:181], v149 offset:53248
	ds_read_b128 v[182:185], v149 offset:54272
	ds_read_b128 v[186:189], v149 offset:55296
	ds_read_b128 v[190:193], v149 offset:56320
	s_add_i32 s25, s56, s30
	v_lshl_add_u64 v[210:211], v[210:211], 0, s[8:9]
	s_mov_b32 m0, s25
	s_nop 0
	global_load_lds_dwordx4 v[210:211], off
	v_lshl_add_u64 v[210:211], v[212:213], 0, s[8:9]
	s_add_i32 m0, s25, 0x2000
	s_nop 0
	global_load_lds_dwordx4 v[210:211], off
	s_mov_b32 m0, s40
	v_lshl_add_u64 v[210:211], v[216:217], 0, s[8:9]
	global_load_lds_dwordx4 v[210:211], off
	v_lshl_add_u64 v[210:211], v[218:219], 0, s[8:9]
	s_mov_b32 m0, s41
	s_nop 0
	global_load_lds_dwordx4 v[210:211], off
	s_add_u32 s20, s20, 0x80080
	s_addc_u32 s21, s21, 0
	s_add_i32 s24, s24, s30
	s_mov_b32 m0, s24
	s_nop 0
	global_load_lds_dwordx4 v136, s[20:21]
	s_add_i32 m0, s24, 0x2000
	s_nop 0
	global_load_lds_dwordx4 v132, s[20:21]
	s_add_i32 s55, s55, 2
	s_add_u32 s6, s6, 0x100
	s_addc_u32 s7, s7, 0
	s_add_u32 s53, s53, 0x100
	s_addc_u32 s54, s54, 0
	s_cmp_gt_u32 s55, 29
	s_waitcnt lgkmcnt(0)
	s_waitcnt vmcnt(6)
	s_barrier
	v_mfma_f32_16x16x32_bf16 v[64:67], v[144:147], v[162:165], v[64:67]
	v_mfma_f32_16x16x32_bf16 v[60:63], v[154:157], v[162:165], v[60:63]
	v_mfma_f32_16x16x32_bf16 v[48:51], v[144:147], v[170:173], v[48:51]
	v_mfma_f32_16x16x32_bf16 v[44:47], v[154:157], v[170:173], v[44:47]
	v_mfma_f32_16x16x32_bf16 v[32:35], v[144:147], v[178:181], v[32:35]
	v_mfma_f32_16x16x32_bf16 v[28:31], v[154:157], v[178:181], v[28:31]
	v_mfma_f32_16x16x32_bf16 v[16:19], v[144:147], v[186:189], v[16:19]
	v_mfma_f32_16x16x32_bf16 v[12:15], v[154:157], v[186:189], v[12:15]
	v_mfma_f32_16x16x32_bf16 v[64:67], v[150:153], v[166:169], v[64:67]
	v_mfma_f32_16x16x32_bf16 v[60:63], v[158:161], v[166:169], v[60:63]
	v_mfma_f32_16x16x32_bf16 v[48:51], v[150:153], v[174:177], v[48:51]
	v_mfma_f32_16x16x32_bf16 v[44:47], v[158:161], v[174:177], v[44:47]
	v_mfma_f32_16x16x32_bf16 v[32:35], v[150:153], v[182:185], v[32:35]
	v_mfma_f32_16x16x32_bf16 v[28:31], v[158:161], v[182:185], v[28:31]
	v_mfma_f32_16x16x32_bf16 v[16:19], v[150:153], v[190:193], v[16:19]
	v_mfma_f32_16x16x32_bf16 v[12:15], v[158:161], v[190:193], v[12:15]
	v_mfma_f32_16x16x32_bf16 v[56:59], v[194:197], v[162:165], v[56:59]
	v_mfma_f32_16x16x32_bf16 v[52:55], v[202:205], v[162:165], v[52:55]
	v_mfma_f32_16x16x32_bf16 v[40:43], v[194:197], v[170:173], v[40:43]
	v_mfma_f32_16x16x32_bf16 v[36:39], v[202:205], v[170:173], v[36:39]
	v_mfma_f32_16x16x32_bf16 v[24:27], v[194:197], v[178:181], v[24:27]
	v_mfma_f32_16x16x32_bf16 v[20:23], v[202:205], v[178:181], v[20:23]
	v_mfma_f32_16x16x32_bf16 v[8:11], v[194:197], v[186:189], v[8:11]
	v_mfma_f32_16x16x32_bf16 v[4:7], v[202:205], v[186:189], v[4:7]
	v_mfma_f32_16x16x32_bf16 v[56:59], v[198:201], v[166:169], v[56:59]
	v_mfma_f32_16x16x32_bf16 v[52:55], v[206:209], v[166:169], v[52:55]
	v_mfma_f32_16x16x32_bf16 v[40:43], v[198:201], v[174:177], v[40:43]
	v_mfma_f32_16x16x32_bf16 v[36:39], v[206:209], v[174:177], v[36:39]
	v_mfma_f32_16x16x32_bf16 v[24:27], v[198:201], v[182:185], v[24:27]
	v_mfma_f32_16x16x32_bf16 v[20:23], v[206:209], v[182:185], v[20:23]
	v_mfma_f32_16x16x32_bf16 v[8:11], v[198:201], v[190:193], v[8:11]
	v_mfma_f32_16x16x32_bf16 v[4:7], v[206:209], v[190:193], v[4:7]
	s_barrier
	s_setprio 0
.LBB0_352:
	s_add_u32 s20, s6, 0xfff80080
	s_addc_u32 s21, s7, -1
	s_add_i32 s56, 0, 0x10000
	v_add_u32_e32 v2, s56, v1
	ds_read_b128 v[144:147], v2
	ds_read_b128 v[150:153], v2 offset:1024
	ds_read_b128 v[154:157], v2 offset:2048
	ds_read_b128 v[158:161], v2 offset:3072
	s_cmp_eq_u32 s55, 28
	s_cselect_b32 s25, s15, s21
	s_cselect_b32 s24, s51, s20
	s_cselect_b32 s21, s1, s54
	s_cselect_b32 s20, s52, s53
	ds_read_b128 v[162:165], v149
	ds_read_b128 v[166:169], v149 offset:1024
	ds_read_b128 v[170:173], v149 offset:2048
	ds_read_b128 v[174:177], v149 offset:3072
	ds_read_b128 v[178:181], v149 offset:4096
	ds_read_b128 v[182:185], v149 offset:5120
	ds_read_b128 v[186:189], v149 offset:6144
	ds_read_b128 v[190:193], v149 offset:7168
	s_add_i32 s58, 0, 0x14000
	v_add_u32_e32 v2, s58, v1
	ds_read_b128 v[194:197], v2
	ds_read_b128 v[198:201], v2 offset:1024
	ds_read_b128 v[202:205], v2 offset:2048
	ds_read_b128 v[206:209], v2 offset:3072
	s_add_i32 m0, s31, 0xc000
	s_nop 0
	global_load_lds_dwordx4 v140, s[6:7]
	s_add_i32 m0, s31, 0xe000
	s_nop 0
	global_load_lds_dwordx4 v142, s[6:7]
	s_waitcnt lgkmcnt(0)
	s_barrier
; #define PG8_STAGE(bufoff, gbase, voff) do { _Pragma("unroll") for (int _i = 0; _i < 2; ++_i) \
;         __builtin_amdgcn_global_load_lds((const unsigned*)((const char*)(gbase) + (voff)[_i]), (LAS unsigned*)(lds + (bufoff) + ldsw + _i * 8192), 16, 0, 0); } while (0)
; #define PG8_LDA(dst, b, h) do { _Pragma("unroll") for (int m = 0; m < 4; ++m) _Pragma("unroll") for (int k = 0; k < 2; ++k) dst[m][k] = *(const LAS bf16x8*)(lds + PG8_SA(b, h) + aoff + m * 2048 + k * 1024); } while (0)
; #define PG8_LDB(dst, b, h) do { _Pragma("unroll") for (int n = 0; n < 2; ++n) _Pragma("unroll") for (int k = 0; k < 2; ++k) dst[n][k] = *(const LAS bf16x8*)(lds + PG8_SB(b, h) + boff + n * 2048 + k * 1024); } while (0)
; #define PG8_MMA(ai, bj, At, Bt) do { __builtin_amdgcn_s_setprio(1); _Pragma("unroll") for (int m = 0; m < 4; ++m) _Pragma("unroll") for (int n = 0; n < 2; ++n) _Pragma("unroll") for (int k = 0; k < 2; ++k) \
;         acc[ai][bj][m][n] = __builtin_amdgcn_mfma_f32_16x16x32_bf16(Bt[n][k], At[m][k], acc[ai][bj][m][n], 0, 0, 0); __builtin_amdgcn_s_setprio(0); } while (0)
; #define PG8_WAIT_V(n) asm volatile("s_waitcnt vmcnt(" #n ")" ::: "memory")
; #define PG8_WAIT_L(n) asm volatile("s_waitcnt lgkmcnt(" #n ")" ::: "memory")
; #define PG8_BAR __builtin_amdgcn_s_barrier()
; #define PG8_SCHED __builtin_amdgcn_sched_barrier(0)
; template <class Epi, class Sched>
; __device__ __forceinline__ void gemm_phase(LAS unsigned char* lds, const Gemm g, const Sched& S, const Epi& E) {
;     ...
;             PG8_WAIT_L(8); PG8_BAR; PG8_WAIT_L(0); PG8_MMA(0, 0, At, B0); PG8_BAR; PG8_SCHED;
;             PG8_LDB(B1, 0, 1); PG8_STAGE(PG8_SB(0, 0), b2, voffB);
;             PG8_BAR; PG8_WAIT_L(0); PG8_MMA(0, 1, At, B1); PG8_BAR;
;             PG8_LDA(At, 0, 1); PG8_STAGE(PG8_SA(0, 0), a2, voffA);
;             PG8_BAR; PG8_WAIT_L(0); PG8_MMA(1, 0, At, B0); PG8_BAR; PG8_SCHED;
;             PG8_STAGE(PG8_SB(0, 1), b2 + hstepB, voffB);
;             PG8_WAIT_V(6); PG8_BAR; PG8_MMA(1, 1, At, B1); PG8_BAR;
;             PG8_LDB(B0, 1, 0); PG8_SCHED; PG8_LDA(At, 1, 0); PG8_STAGE(PG8_SA(0, 1), a2 + hstepA, voffA);
;             PG8_WAIT_L(8); PG8_BAR; PG8_WAIT_L(0); PG8_MMA(0, 0, At, B0); PG8_BAR; PG8_SCHED;
	v_mfma_f32_16x16x32_bf16 v[128:131], v[144:147], v[162:165], v[128:131]
	v_mfma_f32_16x16x32_bf16 v[124:127], v[154:157], v[162:165], v[124:127]
	v_mfma_f32_16x16x32_bf16 v[112:115], v[144:147], v[170:173], v[112:115]
	v_mfma_f32_16x16x32_bf16 v[108:111], v[154:157], v[170:173], v[108:111]
	v_mfma_f32_16x16x32_bf16 v[96:99], v[144:147], v[178:181], v[96:99]
	v_mfma_f32_16x16x32_bf16 v[92:95], v[154:157], v[178:181], v[92:95]
	v_mfma_f32_16x16x32_bf16 v[80:83], v[144:147], v[186:189], v[80:83]
	v_mfma_f32_16x16x32_bf16 v[76:79], v[154:157], v[186:189], v[76:79]
	v_mfma_f32_16x16x32_bf16 v[128:131], v[150:153], v[166:169], v[128:131]
	v_mfma_f32_16x16x32_bf16 v[124:127], v[158:161], v[166:169], v[124:127]
	v_mfma_f32_16x16x32_bf16 v[112:115], v[150:153], v[174:177], v[112:115]
	v_mfma_f32_16x16x32_bf16 v[108:111], v[158:161], v[174:177], v[108:111]
	v_mfma_f32_16x16x32_bf16 v[96:99], v[150:153], v[182:185], v[96:99]
	v_mfma_f32_16x16x32_bf16 v[92:95], v[158:161], v[182:185], v[92:95]
	v_mfma_f32_16x16x32_bf16 v[80:83], v[150:153], v[190:193], v[80:83]
	v_mfma_f32_16x16x32_bf16 v[76:79], v[158:161], v[190:193], v[76:79]
	v_mfma_f32_16x16x32_bf16 v[120:123], v[194:197], v[162:165], v[120:123]
	v_mfma_f32_16x16x32_bf16 v[116:119], v[202:205], v[162:165], v[116:119]
	v_mfma_f32_16x16x32_bf16 v[104:107], v[194:197], v[170:173], v[104:107]
	v_mfma_f32_16x16x32_bf16 v[100:103], v[202:205], v[170:173], v[100:103]
	v_mfma_f32_16x16x32_bf16 v[88:91], v[194:197], v[178:181], v[88:91]
	v_mfma_f32_16x16x32_bf16 v[84:87], v[202:205], v[178:181], v[84:87]
	v_mfma_f32_16x16x32_bf16 v[72:75], v[194:197], v[186:189], v[72:75]
	v_mfma_f32_16x16x32_bf16 v[68:71], v[202:205], v[186:189], v[68:71]
	v_mfma_f32_16x16x32_bf16 v[120:123], v[198:201], v[166:169], v[120:123]
	v_mfma_f32_16x16x32_bf16 v[116:119], v[206:209], v[166:169], v[116:119]
	v_mfma_f32_16x16x32_bf16 v[104:107], v[198:201], v[174:177], v[104:107]
	v_mfma_f32_16x16x32_bf16 v[100:103], v[206:209], v[174:177], v[100:103]
	v_mfma_f32_16x16x32_bf16 v[88:91], v[198:201], v[182:185], v[88:91]
	v_mfma_f32_16x16x32_bf16 v[84:87], v[206:209], v[182:185], v[84:87]
	v_mfma_f32_16x16x32_bf16 v[72:75], v[198:201], v[190:193], v[72:75]
	v_mfma_f32_16x16x32_bf16 v[68:71], v[206:209], v[190:193], v[68:71]
	s_barrier
	ds_read_b128 v[162:165], v149 offset:16384
	ds_read_b128 v[166:169], v149 offset:17408
	ds_read_b128 v[170:173], v149 offset:18432
	ds_read_b128 v[174:177], v149 offset:19456
	ds_read_b128 v[178:181], v149 offset:20480
	ds_read_b128 v[182:185], v149 offset:21504
	ds_read_b128 v[186:189], v149 offset:22528
	ds_read_b128 v[190:193], v149 offset:23552
	s_add_i32 s56, s56, s30
	v_lshl_add_u64 v[210:211], s[20:21], 0, v[136:137]
	s_mov_b32 m0, s56
	s_nop 0
	global_load_lds_dwordx4 v[210:211], off
	v_lshl_add_u64 v[212:213], s[20:21], 0, v[132:133]
	s_add_i32 m0, s56, 0x2000
	s_nop 0
	global_load_lds_dwordx4 v[212:213], off
	s_mov_b32 m0, s31
	v_lshl_add_u64 v[216:217], s[24:25], 0, v[138:139]
	global_load_lds_dwordx4 v[216:217], off
	v_lshl_add_u64 v[218:219], s[24:25], 0, v[134:135]
	s_mov_b32 m0, s35
	s_nop 0
	global_load_lds_dwordx4 v[218:219], off
	s_add_u32 s56, s20, 0x80000
	s_addc_u32 s57, s21, 0
	s_add_i32 s58, s58, s30
	s_mov_b32 m0, s58
	s_nop 0
	global_load_lds_dwordx4 v136, s[56:57]
	s_add_i32 m0, s58, 0x2000
	s_nop 0
	global_load_lds_dwordx4 v132, s[56:57]
	s_waitcnt lgkmcnt(0)
	s_waitcnt vmcnt(6)
	s_barrier
	v_mfma_f32_16x16x32_bf16 v[64:67], v[144:147], v[162:165], v[64:67]
	v_mfma_f32_16x16x32_bf16 v[60:63], v[154:157], v[162:165], v[60:63]
	v_mfma_f32_16x16x32_bf16 v[48:51], v[144:147], v[170:173], v[48:51]
	v_mfma_f32_16x16x32_bf16 v[44:47], v[154:157], v[170:173], v[44:47]
	v_mfma_f32_16x16x32_bf16 v[32:35], v[144:147], v[178:181], v[32:35]
	v_mfma_f32_16x16x32_bf16 v[28:31], v[154:157], v[178:181], v[28:31]
	v_mfma_f32_16x16x32_bf16 v[16:19], v[144:147], v[186:189], v[16:19]
	v_mfma_f32_16x16x32_bf16 v[12:15], v[154:157], v[186:189], v[12:15]
	v_mfma_f32_16x16x32_bf16 v[64:67], v[150:153], v[166:169], v[64:67]
	v_mfma_f32_16x16x32_bf16 v[60:63], v[158:161], v[166:169], v[60:63]
	v_mfma_f32_16x16x32_bf16 v[48:51], v[150:153], v[174:177], v[48:51]
	v_mfma_f32_16x16x32_bf16 v[44:47], v[158:161], v[174:177], v[44:47]
	v_mfma_f32_16x16x32_bf16 v[32:35], v[150:153], v[182:185], v[32:35]
	v_mfma_f32_16x16x32_bf16 v[28:31], v[158:161], v[182:185], v[28:31]
	v_mfma_f32_16x16x32_bf16 v[16:19], v[150:153], v[190:193], v[16:19]
	v_mfma_f32_16x16x32_bf16 v[12:15], v[158:161], v[190:193], v[12:15]
	v_mfma_f32_16x16x32_bf16 v[56:59], v[194:197], v[162:165], v[56:59]
	v_mfma_f32_16x16x32_bf16 v[52:55], v[202:205], v[162:165], v[52:55]
	v_mfma_f32_16x16x32_bf16 v[40:43], v[194:197], v[170:173], v[40:43]
	v_mfma_f32_16x16x32_bf16 v[36:39], v[202:205], v[170:173], v[36:39]
	v_mfma_f32_16x16x32_bf16 v[24:27], v[194:197], v[178:181], v[24:27]
	v_mfma_f32_16x16x32_bf16 v[20:23], v[202:205], v[178:181], v[20:23]
	v_mfma_f32_16x16x32_bf16 v[8:11], v[194:197], v[186:189], v[8:11]
	v_mfma_f32_16x16x32_bf16 v[4:7], v[202:205], v[186:189], v[4:7]
	v_mfma_f32_16x16x32_bf16 v[56:59], v[198:201], v[166:169], v[56:59]
	v_mfma_f32_16x16x32_bf16 v[52:55], v[206:209], v[166:169], v[52:55]
	v_mfma_f32_16x16x32_bf16 v[40:43], v[198:201], v[174:177], v[40:43]
	v_mfma_f32_16x16x32_bf16 v[36:39], v[206:209], v[174:177], v[36:39]
	v_mfma_f32_16x16x32_bf16 v[24:27], v[198:201], v[182:185], v[24:27]
	v_mfma_f32_16x16x32_bf16 v[20:23], v[206:209], v[182:185], v[20:23]
	v_mfma_f32_16x16x32_bf16 v[8:11], v[198:201], v[190:193], v[8:11]
	v_mfma_f32_16x16x32_bf16 v[4:7], v[206:209], v[190:193], v[4:7]
	s_barrier
; #define PG8_STAGE(bufoff, gbase, voff) do { _Pragma("unroll") for (int _i = 0; _i < 2; ++_i) \
;         __builtin_amdgcn_global_load_lds((const unsigned*)((const char*)(gbase) + (voff)[_i]), (LAS unsigned*)(lds + (bufoff) + ldsw + _i * 8192), 16, 0, 0); } while (0)
; #define PG8_LDA(dst, b, h) do { _Pragma("unroll") for (int m = 0; m < 4; ++m) _Pragma("unroll") for (int k = 0; k < 2; ++k) dst[m][k] = *(const LAS bf16x8*)(lds + PG8_SA(b, h) + aoff + m * 2048 + k * 1024); } while (0)
; #define PG8_LDB(dst, b, h) do { _Pragma("unroll") for (int n = 0; n < 2; ++n) _Pragma("unroll") for (int k = 0; k < 2; ++k) dst[n][k] = *(const LAS bf16x8*)(lds + PG8_SB(b, h) + boff + n * 2048 + k * 1024); } while (0)
; #define PG8_MMA(ai, bj, At, Bt) do { __builtin_amdgcn_s_setprio(1); _Pragma("unroll") for (int m = 0; m < 4; ++m) _Pragma("unroll") for (int n = 0; n < 2; ++n) _Pragma("unroll") for (int k = 0; k < 2; ++k) \
;         acc[ai][bj][m][n] = __builtin_amdgcn_mfma_f32_16x16x32_bf16(Bt[n][k], At[m][k], acc[ai][bj][m][n], 0, 0, 0); __builtin_amdgcn_s_setprio(0); } while (0)
; #define PG8_WAIT_V(n) asm volatile("s_waitcnt vmcnt(" #n ")" ::: "memory")
; #define PG8_WAIT_L(n) asm volatile("s_waitcnt lgkmcnt(" #n ")" ::: "memory")
; #define PG8_BAR __builtin_amdgcn_s_barrier()
; #define PG8_SCHED __builtin_amdgcn_sched_barrier(0)
; template <class Epi, class Sched>
; __device__ __forceinline__ void gemm_phase(LAS unsigned char* lds, const Gemm g, const Sched& S, const Epi& E) {
;     ...
;             PG8_LDB(B0, 1, 0); PG8_SCHED; PG8_LDA(At, 1, 0); PG8_STAGE(PG8_SA(0, 1), a2 + hstepA, voffA);
;             PG8_WAIT_L(8); PG8_BAR; PG8_WAIT_L(0); PG8_MMA(0, 0, At, B0); PG8_BAR; PG8_SCHED;
;             PG8_LDB(B1, 1, 1); PG8_STAGE(PG8_SB(1, 0), b3, voffB);
;             PG8_BAR; PG8_WAIT_L(0); PG8_MMA(0, 1, At, B1); PG8_BAR;
;             PG8_LDA(At, 1, 1); PG8_STAGE(PG8_SA(1, 0), a3, voffA);
;             PG8_BAR; PG8_WAIT_L(0); PG8_MMA(1, 0, At, B0); PG8_BAR; PG8_SCHED;
;             PG8_STAGE(PG8_SB(1, 1), b3 + hstepB, voffB);
;             PG8_WAIT_V(6); PG8_BAR; PG8_MMA(1, 1, At, B1); PG8_BAR;
;         }
;     ...
;     PG8_WAIT_V(0);
;     if (wr == 0) PG8_BAR;
	s_add_i32 s56, 0, 0x18000
	v_add_u32_e32 v2, s56, v1
	ds_read_b128 v[144:147], v2
	ds_read_b128 v[150:153], v2 offset:1024
	ds_read_b128 v[154:157], v2 offset:2048
	ds_read_b128 v[158:161], v2 offset:3072
	s_add_u32 s24, s24, 0x80000
	s_addc_u32 s25, s25, 0
	ds_read_b128 v[162:165], v149 offset:32768
	ds_read_b128 v[166:169], v149 offset:33792
	ds_read_b128 v[170:173], v149 offset:34816
	ds_read_b128 v[174:177], v149 offset:35840
	ds_read_b128 v[178:181], v149 offset:36864
	ds_read_b128 v[182:185], v149 offset:37888
	ds_read_b128 v[186:189], v149 offset:38912
	ds_read_b128 v[190:193], v149 offset:39936
	s_mov_b32 m0, s36
	s_nop 0
	global_load_lds_dwordx4 v138, s[24:25]
	s_mov_b32 m0, s37
	s_nop 0
	global_load_lds_dwordx4 v134, s[24:25]
	s_add_i32 s24, 0, 0x1c000
	v_add_u32_e32 v2, s24, v1
	ds_read_b128 v[194:197], v2
	ds_read_b128 v[198:201], v2 offset:1024
	ds_read_b128 v[202:205], v2 offset:2048
	ds_read_b128 v[206:209], v2 offset:3072
	s_waitcnt lgkmcnt(0)
	s_barrier
	v_mfma_f32_16x16x32_bf16 v[128:131], v[144:147], v[162:165], v[128:131]
	v_mfma_f32_16x16x32_bf16 v[124:127], v[154:157], v[162:165], v[124:127]
	v_mfma_f32_16x16x32_bf16 v[112:115], v[144:147], v[170:173], v[112:115]
	v_mfma_f32_16x16x32_bf16 v[108:111], v[154:157], v[170:173], v[108:111]
	v_mfma_f32_16x16x32_bf16 v[96:99], v[144:147], v[178:181], v[96:99]
	v_mfma_f32_16x16x32_bf16 v[92:95], v[154:157], v[178:181], v[92:95]
	v_mfma_f32_16x16x32_bf16 v[80:83], v[144:147], v[186:189], v[80:83]
	v_mfma_f32_16x16x32_bf16 v[76:79], v[154:157], v[186:189], v[76:79]
	v_mfma_f32_16x16x32_bf16 v[128:131], v[150:153], v[166:169], v[128:131]
	v_mfma_f32_16x16x32_bf16 v[124:127], v[158:161], v[166:169], v[124:127]
	v_mfma_f32_16x16x32_bf16 v[112:115], v[150:153], v[174:177], v[112:115]
	v_mfma_f32_16x16x32_bf16 v[108:111], v[158:161], v[174:177], v[108:111]
	v_mfma_f32_16x16x32_bf16 v[96:99], v[150:153], v[182:185], v[96:99]
	v_mfma_f32_16x16x32_bf16 v[92:95], v[158:161], v[182:185], v[92:95]
	v_mfma_f32_16x16x32_bf16 v[80:83], v[150:153], v[190:193], v[80:83]
	v_mfma_f32_16x16x32_bf16 v[76:79], v[158:161], v[190:193], v[76:79]
	v_mfma_f32_16x16x32_bf16 v[120:123], v[194:197], v[162:165], v[120:123]
	v_mfma_f32_16x16x32_bf16 v[116:119], v[202:205], v[162:165], v[116:119]
	v_mfma_f32_16x16x32_bf16 v[104:107], v[194:197], v[170:173], v[104:107]
	v_mfma_f32_16x16x32_bf16 v[100:103], v[202:205], v[170:173], v[100:103]
	v_mfma_f32_16x16x32_bf16 v[88:91], v[194:197], v[178:181], v[88:91]
	v_mfma_f32_16x16x32_bf16 v[84:87], v[202:205], v[178:181], v[84:87]
	v_mfma_f32_16x16x32_bf16 v[72:75], v[194:197], v[186:189], v[72:75]
	v_mfma_f32_16x16x32_bf16 v[68:71], v[202:205], v[186:189], v[68:71]
	v_mfma_f32_16x16x32_bf16 v[120:123], v[198:201], v[166:169], v[120:123]
	v_mfma_f32_16x16x32_bf16 v[116:119], v[206:209], v[166:169], v[116:119]
	v_mfma_f32_16x16x32_bf16 v[104:107], v[198:201], v[174:177], v[104:107]
	v_mfma_f32_16x16x32_bf16 v[100:103], v[206:209], v[174:177], v[100:103]
	v_mfma_f32_16x16x32_bf16 v[88:91], v[198:201], v[182:185], v[88:91]
	v_mfma_f32_16x16x32_bf16 v[84:87], v[206:209], v[182:185], v[84:87]
	v_mfma_f32_16x16x32_bf16 v[72:75], v[198:201], v[190:193], v[72:75]
	v_mfma_f32_16x16x32_bf16 v[68:71], v[206:209], v[190:193], v[68:71]
	s_barrier
	ds_read_b128 v[162:165], v149 offset:49152
	ds_read_b128 v[166:169], v149 offset:50176
	ds_read_b128 v[170:173], v149 offset:51200
	ds_read_b128 v[174:177], v149 offset:52224
	ds_read_b128 v[178:181], v149 offset:53248
	ds_read_b128 v[182:185], v149 offset:54272
	ds_read_b128 v[186:189], v149 offset:55296
	ds_read_b128 v[190:193], v149 offset:56320
	s_add_i32 s25, s56, s30
	v_lshl_add_u64 v[210:211], v[210:211], 0, s[8:9]
	s_mov_b32 m0, s25
	s_nop 0
	global_load_lds_dwordx4 v[210:211], off
	v_lshl_add_u64 v[210:211], v[212:213], 0, s[8:9]
	s_add_i32 m0, s25, 0x2000
	s_nop 0
	global_load_lds_dwordx4 v[210:211], off
	s_mov_b32 m0, s40
	v_lshl_add_u64 v[210:211], v[216:217], 0, s[8:9]
	global_load_lds_dwordx4 v[210:211], off
	v_lshl_add_u64 v[210:211], v[218:219], 0, s[8:9]
	s_mov_b32 m0, s41
	s_nop 0
	global_load_lds_dwordx4 v[210:211], off
	s_add_u32 s20, s20, 0x80080
	s_addc_u32 s21, s21, 0
	s_add_i32 s24, s24, s30
	s_mov_b32 m0, s24
	s_nop 0
	global_load_lds_dwordx4 v136, s[20:21]
	s_add_i32 m0, s24, 0x2000
	s_nop 0
	global_load_lds_dwordx4 v132, s[20:21]
	s_add_i32 s55, s55, 2
	s_add_u32 s6, s6, 0x100
	s_addc_u32 s7, s7, 0
	s_add_u32 s53, s53, 0x100
	s_addc_u32 s54, s54, 0
	s_cmp_gt_u32 s55, 29
	s_waitcnt lgkmcnt(0)
	s_waitcnt vmcnt(6)
	s_barrier
	v_mfma_f32_16x16x32_bf16 v[64:67], v[144:147], v[162:165], v[64:67]
	v_mfma_f32_16x16x32_bf16 v[60:63], v[154:157], v[162:165], v[60:63]
	v_mfma_f32_16x16x32_bf16 v[48:51], v[144:147], v[170:173], v[48:51]
	v_mfma_f32_16x16x32_bf16 v[44:47], v[154:157], v[170:173], v[44:47]
	v_mfma_f32_16x16x32_bf16 v[32:35], v[144:147], v[178:181], v[32:35]
	v_mfma_f32_16x16x32_bf16 v[28:31], v[154:157], v[178:181], v[28:31]
	v_mfma_f32_16x16x32_bf16 v[16:19], v[144:147], v[186:189], v[16:19]
	v_mfma_f32_16x16x32_bf16 v[12:15], v[154:157], v[186:189], v[12:15]
	v_mfma_f32_16x16x32_bf16 v[64:67], v[150:153], v[166:169], v[64:67]
	v_mfma_f32_16x16x32_bf16 v[60:63], v[158:161], v[166:169], v[60:63]
	v_mfma_f32_16x16x32_bf16 v[48:51], v[150:153], v[174:177], v[48:51]
	v_mfma_f32_16x16x32_bf16 v[44:47], v[158:161], v[174:177], v[44:47]
	v_mfma_f32_16x16x32_bf16 v[32:35], v[150:153], v[182:185], v[32:35]
	v_mfma_f32_16x16x32_bf16 v[28:31], v[158:161], v[182:185], v[28:31]
	v_mfma_f32_16x16x32_bf16 v[16:19], v[150:153], v[190:193], v[16:19]
	v_mfma_f32_16x16x32_bf16 v[12:15], v[158:161], v[190:193], v[12:15]
	v_mfma_f32_16x16x32_bf16 v[56:59], v[194:197], v[162:165], v[56:59]
	v_mfma_f32_16x16x32_bf16 v[52:55], v[202:205], v[162:165], v[52:55]
	v_mfma_f32_16x16x32_bf16 v[40:43], v[194:197], v[170:173], v[40:43]
	v_mfma_f32_16x16x32_bf16 v[36:39], v[202:205], v[170:173], v[36:39]
	v_mfma_f32_16x16x32_bf16 v[24:27], v[194:197], v[178:181], v[24:27]
	v_mfma_f32_16x16x32_bf16 v[20:23], v[202:205], v[178:181], v[20:23]
	v_mfma_f32_16x16x32_bf16 v[8:11], v[194:197], v[186:189], v[8:11]
	v_mfma_f32_16x16x32_bf16 v[4:7], v[202:205], v[186:189], v[4:7]
	v_mfma_f32_16x16x32_bf16 v[56:59], v[198:201], v[166:169], v[56:59]
	v_mfma_f32_16x16x32_bf16 v[52:55], v[206:209], v[166:169], v[52:55]
	v_mfma_f32_16x16x32_bf16 v[40:43], v[198:201], v[174:177], v[40:43]
	v_mfma_f32_16x16x32_bf16 v[36:39], v[206:209], v[174:177], v[36:39]
	v_mfma_f32_16x16x32_bf16 v[24:27], v[198:201], v[182:185], v[24:27]
	v_mfma_f32_16x16x32_bf16 v[20:23], v[206:209], v[182:185], v[20:23]
	v_mfma_f32_16x16x32_bf16 v[8:11], v[198:201], v[190:193], v[8:11]
	v_mfma_f32_16x16x32_bf16 v[4:7], v[206:209], v[190:193], v[4:7]
	s_barrier
	s_cbranch_scc0 .LBB0_352
	s_cmpk_gt_u32 s2, 0xff
	s_cbranch_scc1 .Lalign_a_352
	s_barrier

; #define PG8_STAGE(bufoff, gbase, voff) do { _Pragma("unroll") for (int _i = 0; _i < 2; ++_i) \
;         __builtin_amdgcn_global_load_lds((const unsigned*)((const char*)(gbase) + (voff)[_i]), (LAS unsigned*)(lds + (bufoff) + ldsw + _i * 8192), 16, 0, 0); } while (0)
; #define PG8_LDA(dst, b, h) do { _Pragma("unroll") for (int m = 0; m < 4; ++m) _Pragma("unroll") for (int k = 0; k < 2; ++k) dst[m][k] = *(const LAS bf16x8*)(lds + PG8_SA(b, h) + aoff + m * 2048 + k * 1024); } while (0)
; #define PG8_LDB(dst, b, h) do { _Pragma("unroll") for (int n = 0; n < 2; ++n) _Pragma("unroll") for (int k = 0; k < 2; ++k) dst[n][k] = *(const LAS bf16x8*)(lds + PG8_SB(b, h) + boff + n * 2048 + k * 1024); } while (0)
; #define PG8_WAIT_V(n) asm volatile("s_waitcnt vmcnt(" #n ")" ::: "memory")
; #define PG8_WAIT_L(n) asm volatile("s_waitcnt lgkmcnt(" #n ")" ::: "memory")
; #define PG8_BAR __builtin_amdgcn_s_barrier()
; #define PG8_SCHED __builtin_amdgcn_sched_barrier(0)
; template <class Epi, class Sched>
; __device__ __forceinline__ void gemm_phase(LAS unsigned char* lds, const Gemm g, const Sched& S, const Epi& E) {
;     ...
;         const bool has_next = S.next(ui + 1, nxt);
;         const char* nA = has_next ? (const char*)g.A + (size_t)nxt.pm * tstepA : cA; const char* nB = has_next ? (const char*)g.Bt + (size_t)nxt.pn * tstepB : cB;
;         for (int t = 0; t < nt; t += 2) {
;             const bool last = (t == nt - 2);
;             const char* a1 = cA + (size_t)(t + 1) * kstep;
;             const char* a2 = last ? nA : cA + (size_t)(t + 2) * kstep; const char* b2 = last ? nB : cB + (size_t)(t + 2) * kstep;
;             const char* a3 = a2 + kstep; const char* b3 = b2 + kstep;
;             if (last && has_next) S.a_ready(nxt);
;             PG8_LDB(B0, 0, 0); PG8_SCHED; PG8_LDA(At, 0, 0); PG8_STAGE(PG8_SA(1, 1), a1 + hstepA, voffA);
;             PG8_WAIT_L(8); PG8_BAR; PG8_WAIT_L(0); PG8_MMA(0, 0, At, B0); PG8_BAR; PG8_SCHED;
;             PG8_LDB(B1, 0, 1); PG8_STAGE(PG8_SB(0, 0), b2, voffB);
;             PG8_BAR; PG8_WAIT_L(0); PG8_MMA(0, 1, At, B1); PG8_BAR;
;             PG8_LDA(At, 0, 1); PG8_STAGE(PG8_SA(0, 0), a2, voffA);
;             PG8_BAR; PG8_WAIT_L(0); PG8_MMA(1, 0, At, B0); PG8_BAR; PG8_SCHED;
;             PG8_STAGE(PG8_SB(0, 1), b2 + hstepB, voffB);
;             PG8_WAIT_V(6); PG8_BAR; PG8_MMA(1, 1, At, B1); PG8_BAR;
.LBB0_490:
	s_ashr_i32 s53, s52, 31
	s_lshl_b64 s[18:19], s[52:53], 20
	s_add_u32 s54, s25, s18
	v_cmp_lt_i64_e64 s[14:15], s[14:15], 16
	s_addc_u32 s55, s28, s19
	s_and_b64 s[18:19], s[14:15], exec
	s_cselect_b32 s18, s55, s5
	s_cselect_b32 s19, s54, s4
	s_ashr_i32 s51, s50, 31
	s_lshl_b64 s[56:57], s[50:51], 21
	s_add_u32 s56, s44, s56
	s_addc_u32 s57, s45, s57
	s_and_b64 s[14:15], s[14:15], exec
	s_cselect_b32 s51, s57, s7
	s_cselect_b32 s53, s56, s6
	s_add_u32 s4, s4, 0x80080
	s_addc_u32 s5, s5, 0
	s_add_u32 s65, s6, 0x100
	s_addc_u32 s66, s7, 0
	s_mov_b32 s67, -2
	s_waitcnt lgkmcnt(0)
	s_add_u32 s6, s4, 0xfff80080
	s_addc_u32 s7, s5, -1
	s_add_i32 s68, 0, 0x10000
	v_add_u32_e32 v154, s68, v1
	ds_read_b128 v[142:145], v154
	ds_read_b128 v[146:149], v154 offset:1024
	ds_read_b128 v[150:153], v154 offset:2048
	ds_read_b128 v[158:161], v154 offset:3072
	s_cmp_eq_u32 s67, 60
	s_cselect_b32 s15, s18, s7
	s_cselect_b32 s14, s19, s6
	s_cselect_b32 s7, s51, s66
	s_cselect_b32 s6, s53, s65
	ds_read_b128 v[162:165], v156
	ds_read_b128 v[166:169], v156 offset:1024
	ds_read_b128 v[170:173], v156 offset:2048
	ds_read_b128 v[174:177], v156 offset:3072
	ds_read_b128 v[178:181], v156 offset:4096
	ds_read_b128 v[182:185], v156 offset:5120
	ds_read_b128 v[186:189], v156 offset:6144
	ds_read_b128 v[190:193], v156 offset:7168
	s_add_i32 s70, 0, 0x14000
	v_add_u32_e32 v154, s70, v1
	ds_read_b128 v[194:197], v154
	ds_read_b128 v[198:201], v154 offset:1024
	ds_read_b128 v[202:205], v154 offset:2048
	ds_read_b128 v[206:209], v154 offset:3072
	s_add_i32 m0, s30, 0xc000
	s_nop 0
	global_load_lds_dwordx4 v138, s[4:5]
	s_add_i32 m0, s30, 0xe000
	s_nop 0
	global_load_lds_dwordx4 v140, s[4:5]
	s_waitcnt lgkmcnt(0)
	s_barrier
	v_mfma_f32_16x16x32_bf16 v[128:131], v[142:145], v[162:165], 0
	v_mfma_f32_16x16x32_bf16 v[124:127], v[150:153], v[162:165], 0
	v_mfma_f32_16x16x32_bf16 v[120:123], v[142:145], v[170:173], 0
	v_mfma_f32_16x16x32_bf16 v[116:119], v[150:153], v[170:173], 0
	v_mfma_f32_16x16x32_bf16 v[112:115], v[142:145], v[178:181], 0
	v_mfma_f32_16x16x32_bf16 v[108:111], v[150:153], v[178:181], 0
	v_mfma_f32_16x16x32_bf16 v[104:107], v[142:145], v[186:189], 0
	v_mfma_f32_16x16x32_bf16 v[100:103], v[150:153], v[186:189], 0
	v_mfma_f32_16x16x32_bf16 v[128:131], v[146:149], v[166:169], v[128:131]
	v_mfma_f32_16x16x32_bf16 v[124:127], v[158:161], v[166:169], v[124:127]
	v_mfma_f32_16x16x32_bf16 v[120:123], v[146:149], v[174:177], v[120:123]
	v_mfma_f32_16x16x32_bf16 v[116:119], v[158:161], v[174:177], v[116:119]
	v_mfma_f32_16x16x32_bf16 v[112:115], v[146:149], v[182:185], v[112:115]
	v_mfma_f32_16x16x32_bf16 v[108:111], v[158:161], v[182:185], v[108:111]
	v_mfma_f32_16x16x32_bf16 v[104:107], v[146:149], v[190:193], v[104:107]
	v_mfma_f32_16x16x32_bf16 v[100:103], v[158:161], v[190:193], v[100:103]
	v_mfma_f32_16x16x32_bf16 v[64:67], v[194:197], v[162:165], 0
	v_mfma_f32_16x16x32_bf16 v[60:63], v[202:205], v[162:165], 0
	v_mfma_f32_16x16x32_bf16 v[56:59], v[194:197], v[170:173], 0
	v_mfma_f32_16x16x32_bf16 v[52:55], v[202:205], v[170:173], 0
	v_mfma_f32_16x16x32_bf16 v[48:51], v[194:197], v[178:181], 0
	v_mfma_f32_16x16x32_bf16 v[44:47], v[202:205], v[178:181], 0
	v_mfma_f32_16x16x32_bf16 v[40:43], v[194:197], v[186:189], 0
	v_mfma_f32_16x16x32_bf16 v[36:39], v[202:205], v[186:189], 0
	v_mfma_f32_16x16x32_bf16 v[64:67], v[198:201], v[166:169], v[64:67]
	v_mfma_f32_16x16x32_bf16 v[60:63], v[206:209], v[166:169], v[60:63]
	v_mfma_f32_16x16x32_bf16 v[56:59], v[198:201], v[174:177], v[56:59]
	v_mfma_f32_16x16x32_bf16 v[52:55], v[206:209], v[174:177], v[52:55]
	v_mfma_f32_16x16x32_bf16 v[48:51], v[198:201], v[182:185], v[48:51]
	v_mfma_f32_16x16x32_bf16 v[44:47], v[206:209], v[182:185], v[44:47]
	v_mfma_f32_16x16x32_bf16 v[40:43], v[198:201], v[190:193], v[40:43]
	v_mfma_f32_16x16x32_bf16 v[36:39], v[206:209], v[190:193], v[36:39]
	s_barrier
	ds_read_b128 v[162:165], v156 offset:16384
	ds_read_b128 v[166:169], v156 offset:17408
	ds_read_b128 v[170:173], v156 offset:18432
	ds_read_b128 v[174:177], v156 offset:19456
	ds_read_b128 v[178:181], v156 offset:20480
	ds_read_b128 v[182:185], v156 offset:21504
	ds_read_b128 v[186:189], v156 offset:22528
	ds_read_b128 v[190:193], v156 offset:23552
	s_add_i32 s68, s68, s29
	v_lshl_add_u64 v[154:155], s[6:7], 0, v[2:3]
	s_mov_b32 m0, s68
	v_lshl_add_u64 v[210:211], s[6:7], 0, v[136:137]
	global_load_lds_dwordx4 v[154:155], off
	s_add_i32 m0, s68, 0x2000
	s_nop 0
	global_load_lds_dwordx4 v[210:211], off
	s_mov_b32 m0, s30
	v_lshl_add_u64 v[212:213], s[14:15], 0, v[132:133]
	global_load_lds_dwordx4 v[212:213], off
	v_lshl_add_u64 v[216:217], s[14:15], 0, v[134:135]
	s_mov_b32 m0, s31
	s_nop 0
	global_load_lds_dwordx4 v[216:217], off
	s_add_u32 s68, s6, 0x100000
	s_addc_u32 s69, s7, 0
	s_add_i32 s70, s70, s29
	s_mov_b32 m0, s70
	s_nop 0
	global_load_lds_dwordx4 v2, s[68:69]
	s_add_i32 m0, s70, 0x2000
	s_nop 0
	global_load_lds_dwordx4 v136, s[68:69]
	s_waitcnt lgkmcnt(0)
	s_waitcnt vmcnt(6)
	s_barrier
; #define PG8_STAGE(bufoff, gbase, voff) do { _Pragma("unroll") for (int _i = 0; _i < 2; ++_i) \
;         __builtin_amdgcn_global_load_lds((const unsigned*)((const char*)(gbase) + (voff)[_i]), (LAS unsigned*)(lds + (bufoff) + ldsw + _i * 8192), 16, 0, 0); } while (0)
; #define PG8_LDA(dst, b, h) do { _Pragma("unroll") for (int m = 0; m < 4; ++m) _Pragma("unroll") for (int k = 0; k < 2; ++k) dst[m][k] = *(const LAS bf16x8*)(lds + PG8_SA(b, h) + aoff + m * 2048 + k * 1024); } while (0)
; #define PG8_LDB(dst, b, h) do { _Pragma("unroll") for (int n = 0; n < 2; ++n) _Pragma("unroll") for (int k = 0; k < 2; ++k) dst[n][k] = *(const LAS bf16x8*)(lds + PG8_SB(b, h) + boff + n * 2048 + k * 1024); } while (0)
; #define PG8_MMA(ai, bj, At, Bt) do { __builtin_amdgcn_s_setprio(1); _Pragma("unroll") for (int m = 0; m < 4; ++m) _Pragma("unroll") for (int n = 0; n < 2; ++n) _Pragma("unroll") for (int k = 0; k < 2; ++k) \
;         acc[ai][bj][m][n] = __builtin_amdgcn_mfma_f32_16x16x32_bf16(Bt[n][k], At[m][k], acc[ai][bj][m][n], 0, 0, 0); __builtin_amdgcn_s_setprio(0); } while (0)
; #define PG8_WAIT_V(n) asm volatile("s_waitcnt vmcnt(" #n ")" ::: "memory")
; #define PG8_WAIT_L(n) asm volatile("s_waitcnt lgkmcnt(" #n ")" ::: "memory")
; #define PG8_BAR __builtin_amdgcn_s_barrier()
; #define PG8_SCHED __builtin_amdgcn_sched_barrier(0)
; template <class Epi, class Sched>
; __device__ __forceinline__ void gemm_phase(LAS unsigned char* lds, const Gemm g, const Sched& S, const Epi& E) {
;     ...
;             PG8_BAR; PG8_WAIT_L(0); PG8_MMA(0, 1, At, B1); PG8_BAR;
;             PG8_LDA(At, 0, 1); PG8_STAGE(PG8_SA(0, 0), a2, voffA);
;             PG8_BAR; PG8_WAIT_L(0); PG8_MMA(1, 0, At, B0); PG8_BAR; PG8_SCHED;
;             PG8_STAGE(PG8_SB(0, 1), b2 + hstepB, voffB);
;             PG8_WAIT_V(6); PG8_BAR; PG8_MMA(1, 1, At, B1); PG8_BAR;
;             PG8_LDB(B0, 1, 0); PG8_SCHED; PG8_LDA(At, 1, 0); PG8_STAGE(PG8_SA(0, 1), a2 + hstepA, voffA);
;             PG8_WAIT_L(8); PG8_BAR; PG8_WAIT_L(0); PG8_MMA(0, 0, At, B0); PG8_BAR; PG8_SCHED;
;             PG8_LDB(B1, 1, 1); PG8_STAGE(PG8_SB(1, 0), b3, voffB);
;             PG8_BAR; PG8_WAIT_L(0); PG8_MMA(0, 1, At, B1); PG8_BAR;
	v_mfma_f32_16x16x32_bf16 v[96:99], v[142:145], v[162:165], 0
	v_mfma_f32_16x16x32_bf16 v[92:95], v[150:153], v[162:165], 0
	v_mfma_f32_16x16x32_bf16 v[88:91], v[142:145], v[170:173], 0
	v_mfma_f32_16x16x32_bf16 v[84:87], v[150:153], v[170:173], 0
	v_mfma_f32_16x16x32_bf16 v[80:83], v[142:145], v[178:181], 0
	v_mfma_f32_16x16x32_bf16 v[76:79], v[150:153], v[178:181], 0
	v_mfma_f32_16x16x32_bf16 v[72:75], v[142:145], v[186:189], 0
	v_mfma_f32_16x16x32_bf16 v[68:71], v[150:153], v[186:189], 0
	v_mfma_f32_16x16x32_bf16 v[96:99], v[146:149], v[166:169], v[96:99]
	v_mfma_f32_16x16x32_bf16 v[92:95], v[158:161], v[166:169], v[92:95]
	v_mfma_f32_16x16x32_bf16 v[88:91], v[146:149], v[174:177], v[88:91]
	v_mfma_f32_16x16x32_bf16 v[84:87], v[158:161], v[174:177], v[84:87]
	v_mfma_f32_16x16x32_bf16 v[80:83], v[146:149], v[182:185], v[80:83]
	v_mfma_f32_16x16x32_bf16 v[76:79], v[158:161], v[182:185], v[76:79]
	v_mfma_f32_16x16x32_bf16 v[72:75], v[146:149], v[190:193], v[72:75]
	v_mfma_f32_16x16x32_bf16 v[68:71], v[158:161], v[190:193], v[68:71]
	v_mfma_f32_16x16x32_bf16 v[32:35], v[194:197], v[162:165], 0
	v_mfma_f32_16x16x32_bf16 v[28:31], v[202:205], v[162:165], 0
	v_mfma_f32_16x16x32_bf16 v[24:27], v[194:197], v[170:173], 0
	v_mfma_f32_16x16x32_bf16 v[20:23], v[202:205], v[170:173], 0
	v_mfma_f32_16x16x32_bf16 v[16:19], v[194:197], v[178:181], 0
	v_mfma_f32_16x16x32_bf16 v[12:15], v[202:205], v[178:181], 0
	v_mfma_f32_16x16x32_bf16 v[8:11], v[194:197], v[186:189], 0
	v_mfma_f32_16x16x32_bf16 v[4:7], v[202:205], v[186:189], 0
	v_mfma_f32_16x16x32_bf16 v[32:35], v[198:201], v[166:169], v[32:35]
	v_mfma_f32_16x16x32_bf16 v[28:31], v[206:209], v[166:169], v[28:31]
	v_mfma_f32_16x16x32_bf16 v[24:27], v[198:201], v[174:177], v[24:27]
	v_mfma_f32_16x16x32_bf16 v[20:23], v[206:209], v[174:177], v[20:23]
	v_mfma_f32_16x16x32_bf16 v[16:19], v[198:201], v[182:185], v[16:19]
	v_mfma_f32_16x16x32_bf16 v[12:15], v[206:209], v[182:185], v[12:15]
	v_mfma_f32_16x16x32_bf16 v[8:11], v[198:201], v[190:193], v[8:11]
	v_mfma_f32_16x16x32_bf16 v[4:7], v[206:209], v[190:193], v[4:7]
	s_barrier
	s_add_i32 s68, 0, 0x18000
	v_add_u32_e32 v157, s68, v1
	ds_read_b128 v[142:145], v157
	ds_read_b128 v[146:149], v157 offset:1024
	ds_read_b128 v[150:153], v157 offset:2048
	ds_read_b128 v[158:161], v157 offset:3072
	s_add_u32 s14, s14, 0x80000
	s_addc_u32 s15, s15, 0
	ds_read_b128 v[162:165], v156 offset:32768
	ds_read_b128 v[166:169], v156 offset:33792
	ds_read_b128 v[170:173], v156 offset:34816
	ds_read_b128 v[174:177], v156 offset:35840
	ds_read_b128 v[178:181], v156 offset:36864
	ds_read_b128 v[182:185], v156 offset:37888
	ds_read_b128 v[186:189], v156 offset:38912
	ds_read_b128 v[190:193], v156 offset:39936
	s_mov_b32 m0, s38
	s_nop 0
	global_load_lds_dwordx4 v132, s[14:15]
	s_mov_b32 m0, s39
	s_nop 0
	global_load_lds_dwordx4 v134, s[14:15]
	s_add_i32 s14, 0, 0x1c000
	v_add_u32_e32 v157, s14, v1
	ds_read_b128 v[194:197], v157
	ds_read_b128 v[198:201], v157 offset:1024
	ds_read_b128 v[202:205], v157 offset:2048
	ds_read_b128 v[206:209], v157 offset:3072
	s_waitcnt lgkmcnt(0)
	s_barrier
	v_mfma_f32_16x16x32_bf16 v[128:131], v[142:145], v[162:165], v[128:131]
	v_mfma_f32_16x16x32_bf16 v[124:127], v[150:153], v[162:165], v[124:127]
	v_mfma_f32_16x16x32_bf16 v[120:123], v[142:145], v[170:173], v[120:123]
	v_mfma_f32_16x16x32_bf16 v[116:119], v[150:153], v[170:173], v[116:119]
	v_mfma_f32_16x16x32_bf16 v[112:115], v[142:145], v[178:181], v[112:115]
	v_mfma_f32_16x16x32_bf16 v[108:111], v[150:153], v[178:181], v[108:111]
	v_mfma_f32_16x16x32_bf16 v[104:107], v[142:145], v[186:189], v[104:107]
	v_mfma_f32_16x16x32_bf16 v[100:103], v[150:153], v[186:189], v[100:103]
	v_mfma_f32_16x16x32_bf16 v[128:131], v[146:149], v[166:169], v[128:131]
	v_mfma_f32_16x16x32_bf16 v[124:127], v[158:161], v[166:169], v[124:127]
	v_mfma_f32_16x16x32_bf16 v[120:123], v[146:149], v[174:177], v[120:123]
	v_mfma_f32_16x16x32_bf16 v[116:119], v[158:161], v[174:177], v[116:119]
	v_mfma_f32_16x16x32_bf16 v[112:115], v[146:149], v[182:185], v[112:115]
	v_mfma_f32_16x16x32_bf16 v[108:111], v[158:161], v[182:185], v[108:111]
	v_mfma_f32_16x16x32_bf16 v[104:107], v[146:149], v[190:193], v[104:107]
	v_mfma_f32_16x16x32_bf16 v[100:103], v[158:161], v[190:193], v[100:103]
	v_mfma_f32_16x16x32_bf16 v[64:67], v[194:197], v[162:165], v[64:67]
	v_mfma_f32_16x16x32_bf16 v[60:63], v[202:205], v[162:165], v[60:63]
	v_mfma_f32_16x16x32_bf16 v[56:59], v[194:197], v[170:173], v[56:59]
	v_mfma_f32_16x16x32_bf16 v[52:55], v[202:205], v[170:173], v[52:55]
	v_mfma_f32_16x16x32_bf16 v[48:51], v[194:197], v[178:181], v[48:51]
	v_mfma_f32_16x16x32_bf16 v[44:47], v[202:205], v[178:181], v[44:47]
	v_mfma_f32_16x16x32_bf16 v[40:43], v[194:197], v[186:189], v[40:43]
	v_mfma_f32_16x16x32_bf16 v[36:39], v[202:205], v[186:189], v[36:39]
	v_mfma_f32_16x16x32_bf16 v[64:67], v[198:201], v[166:169], v[64:67]
	v_mfma_f32_16x16x32_bf16 v[60:63], v[206:209], v[166:169], v[60:63]
	v_mfma_f32_16x16x32_bf16 v[56:59], v[198:201], v[174:177], v[56:59]
	v_mfma_f32_16x16x32_bf16 v[52:55], v[206:209], v[174:177], v[52:55]
	v_mfma_f32_16x16x32_bf16 v[48:51], v[198:201], v[182:185], v[48:51]
	v_mfma_f32_16x16x32_bf16 v[44:47], v[206:209], v[182:185], v[44:47]
	v_mfma_f32_16x16x32_bf16 v[40:43], v[198:201], v[190:193], v[40:43]
	v_mfma_f32_16x16x32_bf16 v[36:39], v[206:209], v[190:193], v[36:39]
	s_barrier
; #define PG8_STAGE(bufoff, gbase, voff) do { _Pragma("unroll") for (int _i = 0; _i < 2; ++_i) \
;         __builtin_amdgcn_global_load_lds((const unsigned*)((const char*)(gbase) + (voff)[_i]), (LAS unsigned*)(lds + (bufoff) + ldsw + _i * 8192), 16, 0, 0); } while (0)
; #define PG8_LDA(dst, b, h) do { _Pragma("unroll") for (int m = 0; m < 4; ++m) _Pragma("unroll") for (int k = 0; k < 2; ++k) dst[m][k] = *(const LAS bf16x8*)(lds + PG8_SA(b, h) + aoff + m * 2048 + k * 1024); } while (0)
; #define PG8_LDB(dst, b, h) do { _Pragma("unroll") for (int n = 0; n < 2; ++n) _Pragma("unroll") for (int k = 0; k < 2; ++k) dst[n][k] = *(const LAS bf16x8*)(lds + PG8_SB(b, h) + boff + n * 2048 + k * 1024); } while (0)
; #define PG8_MMA(ai, bj, At, Bt) do { __builtin_amdgcn_s_setprio(1); _Pragma("unroll") for (int m = 0; m < 4; ++m) _Pragma("unroll") for (int n = 0; n < 2; ++n) _Pragma("unroll") for (int k = 0; k < 2; ++k) \
;         acc[ai][bj][m][n] = __builtin_amdgcn_mfma_f32_16x16x32_bf16(Bt[n][k], At[m][k], acc[ai][bj][m][n], 0, 0, 0); __builtin_amdgcn_s_setprio(0); } while (0)
; #define PG8_WAIT_V(n) asm volatile("s_waitcnt vmcnt(" #n ")" ::: "memory")
; #define PG8_BAR __builtin_amdgcn_s_barrier()
; template <class Epi, class Sched>
; __device__ __forceinline__ void gemm_phase(LAS unsigned char* lds, const Gemm g, const Sched& S, const Epi& E) {
;     ...
;         for (int t = 0; t < nt; t += 2) {
;             const bool last = (t == nt - 2);
;             const char* a1 = cA + (size_t)(t + 1) * kstep;
;             const char* a2 = last ? nA : cA + (size_t)(t + 2) * kstep; const char* b2 = last ? nB : cB + (size_t)(t + 2) * kstep;
;             const char* a3 = a2 + kstep; const char* b3 = b2 + kstep;
;             if (last && has_next) S.a_ready(nxt);
;             PG8_LDB(B0, 0, 0); PG8_SCHED; PG8_LDA(At, 0, 0); PG8_STAGE(PG8_SA(1, 1), a1 + hstepA, voffA);
;             PG8_WAIT_L(8); PG8_BAR; PG8_WAIT_L(0); PG8_MMA(0, 0, At, B0); PG8_BAR; PG8_SCHED;
;     ...
;             PG8_LDB(B1, 1, 1); PG8_STAGE(PG8_SB(1, 0), b3, voffB);
;             PG8_BAR; PG8_WAIT_L(0); PG8_MMA(0, 1, At, B1); PG8_BAR;
;             PG8_LDA(At, 1, 1); PG8_STAGE(PG8_SA(1, 0), a3, voffA);
;             PG8_BAR; PG8_WAIT_L(0); PG8_MMA(1, 0, At, B0); PG8_BAR; PG8_SCHED;
;             PG8_STAGE(PG8_SB(1, 1), b3 + hstepB, voffB);
;             PG8_WAIT_V(6); PG8_BAR; PG8_MMA(1, 1, At, B1); PG8_BAR;
	ds_read_b128 v[162:165], v156 offset:49152
	ds_read_b128 v[166:169], v156 offset:50176
	ds_read_b128 v[170:173], v156 offset:51200
	ds_read_b128 v[174:177], v156 offset:52224
	ds_read_b128 v[178:181], v156 offset:53248
	ds_read_b128 v[182:185], v156 offset:54272
	ds_read_b128 v[186:189], v156 offset:55296
	ds_read_b128 v[190:193], v156 offset:56320
	s_add_i32 s15, s68, s29
	v_lshl_add_u64 v[154:155], v[154:155], 0, s[8:9]
	s_mov_b32 m0, s15
	s_nop 0
	global_load_lds_dwordx4 v[154:155], off
	v_lshl_add_u64 v[154:155], v[210:211], 0, s[8:9]
	s_add_i32 m0, s15, 0x2000
	s_nop 0
	global_load_lds_dwordx4 v[154:155], off
	s_mov_b32 m0, s62
	v_lshl_add_u64 v[154:155], v[212:213], 0, s[8:9]
	global_load_lds_dwordx4 v[154:155], off
	v_lshl_add_u64 v[154:155], v[216:217], 0, s[8:9]
	s_mov_b32 m0, s63
	s_nop 0
	global_load_lds_dwordx4 v[154:155], off
	s_add_u32 s6, s6, 0x100080
	s_addc_u32 s7, s7, 0
	s_add_i32 s14, s14, s29
	s_mov_b32 m0, s14
	s_nop 0
	global_load_lds_dwordx4 v2, s[6:7]
	s_add_i32 m0, s14, 0x2000
	s_nop 0
	global_load_lds_dwordx4 v136, s[6:7]
	s_add_i32 s67, s67, 2
	s_add_u32 s4, s4, 0x100
	s_addc_u32 s5, s5, 0
	s_add_u32 s65, s65, 0x100
	s_addc_u32 s66, s66, 0
	s_cmp_gt_u32 s67, 61
	s_waitcnt lgkmcnt(0)
	s_waitcnt vmcnt(6)
	s_barrier
	v_mfma_f32_16x16x32_bf16 v[96:99], v[142:145], v[162:165], v[96:99]
	v_mfma_f32_16x16x32_bf16 v[92:95], v[150:153], v[162:165], v[92:95]
	v_mfma_f32_16x16x32_bf16 v[88:91], v[142:145], v[170:173], v[88:91]
	v_mfma_f32_16x16x32_bf16 v[84:87], v[150:153], v[170:173], v[84:87]
	v_mfma_f32_16x16x32_bf16 v[80:83], v[142:145], v[178:181], v[80:83]
	v_mfma_f32_16x16x32_bf16 v[76:79], v[150:153], v[178:181], v[76:79]
	v_mfma_f32_16x16x32_bf16 v[72:75], v[142:145], v[186:189], v[72:75]
	v_mfma_f32_16x16x32_bf16 v[68:71], v[150:153], v[186:189], v[68:71]
	v_mfma_f32_16x16x32_bf16 v[96:99], v[146:149], v[166:169], v[96:99]
	v_mfma_f32_16x16x32_bf16 v[92:95], v[158:161], v[166:169], v[92:95]
	v_mfma_f32_16x16x32_bf16 v[88:91], v[146:149], v[174:177], v[88:91]
	v_mfma_f32_16x16x32_bf16 v[84:87], v[158:161], v[174:177], v[84:87]
	v_mfma_f32_16x16x32_bf16 v[80:83], v[146:149], v[182:185], v[80:83]
	v_mfma_f32_16x16x32_bf16 v[76:79], v[158:161], v[182:185], v[76:79]
	v_mfma_f32_16x16x32_bf16 v[72:75], v[146:149], v[190:193], v[72:75]
	v_mfma_f32_16x16x32_bf16 v[68:71], v[158:161], v[190:193], v[68:71]
	v_mfma_f32_16x16x32_bf16 v[32:35], v[194:197], v[162:165], v[32:35]
	v_mfma_f32_16x16x32_bf16 v[28:31], v[202:205], v[162:165], v[28:31]
	v_mfma_f32_16x16x32_bf16 v[24:27], v[194:197], v[170:173], v[24:27]
	v_mfma_f32_16x16x32_bf16 v[20:23], v[202:205], v[170:173], v[20:23]
	v_mfma_f32_16x16x32_bf16 v[16:19], v[194:197], v[178:181], v[16:19]
	v_mfma_f32_16x16x32_bf16 v[12:15], v[202:205], v[178:181], v[12:15]
	v_mfma_f32_16x16x32_bf16 v[8:11], v[194:197], v[186:189], v[8:11]
	v_mfma_f32_16x16x32_bf16 v[4:7], v[202:205], v[186:189], v[4:7]
	v_mfma_f32_16x16x32_bf16 v[32:35], v[198:201], v[166:169], v[32:35]
	v_mfma_f32_16x16x32_bf16 v[28:31], v[206:209], v[166:169], v[28:31]
	v_mfma_f32_16x16x32_bf16 v[24:27], v[198:201], v[174:177], v[24:27]
	v_mfma_f32_16x16x32_bf16 v[20:23], v[206:209], v[174:177], v[20:23]
	v_mfma_f32_16x16x32_bf16 v[16:19], v[198:201], v[182:185], v[16:19]
	v_mfma_f32_16x16x32_bf16 v[12:15], v[206:209], v[182:185], v[12:15]
	v_mfma_f32_16x16x32_bf16 v[8:11], v[198:201], v[190:193], v[8:11]
	v_mfma_f32_16x16x32_bf16 v[4:7], v[206:209], v[190:193], v[4:7]
	s_barrier
	s_setprio 0
.LBB0_491:
	s_add_u32 s6, s4, 0xfff80080
	s_addc_u32 s7, s5, -1
	s_add_i32 s68, 0, 0x10000
	v_add_u32_e32 v154, s68, v1
	ds_read_b128 v[142:145], v154
	ds_read_b128 v[146:149], v154 offset:1024
	ds_read_b128 v[150:153], v154 offset:2048
	ds_read_b128 v[158:161], v154 offset:3072
	s_cmp_eq_u32 s67, 60
	s_cselect_b32 s15, s18, s7
	s_cselect_b32 s14, s19, s6
	s_cselect_b32 s7, s51, s66
	s_cselect_b32 s6, s53, s65
	ds_read_b128 v[162:165], v156
	ds_read_b128 v[166:169], v156 offset:1024
	ds_read_b128 v[170:173], v156 offset:2048
	ds_read_b128 v[174:177], v156 offset:3072
	ds_read_b128 v[178:181], v156 offset:4096
	ds_read_b128 v[182:185], v156 offset:5120
	ds_read_b128 v[186:189], v156 offset:6144
	ds_read_b128 v[190:193], v156 offset:7168
	s_add_i32 s70, 0, 0x14000
	v_add_u32_e32 v154, s70, v1
	ds_read_b128 v[194:197], v154
	ds_read_b128 v[198:201], v154 offset:1024
	ds_read_b128 v[202:205], v154 offset:2048
	ds_read_b128 v[206:209], v154 offset:3072
	s_add_i32 m0, s30, 0xc000
	s_nop 0
	global_load_lds_dwordx4 v138, s[4:5]
	s_add_i32 m0, s30, 0xe000
	s_nop 0
	global_load_lds_dwordx4 v140, s[4:5]
	s_waitcnt lgkmcnt(0)
	s_barrier
; #define PG8_STAGE(bufoff, gbase, voff) do { _Pragma("unroll") for (int _i = 0; _i < 2; ++_i) \
;         __builtin_amdgcn_global_load_lds((const unsigned*)((const char*)(gbase) + (voff)[_i]), (LAS unsigned*)(lds + (bufoff) + ldsw + _i * 8192), 16, 0, 0); } while (0)
; #define PG8_LDA(dst, b, h) do { _Pragma("unroll") for (int m = 0; m < 4; ++m) _Pragma("unroll") for (int k = 0; k < 2; ++k) dst[m][k] = *(const LAS bf16x8*)(lds + PG8_SA(b, h) + aoff + m * 2048 + k * 1024); } while (0)
; #define PG8_LDB(dst, b, h) do { _Pragma("unroll") for (int n = 0; n < 2; ++n) _Pragma("unroll") for (int k = 0; k < 2; ++k) dst[n][k] = *(const LAS bf16x8*)(lds + PG8_SB(b, h) + boff + n * 2048 + k * 1024); } while (0)
; #define PG8_MMA(ai, bj, At, Bt) do { __builtin_amdgcn_s_setprio(1); _Pragma("unroll") for (int m = 0; m < 4; ++m) _Pragma("unroll") for (int n = 0; n < 2; ++n) _Pragma("unroll") for (int k = 0; k < 2; ++k) \
;         acc[ai][bj][m][n] = __builtin_amdgcn_mfma_f32_16x16x32_bf16(Bt[n][k], At[m][k], acc[ai][bj][m][n], 0, 0, 0); __builtin_amdgcn_s_setprio(0); } while (0)
; #define PG8_WAIT_V(n) asm volatile("s_waitcnt vmcnt(" #n ")" ::: "memory")
; #define PG8_WAIT_L(n) asm volatile("s_waitcnt lgkmcnt(" #n ")" ::: "memory")
; #define PG8_BAR __builtin_amdgcn_s_barrier()
; #define PG8_SCHED __builtin_amdgcn_sched_barrier(0)
; template <class Epi, class Sched>
; __device__ __forceinline__ void gemm_phase(LAS unsigned char* lds, const Gemm g, const Sched& S, const Epi& E) {
;     ...
;             PG8_WAIT_L(8); PG8_BAR; PG8_WAIT_L(0); PG8_MMA(0, 0, At, B0); PG8_BAR; PG8_SCHED;
;             PG8_LDB(B1, 0, 1); PG8_STAGE(PG8_SB(0, 0), b2, voffB);
;             PG8_BAR; PG8_WAIT_L(0); PG8_MMA(0, 1, At, B1); PG8_BAR;
;             PG8_LDA(At, 0, 1); PG8_STAGE(PG8_SA(0, 0), a2, voffA);
;             PG8_BAR; PG8_WAIT_L(0); PG8_MMA(1, 0, At, B0); PG8_BAR; PG8_SCHED;
;             PG8_STAGE(PG8_SB(0, 1), b2 + hstepB, voffB);
;             PG8_WAIT_V(6); PG8_BAR; PG8_MMA(1, 1, At, B1); PG8_BAR;
;             PG8_LDB(B0, 1, 0); PG8_SCHED; PG8_LDA(At, 1, 0); PG8_STAGE(PG8_SA(0, 1), a2 + hstepA, voffA);
;             PG8_WAIT_L(8); PG8_BAR; PG8_WAIT_L(0); PG8_MMA(0, 0, At, B0); PG8_BAR; PG8_SCHED;
	v_mfma_f32_16x16x32_bf16 v[128:131], v[142:145], v[162:165], v[128:131]
	v_mfma_f32_16x16x32_bf16 v[124:127], v[150:153], v[162:165], v[124:127]
	v_mfma_f32_16x16x32_bf16 v[120:123], v[142:145], v[170:173], v[120:123]
	v_mfma_f32_16x16x32_bf16 v[116:119], v[150:153], v[170:173], v[116:119]
	v_mfma_f32_16x16x32_bf16 v[112:115], v[142:145], v[178:181], v[112:115]
	v_mfma_f32_16x16x32_bf16 v[108:111], v[150:153], v[178:181], v[108:111]
	v_mfma_f32_16x16x32_bf16 v[104:107], v[142:145], v[186:189], v[104:107]
	v_mfma_f32_16x16x32_bf16 v[100:103], v[150:153], v[186:189], v[100:103]
	v_mfma_f32_16x16x32_bf16 v[128:131], v[146:149], v[166:169], v[128:131]
	v_mfma_f32_16x16x32_bf16 v[124:127], v[158:161], v[166:169], v[124:127]
	v_mfma_f32_16x16x32_bf16 v[120:123], v[146:149], v[174:177], v[120:123]
	v_mfma_f32_16x16x32_bf16 v[116:119], v[158:161], v[174:177], v[116:119]
	v_mfma_f32_16x16x32_bf16 v[112:115], v[146:149], v[182:185], v[112:115]
	v_mfma_f32_16x16x32_bf16 v[108:111], v[158:161], v[182:185], v[108:111]
	v_mfma_f32_16x16x32_bf16 v[104:107], v[146:149], v[190:193], v[104:107]
	v_mfma_f32_16x16x32_bf16 v[100:103], v[158:161], v[190:193], v[100:103]
	v_mfma_f32_16x16x32_bf16 v[64:67], v[194:197], v[162:165], v[64:67]
	v_mfma_f32_16x16x32_bf16 v[60:63], v[202:205], v[162:165], v[60:63]
	v_mfma_f32_16x16x32_bf16 v[56:59], v[194:197], v[170:173], v[56:59]
	v_mfma_f32_16x16x32_bf16 v[52:55], v[202:205], v[170:173], v[52:55]
	v_mfma_f32_16x16x32_bf16 v[48:51], v[194:197], v[178:181], v[48:51]
	v_mfma_f32_16x16x32_bf16 v[44:47], v[202:205], v[178:181], v[44:47]
	v_mfma_f32_16x16x32_bf16 v[40:43], v[194:197], v[186:189], v[40:43]
	v_mfma_f32_16x16x32_bf16 v[36:39], v[202:205], v[186:189], v[36:39]
	v_mfma_f32_16x16x32_bf16 v[64:67], v[198:201], v[166:169], v[64:67]
	v_mfma_f32_16x16x32_bf16 v[60:63], v[206:209], v[166:169], v[60:63]
	v_mfma_f32_16x16x32_bf16 v[56:59], v[198:201], v[174:177], v[56:59]
	v_mfma_f32_16x16x32_bf16 v[52:55], v[206:209], v[174:177], v[52:55]
	v_mfma_f32_16x16x32_bf16 v[48:51], v[198:201], v[182:185], v[48:51]
	v_mfma_f32_16x16x32_bf16 v[44:47], v[206:209], v[182:185], v[44:47]
	v_mfma_f32_16x16x32_bf16 v[40:43], v[198:201], v[190:193], v[40:43]
	v_mfma_f32_16x16x32_bf16 v[36:39], v[206:209], v[190:193], v[36:39]
	s_barrier
	ds_read_b128 v[162:165], v156 offset:16384
	ds_read_b128 v[166:169], v156 offset:17408
	ds_read_b128 v[170:173], v156 offset:18432
	ds_read_b128 v[174:177], v156 offset:19456
	ds_read_b128 v[178:181], v156 offset:20480
	ds_read_b128 v[182:185], v156 offset:21504
	ds_read_b128 v[186:189], v156 offset:22528
	ds_read_b128 v[190:193], v156 offset:23552
	s_add_i32 s68, s68, s29
	v_lshl_add_u64 v[154:155], s[6:7], 0, v[2:3]
	s_mov_b32 m0, s68
	v_lshl_add_u64 v[210:211], s[6:7], 0, v[136:137]
	global_load_lds_dwordx4 v[154:155], off
	s_add_i32 m0, s68, 0x2000
	s_nop 0
	global_load_lds_dwordx4 v[210:211], off
	s_mov_b32 m0, s30
	v_lshl_add_u64 v[212:213], s[14:15], 0, v[132:133]
	global_load_lds_dwordx4 v[212:213], off
	v_lshl_add_u64 v[216:217], s[14:15], 0, v[134:135]
	s_mov_b32 m0, s31
	s_nop 0
	global_load_lds_dwordx4 v[216:217], off
	s_add_u32 s68, s6, 0x100000
	s_addc_u32 s69, s7, 0
	s_add_i32 s70, s70, s29
	s_mov_b32 m0, s70
	s_nop 0
	global_load_lds_dwordx4 v2, s[68:69]
	s_add_i32 m0, s70, 0x2000
	s_nop 0
	global_load_lds_dwordx4 v136, s[68:69]
	s_waitcnt lgkmcnt(0)
	s_waitcnt vmcnt(6)
	s_barrier
	v_mfma_f32_16x16x32_bf16 v[96:99], v[142:145], v[162:165], v[96:99]
	v_mfma_f32_16x16x32_bf16 v[92:95], v[150:153], v[162:165], v[92:95]
	v_mfma_f32_16x16x32_bf16 v[88:91], v[142:145], v[170:173], v[88:91]
	v_mfma_f32_16x16x32_bf16 v[84:87], v[150:153], v[170:173], v[84:87]
	v_mfma_f32_16x16x32_bf16 v[80:83], v[142:145], v[178:181], v[80:83]
	v_mfma_f32_16x16x32_bf16 v[76:79], v[150:153], v[178:181], v[76:79]
	v_mfma_f32_16x16x32_bf16 v[72:75], v[142:145], v[186:189], v[72:75]
	v_mfma_f32_16x16x32_bf16 v[68:71], v[150:153], v[186:189], v[68:71]
	v_mfma_f32_16x16x32_bf16 v[96:99], v[146:149], v[166:169], v[96:99]
	v_mfma_f32_16x16x32_bf16 v[92:95], v[158:161], v[166:169], v[92:95]
	v_mfma_f32_16x16x32_bf16 v[88:91], v[146:149], v[174:177], v[88:91]
	v_mfma_f32_16x16x32_bf16 v[84:87], v[158:161], v[174:177], v[84:87]
	v_mfma_f32_16x16x32_bf16 v[80:83], v[146:149], v[182:185], v[80:83]
	v_mfma_f32_16x16x32_bf16 v[76:79], v[158:161], v[182:185], v[76:79]
	v_mfma_f32_16x16x32_bf16 v[72:75], v[146:149], v[190:193], v[72:75]
	v_mfma_f32_16x16x32_bf16 v[68:71], v[158:161], v[190:193], v[68:71]
	v_mfma_f32_16x16x32_bf16 v[32:35], v[194:197], v[162:165], v[32:35]
	v_mfma_f32_16x16x32_bf16 v[28:31], v[202:205], v[162:165], v[28:31]
	v_mfma_f32_16x16x32_bf16 v[24:27], v[194:197], v[170:173], v[24:27]
	v_mfma_f32_16x16x32_bf16 v[20:23], v[202:205], v[170:173], v[20:23]
	v_mfma_f32_16x16x32_bf16 v[16:19], v[194:197], v[178:181], v[16:19]
	v_mfma_f32_16x16x32_bf16 v[12:15], v[202:205], v[178:181], v[12:15]
	v_mfma_f32_16x16x32_bf16 v[8:11], v[194:197], v[186:189], v[8:11]
	v_mfma_f32_16x16x32_bf16 v[4:7], v[202:205], v[186:189], v[4:7]
	v_mfma_f32_16x16x32_bf16 v[32:35], v[198:201], v[166:169], v[32:35]
	v_mfma_f32_16x16x32_bf16 v[28:31], v[206:209], v[166:169], v[28:31]
	v_mfma_f32_16x16x32_bf16 v[24:27], v[198:201], v[174:177], v[24:27]
	v_mfma_f32_16x16x32_bf16 v[20:23], v[206:209], v[174:177], v[20:23]
	v_mfma_f32_16x16x32_bf16 v[16:19], v[198:201], v[182:185], v[16:19]
	v_mfma_f32_16x16x32_bf16 v[12:15], v[206:209], v[182:185], v[12:15]
	v_mfma_f32_16x16x32_bf16 v[8:11], v[198:201], v[190:193], v[8:11]
	v_mfma_f32_16x16x32_bf16 v[4:7], v[206:209], v[190:193], v[4:7]
	s_barrier
; #define PG8_STAGE(bufoff, gbase, voff) do { _Pragma("unroll") for (int _i = 0; _i < 2; ++_i) \
;         __builtin_amdgcn_global_load_lds((const unsigned*)((const char*)(gbase) + (voff)[_i]), (LAS unsigned*)(lds + (bufoff) + ldsw + _i * 8192), 16, 0, 0); } while (0)
; #define PG8_LDA(dst, b, h) do { _Pragma("unroll") for (int m = 0; m < 4; ++m) _Pragma("unroll") for (int k = 0; k < 2; ++k) dst[m][k] = *(const LAS bf16x8*)(lds + PG8_SA(b, h) + aoff + m * 2048 + k * 1024); } while (0)
; #define PG8_LDB(dst, b, h) do { _Pragma("unroll") for (int n = 0; n < 2; ++n) _Pragma("unroll") for (int k = 0; k < 2; ++k) dst[n][k] = *(const LAS bf16x8*)(lds + PG8_SB(b, h) + boff + n * 2048 + k * 1024); } while (0)
; #define PG8_MMA(ai, bj, At, Bt) do { __builtin_amdgcn_s_setprio(1); _Pragma("unroll") for (int m = 0; m < 4; ++m) _Pragma("unroll") for (int n = 0; n < 2; ++n) _Pragma("unroll") for (int k = 0; k < 2; ++k) \
;         acc[ai][bj][m][n] = __builtin_amdgcn_mfma_f32_16x16x32_bf16(Bt[n][k], At[m][k], acc[ai][bj][m][n], 0, 0, 0); __builtin_amdgcn_s_setprio(0); } while (0)
; #define PG8_WAIT_L(n) asm volatile("s_waitcnt lgkmcnt(" #n ")" ::: "memory")
; #define PG8_BAR __builtin_amdgcn_s_barrier()
; #define PG8_SCHED __builtin_amdgcn_sched_barrier(0)
; template <class Epi, class Sched>
; __device__ __forceinline__ void gemm_phase(LAS unsigned char* lds, const Gemm g, const Sched& S, const Epi& E) {
;     ...
;             PG8_LDB(B0, 1, 0); PG8_SCHED; PG8_LDA(At, 1, 0); PG8_STAGE(PG8_SA(0, 1), a2 + hstepA, voffA);
;             PG8_WAIT_L(8); PG8_BAR; PG8_WAIT_L(0); PG8_MMA(0, 0, At, B0); PG8_BAR; PG8_SCHED;
;             PG8_LDB(B1, 1, 1); PG8_STAGE(PG8_SB(1, 0), b3, voffB);
;             PG8_BAR; PG8_WAIT_L(0); PG8_MMA(0, 1, At, B1); PG8_BAR;
	s_add_i32 s68, 0, 0x18000
	v_add_u32_e32 v157, s68, v1
	ds_read_b128 v[142:145], v157
	ds_read_b128 v[146:149], v157 offset:1024
	ds_read_b128 v[150:153], v157 offset:2048
	ds_read_b128 v[158:161], v157 offset:3072
	s_add_u32 s14, s14, 0x80000
	s_addc_u32 s15, s15, 0
	ds_read_b128 v[162:165], v156 offset:32768
	ds_read_b128 v[166:169], v156 offset:33792
	ds_read_b128 v[170:173], v156 offset:34816
	ds_read_b128 v[174:177], v156 offset:35840
	ds_read_b128 v[178:181], v156 offset:36864
	ds_read_b128 v[182:185], v156 offset:37888
	ds_read_b128 v[186:189], v156 offset:38912
	ds_read_b128 v[190:193], v156 offset:39936
	s_mov_b32 m0, s38
	s_nop 0
	global_load_lds_dwordx4 v132, s[14:15]
	s_mov_b32 m0, s39
	s_nop 0
	global_load_lds_dwordx4 v134, s[14:15]
	s_add_i32 s14, 0, 0x1c000
	v_add_u32_e32 v157, s14, v1
	ds_read_b128 v[194:197], v157
	ds_read_b128 v[198:201], v157 offset:1024
	ds_read_b128 v[202:205], v157 offset:2048
	ds_read_b128 v[206:209], v157 offset:3072
	s_waitcnt lgkmcnt(0)
	s_barrier
	v_mfma_f32_16x16x32_bf16 v[128:131], v[142:145], v[162:165], v[128:131]
	v_mfma_f32_16x16x32_bf16 v[124:127], v[150:153], v[162:165], v[124:127]
	v_mfma_f32_16x16x32_bf16 v[120:123], v[142:145], v[170:173], v[120:123]
	v_mfma_f32_16x16x32_bf16 v[116:119], v[150:153], v[170:173], v[116:119]
	v_mfma_f32_16x16x32_bf16 v[112:115], v[142:145], v[178:181], v[112:115]
	v_mfma_f32_16x16x32_bf16 v[108:111], v[150:153], v[178:181], v[108:111]
	v_mfma_f32_16x16x32_bf16 v[104:107], v[142:145], v[186:189], v[104:107]
	v_mfma_f32_16x16x32_bf16 v[100:103], v[150:153], v[186:189], v[100:103]
	v_mfma_f32_16x16x32_bf16 v[128:131], v[146:149], v[166:169], v[128:131]
	v_mfma_f32_16x16x32_bf16 v[124:127], v[158:161], v[166:169], v[124:127]
	v_mfma_f32_16x16x32_bf16 v[120:123], v[146:149], v[174:177], v[120:123]
	v_mfma_f32_16x16x32_bf16 v[116:119], v[158:161], v[174:177], v[116:119]
	v_mfma_f32_16x16x32_bf16 v[112:115], v[146:149], v[182:185], v[112:115]
	v_mfma_f32_16x16x32_bf16 v[108:111], v[158:161], v[182:185], v[108:111]
	v_mfma_f32_16x16x32_bf16 v[104:107], v[146:149], v[190:193], v[104:107]
	v_mfma_f32_16x16x32_bf16 v[100:103], v[158:161], v[190:193], v[100:103]
	v_mfma_f32_16x16x32_bf16 v[64:67], v[194:197], v[162:165], v[64:67]
	v_mfma_f32_16x16x32_bf16 v[60:63], v[202:205], v[162:165], v[60:63]
	v_mfma_f32_16x16x32_bf16 v[56:59], v[194:197], v[170:173], v[56:59]
	v_mfma_f32_16x16x32_bf16 v[52:55], v[202:205], v[170:173], v[52:55]
	v_mfma_f32_16x16x32_bf16 v[48:51], v[194:197], v[178:181], v[48:51]
	v_mfma_f32_16x16x32_bf16 v[44:47], v[202:205], v[178:181], v[44:47]
	v_mfma_f32_16x16x32_bf16 v[40:43], v[194:197], v[186:189], v[40:43]
	v_mfma_f32_16x16x32_bf16 v[36:39], v[202:205], v[186:189], v[36:39]
	v_mfma_f32_16x16x32_bf16 v[64:67], v[198:201], v[166:169], v[64:67]
	v_mfma_f32_16x16x32_bf16 v[60:63], v[206:209], v[166:169], v[60:63]
	v_mfma_f32_16x16x32_bf16 v[56:59], v[198:201], v[174:177], v[56:59]
	v_mfma_f32_16x16x32_bf16 v[52:55], v[206:209], v[174:177], v[52:55]
	v_mfma_f32_16x16x32_bf16 v[48:51], v[198:201], v[182:185], v[48:51]
	v_mfma_f32_16x16x32_bf16 v[44:47], v[206:209], v[182:185], v[44:47]
	v_mfma_f32_16x16x32_bf16 v[40:43], v[198:201], v[190:193], v[40:43]
	v_mfma_f32_16x16x32_bf16 v[36:39], v[206:209], v[190:193], v[36:39]
	s_barrier
; #define PG8_STAGE(bufoff, gbase, voff) do { _Pragma("unroll") for (int _i = 0; _i < 2; ++_i) \
;         __builtin_amdgcn_global_load_lds((const unsigned*)((const char*)(gbase) + (voff)[_i]), (LAS unsigned*)(lds + (bufoff) + ldsw + _i * 8192), 16, 0, 0); } while (0)
; #define PG8_LDA(dst, b, h) do { _Pragma("unroll") for (int m = 0; m < 4; ++m) _Pragma("unroll") for (int k = 0; k < 2; ++k) dst[m][k] = *(const LAS bf16x8*)(lds + PG8_SA(b, h) + aoff + m * 2048 + k * 1024); } while (0)
; #define PG8_MMA(ai, bj, At, Bt) do { __builtin_amdgcn_s_setprio(1); _Pragma("unroll") for (int m = 0; m < 4; ++m) _Pragma("unroll") for (int n = 0; n < 2; ++n) _Pragma("unroll") for (int k = 0; k < 2; ++k) \
;         acc[ai][bj][m][n] = __builtin_amdgcn_mfma_f32_16x16x32_bf16(Bt[n][k], At[m][k], acc[ai][bj][m][n], 0, 0, 0); __builtin_amdgcn_s_setprio(0); } while (0)
; #define PG8_WAIT_V(n) asm volatile("s_waitcnt vmcnt(" #n ")" ::: "memory")
; #define PG8_WAIT_L(n) asm volatile("s_waitcnt lgkmcnt(" #n ")" ::: "memory")
; #define PG8_BAR __builtin_amdgcn_s_barrier()
; #define PG8_SCHED __builtin_amdgcn_sched_barrier(0)
; template <class Epi, class Sched>
; __device__ __forceinline__ void gemm_phase(LAS unsigned char* lds, const Gemm g, const Sched& S, const Epi& E) {
;     ...
;             PG8_LDA(At, 1, 1); PG8_STAGE(PG8_SA(1, 0), a3, voffA);
;             PG8_BAR; PG8_WAIT_L(0); PG8_MMA(1, 0, At, B0); PG8_BAR; PG8_SCHED;
;             PG8_STAGE(PG8_SB(1, 1), b3 + hstepB, voffB);
;             PG8_WAIT_V(6); PG8_BAR; PG8_MMA(1, 1, At, B1); PG8_BAR;
;         }
;     __device__ __forceinline__ void operator()(const f32x4 (&acc)[2][2][4][2], const Unit& u, int wr, int wc, int, int) const {
;     ...
;         for (int bj = 0; bj < 2; ++bj) { f32x4 b0 = (f32x4){0.f, 0.f, 0.f, 0.f}, b1 = b0;
; #pragma unroll 8
;             for (int pp = 0; pp < 32; ++pp) { b0 += *(const f32x4*)(bias + pp * 256 + col0 + bj * HALF); b1 += *(const f32x4*)(bias + pp * 256 + col0 + bj * HALF + 4); }
	ds_read_b128 v[162:165], v156 offset:49152
	ds_read_b128 v[166:169], v156 offset:50176
	ds_read_b128 v[170:173], v156 offset:51200
	ds_read_b128 v[174:177], v156 offset:52224
	ds_read_b128 v[178:181], v156 offset:53248
	ds_read_b128 v[182:185], v156 offset:54272
	ds_read_b128 v[186:189], v156 offset:55296
	ds_read_b128 v[190:193], v156 offset:56320
	s_add_i32 s15, s68, s29
	v_lshl_add_u64 v[154:155], v[154:155], 0, s[8:9]
	s_mov_b32 m0, s15
	s_nop 0
	global_load_lds_dwordx4 v[154:155], off
	v_lshl_add_u64 v[154:155], v[210:211], 0, s[8:9]
	s_add_i32 m0, s15, 0x2000
	s_nop 0
	global_load_lds_dwordx4 v[154:155], off
	s_mov_b32 m0, s62
	v_lshl_add_u64 v[154:155], v[212:213], 0, s[8:9]
	global_load_lds_dwordx4 v[154:155], off
	v_lshl_add_u64 v[154:155], v[216:217], 0, s[8:9]
	s_mov_b32 m0, s63
	s_nop 0
	global_load_lds_dwordx4 v[154:155], off
	s_add_u32 s6, s6, 0x100080
	s_addc_u32 s7, s7, 0
	s_add_i32 s14, s14, s29
	s_mov_b32 m0, s14
	s_nop 0
	global_load_lds_dwordx4 v2, s[6:7]
	s_add_i32 m0, s14, 0x2000
	s_nop 0
	global_load_lds_dwordx4 v136, s[6:7]
	s_add_i32 s67, s67, 2
	s_add_u32 s4, s4, 0x100
	s_addc_u32 s5, s5, 0
	s_add_u32 s65, s65, 0x100
	s_addc_u32 s66, s66, 0
	s_cmp_gt_u32 s67, 61
	s_waitcnt lgkmcnt(0)
	s_waitcnt vmcnt(6)
	s_barrier
	v_mfma_f32_16x16x32_bf16 v[96:99], v[142:145], v[162:165], v[96:99]
	v_mfma_f32_16x16x32_bf16 v[92:95], v[150:153], v[162:165], v[92:95]
	v_mfma_f32_16x16x32_bf16 v[88:91], v[142:145], v[170:173], v[88:91]
	v_mfma_f32_16x16x32_bf16 v[84:87], v[150:153], v[170:173], v[84:87]
	v_mfma_f32_16x16x32_bf16 v[80:83], v[142:145], v[178:181], v[80:83]
	v_mfma_f32_16x16x32_bf16 v[76:79], v[150:153], v[178:181], v[76:79]
	v_mfma_f32_16x16x32_bf16 v[72:75], v[142:145], v[186:189], v[72:75]
	v_mfma_f32_16x16x32_bf16 v[68:71], v[150:153], v[186:189], v[68:71]
	v_mfma_f32_16x16x32_bf16 v[96:99], v[146:149], v[166:169], v[96:99]
	v_mfma_f32_16x16x32_bf16 v[92:95], v[158:161], v[166:169], v[92:95]
	v_mfma_f32_16x16x32_bf16 v[88:91], v[146:149], v[174:177], v[88:91]
	v_mfma_f32_16x16x32_bf16 v[84:87], v[158:161], v[174:177], v[84:87]
	v_mfma_f32_16x16x32_bf16 v[80:83], v[146:149], v[182:185], v[80:83]
	v_mfma_f32_16x16x32_bf16 v[76:79], v[158:161], v[182:185], v[76:79]
	v_mfma_f32_16x16x32_bf16 v[72:75], v[146:149], v[190:193], v[72:75]
	v_mfma_f32_16x16x32_bf16 v[68:71], v[158:161], v[190:193], v[68:71]
	v_mfma_f32_16x16x32_bf16 v[32:35], v[194:197], v[162:165], v[32:35]
	v_mfma_f32_16x16x32_bf16 v[28:31], v[202:205], v[162:165], v[28:31]
	v_mfma_f32_16x16x32_bf16 v[24:27], v[194:197], v[170:173], v[24:27]
	v_mfma_f32_16x16x32_bf16 v[20:23], v[202:205], v[170:173], v[20:23]
	v_mfma_f32_16x16x32_bf16 v[16:19], v[194:197], v[178:181], v[16:19]
	v_mfma_f32_16x16x32_bf16 v[12:15], v[202:205], v[178:181], v[12:15]
	v_mfma_f32_16x16x32_bf16 v[8:11], v[194:197], v[186:189], v[8:11]
	v_mfma_f32_16x16x32_bf16 v[4:7], v[202:205], v[186:189], v[4:7]
	v_mfma_f32_16x16x32_bf16 v[32:35], v[198:201], v[166:169], v[32:35]
	v_mfma_f32_16x16x32_bf16 v[28:31], v[206:209], v[166:169], v[28:31]
	v_mfma_f32_16x16x32_bf16 v[24:27], v[198:201], v[174:177], v[24:27]
	v_mfma_f32_16x16x32_bf16 v[20:23], v[206:209], v[174:177], v[20:23]
	v_mfma_f32_16x16x32_bf16 v[16:19], v[198:201], v[182:185], v[16:19]
	v_mfma_f32_16x16x32_bf16 v[12:15], v[206:209], v[182:185], v[12:15]
	v_mfma_f32_16x16x32_bf16 v[8:11], v[198:201], v[190:193], v[8:11]
	v_mfma_f32_16x16x32_bf16 v[4:7], v[206:209], v[190:193], v[4:7]
	s_barrier
	s_cbranch_scc0 .LBB0_491
	v_mov_b32_e32 v157, v0
	s_lshl_b32 s1, s1, 8
	v_lshrrev_b32_e32 v142, 1, v157
	v_and_or_b32 v142, v142, 24, s1
	v_or_b32_e32 v154, s61, v142
	v_ashrrev_i32_e32 v155, 31, v154
	v_mov_b32_e32 v144, 0
	v_lshl_add_u64 v[142:143], v[154:155], 2, s[46:47]
	s_mov_b64 s[4:5], 0
	v_mov_b32_e32 v145, v144
	v_mov_b32_e32 v146, v144
	v_mov_b32_e32 v147, v144
	v_mov_b32_e32 v148, v144
	v_mov_b32_e32 v149, v144
	v_mov_b32_e32 v150, v144
	v_mov_b32_e32 v151, v144

; #define PG8_STAGE(bufoff, gbase, voff) do { _Pragma("unroll") for (int _i = 0; _i < 2; ++_i) \
;         __builtin_amdgcn_global_load_lds((const unsigned*)((const char*)(gbase) + (voff)[_i]), (LAS unsigned*)(lds + (bufoff) + ldsw + _i * 8192), 16, 0, 0); } while (0)
; #define PG8_LDA(dst, b, h) do { _Pragma("unroll") for (int m = 0; m < 4; ++m) _Pragma("unroll") for (int k = 0; k < 2; ++k) dst[m][k] = *(const LAS bf16x8*)(lds + PG8_SA(b, h) + aoff + m * 2048 + k * 1024); } while (0)
; #define PG8_LDB(dst, b, h) do { _Pragma("unroll") for (int n = 0; n < 2; ++n) _Pragma("unroll") for (int k = 0; k < 2; ++k) dst[n][k] = *(const LAS bf16x8*)(lds + PG8_SB(b, h) + boff + n * 2048 + k * 1024); } while (0)
; #define PG8_WAIT_V(n) asm volatile("s_waitcnt vmcnt(" #n ")" ::: "memory")
; #define PG8_WAIT_L(n) asm volatile("s_waitcnt lgkmcnt(" #n ")" ::: "memory")
; #define PG8_BAR __builtin_amdgcn_s_barrier()
; #define PG8_SCHED __builtin_amdgcn_sched_barrier(0)
; template <class Epi, class Sched>
; __device__ __forceinline__ void gemm_phase(LAS unsigned char* lds, const Gemm g, const Sched& S, const Epi& E) {
;     ...
;         const bool has_next = S.next(ui + 1, nxt);
;         const char* nA = has_next ? (const char*)g.A + (size_t)nxt.pm * tstepA : cA; const char* nB = has_next ? (const char*)g.Bt + (size_t)nxt.pn * tstepB : cB;
;         for (int t = 0; t < nt; t += 2) {
;             const bool last = (t == nt - 2);
;             const char* a1 = cA + (size_t)(t + 1) * kstep;
;             const char* a2 = last ? nA : cA + (size_t)(t + 2) * kstep; const char* b2 = last ? nB : cB + (size_t)(t + 2) * kstep;
;             const char* a3 = a2 + kstep; const char* b3 = b2 + kstep;
;             if (last && has_next) S.a_ready(nxt);
;             PG8_LDB(B0, 0, 0); PG8_SCHED; PG8_LDA(At, 0, 0); PG8_STAGE(PG8_SA(1, 1), a1 + hstepA, voffA);
;             PG8_WAIT_L(8); PG8_BAR; PG8_WAIT_L(0); PG8_MMA(0, 0, At, B0); PG8_BAR; PG8_SCHED;
;             PG8_LDB(B1, 0, 1); PG8_STAGE(PG8_SB(0, 0), b2, voffB);
;             PG8_BAR; PG8_WAIT_L(0); PG8_MMA(0, 1, At, B1); PG8_BAR;
;             PG8_LDA(At, 0, 1); PG8_STAGE(PG8_SA(0, 0), a2, voffA);
;             PG8_BAR; PG8_WAIT_L(0); PG8_MMA(1, 0, At, B0); PG8_BAR; PG8_SCHED;
;             PG8_STAGE(PG8_SB(0, 1), b2 + hstepB, voffB);
;             PG8_WAIT_V(6); PG8_BAR; PG8_MMA(1, 1, At, B1); PG8_BAR;
.LBB0_965:
	v_mov_b64_e32 v[4:5], 0x400
	s_ashr_i32 s15, s14, 31
	v_cmp_lt_i64_e32 vcc, s[4:5], v[4:5]
	s_lshl_b64 s[4:5], s[14:15], 20
	v_readlane_b32 s48, v252, 0
	v_readlane_b32 s49, v252, 1
	s_add_u32 s4, s48, s4
	s_addc_u32 s5, s49, s5
	s_and_b64 s[18:19], vcc, exec
	s_cselect_b32 s15, s5, s7
	s_cselect_b32 s47, s4, s6
	s_ashr_i32 s1, s0, 31
	s_lshl_b64 s[18:19], s[0:1], 20
	s_add_u32 s18, s28, s18
	s_addc_u32 s19, s29, s19
	s_and_b64 s[24:25], vcc, exec
	s_cselect_b32 s1, s19, s21
	s_cselect_b32 s48, s18, s20
	s_add_u32 s6, s6, 0x80080
	s_addc_u32 s7, s7, 0
	v_readlane_b32 s50, v252, 2
	v_readlane_b32 s51, v252, 3
	s_add_u32 s49, s20, 0x100
	s_addc_u32 s50, s21, 0
	s_mov_b32 s51, -2
	s_waitcnt lgkmcnt(0)
	s_add_u32 s20, s6, 0xfff80080
	s_addc_u32 s21, s7, -1
	s_add_i32 s52, 0, 0x10000
	v_add_u32_e32 v144, s52, v1
	ds_read_b128 v[132:135], v144
	ds_read_b128 v[136:139], v144 offset:1024
	ds_read_b128 v[140:143], v144 offset:2048
	ds_read_b128 v[144:147], v144 offset:3072
	s_cmp_eq_u32 s51, 28
	s_cselect_b32 s25, s15, s21
	s_cselect_b32 s24, s47, s20
	s_cselect_b32 s21, s1, s50
	s_cselect_b32 s20, s48, s49
	ds_read_b128 v[148:151], v224
	ds_read_b128 v[152:155], v224 offset:1024
	ds_read_b128 v[156:159], v224 offset:2048
	ds_read_b128 v[160:163], v224 offset:3072
	ds_read_b128 v[164:167], v224 offset:4096
	ds_read_b128 v[168:171], v224 offset:5120
	ds_read_b128 v[172:175], v224 offset:6144
	ds_read_b128 v[176:179], v224 offset:7168
	s_add_i32 s54, 0, 0x14000
	v_add_u32_e32 v202, s54, v1
	ds_read_b128 v[180:183], v202
	ds_read_b128 v[184:187], v202 offset:1024
	ds_read_b128 v[188:191], v202 offset:2048
	ds_read_b128 v[202:205], v202 offset:3072
	s_add_i32 m0, s31, 0xc000
	s_nop 0
	global_load_lds_dwordx4 v198, s[6:7]
	s_add_i32 m0, s31, 0xe000
	s_nop 0
	global_load_lds_dwordx4 v200, s[6:7]
	s_waitcnt lgkmcnt(0)
	s_barrier
	v_mfma_f32_16x16x32_bf16 v[128:131], v[132:135], v[148:151], 0
	v_mfma_f32_16x16x32_bf16 v[124:127], v[140:143], v[148:151], 0
	v_mfma_f32_16x16x32_bf16 v[112:115], v[132:135], v[156:159], 0
	v_mfma_f32_16x16x32_bf16 v[108:111], v[140:143], v[156:159], 0
	v_mfma_f32_16x16x32_bf16 v[100:103], v[132:135], v[164:167], 0
	v_mfma_f32_16x16x32_bf16 v[92:95], v[140:143], v[164:167], 0
	v_mfma_f32_16x16x32_bf16 v[84:87], v[132:135], v[172:175], 0
	v_mfma_f32_16x16x32_bf16 v[76:79], v[140:143], v[172:175], 0
	v_mfma_f32_16x16x32_bf16 v[128:131], v[136:139], v[152:155], v[128:131]
	v_mfma_f32_16x16x32_bf16 v[124:127], v[144:147], v[152:155], v[124:127]
	v_mfma_f32_16x16x32_bf16 v[112:115], v[136:139], v[160:163], v[112:115]
	v_mfma_f32_16x16x32_bf16 v[108:111], v[144:147], v[160:163], v[108:111]
	v_mfma_f32_16x16x32_bf16 v[100:103], v[136:139], v[168:171], v[100:103]
	v_mfma_f32_16x16x32_bf16 v[92:95], v[144:147], v[168:171], v[92:95]
	v_mfma_f32_16x16x32_bf16 v[84:87], v[136:139], v[176:179], v[84:87]
	v_mfma_f32_16x16x32_bf16 v[76:79], v[144:147], v[176:179], v[76:79]
	v_mfma_f32_16x16x32_bf16 v[120:123], v[180:183], v[148:151], 0
	v_mfma_f32_16x16x32_bf16 v[116:119], v[188:191], v[148:151], 0
	v_mfma_f32_16x16x32_bf16 v[104:107], v[180:183], v[156:159], 0
	v_mfma_f32_16x16x32_bf16 v[96:99], v[188:191], v[156:159], 0
	v_mfma_f32_16x16x32_bf16 v[88:91], v[180:183], v[164:167], 0
	v_mfma_f32_16x16x32_bf16 v[80:83], v[188:191], v[164:167], 0
	v_mfma_f32_16x16x32_bf16 v[72:75], v[180:183], v[172:175], 0
	v_mfma_f32_16x16x32_bf16 v[68:71], v[188:191], v[172:175], 0
	v_mfma_f32_16x16x32_bf16 v[120:123], v[184:187], v[152:155], v[120:123]
	v_mfma_f32_16x16x32_bf16 v[116:119], v[202:205], v[152:155], v[116:119]
	v_mfma_f32_16x16x32_bf16 v[104:107], v[184:187], v[160:163], v[104:107]
	v_mfma_f32_16x16x32_bf16 v[96:99], v[202:205], v[160:163], v[96:99]
	v_mfma_f32_16x16x32_bf16 v[88:91], v[184:187], v[168:171], v[88:91]
	v_mfma_f32_16x16x32_bf16 v[80:83], v[202:205], v[168:171], v[80:83]
	v_mfma_f32_16x16x32_bf16 v[72:75], v[184:187], v[176:179], v[72:75]
	v_mfma_f32_16x16x32_bf16 v[68:71], v[202:205], v[176:179], v[68:71]
	s_barrier
	ds_read_b128 v[148:151], v224 offset:16384
	ds_read_b128 v[152:155], v224 offset:17408
	ds_read_b128 v[156:159], v224 offset:18432
	ds_read_b128 v[160:163], v224 offset:19456
	ds_read_b128 v[164:167], v224 offset:20480
	ds_read_b128 v[168:171], v224 offset:21504
	ds_read_b128 v[172:175], v224 offset:22528
	ds_read_b128 v[176:179], v224 offset:23552
	s_add_i32 s52, s52, s30
	v_lshl_add_u64 v[206:207], s[20:21], 0, v[2:3]
	s_mov_b32 m0, s52
	s_nop 0
	global_load_lds_dwordx4 v[206:207], off
	v_lshl_add_u64 v[208:209], s[20:21], 0, v[192:193]
	s_add_i32 m0, s52, 0x2000
	s_nop 0
	global_load_lds_dwordx4 v[208:209], off
	s_mov_b32 m0, s31
	v_lshl_add_u64 v[210:211], s[24:25], 0, v[196:197]
	global_load_lds_dwordx4 v[210:211], off
	v_lshl_add_u64 v[212:213], s[24:25], 0, v[194:195]
	s_mov_b32 m0, s35
	s_nop 0
	global_load_lds_dwordx4 v[212:213], off
	s_add_u32 s52, s20, 0x80000
	s_addc_u32 s53, s21, 0
	s_add_i32 s54, s54, s30
	s_mov_b32 m0, s54
	s_nop 0
	global_load_lds_dwordx4 v2, s[52:53]
	s_add_i32 m0, s54, 0x2000
	s_nop 0
	global_load_lds_dwordx4 v192, s[52:53]
	s_waitcnt lgkmcnt(0)
	s_waitcnt vmcnt(6)
	s_barrier
; #define PG8_STAGE(bufoff, gbase, voff) do { _Pragma("unroll") for (int _i = 0; _i < 2; ++_i) \
;         __builtin_amdgcn_global_load_lds((const unsigned*)((const char*)(gbase) + (voff)[_i]), (LAS unsigned*)(lds + (bufoff) + ldsw + _i * 8192), 16, 0, 0); } while (0)
; #define PG8_LDA(dst, b, h) do { _Pragma("unroll") for (int m = 0; m < 4; ++m) _Pragma("unroll") for (int k = 0; k < 2; ++k) dst[m][k] = *(const LAS bf16x8*)(lds + PG8_SA(b, h) + aoff + m * 2048 + k * 1024); } while (0)
; #define PG8_LDB(dst, b, h) do { _Pragma("unroll") for (int n = 0; n < 2; ++n) _Pragma("unroll") for (int k = 0; k < 2; ++k) dst[n][k] = *(const LAS bf16x8*)(lds + PG8_SB(b, h) + boff + n * 2048 + k * 1024); } while (0)
; #define PG8_MMA(ai, bj, At, Bt) do { __builtin_amdgcn_s_setprio(1); _Pragma("unroll") for (int m = 0; m < 4; ++m) _Pragma("unroll") for (int n = 0; n < 2; ++n) _Pragma("unroll") for (int k = 0; k < 2; ++k) \
;         acc[ai][bj][m][n] = __builtin_amdgcn_mfma_f32_16x16x32_bf16(Bt[n][k], At[m][k], acc[ai][bj][m][n], 0, 0, 0); __builtin_amdgcn_s_setprio(0); } while (0)
; #define PG8_WAIT_V(n) asm volatile("s_waitcnt vmcnt(" #n ")" ::: "memory")
; #define PG8_WAIT_L(n) asm volatile("s_waitcnt lgkmcnt(" #n ")" ::: "memory")
; #define PG8_BAR __builtin_amdgcn_s_barrier()
; #define PG8_SCHED __builtin_amdgcn_sched_barrier(0)
; template <class Epi, class Sched>
; __device__ __forceinline__ void gemm_phase(LAS unsigned char* lds, const Gemm g, const Sched& S, const Epi& E) {
;     ...
;             PG8_BAR; PG8_WAIT_L(0); PG8_MMA(0, 1, At, B1); PG8_BAR;
;             PG8_LDA(At, 0, 1); PG8_STAGE(PG8_SA(0, 0), a2, voffA);
;             PG8_BAR; PG8_WAIT_L(0); PG8_MMA(1, 0, At, B0); PG8_BAR; PG8_SCHED;
;             PG8_STAGE(PG8_SB(0, 1), b2 + hstepB, voffB);
;             PG8_WAIT_V(6); PG8_BAR; PG8_MMA(1, 1, At, B1); PG8_BAR;
;             PG8_LDB(B0, 1, 0); PG8_SCHED; PG8_LDA(At, 1, 0); PG8_STAGE(PG8_SA(0, 1), a2 + hstepA, voffA);
;             PG8_WAIT_L(8); PG8_BAR; PG8_WAIT_L(0); PG8_MMA(0, 0, At, B0); PG8_BAR; PG8_SCHED;
;             PG8_LDB(B1, 1, 1); PG8_STAGE(PG8_SB(1, 0), b3, voffB);
;             PG8_BAR; PG8_WAIT_L(0); PG8_MMA(0, 1, At, B1); PG8_BAR;
	v_mfma_f32_16x16x32_bf16 v[64:67], v[132:135], v[148:151], 0
	v_mfma_f32_16x16x32_bf16 v[60:63], v[140:143], v[148:151], 0
	v_mfma_f32_16x16x32_bf16 v[52:55], v[132:135], v[156:159], 0
	v_mfma_f32_16x16x32_bf16 v[44:47], v[140:143], v[156:159], 0
	v_mfma_f32_16x16x32_bf16 v[36:39], v[132:135], v[164:167], 0
	v_mfma_f32_16x16x32_bf16 v[28:31], v[140:143], v[164:167], 0
	v_mfma_f32_16x16x32_bf16 v[20:23], v[132:135], v[172:175], 0
	v_mfma_f32_16x16x32_bf16 v[12:15], v[140:143], v[172:175], 0
	v_mfma_f32_16x16x32_bf16 v[64:67], v[136:139], v[152:155], v[64:67]
	v_mfma_f32_16x16x32_bf16 v[60:63], v[144:147], v[152:155], v[60:63]
	v_mfma_f32_16x16x32_bf16 v[52:55], v[136:139], v[160:163], v[52:55]
	v_mfma_f32_16x16x32_bf16 v[44:47], v[144:147], v[160:163], v[44:47]
	v_mfma_f32_16x16x32_bf16 v[36:39], v[136:139], v[168:171], v[36:39]
	v_mfma_f32_16x16x32_bf16 v[28:31], v[144:147], v[168:171], v[28:31]
	v_mfma_f32_16x16x32_bf16 v[20:23], v[136:139], v[176:179], v[20:23]
	v_mfma_f32_16x16x32_bf16 v[12:15], v[144:147], v[176:179], v[12:15]
	v_mfma_f32_16x16x32_bf16 v[56:59], v[180:183], v[148:151], 0
	v_mfma_f32_16x16x32_bf16 v[48:51], v[188:191], v[148:151], 0
	v_mfma_f32_16x16x32_bf16 v[40:43], v[180:183], v[156:159], 0
	v_mfma_f32_16x16x32_bf16 v[32:35], v[188:191], v[156:159], 0
	v_mfma_f32_16x16x32_bf16 v[24:27], v[180:183], v[164:167], 0
	v_mfma_f32_16x16x32_bf16 v[16:19], v[188:191], v[164:167], 0
	v_mfma_f32_16x16x32_bf16 v[8:11], v[180:183], v[172:175], 0
	v_mfma_f32_16x16x32_bf16 v[4:7], v[188:191], v[172:175], 0
	v_mfma_f32_16x16x32_bf16 v[56:59], v[184:187], v[152:155], v[56:59]
	v_mfma_f32_16x16x32_bf16 v[48:51], v[202:205], v[152:155], v[48:51]
	v_mfma_f32_16x16x32_bf16 v[40:43], v[184:187], v[160:163], v[40:43]
	v_mfma_f32_16x16x32_bf16 v[32:35], v[202:205], v[160:163], v[32:35]
	v_mfma_f32_16x16x32_bf16 v[24:27], v[184:187], v[168:171], v[24:27]
	v_mfma_f32_16x16x32_bf16 v[16:19], v[202:205], v[168:171], v[16:19]
	v_mfma_f32_16x16x32_bf16 v[8:11], v[184:187], v[176:179], v[8:11]
	v_mfma_f32_16x16x32_bf16 v[4:7], v[202:205], v[176:179], v[4:7]
	s_barrier
	s_add_i32 s52, 0, 0x18000
	v_add_u32_e32 v144, s52, v1
	ds_read_b128 v[132:135], v144
	ds_read_b128 v[136:139], v144 offset:1024
	ds_read_b128 v[140:143], v144 offset:2048
	ds_read_b128 v[144:147], v144 offset:3072
	s_add_u32 s24, s24, 0x80000
	s_addc_u32 s25, s25, 0
	ds_read_b128 v[148:151], v224 offset:32768
	ds_read_b128 v[152:155], v224 offset:33792
	ds_read_b128 v[156:159], v224 offset:34816
	ds_read_b128 v[160:163], v224 offset:35840
	ds_read_b128 v[164:167], v224 offset:36864
	ds_read_b128 v[168:171], v224 offset:37888
	ds_read_b128 v[172:175], v224 offset:38912
	ds_read_b128 v[176:179], v224 offset:39936
	s_mov_b32 m0, s36
	s_nop 0
	global_load_lds_dwordx4 v196, s[24:25]
	s_mov_b32 m0, s37
	s_nop 0
	global_load_lds_dwordx4 v194, s[24:25]
	s_add_i32 s24, 0, 0x1c000
	v_add_u32_e32 v202, s24, v1
	ds_read_b128 v[180:183], v202
	ds_read_b128 v[184:187], v202 offset:1024
	ds_read_b128 v[188:191], v202 offset:2048
	ds_read_b128 v[202:205], v202 offset:3072
	s_waitcnt lgkmcnt(0)
	s_barrier
	v_mfma_f32_16x16x32_bf16 v[128:131], v[132:135], v[148:151], v[128:131]
	v_mfma_f32_16x16x32_bf16 v[124:127], v[140:143], v[148:151], v[124:127]
	v_mfma_f32_16x16x32_bf16 v[112:115], v[132:135], v[156:159], v[112:115]
	v_mfma_f32_16x16x32_bf16 v[108:111], v[140:143], v[156:159], v[108:111]
	v_mfma_f32_16x16x32_bf16 v[100:103], v[132:135], v[164:167], v[100:103]
	v_mfma_f32_16x16x32_bf16 v[92:95], v[140:143], v[164:167], v[92:95]
	v_mfma_f32_16x16x32_bf16 v[84:87], v[132:135], v[172:175], v[84:87]
	v_mfma_f32_16x16x32_bf16 v[76:79], v[140:143], v[172:175], v[76:79]
	v_mfma_f32_16x16x32_bf16 v[128:131], v[136:139], v[152:155], v[128:131]
	v_mfma_f32_16x16x32_bf16 v[124:127], v[144:147], v[152:155], v[124:127]
	v_mfma_f32_16x16x32_bf16 v[112:115], v[136:139], v[160:163], v[112:115]
	v_mfma_f32_16x16x32_bf16 v[108:111], v[144:147], v[160:163], v[108:111]
	v_mfma_f32_16x16x32_bf16 v[100:103], v[136:139], v[168:171], v[100:103]
	v_mfma_f32_16x16x32_bf16 v[92:95], v[144:147], v[168:171], v[92:95]
	v_mfma_f32_16x16x32_bf16 v[84:87], v[136:139], v[176:179], v[84:87]
	v_mfma_f32_16x16x32_bf16 v[76:79], v[144:147], v[176:179], v[76:79]
	v_mfma_f32_16x16x32_bf16 v[120:123], v[180:183], v[148:151], v[120:123]
	v_mfma_f32_16x16x32_bf16 v[116:119], v[188:191], v[148:151], v[116:119]
	v_mfma_f32_16x16x32_bf16 v[104:107], v[180:183], v[156:159], v[104:107]
	v_mfma_f32_16x16x32_bf16 v[96:99], v[188:191], v[156:159], v[96:99]
	v_mfma_f32_16x16x32_bf16 v[88:91], v[180:183], v[164:167], v[88:91]
	v_mfma_f32_16x16x32_bf16 v[80:83], v[188:191], v[164:167], v[80:83]
	v_mfma_f32_16x16x32_bf16 v[72:75], v[180:183], v[172:175], v[72:75]
	v_mfma_f32_16x16x32_bf16 v[68:71], v[188:191], v[172:175], v[68:71]
	v_mfma_f32_16x16x32_bf16 v[120:123], v[184:187], v[152:155], v[120:123]
	v_mfma_f32_16x16x32_bf16 v[116:119], v[202:205], v[152:155], v[116:119]
	v_mfma_f32_16x16x32_bf16 v[104:107], v[184:187], v[160:163], v[104:107]
	v_mfma_f32_16x16x32_bf16 v[96:99], v[202:205], v[160:163], v[96:99]
	v_mfma_f32_16x16x32_bf16 v[88:91], v[184:187], v[168:171], v[88:91]
	v_mfma_f32_16x16x32_bf16 v[80:83], v[202:205], v[168:171], v[80:83]
	v_mfma_f32_16x16x32_bf16 v[72:75], v[184:187], v[176:179], v[72:75]
	v_mfma_f32_16x16x32_bf16 v[68:71], v[202:205], v[176:179], v[68:71]
	s_barrier
; #define PG8_STAGE(bufoff, gbase, voff) do { _Pragma("unroll") for (int _i = 0; _i < 2; ++_i) \
;         __builtin_amdgcn_global_load_lds((const unsigned*)((const char*)(gbase) + (voff)[_i]), (LAS unsigned*)(lds + (bufoff) + ldsw + _i * 8192), 16, 0, 0); } while (0)
; #define PG8_LDA(dst, b, h) do { _Pragma("unroll") for (int m = 0; m < 4; ++m) _Pragma("unroll") for (int k = 0; k < 2; ++k) dst[m][k] = *(const LAS bf16x8*)(lds + PG8_SA(b, h) + aoff + m * 2048 + k * 1024); } while (0)
; #define PG8_LDB(dst, b, h) do { _Pragma("unroll") for (int n = 0; n < 2; ++n) _Pragma("unroll") for (int k = 0; k < 2; ++k) dst[n][k] = *(const LAS bf16x8*)(lds + PG8_SB(b, h) + boff + n * 2048 + k * 1024); } while (0)
; #define PG8_MMA(ai, bj, At, Bt) do { __builtin_amdgcn_s_setprio(1); _Pragma("unroll") for (int m = 0; m < 4; ++m) _Pragma("unroll") for (int n = 0; n < 2; ++n) _Pragma("unroll") for (int k = 0; k < 2; ++k) \
;         acc[ai][bj][m][n] = __builtin_amdgcn_mfma_f32_16x16x32_bf16(Bt[n][k], At[m][k], acc[ai][bj][m][n], 0, 0, 0); __builtin_amdgcn_s_setprio(0); } while (0)
; #define PG8_WAIT_V(n) asm volatile("s_waitcnt vmcnt(" #n ")" ::: "memory")
; #define PG8_BAR __builtin_amdgcn_s_barrier()
; template <class Epi, class Sched>
; __device__ __forceinline__ void gemm_phase(LAS unsigned char* lds, const Gemm g, const Sched& S, const Epi& E) {
;     ...
;         for (int t = 0; t < nt; t += 2) {
;             const bool last = (t == nt - 2);
;             const char* a1 = cA + (size_t)(t + 1) * kstep;
;             const char* a2 = last ? nA : cA + (size_t)(t + 2) * kstep; const char* b2 = last ? nB : cB + (size_t)(t + 2) * kstep;
;             const char* a3 = a2 + kstep; const char* b3 = b2 + kstep;
;             if (last && has_next) S.a_ready(nxt);
;             PG8_LDB(B0, 0, 0); PG8_SCHED; PG8_LDA(At, 0, 0); PG8_STAGE(PG8_SA(1, 1), a1 + hstepA, voffA);
;             PG8_WAIT_L(8); PG8_BAR; PG8_WAIT_L(0); PG8_MMA(0, 0, At, B0); PG8_BAR; PG8_SCHED;
;     ...
;             PG8_LDB(B1, 1, 1); PG8_STAGE(PG8_SB(1, 0), b3, voffB);
;             PG8_BAR; PG8_WAIT_L(0); PG8_MMA(0, 1, At, B1); PG8_BAR;
;             PG8_LDA(At, 1, 1); PG8_STAGE(PG8_SA(1, 0), a3, voffA);
;             PG8_BAR; PG8_WAIT_L(0); PG8_MMA(1, 0, At, B0); PG8_BAR; PG8_SCHED;
;             PG8_STAGE(PG8_SB(1, 1), b3 + hstepB, voffB);
;             PG8_WAIT_V(6); PG8_BAR; PG8_MMA(1, 1, At, B1); PG8_BAR;
	ds_read_b128 v[148:151], v224 offset:49152
	ds_read_b128 v[152:155], v224 offset:50176
	ds_read_b128 v[156:159], v224 offset:51200
	ds_read_b128 v[160:163], v224 offset:52224
	ds_read_b128 v[164:167], v224 offset:53248
	ds_read_b128 v[168:171], v224 offset:54272
	ds_read_b128 v[172:175], v224 offset:55296
	ds_read_b128 v[176:179], v224 offset:56320
	s_add_i32 s25, s52, s30
	v_lshl_add_u64 v[206:207], v[206:207], 0, s[8:9]
	s_mov_b32 m0, s25
	s_nop 0
	global_load_lds_dwordx4 v[206:207], off
	v_lshl_add_u64 v[206:207], v[208:209], 0, s[8:9]
	s_add_i32 m0, s25, 0x2000
	s_nop 0
	global_load_lds_dwordx4 v[206:207], off
	s_mov_b32 m0, s40
	v_lshl_add_u64 v[206:207], v[210:211], 0, s[8:9]
	global_load_lds_dwordx4 v[206:207], off
	v_lshl_add_u64 v[206:207], v[212:213], 0, s[8:9]
	s_mov_b32 m0, s41
	s_nop 0
	global_load_lds_dwordx4 v[206:207], off
	s_add_u32 s20, s20, 0x80080
	s_addc_u32 s21, s21, 0
	s_add_i32 s24, s24, s30
	s_mov_b32 m0, s24
	s_nop 0
	global_load_lds_dwordx4 v2, s[20:21]
	s_add_i32 m0, s24, 0x2000
	s_nop 0
	global_load_lds_dwordx4 v192, s[20:21]
	s_add_i32 s51, s51, 2
	s_add_u32 s6, s6, 0x100
	s_addc_u32 s7, s7, 0
	s_add_u32 s49, s49, 0x100
	s_addc_u32 s50, s50, 0
	s_cmp_gt_u32 s51, 29
	s_waitcnt lgkmcnt(0)
	s_waitcnt vmcnt(6)
	s_barrier
	v_mfma_f32_16x16x32_bf16 v[64:67], v[132:135], v[148:151], v[64:67]
	v_mfma_f32_16x16x32_bf16 v[60:63], v[140:143], v[148:151], v[60:63]
	v_mfma_f32_16x16x32_bf16 v[52:55], v[132:135], v[156:159], v[52:55]
	v_mfma_f32_16x16x32_bf16 v[44:47], v[140:143], v[156:159], v[44:47]
	v_mfma_f32_16x16x32_bf16 v[36:39], v[132:135], v[164:167], v[36:39]
	v_mfma_f32_16x16x32_bf16 v[28:31], v[140:143], v[164:167], v[28:31]
	v_mfma_f32_16x16x32_bf16 v[20:23], v[132:135], v[172:175], v[20:23]
	v_mfma_f32_16x16x32_bf16 v[12:15], v[140:143], v[172:175], v[12:15]
	v_mfma_f32_16x16x32_bf16 v[64:67], v[136:139], v[152:155], v[64:67]
	v_mfma_f32_16x16x32_bf16 v[60:63], v[144:147], v[152:155], v[60:63]
	v_mfma_f32_16x16x32_bf16 v[52:55], v[136:139], v[160:163], v[52:55]
	v_mfma_f32_16x16x32_bf16 v[44:47], v[144:147], v[160:163], v[44:47]
	v_mfma_f32_16x16x32_bf16 v[36:39], v[136:139], v[168:171], v[36:39]
	v_mfma_f32_16x16x32_bf16 v[28:31], v[144:147], v[168:171], v[28:31]
	v_mfma_f32_16x16x32_bf16 v[20:23], v[136:139], v[176:179], v[20:23]
	v_mfma_f32_16x16x32_bf16 v[12:15], v[144:147], v[176:179], v[12:15]
	v_mfma_f32_16x16x32_bf16 v[56:59], v[180:183], v[148:151], v[56:59]
	v_mfma_f32_16x16x32_bf16 v[48:51], v[188:191], v[148:151], v[48:51]
	v_mfma_f32_16x16x32_bf16 v[40:43], v[180:183], v[156:159], v[40:43]
	v_mfma_f32_16x16x32_bf16 v[32:35], v[188:191], v[156:159], v[32:35]
	v_mfma_f32_16x16x32_bf16 v[24:27], v[180:183], v[164:167], v[24:27]
	v_mfma_f32_16x16x32_bf16 v[16:19], v[188:191], v[164:167], v[16:19]
	v_mfma_f32_16x16x32_bf16 v[8:11], v[180:183], v[172:175], v[8:11]
	v_mfma_f32_16x16x32_bf16 v[4:7], v[188:191], v[172:175], v[4:7]
	v_mfma_f32_16x16x32_bf16 v[56:59], v[184:187], v[152:155], v[56:59]
	v_mfma_f32_16x16x32_bf16 v[48:51], v[202:205], v[152:155], v[48:51]
	v_mfma_f32_16x16x32_bf16 v[40:43], v[184:187], v[160:163], v[40:43]
	v_mfma_f32_16x16x32_bf16 v[32:35], v[202:205], v[160:163], v[32:35]
	v_mfma_f32_16x16x32_bf16 v[24:27], v[184:187], v[168:171], v[24:27]
	v_mfma_f32_16x16x32_bf16 v[16:19], v[202:205], v[168:171], v[16:19]
	v_mfma_f32_16x16x32_bf16 v[8:11], v[184:187], v[176:179], v[8:11]
	v_mfma_f32_16x16x32_bf16 v[4:7], v[202:205], v[176:179], v[4:7]
	s_barrier
	s_setprio 0
.LBB0_966:
	s_add_u32 s20, s6, 0xfff80080
	s_addc_u32 s21, s7, -1
	s_add_i32 s52, 0, 0x10000
	v_add_u32_e32 v144, s52, v1
	ds_read_b128 v[132:135], v144
	ds_read_b128 v[136:139], v144 offset:1024
	ds_read_b128 v[140:143], v144 offset:2048
	ds_read_b128 v[144:147], v144 offset:3072
	s_cmp_eq_u32 s51, 28
	s_cselect_b32 s25, s15, s21
	s_cselect_b32 s24, s47, s20
	s_cselect_b32 s21, s1, s50
	s_cselect_b32 s20, s48, s49
	ds_read_b128 v[148:151], v224
	ds_read_b128 v[152:155], v224 offset:1024
	ds_read_b128 v[156:159], v224 offset:2048
	ds_read_b128 v[160:163], v224 offset:3072
	ds_read_b128 v[164:167], v224 offset:4096
	ds_read_b128 v[168:171], v224 offset:5120
	ds_read_b128 v[172:175], v224 offset:6144
	ds_read_b128 v[176:179], v224 offset:7168
	s_add_i32 s54, 0, 0x14000
	v_add_u32_e32 v202, s54, v1
	ds_read_b128 v[180:183], v202
	ds_read_b128 v[184:187], v202 offset:1024
	ds_read_b128 v[188:191], v202 offset:2048
	ds_read_b128 v[202:205], v202 offset:3072
	s_add_i32 m0, s31, 0xc000
	s_nop 0
	global_load_lds_dwordx4 v198, s[6:7]
	s_add_i32 m0, s31, 0xe000
	s_nop 0
	global_load_lds_dwordx4 v200, s[6:7]
	s_waitcnt lgkmcnt(0)
	s_barrier
; #define PG8_STAGE(bufoff, gbase, voff) do { _Pragma("unroll") for (int _i = 0; _i < 2; ++_i) \
;         __builtin_amdgcn_global_load_lds((const unsigned*)((const char*)(gbase) + (voff)[_i]), (LAS unsigned*)(lds + (bufoff) + ldsw + _i * 8192), 16, 0, 0); } while (0)
; #define PG8_LDA(dst, b, h) do { _Pragma("unroll") for (int m = 0; m < 4; ++m) _Pragma("unroll") for (int k = 0; k < 2; ++k) dst[m][k] = *(const LAS bf16x8*)(lds + PG8_SA(b, h) + aoff + m * 2048 + k * 1024); } while (0)
; #define PG8_LDB(dst, b, h) do { _Pragma("unroll") for (int n = 0; n < 2; ++n) _Pragma("unroll") for (int k = 0; k < 2; ++k) dst[n][k] = *(const LAS bf16x8*)(lds + PG8_SB(b, h) + boff + n * 2048 + k * 1024); } while (0)
; #define PG8_MMA(ai, bj, At, Bt) do { __builtin_amdgcn_s_setprio(1); _Pragma("unroll") for (int m = 0; m < 4; ++m) _Pragma("unroll") for (int n = 0; n < 2; ++n) _Pragma("unroll") for (int k = 0; k < 2; ++k) \
;         acc[ai][bj][m][n] = __builtin_amdgcn_mfma_f32_16x16x32_bf16(Bt[n][k], At[m][k], acc[ai][bj][m][n], 0, 0, 0); __builtin_amdgcn_s_setprio(0); } while (0)
; #define PG8_WAIT_V(n) asm volatile("s_waitcnt vmcnt(" #n ")" ::: "memory")
; #define PG8_WAIT_L(n) asm volatile("s_waitcnt lgkmcnt(" #n ")" ::: "memory")
; #define PG8_BAR __builtin_amdgcn_s_barrier()
; #define PG8_SCHED __builtin_amdgcn_sched_barrier(0)
; template <class Epi, class Sched>
; __device__ __forceinline__ void gemm_phase(LAS unsigned char* lds, const Gemm g, const Sched& S, const Epi& E) {
;     ...
;             PG8_WAIT_L(8); PG8_BAR; PG8_WAIT_L(0); PG8_MMA(0, 0, At, B0); PG8_BAR; PG8_SCHED;
;             PG8_LDB(B1, 0, 1); PG8_STAGE(PG8_SB(0, 0), b2, voffB);
;             PG8_BAR; PG8_WAIT_L(0); PG8_MMA(0, 1, At, B1); PG8_BAR;
;             PG8_LDA(At, 0, 1); PG8_STAGE(PG8_SA(0, 0), a2, voffA);
;             PG8_BAR; PG8_WAIT_L(0); PG8_MMA(1, 0, At, B0); PG8_BAR; PG8_SCHED;
;             PG8_STAGE(PG8_SB(0, 1), b2 + hstepB, voffB);
;             PG8_WAIT_V(6); PG8_BAR; PG8_MMA(1, 1, At, B1); PG8_BAR;
;             PG8_LDB(B0, 1, 0); PG8_SCHED; PG8_LDA(At, 1, 0); PG8_STAGE(PG8_SA(0, 1), a2 + hstepA, voffA);
;             PG8_WAIT_L(8); PG8_BAR; PG8_WAIT_L(0); PG8_MMA(0, 0, At, B0); PG8_BAR; PG8_SCHED;
	v_mfma_f32_16x16x32_bf16 v[128:131], v[132:135], v[148:151], v[128:131]
	v_mfma_f32_16x16x32_bf16 v[124:127], v[140:143], v[148:151], v[124:127]
	v_mfma_f32_16x16x32_bf16 v[112:115], v[132:135], v[156:159], v[112:115]
	v_mfma_f32_16x16x32_bf16 v[108:111], v[140:143], v[156:159], v[108:111]
	v_mfma_f32_16x16x32_bf16 v[100:103], v[132:135], v[164:167], v[100:103]
	v_mfma_f32_16x16x32_bf16 v[92:95], v[140:143], v[164:167], v[92:95]
	v_mfma_f32_16x16x32_bf16 v[84:87], v[132:135], v[172:175], v[84:87]
	v_mfma_f32_16x16x32_bf16 v[76:79], v[140:143], v[172:175], v[76:79]
	v_mfma_f32_16x16x32_bf16 v[128:131], v[136:139], v[152:155], v[128:131]
	v_mfma_f32_16x16x32_bf16 v[124:127], v[144:147], v[152:155], v[124:127]
	v_mfma_f32_16x16x32_bf16 v[112:115], v[136:139], v[160:163], v[112:115]
	v_mfma_f32_16x16x32_bf16 v[108:111], v[144:147], v[160:163], v[108:111]
	v_mfma_f32_16x16x32_bf16 v[100:103], v[136:139], v[168:171], v[100:103]
	v_mfma_f32_16x16x32_bf16 v[92:95], v[144:147], v[168:171], v[92:95]
	v_mfma_f32_16x16x32_bf16 v[84:87], v[136:139], v[176:179], v[84:87]
	v_mfma_f32_16x16x32_bf16 v[76:79], v[144:147], v[176:179], v[76:79]
	v_mfma_f32_16x16x32_bf16 v[120:123], v[180:183], v[148:151], v[120:123]
	v_mfma_f32_16x16x32_bf16 v[116:119], v[188:191], v[148:151], v[116:119]
	v_mfma_f32_16x16x32_bf16 v[104:107], v[180:183], v[156:159], v[104:107]
	v_mfma_f32_16x16x32_bf16 v[96:99], v[188:191], v[156:159], v[96:99]
	v_mfma_f32_16x16x32_bf16 v[88:91], v[180:183], v[164:167], v[88:91]
	v_mfma_f32_16x16x32_bf16 v[80:83], v[188:191], v[164:167], v[80:83]
	v_mfma_f32_16x16x32_bf16 v[72:75], v[180:183], v[172:175], v[72:75]
	v_mfma_f32_16x16x32_bf16 v[68:71], v[188:191], v[172:175], v[68:71]
	v_mfma_f32_16x16x32_bf16 v[120:123], v[184:187], v[152:155], v[120:123]
	v_mfma_f32_16x16x32_bf16 v[116:119], v[202:205], v[152:155], v[116:119]
	v_mfma_f32_16x16x32_bf16 v[104:107], v[184:187], v[160:163], v[104:107]
	v_mfma_f32_16x16x32_bf16 v[96:99], v[202:205], v[160:163], v[96:99]
	v_mfma_f32_16x16x32_bf16 v[88:91], v[184:187], v[168:171], v[88:91]
	v_mfma_f32_16x16x32_bf16 v[80:83], v[202:205], v[168:171], v[80:83]
	v_mfma_f32_16x16x32_bf16 v[72:75], v[184:187], v[176:179], v[72:75]
	v_mfma_f32_16x16x32_bf16 v[68:71], v[202:205], v[176:179], v[68:71]
	s_barrier
	ds_read_b128 v[148:151], v224 offset:16384
	ds_read_b128 v[152:155], v224 offset:17408
	ds_read_b128 v[156:159], v224 offset:18432
	ds_read_b128 v[160:163], v224 offset:19456
	ds_read_b128 v[164:167], v224 offset:20480
	ds_read_b128 v[168:171], v224 offset:21504
	ds_read_b128 v[172:175], v224 offset:22528
	ds_read_b128 v[176:179], v224 offset:23552
	s_add_i32 s52, s52, s30
	v_lshl_add_u64 v[206:207], s[20:21], 0, v[2:3]
	s_mov_b32 m0, s52
	s_nop 0
	global_load_lds_dwordx4 v[206:207], off
	v_lshl_add_u64 v[208:209], s[20:21], 0, v[192:193]
	s_add_i32 m0, s52, 0x2000
	s_nop 0
	global_load_lds_dwordx4 v[208:209], off
	s_mov_b32 m0, s31
	v_lshl_add_u64 v[210:211], s[24:25], 0, v[196:197]
	global_load_lds_dwordx4 v[210:211], off
	v_lshl_add_u64 v[212:213], s[24:25], 0, v[194:195]
	s_mov_b32 m0, s35
	s_nop 0
	global_load_lds_dwordx4 v[212:213], off
	s_add_u32 s52, s20, 0x80000
	s_addc_u32 s53, s21, 0
	s_add_i32 s54, s54, s30
	s_mov_b32 m0, s54
	s_nop 0
	global_load_lds_dwordx4 v2, s[52:53]
	s_add_i32 m0, s54, 0x2000
	s_nop 0
	global_load_lds_dwordx4 v192, s[52:53]
	s_waitcnt lgkmcnt(0)
	s_waitcnt vmcnt(6)
	s_barrier
	v_mfma_f32_16x16x32_bf16 v[64:67], v[132:135], v[148:151], v[64:67]
	v_mfma_f32_16x16x32_bf16 v[60:63], v[140:143], v[148:151], v[60:63]
	v_mfma_f32_16x16x32_bf16 v[52:55], v[132:135], v[156:159], v[52:55]
	v_mfma_f32_16x16x32_bf16 v[44:47], v[140:143], v[156:159], v[44:47]
	v_mfma_f32_16x16x32_bf16 v[36:39], v[132:135], v[164:167], v[36:39]
	v_mfma_f32_16x16x32_bf16 v[28:31], v[140:143], v[164:167], v[28:31]
	v_mfma_f32_16x16x32_bf16 v[20:23], v[132:135], v[172:175], v[20:23]
	v_mfma_f32_16x16x32_bf16 v[12:15], v[140:143], v[172:175], v[12:15]
	v_mfma_f32_16x16x32_bf16 v[64:67], v[136:139], v[152:155], v[64:67]
	v_mfma_f32_16x16x32_bf16 v[60:63], v[144:147], v[152:155], v[60:63]
	v_mfma_f32_16x16x32_bf16 v[52:55], v[136:139], v[160:163], v[52:55]
	v_mfma_f32_16x16x32_bf16 v[44:47], v[144:147], v[160:163], v[44:47]
	v_mfma_f32_16x16x32_bf16 v[36:39], v[136:139], v[168:171], v[36:39]
	v_mfma_f32_16x16x32_bf16 v[28:31], v[144:147], v[168:171], v[28:31]
	v_mfma_f32_16x16x32_bf16 v[20:23], v[136:139], v[176:179], v[20:23]
	v_mfma_f32_16x16x32_bf16 v[12:15], v[144:147], v[176:179], v[12:15]
	v_mfma_f32_16x16x32_bf16 v[56:59], v[180:183], v[148:151], v[56:59]
	v_mfma_f32_16x16x32_bf16 v[48:51], v[188:191], v[148:151], v[48:51]
	v_mfma_f32_16x16x32_bf16 v[40:43], v[180:183], v[156:159], v[40:43]
	v_mfma_f32_16x16x32_bf16 v[32:35], v[188:191], v[156:159], v[32:35]
	v_mfma_f32_16x16x32_bf16 v[24:27], v[180:183], v[164:167], v[24:27]
	v_mfma_f32_16x16x32_bf16 v[16:19], v[188:191], v[164:167], v[16:19]
	v_mfma_f32_16x16x32_bf16 v[8:11], v[180:183], v[172:175], v[8:11]
	v_mfma_f32_16x16x32_bf16 v[4:7], v[188:191], v[172:175], v[4:7]
	v_mfma_f32_16x16x32_bf16 v[56:59], v[184:187], v[152:155], v[56:59]
	v_mfma_f32_16x16x32_bf16 v[48:51], v[202:205], v[152:155], v[48:51]
	v_mfma_f32_16x16x32_bf16 v[40:43], v[184:187], v[160:163], v[40:43]
	v_mfma_f32_16x16x32_bf16 v[32:35], v[202:205], v[160:163], v[32:35]
	v_mfma_f32_16x16x32_bf16 v[24:27], v[184:187], v[168:171], v[24:27]
	v_mfma_f32_16x16x32_bf16 v[16:19], v[202:205], v[168:171], v[16:19]
	v_mfma_f32_16x16x32_bf16 v[8:11], v[184:187], v[176:179], v[8:11]
	v_mfma_f32_16x16x32_bf16 v[4:7], v[202:205], v[176:179], v[4:7]
	s_barrier
; #define PG8_STAGE(bufoff, gbase, voff) do { _Pragma("unroll") for (int _i = 0; _i < 2; ++_i) \
;         __builtin_amdgcn_global_load_lds((const unsigned*)((const char*)(gbase) + (voff)[_i]), (LAS unsigned*)(lds + (bufoff) + ldsw + _i * 8192), 16, 0, 0); } while (0)
; #define PG8_LDA(dst, b, h) do { _Pragma("unroll") for (int m = 0; m < 4; ++m) _Pragma("unroll") for (int k = 0; k < 2; ++k) dst[m][k] = *(const LAS bf16x8*)(lds + PG8_SA(b, h) + aoff + m * 2048 + k * 1024); } while (0)
; #define PG8_LDB(dst, b, h) do { _Pragma("unroll") for (int n = 0; n < 2; ++n) _Pragma("unroll") for (int k = 0; k < 2; ++k) dst[n][k] = *(const LAS bf16x8*)(lds + PG8_SB(b, h) + boff + n * 2048 + k * 1024); } while (0)
; #define PG8_MMA(ai, bj, At, Bt) do { __builtin_amdgcn_s_setprio(1); _Pragma("unroll") for (int m = 0; m < 4; ++m) _Pragma("unroll") for (int n = 0; n < 2; ++n) _Pragma("unroll") for (int k = 0; k < 2; ++k) \
;         acc[ai][bj][m][n] = __builtin_amdgcn_mfma_f32_16x16x32_bf16(Bt[n][k], At[m][k], acc[ai][bj][m][n], 0, 0, 0); __builtin_amdgcn_s_setprio(0); } while (0)
; #define PG8_WAIT_V(n) asm volatile("s_waitcnt vmcnt(" #n ")" ::: "memory")
; #define PG8_WAIT_L(n) asm volatile("s_waitcnt lgkmcnt(" #n ")" ::: "memory")
; #define PG8_BAR __builtin_amdgcn_s_barrier()
; #define PG8_SCHED __builtin_amdgcn_sched_barrier(0)
; template <class Epi, class Sched>
; __device__ __forceinline__ void gemm_phase(LAS unsigned char* lds, const Gemm g, const Sched& S, const Epi& E) {
;     ...
;             PG8_LDB(B0, 1, 0); PG8_SCHED; PG8_LDA(At, 1, 0); PG8_STAGE(PG8_SA(0, 1), a2 + hstepA, voffA);
;             PG8_WAIT_L(8); PG8_BAR; PG8_WAIT_L(0); PG8_MMA(0, 0, At, B0); PG8_BAR; PG8_SCHED;
;             PG8_LDB(B1, 1, 1); PG8_STAGE(PG8_SB(1, 0), b3, voffB);
;             PG8_BAR; PG8_WAIT_L(0); PG8_MMA(0, 1, At, B1); PG8_BAR;
;             PG8_LDA(At, 1, 1); PG8_STAGE(PG8_SA(1, 0), a3, voffA);
;             PG8_BAR; PG8_WAIT_L(0); PG8_MMA(1, 0, At, B0); PG8_BAR; PG8_SCHED;
;             PG8_STAGE(PG8_SB(1, 1), b3 + hstepB, voffB);
;             PG8_WAIT_V(6); PG8_BAR; PG8_MMA(1, 1, At, B1); PG8_BAR;
;         }
;     ...
;     PG8_WAIT_V(0);
;     if (wr == 0) PG8_BAR;
	s_add_i32 s52, 0, 0x18000
	v_add_u32_e32 v144, s52, v1
	ds_read_b128 v[132:135], v144
	ds_read_b128 v[136:139], v144 offset:1024
	ds_read_b128 v[140:143], v144 offset:2048
	ds_read_b128 v[144:147], v144 offset:3072
	s_add_u32 s24, s24, 0x80000
	s_addc_u32 s25, s25, 0
	ds_read_b128 v[148:151], v224 offset:32768
	ds_read_b128 v[152:155], v224 offset:33792
	ds_read_b128 v[156:159], v224 offset:34816
	ds_read_b128 v[160:163], v224 offset:35840
	ds_read_b128 v[164:167], v224 offset:36864
	ds_read_b128 v[168:171], v224 offset:37888
	ds_read_b128 v[172:175], v224 offset:38912
	ds_read_b128 v[176:179], v224 offset:39936
	s_mov_b32 m0, s36
	s_nop 0
	global_load_lds_dwordx4 v196, s[24:25]
	s_mov_b32 m0, s37
	s_nop 0
	global_load_lds_dwordx4 v194, s[24:25]
	s_add_i32 s24, 0, 0x1c000
	v_add_u32_e32 v202, s24, v1
	ds_read_b128 v[180:183], v202
	ds_read_b128 v[184:187], v202 offset:1024
	ds_read_b128 v[188:191], v202 offset:2048
	ds_read_b128 v[202:205], v202 offset:3072
	s_waitcnt lgkmcnt(0)
	s_barrier
	v_mfma_f32_16x16x32_bf16 v[128:131], v[132:135], v[148:151], v[128:131]
	v_mfma_f32_16x16x32_bf16 v[124:127], v[140:143], v[148:151], v[124:127]
	v_mfma_f32_16x16x32_bf16 v[112:115], v[132:135], v[156:159], v[112:115]
	v_mfma_f32_16x16x32_bf16 v[108:111], v[140:143], v[156:159], v[108:111]
	v_mfma_f32_16x16x32_bf16 v[100:103], v[132:135], v[164:167], v[100:103]
	v_mfma_f32_16x16x32_bf16 v[92:95], v[140:143], v[164:167], v[92:95]
	v_mfma_f32_16x16x32_bf16 v[84:87], v[132:135], v[172:175], v[84:87]
	v_mfma_f32_16x16x32_bf16 v[76:79], v[140:143], v[172:175], v[76:79]
	v_mfma_f32_16x16x32_bf16 v[128:131], v[136:139], v[152:155], v[128:131]
	v_mfma_f32_16x16x32_bf16 v[124:127], v[144:147], v[152:155], v[124:127]
	v_mfma_f32_16x16x32_bf16 v[112:115], v[136:139], v[160:163], v[112:115]
	v_mfma_f32_16x16x32_bf16 v[108:111], v[144:147], v[160:163], v[108:111]
	v_mfma_f32_16x16x32_bf16 v[100:103], v[136:139], v[168:171], v[100:103]
	v_mfma_f32_16x16x32_bf16 v[92:95], v[144:147], v[168:171], v[92:95]
	v_mfma_f32_16x16x32_bf16 v[84:87], v[136:139], v[176:179], v[84:87]
	v_mfma_f32_16x16x32_bf16 v[76:79], v[144:147], v[176:179], v[76:79]
	v_mfma_f32_16x16x32_bf16 v[120:123], v[180:183], v[148:151], v[120:123]
	v_mfma_f32_16x16x32_bf16 v[116:119], v[188:191], v[148:151], v[116:119]
	v_mfma_f32_16x16x32_bf16 v[104:107], v[180:183], v[156:159], v[104:107]
	v_mfma_f32_16x16x32_bf16 v[96:99], v[188:191], v[156:159], v[96:99]
	v_mfma_f32_16x16x32_bf16 v[88:91], v[180:183], v[164:167], v[88:91]
	v_mfma_f32_16x16x32_bf16 v[80:83], v[188:191], v[164:167], v[80:83]
	v_mfma_f32_16x16x32_bf16 v[72:75], v[180:183], v[172:175], v[72:75]
	v_mfma_f32_16x16x32_bf16 v[68:71], v[188:191], v[172:175], v[68:71]
	v_mfma_f32_16x16x32_bf16 v[120:123], v[184:187], v[152:155], v[120:123]
	v_mfma_f32_16x16x32_bf16 v[116:119], v[202:205], v[152:155], v[116:119]
	v_mfma_f32_16x16x32_bf16 v[104:107], v[184:187], v[160:163], v[104:107]
	v_mfma_f32_16x16x32_bf16 v[96:99], v[202:205], v[160:163], v[96:99]
	v_mfma_f32_16x16x32_bf16 v[88:91], v[184:187], v[168:171], v[88:91]
	v_mfma_f32_16x16x32_bf16 v[80:83], v[202:205], v[168:171], v[80:83]
	v_mfma_f32_16x16x32_bf16 v[72:75], v[184:187], v[176:179], v[72:75]
	v_mfma_f32_16x16x32_bf16 v[68:71], v[202:205], v[176:179], v[68:71]
	s_barrier
	ds_read_b128 v[148:151], v224 offset:49152
	ds_read_b128 v[152:155], v224 offset:50176
	ds_read_b128 v[156:159], v224 offset:51200
	ds_read_b128 v[160:163], v224 offset:52224
	ds_read_b128 v[164:167], v224 offset:53248
	ds_read_b128 v[168:171], v224 offset:54272
	ds_read_b128 v[172:175], v224 offset:55296
	ds_read_b128 v[176:179], v224 offset:56320
	s_add_i32 s25, s52, s30
	v_lshl_add_u64 v[206:207], v[206:207], 0, s[8:9]
	s_mov_b32 m0, s25
	s_nop 0
	global_load_lds_dwordx4 v[206:207], off
	v_lshl_add_u64 v[206:207], v[208:209], 0, s[8:9]
	s_add_i32 m0, s25, 0x2000
	s_nop 0
	global_load_lds_dwordx4 v[206:207], off
	s_mov_b32 m0, s40
	v_lshl_add_u64 v[206:207], v[210:211], 0, s[8:9]
	global_load_lds_dwordx4 v[206:207], off
	v_lshl_add_u64 v[206:207], v[212:213], 0, s[8:9]
	s_mov_b32 m0, s41
	s_nop 0
	global_load_lds_dwordx4 v[206:207], off
	s_add_u32 s20, s20, 0x80080
	s_addc_u32 s21, s21, 0
	s_add_i32 s24, s24, s30
	s_mov_b32 m0, s24
	s_nop 0
	global_load_lds_dwordx4 v2, s[20:21]
	s_add_i32 m0, s24, 0x2000
	s_nop 0
	global_load_lds_dwordx4 v192, s[20:21]
	s_add_i32 s51, s51, 2
	s_add_u32 s6, s6, 0x100
	s_addc_u32 s7, s7, 0
	s_add_u32 s49, s49, 0x100
	s_addc_u32 s50, s50, 0
	s_cmp_gt_u32 s51, 29
	s_waitcnt lgkmcnt(0)
	s_waitcnt vmcnt(6)
	s_barrier
	v_mfma_f32_16x16x32_bf16 v[64:67], v[132:135], v[148:151], v[64:67]
	v_mfma_f32_16x16x32_bf16 v[60:63], v[140:143], v[148:151], v[60:63]
	v_mfma_f32_16x16x32_bf16 v[52:55], v[132:135], v[156:159], v[52:55]
	v_mfma_f32_16x16x32_bf16 v[44:47], v[140:143], v[156:159], v[44:47]
	v_mfma_f32_16x16x32_bf16 v[36:39], v[132:135], v[164:167], v[36:39]
	v_mfma_f32_16x16x32_bf16 v[28:31], v[140:143], v[164:167], v[28:31]
	v_mfma_f32_16x16x32_bf16 v[20:23], v[132:135], v[172:175], v[20:23]
	v_mfma_f32_16x16x32_bf16 v[12:15], v[140:143], v[172:175], v[12:15]
	v_mfma_f32_16x16x32_bf16 v[64:67], v[136:139], v[152:155], v[64:67]
	v_mfma_f32_16x16x32_bf16 v[60:63], v[144:147], v[152:155], v[60:63]
	v_mfma_f32_16x16x32_bf16 v[52:55], v[136:139], v[160:163], v[52:55]
	v_mfma_f32_16x16x32_bf16 v[44:47], v[144:147], v[160:163], v[44:47]
	v_mfma_f32_16x16x32_bf16 v[36:39], v[136:139], v[168:171], v[36:39]
	v_mfma_f32_16x16x32_bf16 v[28:31], v[144:147], v[168:171], v[28:31]
	v_mfma_f32_16x16x32_bf16 v[20:23], v[136:139], v[176:179], v[20:23]
	v_mfma_f32_16x16x32_bf16 v[12:15], v[144:147], v[176:179], v[12:15]
	v_mfma_f32_16x16x32_bf16 v[56:59], v[180:183], v[148:151], v[56:59]
	v_mfma_f32_16x16x32_bf16 v[48:51], v[188:191], v[148:151], v[48:51]
	v_mfma_f32_16x16x32_bf16 v[40:43], v[180:183], v[156:159], v[40:43]
	v_mfma_f32_16x16x32_bf16 v[32:35], v[188:191], v[156:159], v[32:35]
	v_mfma_f32_16x16x32_bf16 v[24:27], v[180:183], v[164:167], v[24:27]
	v_mfma_f32_16x16x32_bf16 v[16:19], v[188:191], v[164:167], v[16:19]
	v_mfma_f32_16x16x32_bf16 v[8:11], v[180:183], v[172:175], v[8:11]
	v_mfma_f32_16x16x32_bf16 v[4:7], v[188:191], v[172:175], v[4:7]
	v_mfma_f32_16x16x32_bf16 v[56:59], v[184:187], v[152:155], v[56:59]
	v_mfma_f32_16x16x32_bf16 v[48:51], v[202:205], v[152:155], v[48:51]
	v_mfma_f32_16x16x32_bf16 v[40:43], v[184:187], v[160:163], v[40:43]
	v_mfma_f32_16x16x32_bf16 v[32:35], v[202:205], v[160:163], v[32:35]
	v_mfma_f32_16x16x32_bf16 v[24:27], v[184:187], v[168:171], v[24:27]
	v_mfma_f32_16x16x32_bf16 v[16:19], v[202:205], v[168:171], v[16:19]
	v_mfma_f32_16x16x32_bf16 v[8:11], v[184:187], v[176:179], v[8:11]
	v_mfma_f32_16x16x32_bf16 v[4:7], v[202:205], v[176:179], v[4:7]
	s_barrier
	s_cbranch_scc0 .LBB0_966
	s_cmpk_gt_u32 s2, 0xff
	s_cbranch_scc1 .Lalign_a_966
	s_barrier
; __device__ __forceinline__ unsigned cvt_pk_bf16(float lo, float hi) { const f32x2 v = {lo, hi}; const bf16v2_ r = __builtin_convertvector(v, bf16v2_); return __builtin_bit_cast(unsigned, r); }
; __device__ __forceinline__ float bflo(unsigned w) { return __uint_as_float(w << 16); }
; __device__ __forceinline__ float bfhi(unsigned w) { return __uint_as_float(w & 0xffff0000u); }
; __device__ __forceinline__ int opaque_tid() { int t = threadIdx.x; asm volatile("" : "+v"(t)); return t; }
;     __device__ __forceinline__ void operator()(const f32x4 (&acc)[2][2][4][2], const Unit& u, int wr, int wc, int, int) const {
;         const int ol_ = opaque_tid() & 63, fr = ol_ & 15, fq = ol_ >> 4;
;         const int row0 = u.pm * BM + wr * 64 + fr, col0 = u.pn * BM + wc * 32 + 8 * fq;
;         u32x4 cin[2][4][2];
; #pragma unroll
;         for (int ai = 0; ai < 2; ++ai)
; #pragma unroll
;             for (int m = 0; m < 4; ++m)
; #pragma unroll
;                 for (int bj = 0; bj < 2; ++bj) cin[ai][m][bj] = *(const u32x4*)(C + (size_t)(row0 + ai * HALF + m * 16) * ldc + col0 + bj * HALF);
; #pragma unroll
;         for (int ai = 0; ai < 2; ++ai)
; #pragma unroll
;             for (int m = 0; m < 4; ++m)
; #pragma unroll
;                 for (int bj = 0; bj < 2; ++bj) { const u32x4 c = cin[ai][m][bj]; const f32x4 v0 = acc[ai][bj][m][0], v1 = acc[ai][bj][m][1];
;                     u32x4 w; w.x = cvt_pk_bf16(bflo(c.x) + v0[0], bfhi(c.x) + v0[1]); w.y = cvt_pk_bf16(bflo(c.y) + v0[2], bfhi(c.y) + v0[3]);
;                     w.z = cvt_pk_bf16(bflo(c.z) + v1[0], bfhi(c.z) + v1[1]); w.w = cvt_pk_bf16(bflo(c.w) + v1[2], bfhi(c.w) + v1[3]);
;                     *(u32x4*)(C + (size_t)(row0 + ai * HALF + m * 16) * ldc + col0 + bj * HALF) = w; }
.Lalign_a_966:
	v_mov_b32_e32 v133, v0
	s_lshl_b32 s1, s46, 8
	s_add_i32 s1, s1, s38
	v_and_or_b32 v132, v133, 15, s1
	s_lshl_b32 s1, s45, 8
	v_lshrrev_b32_e32 v133, 1, v133
	v_and_or_b32 v133, v133, 24, s1
	v_or_b32_e32 v134, s39, v133
	v_ashrrev_i32_e32 v135, 31, v134
	v_lshlrev_b64 v[202:203], 1, v[134:135]
	v_ashrrev_i32_e32 v133, 31, v132
	v_lshl_add_u64 v[134:135], s[88:89], 0, v[202:203]
	v_lshlrev_b64 v[226:227], 12, v[132:133]
	v_lshl_add_u64 v[136:137], v[134:135], 0, v[226:227]
	global_load_dwordx4 v[216:219], v[136:137], off
	global_load_dwordx4 v[188:191], v[136:137], off offset:256
	v_or_b32_e32 v136, 16, v132
	v_ashrrev_i32_e32 v137, 31, v136
	v_lshlrev_b64 v[222:223], 12, v[136:137]
	v_lshl_add_u64 v[136:137], v[134:135], 0, v[222:223]
	global_load_dwordx4 v[184:187], v[136:137], off
	global_load_dwordx4 v[180:183], v[136:137], off offset:256
	v_or_b32_e32 v136, 32, v132
	v_ashrrev_i32_e32 v137, 31, v136
	v_lshlrev_b64 v[220:221], 12, v[136:137]
	v_lshl_add_u64 v[136:137], v[134:135], 0, v[220:221]
	global_load_dwordx4 v[176:179], v[136:137], off
	global_load_dwordx4 v[168:171], v[136:137], off offset:256
	v_or_b32_e32 v132, 48, v132
	v_ashrrev_i32_e32 v133, 31, v132
	v_lshlrev_b64 v[212:213], 12, v[132:133]
	v_lshl_add_u64 v[132:133], v[134:135], 0, v[212:213]
	global_load_dwordx4 v[172:175], v[132:133], off
	global_load_dwordx4 v[164:167], v[132:133], off offset:256
	s_mov_b64 s[6:7], 0x80000
	v_lshl_add_u64 v[210:211], v[226:227], 0, s[6:7]
	v_lshl_add_u64 v[132:133], v[134:135], 0, v[210:211]
	global_load_dwordx4 v[160:163], v[132:133], off
	global_load_dwordx4 v[156:159], v[132:133], off offset:256
	s_mov_b64 s[6:7], 0x90000
	v_lshl_add_u64 v[208:209], v[226:227], 0, s[6:7]
	v_lshl_add_u64 v[132:133], v[134:135], 0, v[208:209]
	global_load_dwordx4 v[152:155], v[132:133], off
	global_load_dwordx4 v[148:151], v[132:133], off offset:256
	s_mov_b64 s[6:7], 0xa0000
	v_lshl_add_u64 v[206:207], v[226:227], 0, s[6:7]
	v_lshl_add_u64 v[132:133], v[134:135], 0, v[206:207]
	global_load_dwordx4 v[144:147], v[132:133], off
	global_load_dwordx4 v[140:143], v[132:133], off offset:256
	s_mov_b64 s[6:7], 0xb0000
	v_lshl_add_u64 v[204:205], v[226:227], 0, s[6:7]
	v_lshl_add_u64 v[132:133], v[134:135], 0, v[204:205]
	global_load_dwordx4 v[136:139], v[132:133], off
	s_nop 0
	global_load_dwordx4 v[132:135], v[132:133], off offset:256
	s_and_b64 vcc, exec, s[42:43]
	s_mov_b32 s45, s0
	s_mov_b32 s46, s14
	s_mov_b64 s[20:21], s[18:19]
	s_mov_b64 s[6:7], s[4:5]
	s_waitcnt vmcnt(15)
	v_lshlrev_b32_e32 v228, 16, v216
	v_and_b32_e32 v229, 0xffff0000, v216
	v_lshlrev_b32_e32 v216, 16, v217
	v_and_b32_e32 v217, 0xffff0000, v217
	v_pk_add_f32 v[128:129], v[128:129], v[228:229]
	v_pk_add_f32 v[130:131], v[130:131], v[216:217]
	v_cvt_pk_bf16_f32 v128, v128, v129
	v_cvt_pk_bf16_f32 v129, v130, v131
	v_lshlrev_b32_e32 v130, 16, v218
	v_and_b32_e32 v131, 0xffff0000, v218
	v_pk_add_f32 v[124:125], v[124:125], v[130:131]
	s_nop 0
	v_cvt_pk_bf16_f32 v130, v124, v125
	v_lshlrev_b32_e32 v124, 16, v219
	v_and_b32_e32 v125, 0xffff0000, v219
	v_pk_add_f32 v[124:125], v[126:127], v[124:125]
	s_waitcnt vmcnt(14)
	v_lshlrev_b32_e32 v126, 16, v188
	v_and_b32_e32 v127, 0xffff0000, v188
	v_pk_add_f32 v[120:121], v[120:121], v[126:127]
	v_lshlrev_b32_e32 v126, 16, v189
	v_and_b32_e32 v127, 0xffff0000, v189
	v_pk_add_f32 v[122:123], v[122:123], v[126:127]
	v_cvt_pk_bf16_f32 v120, v120, v121
	v_cvt_pk_bf16_f32 v121, v122, v123
	v_lshlrev_b32_e32 v122, 16, v190
	v_and_b32_e32 v123, 0xffff0000, v190
	v_pk_add_f32 v[116:117], v[116:117], v[122:123]
	v_cvt_pk_bf16_f32 v131, v124, v125
	v_cvt_pk_bf16_f32 v122, v116, v117
	v_lshlrev_b32_e32 v116, 16, v191
	v_and_b32_e32 v117, 0xffff0000, v191
	v_pk_add_f32 v[116:117], v[118:119], v[116:117]
	v_lshl_add_u64 v[124:125], s[88:89], 0, v[226:227]
	v_cvt_pk_bf16_f32 v123, v116, v117
	s_waitcnt vmcnt(13)
	v_lshlrev_b32_e32 v116, 16, v184
	v_and_b32_e32 v117, 0xffff0000, v184
	v_pk_add_f32 v[112:113], v[112:113], v[116:117]
	v_lshlrev_b32_e32 v116, 16, v185
	v_and_b32_e32 v117, 0xffff0000, v185
	v_pk_add_f32 v[114:115], v[114:115], v[116:117]
	v_cvt_pk_bf16_f32 v112, v112, v113
	v_cvt_pk_bf16_f32 v113, v114, v115
	v_lshlrev_b32_e32 v114, 16, v186
	v_and_b32_e32 v115, 0xffff0000, v186
	v_pk_add_f32 v[108:109], v[108:109], v[114:115]
	v_lshl_add_u64 v[124:125], v[124:125], 0, v[202:203]
	v_cvt_pk_bf16_f32 v114, v108, v109
	v_lshlrev_b32_e32 v108, 16, v187
	v_and_b32_e32 v109, 0xffff0000, v187
	v_pk_add_f32 v[108:109], v[110:111], v[108:109]
	s_waitcnt vmcnt(12)
	v_lshlrev_b32_e32 v110, 16, v180
	v_and_b32_e32 v111, 0xffff0000, v180
	v_pk_add_f32 v[104:105], v[104:105], v[110:111]
	v_lshlrev_b32_e32 v110, 16, v181
	v_and_b32_e32 v111, 0xffff0000, v181
	v_pk_add_f32 v[106:107], v[106:107], v[110:111]
	v_cvt_pk_bf16_f32 v104, v104, v105
	v_cvt_pk_bf16_f32 v105, v106, v107
	v_lshlrev_b32_e32 v106, 16, v182
	v_and_b32_e32 v107, 0xffff0000, v182
	v_pk_add_f32 v[96:97], v[96:97], v[106:107]
	v_cvt_pk_bf16_f32 v115, v108, v109
	v_cvt_pk_bf16_f32 v106, v96, v97
	v_lshlrev_b32_e32 v96, 16, v183
	v_and_b32_e32 v97, 0xffff0000, v183
	v_pk_add_f32 v[96:97], v[98:99], v[96:97]
	s_waitcnt vmcnt(11)
	v_lshlrev_b32_e32 v98, 16, v177
	v_cvt_pk_bf16_f32 v107, v96, v97
	v_lshlrev_b32_e32 v96, 16, v176
	v_and_b32_e32 v97, 0xffff0000, v176
	v_and_b32_e32 v99, 0xffff0000, v177
	v_pk_add_f32 v[96:97], v[100:101], v[96:97]
	v_pk_add_f32 v[98:99], v[102:103], v[98:99]
	v_cvt_pk_bf16_f32 v96, v96, v97
	v_cvt_pk_bf16_f32 v97, v98, v99
	v_lshlrev_b32_e32 v98, 16, v178
	v_and_b32_e32 v99, 0xffff0000, v178
	v_pk_add_f32 v[92:93], v[92:93], v[98:99]
	v_lshl_add_u64 v[108:109], s[88:89], 0, v[222:223]
	v_cvt_pk_bf16_f32 v98, v92, v93
	v_lshlrev_b32_e32 v92, 16, v179
	v_and_b32_e32 v93, 0xffff0000, v179
	v_pk_add_f32 v[92:93], v[94:95], v[92:93]
	s_waitcnt vmcnt(10)
; __device__ __forceinline__ unsigned cvt_pk_bf16(float lo, float hi) { const f32x2 v = {lo, hi}; const bf16v2_ r = __builtin_convertvector(v, bf16v2_); return __builtin_bit_cast(unsigned, r); }
; __device__ __forceinline__ float bflo(unsigned w) { return __uint_as_float(w << 16); }
; __device__ __forceinline__ float bfhi(unsigned w) { return __uint_as_float(w & 0xffff0000u); }
;     __device__ __forceinline__ void operator()(const f32x4 (&acc)[2][2][4][2], const Unit& u, int wr, int wc, int, int) const {
;     ...
;         for (int ai = 0; ai < 2; ++ai)
; #pragma unroll
;             for (int m = 0; m < 4; ++m)
; #pragma unroll
;                 for (int bj = 0; bj < 2; ++bj) { const u32x4 c = cin[ai][m][bj]; const f32x4 v0 = acc[ai][bj][m][0], v1 = acc[ai][bj][m][1];
;                     u32x4 w; w.x = cvt_pk_bf16(bflo(c.x) + v0[0], bfhi(c.x) + v0[1]); w.y = cvt_pk_bf16(bflo(c.y) + v0[2], bfhi(c.y) + v0[3]);
;                     w.z = cvt_pk_bf16(bflo(c.z) + v1[0], bfhi(c.z) + v1[1]); w.w = cvt_pk_bf16(bflo(c.w) + v1[2], bfhi(c.w) + v1[3]);
;                     *(u32x4*)(C + (size_t)(row0 + ai * HALF + m * 16) * ldc + col0 + bj * HALF) = w; }
	v_lshlrev_b32_e32 v94, 16, v168
	v_and_b32_e32 v95, 0xffff0000, v168
	v_pk_add_f32 v[88:89], v[88:89], v[94:95]
	v_lshlrev_b32_e32 v94, 16, v169
	v_and_b32_e32 v95, 0xffff0000, v169
	v_pk_add_f32 v[90:91], v[90:91], v[94:95]
	v_cvt_pk_bf16_f32 v88, v88, v89
	v_cvt_pk_bf16_f32 v89, v90, v91
	v_lshlrev_b32_e32 v90, 16, v170
	v_and_b32_e32 v91, 0xffff0000, v170
	v_pk_add_f32 v[80:81], v[80:81], v[90:91]
	v_cvt_pk_bf16_f32 v99, v92, v93
	v_cvt_pk_bf16_f32 v90, v80, v81
	v_lshlrev_b32_e32 v80, 16, v171
	v_and_b32_e32 v81, 0xffff0000, v171
	v_pk_add_f32 v[80:81], v[82:83], v[80:81]
	s_waitcnt vmcnt(9)
	v_lshlrev_b32_e32 v82, 16, v173
	v_cvt_pk_bf16_f32 v91, v80, v81
	v_lshlrev_b32_e32 v80, 16, v172
	v_and_b32_e32 v81, 0xffff0000, v172
	v_and_b32_e32 v83, 0xffff0000, v173
	v_pk_add_f32 v[80:81], v[84:85], v[80:81]
	v_pk_add_f32 v[82:83], v[86:87], v[82:83]
	v_cvt_pk_bf16_f32 v80, v80, v81
	v_cvt_pk_bf16_f32 v81, v82, v83
	v_lshlrev_b32_e32 v82, 16, v174
	v_and_b32_e32 v83, 0xffff0000, v174
	v_pk_add_f32 v[76:77], v[76:77], v[82:83]
	v_lshl_add_u64 v[92:93], s[88:89], 0, v[220:221]
	v_cvt_pk_bf16_f32 v82, v76, v77
	v_lshlrev_b32_e32 v76, 16, v175
	v_and_b32_e32 v77, 0xffff0000, v175
	v_pk_add_f32 v[76:77], v[78:79], v[76:77]
	s_waitcnt vmcnt(8)
	v_lshlrev_b32_e32 v78, 16, v164
	v_and_b32_e32 v79, 0xffff0000, v164
	v_pk_add_f32 v[72:73], v[72:73], v[78:79]
	v_lshlrev_b32_e32 v78, 16, v165
	v_and_b32_e32 v79, 0xffff0000, v165
	v_pk_add_f32 v[74:75], v[74:75], v[78:79]
	v_cvt_pk_bf16_f32 v72, v72, v73
	v_cvt_pk_bf16_f32 v73, v74, v75
	v_lshlrev_b32_e32 v74, 16, v166
	v_and_b32_e32 v75, 0xffff0000, v166
	v_pk_add_f32 v[68:69], v[68:69], v[74:75]
	v_cvt_pk_bf16_f32 v83, v76, v77
	v_cvt_pk_bf16_f32 v74, v68, v69
	v_lshlrev_b32_e32 v68, 16, v167
	v_and_b32_e32 v69, 0xffff0000, v167
	v_pk_add_f32 v[68:69], v[70:71], v[68:69]
	v_lshl_add_u64 v[76:77], s[88:89], 0, v[212:213]
	v_cvt_pk_bf16_f32 v75, v68, v69
	s_waitcnt vmcnt(7)
	v_lshlrev_b32_e32 v68, 16, v160
	v_and_b32_e32 v69, 0xffff0000, v160
	v_pk_add_f32 v[64:65], v[64:65], v[68:69]
	v_lshlrev_b32_e32 v68, 16, v161
	v_and_b32_e32 v69, 0xffff0000, v161
	v_pk_add_f32 v[66:67], v[66:67], v[68:69]
	v_cvt_pk_bf16_f32 v64, v64, v65
	v_cvt_pk_bf16_f32 v65, v66, v67
	v_lshlrev_b32_e32 v66, 16, v162
	v_and_b32_e32 v67, 0xffff0000, v162
	v_pk_add_f32 v[60:61], v[60:61], v[66:67]
	v_lshl_add_u64 v[108:109], v[108:109], 0, v[202:203]
	v_cvt_pk_bf16_f32 v66, v60, v61
	v_lshlrev_b32_e32 v60, 16, v163
	v_and_b32_e32 v61, 0xffff0000, v163
	v_pk_add_f32 v[60:61], v[62:63], v[60:61]
	s_waitcnt vmcnt(6)
	v_lshlrev_b32_e32 v62, 16, v156
	v_and_b32_e32 v63, 0xffff0000, v156
	v_pk_add_f32 v[56:57], v[56:57], v[62:63]
	v_lshlrev_b32_e32 v62, 16, v157
	v_and_b32_e32 v63, 0xffff0000, v157
	v_pk_add_f32 v[58:59], v[58:59], v[62:63]
	v_cvt_pk_bf16_f32 v56, v56, v57
	v_cvt_pk_bf16_f32 v57, v58, v59
	v_lshlrev_b32_e32 v58, 16, v158
	v_and_b32_e32 v59, 0xffff0000, v158
	v_pk_add_f32 v[48:49], v[48:49], v[58:59]
	v_cvt_pk_bf16_f32 v67, v60, v61
	v_cvt_pk_bf16_f32 v58, v48, v49
	v_lshlrev_b32_e32 v48, 16, v159
	v_and_b32_e32 v49, 0xffff0000, v159
	v_pk_add_f32 v[48:49], v[50:51], v[48:49]
	s_waitcnt vmcnt(5)
	v_lshlrev_b32_e32 v50, 16, v153
	v_cvt_pk_bf16_f32 v59, v48, v49
	v_lshlrev_b32_e32 v48, 16, v152
	v_and_b32_e32 v49, 0xffff0000, v152
	v_and_b32_e32 v51, 0xffff0000, v153
	v_pk_add_f32 v[48:49], v[52:53], v[48:49]
	v_pk_add_f32 v[50:51], v[54:55], v[50:51]
	v_cvt_pk_bf16_f32 v48, v48, v49
	v_cvt_pk_bf16_f32 v49, v50, v51
	v_lshlrev_b32_e32 v50, 16, v154
	v_and_b32_e32 v51, 0xffff0000, v154
	v_pk_add_f32 v[44:45], v[44:45], v[50:51]
	v_lshl_add_u64 v[60:61], s[88:89], 0, v[210:211]
	v_cvt_pk_bf16_f32 v50, v44, v45
	v_lshlrev_b32_e32 v44, 16, v155
	v_and_b32_e32 v45, 0xffff0000, v155
	v_pk_add_f32 v[44:45], v[46:47], v[44:45]
	s_waitcnt vmcnt(4)
; __device__ __forceinline__ unsigned cvt_pk_bf16(float lo, float hi) { const f32x2 v = {lo, hi}; const bf16v2_ r = __builtin_convertvector(v, bf16v2_); return __builtin_bit_cast(unsigned, r); }
; __device__ __forceinline__ float bflo(unsigned w) { return __uint_as_float(w << 16); }
; __device__ __forceinline__ float bfhi(unsigned w) { return __uint_as_float(w & 0xffff0000u); }
;     __device__ __forceinline__ void operator()(const f32x4 (&acc)[2][2][4][2], const Unit& u, int wr, int wc, int, int) const {
;     ...
; #pragma unroll
;         for (int ai = 0; ai < 2; ++ai)
; #pragma unroll
;             for (int m = 0; m < 4; ++m)
; #pragma unroll
;                 for (int bj = 0; bj < 2; ++bj) { const u32x4 c = cin[ai][m][bj]; const f32x4 v0 = acc[ai][bj][m][0], v1 = acc[ai][bj][m][1];
;                     u32x4 w; w.x = cvt_pk_bf16(bflo(c.x) + v0[0], bfhi(c.x) + v0[1]); w.y = cvt_pk_bf16(bflo(c.y) + v0[2], bfhi(c.y) + v0[3]);
;                     w.z = cvt_pk_bf16(bflo(c.z) + v1[0], bfhi(c.z) + v1[1]); w.w = cvt_pk_bf16(bflo(c.w) + v1[2], bfhi(c.w) + v1[3]);
;                     *(u32x4*)(C + (size_t)(row0 + ai * HALF + m * 16) * ldc + col0 + bj * HALF) = w; }
	v_lshlrev_b32_e32 v46, 16, v148
	v_and_b32_e32 v47, 0xffff0000, v148
	v_pk_add_f32 v[40:41], v[40:41], v[46:47]
	v_lshlrev_b32_e32 v46, 16, v149
	v_and_b32_e32 v47, 0xffff0000, v149
	v_pk_add_f32 v[42:43], v[42:43], v[46:47]
	v_cvt_pk_bf16_f32 v40, v40, v41
	v_cvt_pk_bf16_f32 v41, v42, v43
	v_lshlrev_b32_e32 v42, 16, v150
	v_and_b32_e32 v43, 0xffff0000, v150
	v_pk_add_f32 v[32:33], v[32:33], v[42:43]
	v_cvt_pk_bf16_f32 v51, v44, v45
	v_cvt_pk_bf16_f32 v42, v32, v33
	v_lshlrev_b32_e32 v32, 16, v151
	v_and_b32_e32 v33, 0xffff0000, v151
	v_pk_add_f32 v[32:33], v[34:35], v[32:33]
	s_waitcnt vmcnt(3)
	v_lshlrev_b32_e32 v34, 16, v145
	v_cvt_pk_bf16_f32 v43, v32, v33
	v_lshlrev_b32_e32 v32, 16, v144
	v_and_b32_e32 v33, 0xffff0000, v144
	v_and_b32_e32 v35, 0xffff0000, v145
	v_pk_add_f32 v[32:33], v[36:37], v[32:33]
	v_pk_add_f32 v[34:35], v[38:39], v[34:35]
	v_cvt_pk_bf16_f32 v32, v32, v33
	v_cvt_pk_bf16_f32 v33, v34, v35
	v_lshlrev_b32_e32 v34, 16, v146
	v_and_b32_e32 v35, 0xffff0000, v146
	v_pk_add_f32 v[28:29], v[28:29], v[34:35]
	v_lshl_add_u64 v[44:45], s[88:89], 0, v[208:209]
	v_cvt_pk_bf16_f32 v34, v28, v29
	v_lshlrev_b32_e32 v28, 16, v147
	v_and_b32_e32 v29, 0xffff0000, v147
	v_pk_add_f32 v[28:29], v[30:31], v[28:29]
	s_waitcnt vmcnt(2)
	v_lshlrev_b32_e32 v30, 16, v140
	v_and_b32_e32 v31, 0xffff0000, v140
	v_pk_add_f32 v[24:25], v[24:25], v[30:31]
	v_lshlrev_b32_e32 v30, 16, v141
	v_and_b32_e32 v31, 0xffff0000, v141
	v_pk_add_f32 v[26:27], v[26:27], v[30:31]
	v_cvt_pk_bf16_f32 v24, v24, v25
	v_cvt_pk_bf16_f32 v25, v26, v27
	v_lshlrev_b32_e32 v26, 16, v142
	v_and_b32_e32 v27, 0xffff0000, v142
	v_pk_add_f32 v[16:17], v[16:17], v[26:27]
	v_cvt_pk_bf16_f32 v35, v28, v29
	v_cvt_pk_bf16_f32 v26, v16, v17
	v_lshlrev_b32_e32 v16, 16, v143
	v_and_b32_e32 v17, 0xffff0000, v143
	v_pk_add_f32 v[16:17], v[18:19], v[16:17]
	s_waitcnt vmcnt(1)
	v_lshlrev_b32_e32 v18, 16, v137
	v_cvt_pk_bf16_f32 v27, v16, v17
	v_lshlrev_b32_e32 v16, 16, v136
	v_and_b32_e32 v17, 0xffff0000, v136
	v_and_b32_e32 v19, 0xffff0000, v137
	v_pk_add_f32 v[16:17], v[20:21], v[16:17]
	v_pk_add_f32 v[18:19], v[22:23], v[18:19]
	v_cvt_pk_bf16_f32 v16, v16, v17
	v_cvt_pk_bf16_f32 v17, v18, v19
	v_lshlrev_b32_e32 v18, 16, v138
	v_and_b32_e32 v19, 0xffff0000, v138
	v_pk_add_f32 v[12:13], v[12:13], v[18:19]
	v_lshl_add_u64 v[28:29], s[88:89], 0, v[206:207]
	v_cvt_pk_bf16_f32 v18, v12, v13
	v_lshlrev_b32_e32 v12, 16, v139
	v_and_b32_e32 v13, 0xffff0000, v139
	v_pk_add_f32 v[12:13], v[14:15], v[12:13]
	s_waitcnt vmcnt(0)
	v_lshlrev_b32_e32 v14, 16, v132
	v_and_b32_e32 v15, 0xffff0000, v132
	v_pk_add_f32 v[8:9], v[8:9], v[14:15]
	v_lshlrev_b32_e32 v14, 16, v133
	v_and_b32_e32 v15, 0xffff0000, v133
	v_pk_add_f32 v[10:11], v[10:11], v[14:15]
	v_cvt_pk_bf16_f32 v8, v8, v9
	v_cvt_pk_bf16_f32 v9, v10, v11
	v_lshlrev_b32_e32 v10, 16, v134
	v_and_b32_e32 v11, 0xffff0000, v134
	v_pk_add_f32 v[4:5], v[4:5], v[10:11]
	v_cvt_pk_bf16_f32 v19, v12, v13
	v_cvt_pk_bf16_f32 v10, v4, v5
	v_lshlrev_b32_e32 v4, 16, v135
	v_and_b32_e32 v5, 0xffff0000, v135
	v_lshl_add_u64 v[12:13], s[88:89], 0, v[204:205]
	v_pk_add_f32 v[4:5], v[6:7], v[4:5]
	v_lshl_add_u64 v[92:93], v[92:93], 0, v[202:203]
	v_lshl_add_u64 v[76:77], v[76:77], 0, v[202:203]
	v_lshl_add_u64 v[60:61], v[60:61], 0, v[202:203]
	v_lshl_add_u64 v[44:45], v[44:45], 0, v[202:203]
	v_lshl_add_u64 v[28:29], v[28:29], 0, v[202:203]
	v_lshl_add_u64 v[12:13], v[12:13], 0, v[202:203]
	v_cvt_pk_bf16_f32 v11, v4, v5
	global_store_dwordx4 v[124:125], v[128:131], off
	global_store_dwordx4 v[124:125], v[120:123], off offset:256
	global_store_dwordx4 v[108:109], v[112:115], off
	global_store_dwordx4 v[108:109], v[104:107], off offset:256
	global_store_dwordx4 v[92:93], v[96:99], off
	global_store_dwordx4 v[92:93], v[88:91], off offset:256
	global_store_dwordx4 v[76:77], v[80:83], off
	global_store_dwordx4 v[76:77], v[72:75], off offset:256
	global_store_dwordx4 v[60:61], v[64:67], off
	global_store_dwordx4 v[60:61], v[56:59], off offset:256
	global_store_dwordx4 v[44:45], v[48:51], off
	global_store_dwordx4 v[44:45], v[40:43], off offset:256
	global_store_dwordx4 v[28:29], v[32:35], off
	global_store_dwordx4 v[28:29], v[24:27], off offset:256
	global_store_dwordx4 v[12:13], v[16:19], off
	global_store_dwordx4 v[12:13], v[8:11], off offset:256
	s_cmpk_lt_u32 s2, 0x100
	s_cbranch_scc1 .Lalign_b_966
	s_barrier
	s_setprio 1

; #define PG8_STAGE(bufoff, gbase, voff) do { _Pragma("unroll") for (int _i = 0; _i < 2; ++_i) \
;         __builtin_amdgcn_global_load_lds((const unsigned*)((const char*)(gbase) + (voff)[_i]), (LAS unsigned*)(lds + (bufoff) + ldsw + _i * 8192), 16, 0, 0); } while (0)
; #define PG8_LDA(dst, b, h) do { _Pragma("unroll") for (int m = 0; m < 4; ++m) _Pragma("unroll") for (int k = 0; k < 2; ++k) dst[m][k] = *(const LAS bf16x8*)(lds + PG8_SA(b, h) + aoff + m * 2048 + k * 1024); } while (0)
; #define PG8_LDB(dst, b, h) do { _Pragma("unroll") for (int n = 0; n < 2; ++n) _Pragma("unroll") for (int k = 0; k < 2; ++k) dst[n][k] = *(const LAS bf16x8*)(lds + PG8_SB(b, h) + boff + n * 2048 + k * 1024); } while (0)
; #define PG8_WAIT_V(n) asm volatile("s_waitcnt vmcnt(" #n ")" ::: "memory")
; #define PG8_WAIT_L(n) asm volatile("s_waitcnt lgkmcnt(" #n ")" ::: "memory")
; #define PG8_BAR __builtin_amdgcn_s_barrier()
; #define PG8_SCHED __builtin_amdgcn_sched_barrier(0)
; template <class Epi, class Sched>
; __device__ __forceinline__ void gemm_phase(LAS unsigned char* lds, const Gemm g, const Sched& S, const Epi& E) {
;     ...
;         const char* nA = has_next ? (const char*)g.A + (size_t)nxt.pm * tstepA : cA; const char* nB = has_next ? (const char*)g.Bt + (size_t)nxt.pn * tstepB : cB;
;         for (int t = 0; t < nt; t += 2) {
;             const bool last = (t == nt - 2);
;             const char* a1 = cA + (size_t)(t + 1) * kstep;
;             const char* a2 = last ? nA : cA + (size_t)(t + 2) * kstep; const char* b2 = last ? nB : cB + (size_t)(t + 2) * kstep;
;             const char* a3 = a2 + kstep; const char* b3 = b2 + kstep;
;             if (last && has_next) S.a_ready(nxt);
;             PG8_LDB(B0, 0, 0); PG8_SCHED; PG8_LDA(At, 0, 0); PG8_STAGE(PG8_SA(1, 1), a1 + hstepA, voffA);
;             PG8_WAIT_L(8); PG8_BAR; PG8_WAIT_L(0); PG8_MMA(0, 0, At, B0); PG8_BAR; PG8_SCHED;
;             PG8_LDB(B1, 0, 1); PG8_STAGE(PG8_SB(0, 0), b2, voffB);
;             PG8_BAR; PG8_WAIT_L(0); PG8_MMA(0, 1, At, B1); PG8_BAR;
;             PG8_LDA(At, 0, 1); PG8_STAGE(PG8_SA(0, 0), a2, voffA);
;             PG8_BAR; PG8_WAIT_L(0); PG8_MMA(1, 0, At, B0); PG8_BAR; PG8_SCHED;
;             PG8_STAGE(PG8_SB(0, 1), b2 + hstepB, voffB);
;             PG8_WAIT_V(6); PG8_BAR; PG8_MMA(1, 1, At, B1); PG8_BAR;
.LBB0_1093:
	v_mov_b64_e32 v[4:5], 0x900
	s_ashr_i32 s5, s4, 31
	v_cmp_lt_i64_e32 vcc, s[6:7], v[4:5]
	s_lshl_b64 s[6:7], s[4:5], 20
	s_add_u32 s6, s88, s6
	s_addc_u32 s7, s89, s7
	s_and_b64 s[14:15], vcc, exec
	s_cselect_b32 s5, s7, s19
	s_cselect_b32 s49, s6, s18
	s_ashr_i32 s1, s0, 31
	s_lshl_b64 s[14:15], s[0:1], 20
	s_add_u32 s14, s28, s14
	s_addc_u32 s15, s29, s15
	s_and_b64 s[24:25], vcc, exec
	s_cselect_b32 s1, s15, s21
	s_cselect_b32 s50, s14, s20
	s_add_u32 s18, s18, 0x80080
	s_addc_u32 s19, s19, 0
	s_add_u32 s51, s20, 0x100
	s_addc_u32 s52, s21, 0
	s_mov_b32 s53, -2
	s_add_u32 s20, s18, 0xfff80080
	s_addc_u32 s21, s19, -1
	s_add_i32 s54, 0, 0x10000
	v_add_u32_e32 v146, s54, v1
	ds_read_b128 v[142:145], v146
	ds_read_b128 v[150:153], v146 offset:1024
	ds_read_b128 v[154:157], v146 offset:2048
	ds_read_b128 v[158:161], v146 offset:3072
	s_cmp_eq_u32 s53, 28
	s_cselect_b32 s25, s5, s21
	s_cselect_b32 s24, s49, s20
	s_cselect_b32 s21, s1, s52
	s_cselect_b32 s20, s50, s51
	ds_read_b128 v[162:165], v148
	ds_read_b128 v[166:169], v148 offset:1024
	ds_read_b128 v[170:173], v148 offset:2048
	ds_read_b128 v[174:177], v148 offset:3072
	ds_read_b128 v[178:181], v148 offset:4096
	ds_read_b128 v[182:185], v148 offset:5120
	ds_read_b128 v[186:189], v148 offset:6144
	ds_read_b128 v[190:193], v148 offset:7168
	s_add_i32 s56, 0, 0x14000
	v_add_u32_e32 v146, s56, v1
	ds_read_b128 v[194:197], v146
	ds_read_b128 v[198:201], v146 offset:1024
	ds_read_b128 v[202:205], v146 offset:2048
	ds_read_b128 v[206:209], v146 offset:3072
	s_add_i32 m0, s31, 0xc000
	s_nop 0
	global_load_lds_dwordx4 v138, s[18:19]
	s_add_i32 m0, s31, 0xe000
	s_nop 0
	global_load_lds_dwordx4 v140, s[18:19]
	s_waitcnt lgkmcnt(0)
	s_barrier
	v_mfma_f32_16x16x32_bf16 v[128:131], v[142:145], v[162:165], 0
	v_mfma_f32_16x16x32_bf16 v[124:127], v[154:157], v[162:165], 0
	v_mfma_f32_16x16x32_bf16 v[120:123], v[142:145], v[170:173], 0
	v_mfma_f32_16x16x32_bf16 v[112:115], v[154:157], v[170:173], 0
	v_mfma_f32_16x16x32_bf16 v[104:107], v[142:145], v[178:181], 0
	v_mfma_f32_16x16x32_bf16 v[96:99], v[154:157], v[178:181], 0
	v_mfma_f32_16x16x32_bf16 v[88:91], v[142:145], v[186:189], 0
	v_mfma_f32_16x16x32_bf16 v[80:83], v[154:157], v[186:189], 0
	v_mfma_f32_16x16x32_bf16 v[128:131], v[150:153], v[166:169], v[128:131]
	v_mfma_f32_16x16x32_bf16 v[124:127], v[158:161], v[166:169], v[124:127]
	v_mfma_f32_16x16x32_bf16 v[120:123], v[150:153], v[174:177], v[120:123]
	v_mfma_f32_16x16x32_bf16 v[112:115], v[158:161], v[174:177], v[112:115]
	v_mfma_f32_16x16x32_bf16 v[104:107], v[150:153], v[182:185], v[104:107]
	v_mfma_f32_16x16x32_bf16 v[96:99], v[158:161], v[182:185], v[96:99]
	v_mfma_f32_16x16x32_bf16 v[88:91], v[150:153], v[190:193], v[88:91]
	v_mfma_f32_16x16x32_bf16 v[80:83], v[158:161], v[190:193], v[80:83]
	v_mfma_f32_16x16x32_bf16 v[116:119], v[194:197], v[162:165], 0
	v_mfma_f32_16x16x32_bf16 v[108:111], v[202:205], v[162:165], 0
	v_mfma_f32_16x16x32_bf16 v[100:103], v[194:197], v[170:173], 0
	v_mfma_f32_16x16x32_bf16 v[92:95], v[202:205], v[170:173], 0
	v_mfma_f32_16x16x32_bf16 v[84:87], v[194:197], v[178:181], 0
	v_mfma_f32_16x16x32_bf16 v[76:79], v[202:205], v[178:181], 0
	v_mfma_f32_16x16x32_bf16 v[72:75], v[194:197], v[186:189], 0
	v_mfma_f32_16x16x32_bf16 v[68:71], v[202:205], v[186:189], 0
	v_mfma_f32_16x16x32_bf16 v[116:119], v[198:201], v[166:169], v[116:119]
	v_mfma_f32_16x16x32_bf16 v[108:111], v[206:209], v[166:169], v[108:111]
	v_mfma_f32_16x16x32_bf16 v[100:103], v[198:201], v[174:177], v[100:103]
	v_mfma_f32_16x16x32_bf16 v[92:95], v[206:209], v[174:177], v[92:95]
	v_mfma_f32_16x16x32_bf16 v[84:87], v[198:201], v[182:185], v[84:87]
	v_mfma_f32_16x16x32_bf16 v[76:79], v[206:209], v[182:185], v[76:79]
	v_mfma_f32_16x16x32_bf16 v[72:75], v[198:201], v[190:193], v[72:75]
	v_mfma_f32_16x16x32_bf16 v[68:71], v[206:209], v[190:193], v[68:71]
	s_barrier
	ds_read_b128 v[162:165], v148 offset:16384
	ds_read_b128 v[166:169], v148 offset:17408
	ds_read_b128 v[170:173], v148 offset:18432
	ds_read_b128 v[174:177], v148 offset:19456
	ds_read_b128 v[178:181], v148 offset:20480
	ds_read_b128 v[182:185], v148 offset:21504
	ds_read_b128 v[186:189], v148 offset:22528
	ds_read_b128 v[190:193], v148 offset:23552
	s_add_i32 s54, s54, s30
	v_lshl_add_u64 v[146:147], s[20:21], 0, v[2:3]
	s_mov_b32 m0, s54
	v_lshl_add_u64 v[210:211], s[20:21], 0, v[132:133]
	global_load_lds_dwordx4 v[146:147], off
	s_add_i32 m0, s54, 0x2000
	s_nop 0
	global_load_lds_dwordx4 v[210:211], off
	s_mov_b32 m0, s31
	v_lshl_add_u64 v[212:213], s[24:25], 0, v[136:137]
	global_load_lds_dwordx4 v[212:213], off
	v_lshl_add_u64 v[216:217], s[24:25], 0, v[134:135]
	s_mov_b32 m0, s35
	s_nop 0
	global_load_lds_dwordx4 v[216:217], off
	s_add_u32 s54, s20, 0x80000
	s_addc_u32 s55, s21, 0
	s_add_i32 s56, s56, s30
	s_mov_b32 m0, s56
	s_nop 0
	global_load_lds_dwordx4 v2, s[54:55]
	s_add_i32 m0, s56, 0x2000
	s_nop 0
	global_load_lds_dwordx4 v132, s[54:55]
	s_waitcnt lgkmcnt(0)
	s_waitcnt vmcnt(6)
	s_barrier
; #define PG8_STAGE(bufoff, gbase, voff) do { _Pragma("unroll") for (int _i = 0; _i < 2; ++_i) \
;         __builtin_amdgcn_global_load_lds((const unsigned*)((const char*)(gbase) + (voff)[_i]), (LAS unsigned*)(lds + (bufoff) + ldsw + _i * 8192), 16, 0, 0); } while (0)
; #define PG8_LDA(dst, b, h) do { _Pragma("unroll") for (int m = 0; m < 4; ++m) _Pragma("unroll") for (int k = 0; k < 2; ++k) dst[m][k] = *(const LAS bf16x8*)(lds + PG8_SA(b, h) + aoff + m * 2048 + k * 1024); } while (0)
; #define PG8_LDB(dst, b, h) do { _Pragma("unroll") for (int n = 0; n < 2; ++n) _Pragma("unroll") for (int k = 0; k < 2; ++k) dst[n][k] = *(const LAS bf16x8*)(lds + PG8_SB(b, h) + boff + n * 2048 + k * 1024); } while (0)
; #define PG8_WAIT_V(n) asm volatile("s_waitcnt vmcnt(" #n ")" ::: "memory")
; #define PG8_WAIT_L(n) asm volatile("s_waitcnt lgkmcnt(" #n ")" ::: "memory")
; #define PG8_BAR __builtin_amdgcn_s_barrier()
; #define PG8_SCHED __builtin_amdgcn_sched_barrier(0)
; template <class Epi, class Sched>
; __device__ __forceinline__ void gemm_phase(LAS unsigned char* lds, const Gemm g, const Sched& S, const Epi& E) {
;     ...
;             PG8_LDB(B0, 0, 0); PG8_SCHED; PG8_LDA(At, 0, 0); PG8_STAGE(PG8_SA(1, 1), a1 + hstepA, voffA);
;             PG8_WAIT_L(8); PG8_BAR; PG8_WAIT_L(0); PG8_MMA(0, 0, At, B0); PG8_BAR; PG8_SCHED;
;             PG8_LDB(B1, 0, 1); PG8_STAGE(PG8_SB(0, 0), b2, voffB);
;             PG8_BAR; PG8_WAIT_L(0); PG8_MMA(0, 1, At, B1); PG8_BAR;
;             PG8_LDA(At, 0, 1); PG8_STAGE(PG8_SA(0, 0), a2, voffA);
;             PG8_BAR; PG8_WAIT_L(0); PG8_MMA(1, 0, At, B0); PG8_BAR; PG8_SCHED;
;             PG8_STAGE(PG8_SB(0, 1), b2 + hstepB, voffB);
;             PG8_WAIT_V(6); PG8_BAR; PG8_MMA(1, 1, At, B1); PG8_BAR;
;             PG8_LDB(B0, 1, 0); PG8_SCHED; PG8_LDA(At, 1, 0); PG8_STAGE(PG8_SA(0, 1), a2 + hstepA, voffA);
;             PG8_WAIT_L(8); PG8_BAR; PG8_WAIT_L(0); PG8_MMA(0, 0, At, B0); PG8_BAR; PG8_SCHED;
;             PG8_LDB(B1, 1, 1); PG8_STAGE(PG8_SB(1, 0), b3, voffB);
;             PG8_BAR; PG8_WAIT_L(0); PG8_MMA(0, 1, At, B1); PG8_BAR;
;             PG8_LDA(At, 1, 1); PG8_STAGE(PG8_SA(1, 0), a3, voffA);
;             PG8_BAR; PG8_WAIT_L(0); PG8_MMA(1, 0, At, B0); PG8_BAR; PG8_SCHED;
;             PG8_STAGE(PG8_SB(1, 1), b3 + hstepB, voffB);
;             PG8_WAIT_V(6); PG8_BAR; PG8_MMA(1, 1, At, B1); PG8_BAR;
	v_mfma_f32_16x16x32_bf16 v[64:67], v[142:145], v[162:165], 0
	v_mfma_f32_16x16x32_bf16 v[60:63], v[154:157], v[162:165], 0
	v_mfma_f32_16x16x32_bf16 v[56:59], v[142:145], v[170:173], 0
	v_mfma_f32_16x16x32_bf16 v[48:51], v[154:157], v[170:173], 0
	v_mfma_f32_16x16x32_bf16 v[40:43], v[142:145], v[178:181], 0
	v_mfma_f32_16x16x32_bf16 v[32:35], v[154:157], v[178:181], 0
	v_mfma_f32_16x16x32_bf16 v[24:27], v[142:145], v[186:189], 0
	v_mfma_f32_16x16x32_bf16 v[16:19], v[154:157], v[186:189], 0
	v_mfma_f32_16x16x32_bf16 v[64:67], v[150:153], v[166:169], v[64:67]
	v_mfma_f32_16x16x32_bf16 v[60:63], v[158:161], v[166:169], v[60:63]
	v_mfma_f32_16x16x32_bf16 v[56:59], v[150:153], v[174:177], v[56:59]
	v_mfma_f32_16x16x32_bf16 v[48:51], v[158:161], v[174:177], v[48:51]
	v_mfma_f32_16x16x32_bf16 v[40:43], v[150:153], v[182:185], v[40:43]
	v_mfma_f32_16x16x32_bf16 v[32:35], v[158:161], v[182:185], v[32:35]
	v_mfma_f32_16x16x32_bf16 v[24:27], v[150:153], v[190:193], v[24:27]
	v_mfma_f32_16x16x32_bf16 v[16:19], v[158:161], v[190:193], v[16:19]
	v_mfma_f32_16x16x32_bf16 v[52:55], v[194:197], v[162:165], 0
	v_mfma_f32_16x16x32_bf16 v[44:47], v[202:205], v[162:165], 0
	v_mfma_f32_16x16x32_bf16 v[36:39], v[194:197], v[170:173], 0
	v_mfma_f32_16x16x32_bf16 v[28:31], v[202:205], v[170:173], 0
	v_mfma_f32_16x16x32_bf16 v[20:23], v[194:197], v[178:181], 0
	v_mfma_f32_16x16x32_bf16 v[12:15], v[202:205], v[178:181], 0
	v_mfma_f32_16x16x32_bf16 v[8:11], v[194:197], v[186:189], 0
	v_mfma_f32_16x16x32_bf16 v[4:7], v[202:205], v[186:189], 0
	v_mfma_f32_16x16x32_bf16 v[52:55], v[198:201], v[166:169], v[52:55]
	v_mfma_f32_16x16x32_bf16 v[44:47], v[206:209], v[166:169], v[44:47]
	v_mfma_f32_16x16x32_bf16 v[36:39], v[198:201], v[174:177], v[36:39]
	v_mfma_f32_16x16x32_bf16 v[28:31], v[206:209], v[174:177], v[28:31]
	v_mfma_f32_16x16x32_bf16 v[20:23], v[198:201], v[182:185], v[20:23]
	v_mfma_f32_16x16x32_bf16 v[12:15], v[206:209], v[182:185], v[12:15]
	v_mfma_f32_16x16x32_bf16 v[8:11], v[198:201], v[190:193], v[8:11]
	v_mfma_f32_16x16x32_bf16 v[4:7], v[206:209], v[190:193], v[4:7]
	s_barrier
	s_add_i32 s54, 0, 0x18000
	v_add_u32_e32 v149, s54, v1
	ds_read_b128 v[142:145], v149
	ds_read_b128 v[150:153], v149 offset:1024
	ds_read_b128 v[154:157], v149 offset:2048
	ds_read_b128 v[158:161], v149 offset:3072
	s_add_u32 s24, s24, 0x80000
	s_addc_u32 s25, s25, 0
	ds_read_b128 v[162:165], v148 offset:32768
	ds_read_b128 v[166:169], v148 offset:33792
	ds_read_b128 v[170:173], v148 offset:34816
	ds_read_b128 v[174:177], v148 offset:35840
	ds_read_b128 v[178:181], v148 offset:36864
	ds_read_b128 v[182:185], v148 offset:37888
	ds_read_b128 v[186:189], v148 offset:38912
	ds_read_b128 v[190:193], v148 offset:39936
	s_mov_b32 m0, s36
	s_nop 0
	global_load_lds_dwordx4 v136, s[24:25]
	s_mov_b32 m0, s37
	s_nop 0
	global_load_lds_dwordx4 v134, s[24:25]
	s_add_i32 s24, 0, 0x1c000
	v_add_u32_e32 v149, s24, v1
	ds_read_b128 v[194:197], v149
	ds_read_b128 v[198:201], v149 offset:1024
	ds_read_b128 v[202:205], v149 offset:2048
	ds_read_b128 v[206:209], v149 offset:3072
	s_waitcnt lgkmcnt(0)
	s_barrier
	v_mfma_f32_16x16x32_bf16 v[128:131], v[142:145], v[162:165], v[128:131]
	v_mfma_f32_16x16x32_bf16 v[124:127], v[154:157], v[162:165], v[124:127]
	v_mfma_f32_16x16x32_bf16 v[120:123], v[142:145], v[170:173], v[120:123]
	v_mfma_f32_16x16x32_bf16 v[112:115], v[154:157], v[170:173], v[112:115]
	v_mfma_f32_16x16x32_bf16 v[104:107], v[142:145], v[178:181], v[104:107]
	v_mfma_f32_16x16x32_bf16 v[96:99], v[154:157], v[178:181], v[96:99]
	v_mfma_f32_16x16x32_bf16 v[88:91], v[142:145], v[186:189], v[88:91]
	v_mfma_f32_16x16x32_bf16 v[80:83], v[154:157], v[186:189], v[80:83]
	v_mfma_f32_16x16x32_bf16 v[128:131], v[150:153], v[166:169], v[128:131]
	v_mfma_f32_16x16x32_bf16 v[124:127], v[158:161], v[166:169], v[124:127]
	v_mfma_f32_16x16x32_bf16 v[120:123], v[150:153], v[174:177], v[120:123]
	v_mfma_f32_16x16x32_bf16 v[112:115], v[158:161], v[174:177], v[112:115]
	v_mfma_f32_16x16x32_bf16 v[104:107], v[150:153], v[182:185], v[104:107]
	v_mfma_f32_16x16x32_bf16 v[96:99], v[158:161], v[182:185], v[96:99]
	v_mfma_f32_16x16x32_bf16 v[88:91], v[150:153], v[190:193], v[88:91]
	v_mfma_f32_16x16x32_bf16 v[80:83], v[158:161], v[190:193], v[80:83]
	v_mfma_f32_16x16x32_bf16 v[116:119], v[194:197], v[162:165], v[116:119]
	v_mfma_f32_16x16x32_bf16 v[108:111], v[202:205], v[162:165], v[108:111]
	v_mfma_f32_16x16x32_bf16 v[100:103], v[194:197], v[170:173], v[100:103]
	v_mfma_f32_16x16x32_bf16 v[92:95], v[202:205], v[170:173], v[92:95]
	v_mfma_f32_16x16x32_bf16 v[84:87], v[194:197], v[178:181], v[84:87]
	v_mfma_f32_16x16x32_bf16 v[76:79], v[202:205], v[178:181], v[76:79]
	v_mfma_f32_16x16x32_bf16 v[72:75], v[194:197], v[186:189], v[72:75]
	v_mfma_f32_16x16x32_bf16 v[68:71], v[202:205], v[186:189], v[68:71]
	v_mfma_f32_16x16x32_bf16 v[116:119], v[198:201], v[166:169], v[116:119]
	v_mfma_f32_16x16x32_bf16 v[108:111], v[206:209], v[166:169], v[108:111]
	v_mfma_f32_16x16x32_bf16 v[100:103], v[198:201], v[174:177], v[100:103]
	v_mfma_f32_16x16x32_bf16 v[92:95], v[206:209], v[174:177], v[92:95]
	v_mfma_f32_16x16x32_bf16 v[84:87], v[198:201], v[182:185], v[84:87]
	v_mfma_f32_16x16x32_bf16 v[76:79], v[206:209], v[182:185], v[76:79]
	v_mfma_f32_16x16x32_bf16 v[72:75], v[198:201], v[190:193], v[72:75]
	v_mfma_f32_16x16x32_bf16 v[68:71], v[206:209], v[190:193], v[68:71]
	s_barrier
; #define PG8_STAGE(bufoff, gbase, voff) do { _Pragma("unroll") for (int _i = 0; _i < 2; ++_i) \
;         __builtin_amdgcn_global_load_lds((const unsigned*)((const char*)(gbase) + (voff)[_i]), (LAS unsigned*)(lds + (bufoff) + ldsw + _i * 8192), 16, 0, 0); } while (0)
; #define PG8_LDA(dst, b, h) do { _Pragma("unroll") for (int m = 0; m < 4; ++m) _Pragma("unroll") for (int k = 0; k < 2; ++k) dst[m][k] = *(const LAS bf16x8*)(lds + PG8_SA(b, h) + aoff + m * 2048 + k * 1024); } while (0)
; #define PG8_LDB(dst, b, h) do { _Pragma("unroll") for (int n = 0; n < 2; ++n) _Pragma("unroll") for (int k = 0; k < 2; ++k) dst[n][k] = *(const LAS bf16x8*)(lds + PG8_SB(b, h) + boff + n * 2048 + k * 1024); } while (0)
; #define PG8_MMA(ai, bj, At, Bt) do { __builtin_amdgcn_s_setprio(1); _Pragma("unroll") for (int m = 0; m < 4; ++m) _Pragma("unroll") for (int n = 0; n < 2; ++n) _Pragma("unroll") for (int k = 0; k < 2; ++k) \
;         acc[ai][bj][m][n] = __builtin_amdgcn_mfma_f32_16x16x32_bf16(Bt[n][k], At[m][k], acc[ai][bj][m][n], 0, 0, 0); __builtin_amdgcn_s_setprio(0); } while (0)
; #define PG8_WAIT_V(n) asm volatile("s_waitcnt vmcnt(" #n ")" ::: "memory")
; #define PG8_WAIT_L(n) asm volatile("s_waitcnt lgkmcnt(" #n ")" ::: "memory")
; #define PG8_BAR __builtin_amdgcn_s_barrier()
; #define PG8_SCHED __builtin_amdgcn_sched_barrier(0)
; template <class Epi, class Sched>
; __device__ __forceinline__ void gemm_phase(LAS unsigned char* lds, const Gemm g, const Sched& S, const Epi& E) {
;     ...
;             PG8_LDB(B0, 0, 0); PG8_SCHED; PG8_LDA(At, 0, 0); PG8_STAGE(PG8_SA(1, 1), a1 + hstepA, voffA);
;             PG8_WAIT_L(8); PG8_BAR; PG8_WAIT_L(0); PG8_MMA(0, 0, At, B0); PG8_BAR; PG8_SCHED;
;     ...
;             PG8_LDB(B0, 1, 0); PG8_SCHED; PG8_LDA(At, 1, 0); PG8_STAGE(PG8_SA(0, 1), a2 + hstepA, voffA);
;             PG8_WAIT_L(8); PG8_BAR; PG8_WAIT_L(0); PG8_MMA(0, 0, At, B0); PG8_BAR; PG8_SCHED;
;             PG8_LDB(B1, 1, 1); PG8_STAGE(PG8_SB(1, 0), b3, voffB);
;             PG8_BAR; PG8_WAIT_L(0); PG8_MMA(0, 1, At, B1); PG8_BAR;
;             PG8_LDA(At, 1, 1); PG8_STAGE(PG8_SA(1, 0), a3, voffA);
;             PG8_BAR; PG8_WAIT_L(0); PG8_MMA(1, 0, At, B0); PG8_BAR; PG8_SCHED;
;             PG8_STAGE(PG8_SB(1, 1), b3 + hstepB, voffB);
;             PG8_WAIT_V(6); PG8_BAR; PG8_MMA(1, 1, At, B1); PG8_BAR;
	ds_read_b128 v[162:165], v148 offset:49152
	ds_read_b128 v[166:169], v148 offset:50176
	ds_read_b128 v[170:173], v148 offset:51200
	ds_read_b128 v[174:177], v148 offset:52224
	ds_read_b128 v[178:181], v148 offset:53248
	ds_read_b128 v[182:185], v148 offset:54272
	ds_read_b128 v[186:189], v148 offset:55296
	ds_read_b128 v[190:193], v148 offset:56320
	s_add_i32 s25, s54, s30
	v_lshl_add_u64 v[146:147], v[146:147], 0, s[8:9]
	s_mov_b32 m0, s25
	s_nop 0
	global_load_lds_dwordx4 v[146:147], off
	v_lshl_add_u64 v[146:147], v[210:211], 0, s[8:9]
	s_add_i32 m0, s25, 0x2000
	s_nop 0
	global_load_lds_dwordx4 v[146:147], off
	s_mov_b32 m0, s42
	v_lshl_add_u64 v[146:147], v[212:213], 0, s[8:9]
	global_load_lds_dwordx4 v[146:147], off
	v_lshl_add_u64 v[146:147], v[216:217], 0, s[8:9]
	s_mov_b32 m0, s43
	s_nop 0
	global_load_lds_dwordx4 v[146:147], off
	s_add_u32 s20, s20, 0x80080
	s_addc_u32 s21, s21, 0
	s_add_i32 s24, s24, s30
	s_mov_b32 m0, s24
	s_nop 0
	global_load_lds_dwordx4 v2, s[20:21]
	s_add_i32 m0, s24, 0x2000
	s_nop 0
	global_load_lds_dwordx4 v132, s[20:21]
	s_add_i32 s53, s53, 2
	s_add_u32 s18, s18, 0x100
	s_addc_u32 s19, s19, 0
	s_add_u32 s51, s51, 0x100
	s_addc_u32 s52, s52, 0
	s_cmp_gt_u32 s53, 29
	s_waitcnt lgkmcnt(0)
	s_waitcnt vmcnt(6)
	s_barrier
	v_mfma_f32_16x16x32_bf16 v[64:67], v[142:145], v[162:165], v[64:67]
	v_mfma_f32_16x16x32_bf16 v[60:63], v[154:157], v[162:165], v[60:63]
	v_mfma_f32_16x16x32_bf16 v[56:59], v[142:145], v[170:173], v[56:59]
	v_mfma_f32_16x16x32_bf16 v[48:51], v[154:157], v[170:173], v[48:51]
	v_mfma_f32_16x16x32_bf16 v[40:43], v[142:145], v[178:181], v[40:43]
	v_mfma_f32_16x16x32_bf16 v[32:35], v[154:157], v[178:181], v[32:35]
	v_mfma_f32_16x16x32_bf16 v[24:27], v[142:145], v[186:189], v[24:27]
	v_mfma_f32_16x16x32_bf16 v[16:19], v[154:157], v[186:189], v[16:19]
	v_mfma_f32_16x16x32_bf16 v[64:67], v[150:153], v[166:169], v[64:67]
	v_mfma_f32_16x16x32_bf16 v[60:63], v[158:161], v[166:169], v[60:63]
	v_mfma_f32_16x16x32_bf16 v[56:59], v[150:153], v[174:177], v[56:59]
	v_mfma_f32_16x16x32_bf16 v[48:51], v[158:161], v[174:177], v[48:51]
	v_mfma_f32_16x16x32_bf16 v[40:43], v[150:153], v[182:185], v[40:43]
	v_mfma_f32_16x16x32_bf16 v[32:35], v[158:161], v[182:185], v[32:35]
	v_mfma_f32_16x16x32_bf16 v[24:27], v[150:153], v[190:193], v[24:27]
	v_mfma_f32_16x16x32_bf16 v[16:19], v[158:161], v[190:193], v[16:19]
	v_mfma_f32_16x16x32_bf16 v[52:55], v[194:197], v[162:165], v[52:55]
	v_mfma_f32_16x16x32_bf16 v[44:47], v[202:205], v[162:165], v[44:47]
	v_mfma_f32_16x16x32_bf16 v[36:39], v[194:197], v[170:173], v[36:39]
	v_mfma_f32_16x16x32_bf16 v[28:31], v[202:205], v[170:173], v[28:31]
	v_mfma_f32_16x16x32_bf16 v[20:23], v[194:197], v[178:181], v[20:23]
	v_mfma_f32_16x16x32_bf16 v[12:15], v[202:205], v[178:181], v[12:15]
	v_mfma_f32_16x16x32_bf16 v[8:11], v[194:197], v[186:189], v[8:11]
	v_mfma_f32_16x16x32_bf16 v[4:7], v[202:205], v[186:189], v[4:7]
	v_mfma_f32_16x16x32_bf16 v[52:55], v[198:201], v[166:169], v[52:55]
	v_mfma_f32_16x16x32_bf16 v[44:47], v[206:209], v[166:169], v[44:47]
	v_mfma_f32_16x16x32_bf16 v[36:39], v[198:201], v[174:177], v[36:39]
	v_mfma_f32_16x16x32_bf16 v[28:31], v[206:209], v[174:177], v[28:31]
	v_mfma_f32_16x16x32_bf16 v[20:23], v[198:201], v[182:185], v[20:23]
	v_mfma_f32_16x16x32_bf16 v[12:15], v[206:209], v[182:185], v[12:15]
	v_mfma_f32_16x16x32_bf16 v[8:11], v[198:201], v[190:193], v[8:11]
	v_mfma_f32_16x16x32_bf16 v[4:7], v[206:209], v[190:193], v[4:7]
	s_barrier
	s_setprio 0
.LBB0_1094:
	s_add_u32 s20, s18, 0xfff80080
	s_addc_u32 s21, s19, -1
	s_add_i32 s54, 0, 0x10000
	v_add_u32_e32 v146, s54, v1
	ds_read_b128 v[142:145], v146
	ds_read_b128 v[150:153], v146 offset:1024
	ds_read_b128 v[154:157], v146 offset:2048
	ds_read_b128 v[158:161], v146 offset:3072
	s_cmp_eq_u32 s53, 28
	s_cselect_b32 s25, s5, s21
	s_cselect_b32 s24, s49, s20
	s_cselect_b32 s21, s1, s52
	s_cselect_b32 s20, s50, s51
	ds_read_b128 v[162:165], v148
	ds_read_b128 v[166:169], v148 offset:1024
	ds_read_b128 v[170:173], v148 offset:2048
	ds_read_b128 v[174:177], v148 offset:3072
	ds_read_b128 v[178:181], v148 offset:4096
	ds_read_b128 v[182:185], v148 offset:5120
	ds_read_b128 v[186:189], v148 offset:6144
	ds_read_b128 v[190:193], v148 offset:7168
	s_add_i32 s56, 0, 0x14000
	v_add_u32_e32 v146, s56, v1
	ds_read_b128 v[194:197], v146
	ds_read_b128 v[198:201], v146 offset:1024
	ds_read_b128 v[202:205], v146 offset:2048
	ds_read_b128 v[206:209], v146 offset:3072
	s_add_i32 m0, s31, 0xc000
	s_nop 0
	global_load_lds_dwordx4 v138, s[18:19]
	s_add_i32 m0, s31, 0xe000
	s_nop 0
	global_load_lds_dwordx4 v140, s[18:19]
	s_waitcnt lgkmcnt(0)
	s_barrier
; #define PG8_STAGE(bufoff, gbase, voff) do { _Pragma("unroll") for (int _i = 0; _i < 2; ++_i) \
;         __builtin_amdgcn_global_load_lds((const unsigned*)((const char*)(gbase) + (voff)[_i]), (LAS unsigned*)(lds + (bufoff) + ldsw + _i * 8192), 16, 0, 0); } while (0)
; #define PG8_LDA(dst, b, h) do { _Pragma("unroll") for (int m = 0; m < 4; ++m) _Pragma("unroll") for (int k = 0; k < 2; ++k) dst[m][k] = *(const LAS bf16x8*)(lds + PG8_SA(b, h) + aoff + m * 2048 + k * 1024); } while (0)
; #define PG8_LDB(dst, b, h) do { _Pragma("unroll") for (int n = 0; n < 2; ++n) _Pragma("unroll") for (int k = 0; k < 2; ++k) dst[n][k] = *(const LAS bf16x8*)(lds + PG8_SB(b, h) + boff + n * 2048 + k * 1024); } while (0)
; #define PG8_MMA(ai, bj, At, Bt) do { __builtin_amdgcn_s_setprio(1); _Pragma("unroll") for (int m = 0; m < 4; ++m) _Pragma("unroll") for (int n = 0; n < 2; ++n) _Pragma("unroll") for (int k = 0; k < 2; ++k) \
;         acc[ai][bj][m][n] = __builtin_amdgcn_mfma_f32_16x16x32_bf16(Bt[n][k], At[m][k], acc[ai][bj][m][n], 0, 0, 0); __builtin_amdgcn_s_setprio(0); } while (0)
; #define PG8_WAIT_V(n) asm volatile("s_waitcnt vmcnt(" #n ")" ::: "memory")
; #define PG8_WAIT_L(n) asm volatile("s_waitcnt lgkmcnt(" #n ")" ::: "memory")
; #define PG8_BAR __builtin_amdgcn_s_barrier()
; #define PG8_SCHED __builtin_amdgcn_sched_barrier(0)
; template <class Epi, class Sched>
; __device__ __forceinline__ void gemm_phase(LAS unsigned char* lds, const Gemm g, const Sched& S, const Epi& E) {
;     ...
;             PG8_WAIT_L(8); PG8_BAR; PG8_WAIT_L(0); PG8_MMA(0, 0, At, B0); PG8_BAR; PG8_SCHED;
;             PG8_LDB(B1, 0, 1); PG8_STAGE(PG8_SB(0, 0), b2, voffB);
;             PG8_BAR; PG8_WAIT_L(0); PG8_MMA(0, 1, At, B1); PG8_BAR;
;             PG8_LDA(At, 0, 1); PG8_STAGE(PG8_SA(0, 0), a2, voffA);
;             PG8_BAR; PG8_WAIT_L(0); PG8_MMA(1, 0, At, B0); PG8_BAR; PG8_SCHED;
;             PG8_STAGE(PG8_SB(0, 1), b2 + hstepB, voffB);
;             PG8_WAIT_V(6); PG8_BAR; PG8_MMA(1, 1, At, B1); PG8_BAR;
;             PG8_LDB(B0, 1, 0); PG8_SCHED; PG8_LDA(At, 1, 0); PG8_STAGE(PG8_SA(0, 1), a2 + hstepA, voffA);
;             PG8_WAIT_L(8); PG8_BAR; PG8_WAIT_L(0); PG8_MMA(0, 0, At, B0); PG8_BAR; PG8_SCHED;
	v_mfma_f32_16x16x32_bf16 v[128:131], v[142:145], v[162:165], v[128:131]
	v_mfma_f32_16x16x32_bf16 v[124:127], v[154:157], v[162:165], v[124:127]
	v_mfma_f32_16x16x32_bf16 v[120:123], v[142:145], v[170:173], v[120:123]
	v_mfma_f32_16x16x32_bf16 v[112:115], v[154:157], v[170:173], v[112:115]
	v_mfma_f32_16x16x32_bf16 v[104:107], v[142:145], v[178:181], v[104:107]
	v_mfma_f32_16x16x32_bf16 v[96:99], v[154:157], v[178:181], v[96:99]
	v_mfma_f32_16x16x32_bf16 v[88:91], v[142:145], v[186:189], v[88:91]
	v_mfma_f32_16x16x32_bf16 v[80:83], v[154:157], v[186:189], v[80:83]
	v_mfma_f32_16x16x32_bf16 v[128:131], v[150:153], v[166:169], v[128:131]
	v_mfma_f32_16x16x32_bf16 v[124:127], v[158:161], v[166:169], v[124:127]
	v_mfma_f32_16x16x32_bf16 v[120:123], v[150:153], v[174:177], v[120:123]
	v_mfma_f32_16x16x32_bf16 v[112:115], v[158:161], v[174:177], v[112:115]
	v_mfma_f32_16x16x32_bf16 v[104:107], v[150:153], v[182:185], v[104:107]
	v_mfma_f32_16x16x32_bf16 v[96:99], v[158:161], v[182:185], v[96:99]
	v_mfma_f32_16x16x32_bf16 v[88:91], v[150:153], v[190:193], v[88:91]
	v_mfma_f32_16x16x32_bf16 v[80:83], v[158:161], v[190:193], v[80:83]
	v_mfma_f32_16x16x32_bf16 v[116:119], v[194:197], v[162:165], v[116:119]
	v_mfma_f32_16x16x32_bf16 v[108:111], v[202:205], v[162:165], v[108:111]
	v_mfma_f32_16x16x32_bf16 v[100:103], v[194:197], v[170:173], v[100:103]
	v_mfma_f32_16x16x32_bf16 v[92:95], v[202:205], v[170:173], v[92:95]
	v_mfma_f32_16x16x32_bf16 v[84:87], v[194:197], v[178:181], v[84:87]
	v_mfma_f32_16x16x32_bf16 v[76:79], v[202:205], v[178:181], v[76:79]
	v_mfma_f32_16x16x32_bf16 v[72:75], v[194:197], v[186:189], v[72:75]
	v_mfma_f32_16x16x32_bf16 v[68:71], v[202:205], v[186:189], v[68:71]
	v_mfma_f32_16x16x32_bf16 v[116:119], v[198:201], v[166:169], v[116:119]
	v_mfma_f32_16x16x32_bf16 v[108:111], v[206:209], v[166:169], v[108:111]
	v_mfma_f32_16x16x32_bf16 v[100:103], v[198:201], v[174:177], v[100:103]
	v_mfma_f32_16x16x32_bf16 v[92:95], v[206:209], v[174:177], v[92:95]
	v_mfma_f32_16x16x32_bf16 v[84:87], v[198:201], v[182:185], v[84:87]
	v_mfma_f32_16x16x32_bf16 v[76:79], v[206:209], v[182:185], v[76:79]
	v_mfma_f32_16x16x32_bf16 v[72:75], v[198:201], v[190:193], v[72:75]
	v_mfma_f32_16x16x32_bf16 v[68:71], v[206:209], v[190:193], v[68:71]
	s_barrier
	ds_read_b128 v[162:165], v148 offset:16384
	ds_read_b128 v[166:169], v148 offset:17408
	ds_read_b128 v[170:173], v148 offset:18432
	ds_read_b128 v[174:177], v148 offset:19456
	ds_read_b128 v[178:181], v148 offset:20480
	ds_read_b128 v[182:185], v148 offset:21504
	ds_read_b128 v[186:189], v148 offset:22528
	ds_read_b128 v[190:193], v148 offset:23552
	s_add_i32 s54, s54, s30
	v_lshl_add_u64 v[146:147], s[20:21], 0, v[2:3]
	s_mov_b32 m0, s54
	v_lshl_add_u64 v[210:211], s[20:21], 0, v[132:133]
	global_load_lds_dwordx4 v[146:147], off
	s_add_i32 m0, s54, 0x2000
	s_nop 0
	global_load_lds_dwordx4 v[210:211], off
	s_mov_b32 m0, s31
	v_lshl_add_u64 v[212:213], s[24:25], 0, v[136:137]
	global_load_lds_dwordx4 v[212:213], off
	v_lshl_add_u64 v[216:217], s[24:25], 0, v[134:135]
	s_mov_b32 m0, s35
	s_nop 0
	global_load_lds_dwordx4 v[216:217], off
	s_add_u32 s54, s20, 0x80000
	s_addc_u32 s55, s21, 0
	s_add_i32 s56, s56, s30
	s_mov_b32 m0, s56
	s_nop 0
	global_load_lds_dwordx4 v2, s[54:55]
	s_add_i32 m0, s56, 0x2000
	s_nop 0
	global_load_lds_dwordx4 v132, s[54:55]
	s_waitcnt lgkmcnt(0)
	s_waitcnt vmcnt(6)
	s_barrier
	v_mfma_f32_16x16x32_bf16 v[64:67], v[142:145], v[162:165], v[64:67]
	v_mfma_f32_16x16x32_bf16 v[60:63], v[154:157], v[162:165], v[60:63]
	v_mfma_f32_16x16x32_bf16 v[56:59], v[142:145], v[170:173], v[56:59]
	v_mfma_f32_16x16x32_bf16 v[48:51], v[154:157], v[170:173], v[48:51]
	v_mfma_f32_16x16x32_bf16 v[40:43], v[142:145], v[178:181], v[40:43]
	v_mfma_f32_16x16x32_bf16 v[32:35], v[154:157], v[178:181], v[32:35]
	v_mfma_f32_16x16x32_bf16 v[24:27], v[142:145], v[186:189], v[24:27]
	v_mfma_f32_16x16x32_bf16 v[16:19], v[154:157], v[186:189], v[16:19]
	v_mfma_f32_16x16x32_bf16 v[64:67], v[150:153], v[166:169], v[64:67]
	v_mfma_f32_16x16x32_bf16 v[60:63], v[158:161], v[166:169], v[60:63]
	v_mfma_f32_16x16x32_bf16 v[56:59], v[150:153], v[174:177], v[56:59]
	v_mfma_f32_16x16x32_bf16 v[48:51], v[158:161], v[174:177], v[48:51]
	v_mfma_f32_16x16x32_bf16 v[40:43], v[150:153], v[182:185], v[40:43]
	v_mfma_f32_16x16x32_bf16 v[32:35], v[158:161], v[182:185], v[32:35]
	v_mfma_f32_16x16x32_bf16 v[24:27], v[150:153], v[190:193], v[24:27]
	v_mfma_f32_16x16x32_bf16 v[16:19], v[158:161], v[190:193], v[16:19]
	v_mfma_f32_16x16x32_bf16 v[52:55], v[194:197], v[162:165], v[52:55]
	v_mfma_f32_16x16x32_bf16 v[44:47], v[202:205], v[162:165], v[44:47]
	v_mfma_f32_16x16x32_bf16 v[36:39], v[194:197], v[170:173], v[36:39]
	v_mfma_f32_16x16x32_bf16 v[28:31], v[202:205], v[170:173], v[28:31]
	v_mfma_f32_16x16x32_bf16 v[20:23], v[194:197], v[178:181], v[20:23]
	v_mfma_f32_16x16x32_bf16 v[12:15], v[202:205], v[178:181], v[12:15]
	v_mfma_f32_16x16x32_bf16 v[8:11], v[194:197], v[186:189], v[8:11]
	v_mfma_f32_16x16x32_bf16 v[4:7], v[202:205], v[186:189], v[4:7]
	v_mfma_f32_16x16x32_bf16 v[52:55], v[198:201], v[166:169], v[52:55]
	v_mfma_f32_16x16x32_bf16 v[44:47], v[206:209], v[166:169], v[44:47]
	v_mfma_f32_16x16x32_bf16 v[36:39], v[198:201], v[174:177], v[36:39]
	v_mfma_f32_16x16x32_bf16 v[28:31], v[206:209], v[174:177], v[28:31]
	v_mfma_f32_16x16x32_bf16 v[20:23], v[198:201], v[182:185], v[20:23]
	v_mfma_f32_16x16x32_bf16 v[12:15], v[206:209], v[182:185], v[12:15]
	v_mfma_f32_16x16x32_bf16 v[8:11], v[198:201], v[190:193], v[8:11]
	v_mfma_f32_16x16x32_bf16 v[4:7], v[206:209], v[190:193], v[4:7]
	s_barrier
; #define PG8_STAGE(bufoff, gbase, voff) do { _Pragma("unroll") for (int _i = 0; _i < 2; ++_i) \
;         __builtin_amdgcn_global_load_lds((const unsigned*)((const char*)(gbase) + (voff)[_i]), (LAS unsigned*)(lds + (bufoff) + ldsw + _i * 8192), 16, 0, 0); } while (0)
; #define PG8_LDA(dst, b, h) do { _Pragma("unroll") for (int m = 0; m < 4; ++m) _Pragma("unroll") for (int k = 0; k < 2; ++k) dst[m][k] = *(const LAS bf16x8*)(lds + PG8_SA(b, h) + aoff + m * 2048 + k * 1024); } while (0)
; #define PG8_LDB(dst, b, h) do { _Pragma("unroll") for (int n = 0; n < 2; ++n) _Pragma("unroll") for (int k = 0; k < 2; ++k) dst[n][k] = *(const LAS bf16x8*)(lds + PG8_SB(b, h) + boff + n * 2048 + k * 1024); } while (0)
; #define PG8_MMA(ai, bj, At, Bt) do { __builtin_amdgcn_s_setprio(1); _Pragma("unroll") for (int m = 0; m < 4; ++m) _Pragma("unroll") for (int n = 0; n < 2; ++n) _Pragma("unroll") for (int k = 0; k < 2; ++k) \
;         acc[ai][bj][m][n] = __builtin_amdgcn_mfma_f32_16x16x32_bf16(Bt[n][k], At[m][k], acc[ai][bj][m][n], 0, 0, 0); __builtin_amdgcn_s_setprio(0); } while (0)
; #define PG8_WAIT_V(n) asm volatile("s_waitcnt vmcnt(" #n ")" ::: "memory")
; #define PG8_WAIT_L(n) asm volatile("s_waitcnt lgkmcnt(" #n ")" ::: "memory")
; #define PG8_BAR __builtin_amdgcn_s_barrier()
; #define PG8_SCHED __builtin_amdgcn_sched_barrier(0)
; template <class Epi, class Sched>
; __device__ __forceinline__ void gemm_phase(LAS unsigned char* lds, const Gemm g, const Sched& S, const Epi& E) {
;     ...
;             PG8_LDB(B1, 1, 1); PG8_STAGE(PG8_SB(1, 0), b3, voffB);
;             PG8_BAR; PG8_WAIT_L(0); PG8_MMA(0, 1, At, B1); PG8_BAR;
;             PG8_LDA(At, 1, 1); PG8_STAGE(PG8_SA(1, 0), a3, voffA);
;             PG8_BAR; PG8_WAIT_L(0); PG8_MMA(1, 0, At, B0); PG8_BAR; PG8_SCHED;
;             PG8_STAGE(PG8_SB(1, 1), b3 + hstepB, voffB);
;             PG8_WAIT_V(6); PG8_BAR; PG8_MMA(1, 1, At, B1); PG8_BAR;
;         }
;         E(acc, cur, wr, wc, ui, fq);
	s_add_i32 s54, 0, 0x18000
	v_add_u32_e32 v149, s54, v1
	ds_read_b128 v[142:145], v149
	ds_read_b128 v[150:153], v149 offset:1024
	ds_read_b128 v[154:157], v149 offset:2048
	ds_read_b128 v[158:161], v149 offset:3072
	s_add_u32 s24, s24, 0x80000
	s_addc_u32 s25, s25, 0
	ds_read_b128 v[162:165], v148 offset:32768
	ds_read_b128 v[166:169], v148 offset:33792
	ds_read_b128 v[170:173], v148 offset:34816
	ds_read_b128 v[174:177], v148 offset:35840
	ds_read_b128 v[178:181], v148 offset:36864
	ds_read_b128 v[182:185], v148 offset:37888
	ds_read_b128 v[186:189], v148 offset:38912
	ds_read_b128 v[190:193], v148 offset:39936
	s_mov_b32 m0, s36
	s_nop 0
	global_load_lds_dwordx4 v136, s[24:25]
	s_mov_b32 m0, s37
	s_nop 0
	global_load_lds_dwordx4 v134, s[24:25]
	s_add_i32 s24, 0, 0x1c000
	v_add_u32_e32 v149, s24, v1
	ds_read_b128 v[194:197], v149
	ds_read_b128 v[198:201], v149 offset:1024
	ds_read_b128 v[202:205], v149 offset:2048
	ds_read_b128 v[206:209], v149 offset:3072
	s_waitcnt lgkmcnt(0)
	s_barrier
	v_mfma_f32_16x16x32_bf16 v[128:131], v[142:145], v[162:165], v[128:131]
	v_mfma_f32_16x16x32_bf16 v[124:127], v[154:157], v[162:165], v[124:127]
	v_mfma_f32_16x16x32_bf16 v[120:123], v[142:145], v[170:173], v[120:123]
	v_mfma_f32_16x16x32_bf16 v[112:115], v[154:157], v[170:173], v[112:115]
	v_mfma_f32_16x16x32_bf16 v[104:107], v[142:145], v[178:181], v[104:107]
	v_mfma_f32_16x16x32_bf16 v[96:99], v[154:157], v[178:181], v[96:99]
	v_mfma_f32_16x16x32_bf16 v[88:91], v[142:145], v[186:189], v[88:91]
	v_mfma_f32_16x16x32_bf16 v[80:83], v[154:157], v[186:189], v[80:83]
	v_mfma_f32_16x16x32_bf16 v[128:131], v[150:153], v[166:169], v[128:131]
	v_mfma_f32_16x16x32_bf16 v[124:127], v[158:161], v[166:169], v[124:127]
	v_mfma_f32_16x16x32_bf16 v[120:123], v[150:153], v[174:177], v[120:123]
	v_mfma_f32_16x16x32_bf16 v[112:115], v[158:161], v[174:177], v[112:115]
	v_mfma_f32_16x16x32_bf16 v[104:107], v[150:153], v[182:185], v[104:107]
	v_mfma_f32_16x16x32_bf16 v[96:99], v[158:161], v[182:185], v[96:99]
	v_mfma_f32_16x16x32_bf16 v[88:91], v[150:153], v[190:193], v[88:91]
	v_mfma_f32_16x16x32_bf16 v[80:83], v[158:161], v[190:193], v[80:83]
	v_mfma_f32_16x16x32_bf16 v[116:119], v[194:197], v[162:165], v[116:119]
	v_mfma_f32_16x16x32_bf16 v[108:111], v[202:205], v[162:165], v[108:111]
	v_mfma_f32_16x16x32_bf16 v[100:103], v[194:197], v[170:173], v[100:103]
	v_mfma_f32_16x16x32_bf16 v[92:95], v[202:205], v[170:173], v[92:95]
	v_mfma_f32_16x16x32_bf16 v[84:87], v[194:197], v[178:181], v[84:87]
	v_mfma_f32_16x16x32_bf16 v[76:79], v[202:205], v[178:181], v[76:79]
	v_mfma_f32_16x16x32_bf16 v[72:75], v[194:197], v[186:189], v[72:75]
	v_mfma_f32_16x16x32_bf16 v[68:71], v[202:205], v[186:189], v[68:71]
	v_mfma_f32_16x16x32_bf16 v[116:119], v[198:201], v[166:169], v[116:119]
	v_mfma_f32_16x16x32_bf16 v[108:111], v[206:209], v[166:169], v[108:111]
	v_mfma_f32_16x16x32_bf16 v[100:103], v[198:201], v[174:177], v[100:103]
	v_mfma_f32_16x16x32_bf16 v[92:95], v[206:209], v[174:177], v[92:95]
	v_mfma_f32_16x16x32_bf16 v[84:87], v[198:201], v[182:185], v[84:87]
	v_mfma_f32_16x16x32_bf16 v[76:79], v[206:209], v[182:185], v[76:79]
	v_mfma_f32_16x16x32_bf16 v[72:75], v[198:201], v[190:193], v[72:75]
	v_mfma_f32_16x16x32_bf16 v[68:71], v[206:209], v[190:193], v[68:71]
	s_barrier
	ds_read_b128 v[162:165], v148 offset:49152
	ds_read_b128 v[166:169], v148 offset:50176
	ds_read_b128 v[170:173], v148 offset:51200
	ds_read_b128 v[174:177], v148 offset:52224
	ds_read_b128 v[178:181], v148 offset:53248
	ds_read_b128 v[182:185], v148 offset:54272
	ds_read_b128 v[186:189], v148 offset:55296
	ds_read_b128 v[190:193], v148 offset:56320
	s_add_i32 s25, s54, s30
	v_lshl_add_u64 v[146:147], v[146:147], 0, s[8:9]
	s_mov_b32 m0, s25
	s_nop 0
	global_load_lds_dwordx4 v[146:147], off
	v_lshl_add_u64 v[146:147], v[210:211], 0, s[8:9]
	s_add_i32 m0, s25, 0x2000
	s_nop 0
	global_load_lds_dwordx4 v[146:147], off
	s_mov_b32 m0, s42
	v_lshl_add_u64 v[146:147], v[212:213], 0, s[8:9]
	global_load_lds_dwordx4 v[146:147], off
	v_lshl_add_u64 v[146:147], v[216:217], 0, s[8:9]
	s_mov_b32 m0, s43
	s_nop 0
	global_load_lds_dwordx4 v[146:147], off
	s_add_u32 s20, s20, 0x80080
	s_addc_u32 s21, s21, 0
	s_add_i32 s24, s24, s30
	s_mov_b32 m0, s24
	s_nop 0
	global_load_lds_dwordx4 v2, s[20:21]
	s_add_i32 m0, s24, 0x2000
	s_nop 0
	global_load_lds_dwordx4 v132, s[20:21]
	s_add_i32 s53, s53, 2
	s_add_u32 s18, s18, 0x100
	s_addc_u32 s19, s19, 0
	s_add_u32 s51, s51, 0x100
	s_addc_u32 s52, s52, 0
	s_cmp_gt_u32 s53, 29
	s_waitcnt lgkmcnt(0)
	s_waitcnt vmcnt(6)
	s_barrier
	v_mfma_f32_16x16x32_bf16 v[64:67], v[142:145], v[162:165], v[64:67]
	v_mfma_f32_16x16x32_bf16 v[60:63], v[154:157], v[162:165], v[60:63]
	v_mfma_f32_16x16x32_bf16 v[56:59], v[142:145], v[170:173], v[56:59]
	v_mfma_f32_16x16x32_bf16 v[48:51], v[154:157], v[170:173], v[48:51]
	v_mfma_f32_16x16x32_bf16 v[40:43], v[142:145], v[178:181], v[40:43]
	v_mfma_f32_16x16x32_bf16 v[32:35], v[154:157], v[178:181], v[32:35]
	v_mfma_f32_16x16x32_bf16 v[24:27], v[142:145], v[186:189], v[24:27]
	v_mfma_f32_16x16x32_bf16 v[16:19], v[154:157], v[186:189], v[16:19]
	v_mfma_f32_16x16x32_bf16 v[64:67], v[150:153], v[166:169], v[64:67]
	v_mfma_f32_16x16x32_bf16 v[60:63], v[158:161], v[166:169], v[60:63]
	v_mfma_f32_16x16x32_bf16 v[56:59], v[150:153], v[174:177], v[56:59]
	v_mfma_f32_16x16x32_bf16 v[48:51], v[158:161], v[174:177], v[48:51]
	v_mfma_f32_16x16x32_bf16 v[40:43], v[150:153], v[182:185], v[40:43]
	v_mfma_f32_16x16x32_bf16 v[32:35], v[158:161], v[182:185], v[32:35]
	v_mfma_f32_16x16x32_bf16 v[24:27], v[150:153], v[190:193], v[24:27]
	v_mfma_f32_16x16x32_bf16 v[16:19], v[158:161], v[190:193], v[16:19]
	v_mfma_f32_16x16x32_bf16 v[52:55], v[194:197], v[162:165], v[52:55]
	v_mfma_f32_16x16x32_bf16 v[44:47], v[202:205], v[162:165], v[44:47]
	v_mfma_f32_16x16x32_bf16 v[36:39], v[194:197], v[170:173], v[36:39]
	v_mfma_f32_16x16x32_bf16 v[28:31], v[202:205], v[170:173], v[28:31]
	v_mfma_f32_16x16x32_bf16 v[20:23], v[194:197], v[178:181], v[20:23]
	v_mfma_f32_16x16x32_bf16 v[12:15], v[202:205], v[178:181], v[12:15]
	v_mfma_f32_16x16x32_bf16 v[8:11], v[194:197], v[186:189], v[8:11]
	v_mfma_f32_16x16x32_bf16 v[4:7], v[202:205], v[186:189], v[4:7]
	v_mfma_f32_16x16x32_bf16 v[52:55], v[198:201], v[166:169], v[52:55]
	v_mfma_f32_16x16x32_bf16 v[44:47], v[206:209], v[166:169], v[44:47]
	v_mfma_f32_16x16x32_bf16 v[36:39], v[198:201], v[174:177], v[36:39]
	v_mfma_f32_16x16x32_bf16 v[28:31], v[206:209], v[174:177], v[28:31]
	v_mfma_f32_16x16x32_bf16 v[20:23], v[198:201], v[182:185], v[20:23]
	v_mfma_f32_16x16x32_bf16 v[12:15], v[206:209], v[182:185], v[12:15]
	v_mfma_f32_16x16x32_bf16 v[8:11], v[198:201], v[190:193], v[8:11]
	v_mfma_f32_16x16x32_bf16 v[4:7], v[206:209], v[190:193], v[4:7]
	s_barrier
	s_cbranch_scc0 .LBB0_1094
	s_cmpk_gt_u32 s2, 0xff
	s_cbranch_scc1 .Lalign_a_1094
	s_barrier
; #define LAS __attribute__((address_space(3)))
; __device__ __forceinline__ unsigned cvt_pk_bf16(float lo, float hi) { const f32x2 v = {lo, hi}; const bf16v2_ r = __builtin_convertvector(v, bf16v2_); return __builtin_bit_cast(unsigned, r); }
; __device__ __forceinline__ int opaque_tid() { int t = threadIdx.x; asm volatile("" : "+v"(t)); return t; }
; __device__ __forceinline__ void rs_read(float (&r_)[2][4], int ui, int wr, int fr) {
;     extern __shared__ __attribute__((aligned(16))) unsigned char lds_dyn_[];
;     const LAS float* rl = (const LAS float*)((LAS unsigned char*)lds_dyn_ + L_RSPF + (ui & 1) * 1024) + wr * 64 + fr;
; #pragma unroll
;     for (int ai = 0; ai < 2; ++ai)
; #pragma unroll
;         for (int m = 0; m < 4; ++m) r_[ai][m] = rl[ai * HALF + m * 16];
; }
;     __device__ __forceinline__ void operator()(const f32x4 (&acc)[2][2][4][2], const Unit& u, int wr, int wc, int ui, int) const {
;         const int ol_ = opaque_tid() & 63, fr = ol_ & 15, fq = ol_ >> 4;
;         const int row0 = u.pm * BM + wr * 64 + fr, col0 = u.pn * BM + wc * 32 + 8 * fq;
;         float r_[2][4];
;         if (rs) rs_read(r_, ui, wr, fr);
;         else {
; #pragma unroll
;             for (int ai = 0; ai < 2; ++ai)
; #pragma unroll
;                 for (int m = 0; m < 4; ++m) r_[ai][m] = 1.f;
;         }
; #pragma unroll
;         for (int ai = 0; ai < 2; ++ai)
; #pragma unroll
;             for (int m = 0; m < 4; ++m) { bf16_t* rowp = O + (size_t)(row0 + ai * HALF + m * 16) * ldc + col0; const float r = r_[ai][m];
; #pragma unroll
;                 for (int bj = 0; bj < 2; ++bj) { const f32x4 v0 = acc[ai][bj][m][0] * r, v1 = acc[ai][bj][m][1] * r;
;                     u32x4 w; w.x = cvt_pk_bf16(v0[0], v0[1]); w.y = cvt_pk_bf16(v0[2], v0[3]); w.z = cvt_pk_bf16(v1[0], v1[1]); w.w = cvt_pk_bf16(v1[2], v1[3]);
;                     *(u32x4*)(rowp + bj * HALF) = w; } }
.Lalign_a_1094:
	s_lshl_b32 s1, s48, 10
	v_mov_b32_e32 v144, v0
	s_and_b32 s1, s1, 0x400
	s_add_i32 s1, s44, s1
	v_and_b32_e32 v145, 15, v144
	v_lshl_add_u32 v142, v145, 2, s1
	s_lshl_b32 s1, s47, 8
	v_lshrrev_b32_e32 v144, 1, v144
	v_and_or_b32 v144, v144, 24, s1
	ds_read2_b32 v[150:151], v142 offset1:16
	ds_read2_b32 v[152:153], v142 offset0:32 offset1:48
	ds_read2_b32 v[154:155], v142 offset0:128 offset1:144
	ds_read2_b32 v[142:143], v142 offset0:160 offset1:176
	v_or_b32_e32 v146, s39, v144
	v_or_b32_e32 v144, s38, v145
	v_lshl_add_u32 v149, s46, 8, v144
	v_ashrrev_i32_e32 v147, 31, v146
	v_mov_b64_e32 v[144:145], s[92:93]
	v_mad_i64_i32 v[156:157], s[18:19], v149, s11, v[144:145]
	v_lshlrev_b64 v[146:147], 1, v[146:147]
	s_waitcnt lgkmcnt(0)
	v_pk_mul_f32 v[130:131], v[130:131], v[150:151] op_sel_hi:[1,0]
	v_pk_mul_f32 v[128:129], v[128:129], v[150:151] op_sel_hi:[1,0]
	v_pk_mul_f32 v[158:159], v[126:127], v[150:151] op_sel_hi:[1,0]
	v_pk_mul_f32 v[126:127], v[124:125], v[150:151] op_sel_hi:[1,0]
	v_lshl_add_u64 v[156:157], v[156:157], 0, v[146:147]
	v_cvt_pk_bf16_f32 v124, v128, v129
	v_cvt_pk_bf16_f32 v125, v130, v131
	v_cvt_pk_bf16_f32 v126, v126, v127
	v_cvt_pk_bf16_f32 v127, v158, v159
	global_store_dwordx4 v[156:157], v[124:127], off
	v_pk_mul_f32 v[118:119], v[118:119], v[150:151] op_sel_hi:[1,0]
	v_pk_mul_f32 v[116:117], v[116:117], v[150:151] op_sel_hi:[1,0]
	v_pk_mul_f32 v[124:125], v[110:111], v[150:151] op_sel_hi:[1,0]
	v_pk_mul_f32 v[110:111], v[108:109], v[150:151] op_sel_hi:[1,0]
	v_cvt_pk_bf16_f32 v108, v116, v117
	v_cvt_pk_bf16_f32 v109, v118, v119
	v_cvt_pk_bf16_f32 v110, v110, v111
	v_cvt_pk_bf16_f32 v111, v124, v125
	global_store_dwordx4 v[156:157], v[108:111], off offset:256
	v_mov_b32_e32 v118, v151
	v_pk_mul_f32 v[114:115], v[114:115], v[118:119] op_sel_hi:[1,0]
	v_or_b32_e32 v108, 16, v149
	v_mad_i64_i32 v[108:109], s[18:19], v108, s11, v[144:145]
	v_lshl_add_u64 v[116:117], v[108:109], 0, v[146:147]
	v_pk_mul_f32 v[110:111], v[122:123], v[118:119] op_sel_hi:[1,0]
	v_pk_mul_f32 v[108:109], v[120:121], v[118:119] op_sel_hi:[1,0]
	v_pk_mul_f32 v[112:113], v[112:113], v[118:119] op_sel_hi:[1,0]
	v_cvt_pk_bf16_f32 v108, v108, v109
	v_cvt_pk_bf16_f32 v109, v110, v111
	v_cvt_pk_bf16_f32 v110, v112, v113
	v_cvt_pk_bf16_f32 v111, v114, v115
	global_store_dwordx4 v[116:117], v[108:111], off
	v_pk_mul_f32 v[102:103], v[102:103], v[118:119] op_sel_hi:[1,0]
	v_pk_mul_f32 v[100:101], v[100:101], v[118:119] op_sel_hi:[1,0]
	v_pk_mul_f32 v[108:109], v[94:95], v[118:119] op_sel_hi:[1,0]
	v_pk_mul_f32 v[94:95], v[92:93], v[118:119] op_sel_hi:[1,0]
	v_cvt_pk_bf16_f32 v92, v100, v101
	v_cvt_pk_bf16_f32 v93, v102, v103
	v_cvt_pk_bf16_f32 v94, v94, v95
	v_cvt_pk_bf16_f32 v95, v108, v109
	global_store_dwordx4 v[116:117], v[92:95], off offset:256
	v_pk_mul_f32 v[98:99], v[98:99], v[152:153] op_sel_hi:[1,0]
	v_pk_mul_f32 v[96:97], v[96:97], v[152:153] op_sel_hi:[1,0]
	v_or_b32_e32 v92, 32, v149
	v_mad_i64_i32 v[92:93], s[18:19], v92, s11, v[144:145]
	v_lshl_add_u64 v[100:101], v[92:93], 0, v[146:147]
	v_pk_mul_f32 v[94:95], v[106:107], v[152:153] op_sel_hi:[1,0]
	v_pk_mul_f32 v[92:93], v[104:105], v[152:153] op_sel_hi:[1,0]
	v_pk_mul_f32 v[86:87], v[86:87], v[152:153] op_sel_hi:[1,0]
	v_cvt_pk_bf16_f32 v92, v92, v93
	v_cvt_pk_bf16_f32 v93, v94, v95
	v_cvt_pk_bf16_f32 v94, v96, v97
	v_cvt_pk_bf16_f32 v95, v98, v99
	global_store_dwordx4 v[100:101], v[92:95], off
	v_pk_mul_f32 v[84:85], v[84:85], v[152:153] op_sel_hi:[1,0]
	v_pk_mul_f32 v[66:67], v[66:67], v[154:155] op_sel_hi:[1,0]
	v_pk_mul_f32 v[92:93], v[78:79], v[152:153] op_sel_hi:[1,0]
	v_pk_mul_f32 v[78:79], v[76:77], v[152:153] op_sel_hi:[1,0]
	v_cvt_pk_bf16_f32 v76, v84, v85
	v_cvt_pk_bf16_f32 v77, v86, v87
	v_cvt_pk_bf16_f32 v78, v78, v79
	v_cvt_pk_bf16_f32 v79, v92, v93
	global_store_dwordx4 v[100:101], v[76:79], off offset:256
	v_mov_b32_e32 v86, v153
	v_pk_mul_f32 v[82:83], v[82:83], v[86:87] op_sel_hi:[1,0]
	v_or_b32_e32 v76, 48, v149
	v_mad_i64_i32 v[76:77], s[18:19], v76, s11, v[144:145]
	v_lshl_add_u64 v[84:85], v[76:77], 0, v[146:147]
	v_pk_mul_f32 v[78:79], v[90:91], v[86:87] op_sel_hi:[1,0]
	v_pk_mul_f32 v[76:77], v[88:89], v[86:87] op_sel_hi:[1,0]
	v_pk_mul_f32 v[80:81], v[80:81], v[86:87] op_sel_hi:[1,0]
	v_cvt_pk_bf16_f32 v76, v76, v77
	v_cvt_pk_bf16_f32 v77, v78, v79
	v_cvt_pk_bf16_f32 v78, v80, v81
	v_cvt_pk_bf16_f32 v79, v82, v83
	global_store_dwordx4 v[84:85], v[76:79], off
	v_pk_mul_f32 v[74:75], v[74:75], v[86:87] op_sel_hi:[1,0]
; __device__ __forceinline__ unsigned cvt_pk_bf16(float lo, float hi) { const f32x2 v = {lo, hi}; const bf16v2_ r = __builtin_convertvector(v, bf16v2_); return __builtin_bit_cast(unsigned, r); }
;     __device__ __forceinline__ void operator()(const f32x4 (&acc)[2][2][4][2], const Unit& u, int wr, int wc, int ui, int) const {
;     ...
;         for (int ai = 0; ai < 2; ++ai)
; #pragma unroll
;             for (int m = 0; m < 4; ++m) { bf16_t* rowp = O + (size_t)(row0 + ai * HALF + m * 16) * ldc + col0; const float r = r_[ai][m];
; #pragma unroll
;                 for (int bj = 0; bj < 2; ++bj) { const f32x4 v0 = acc[ai][bj][m][0] * r, v1 = acc[ai][bj][m][1] * r;
;                     u32x4 w; w.x = cvt_pk_bf16(v0[0], v0[1]); w.y = cvt_pk_bf16(v0[2], v0[3]); w.z = cvt_pk_bf16(v1[0], v1[1]); w.w = cvt_pk_bf16(v1[2], v1[3]);
;                     *(u32x4*)(rowp + bj * HALF) = w; } }
; template <class Epi, class Sched>
; __device__ __forceinline__ void gemm_phase(LAS unsigned char* lds, const Gemm g, const Sched& S, const Epi& E) {
;     ...
;         cur = nxt; cA = nA; cB = nB; ++ui;
	v_pk_mul_f32 v[72:73], v[72:73], v[86:87] op_sel_hi:[1,0]
	v_pk_mul_f32 v[76:77], v[70:71], v[86:87] op_sel_hi:[1,0]
	v_pk_mul_f32 v[70:71], v[68:69], v[86:87] op_sel_hi:[1,0]
	v_cvt_pk_bf16_f32 v68, v72, v73
	v_cvt_pk_bf16_f32 v69, v74, v75
	v_cvt_pk_bf16_f32 v70, v70, v71
	v_cvt_pk_bf16_f32 v71, v76, v77
	global_store_dwordx4 v[84:85], v[68:71], off offset:256
	v_pk_mul_f32 v[64:65], v[64:65], v[154:155] op_sel_hi:[1,0]
	v_pk_mul_f32 v[54:55], v[54:55], v[154:155] op_sel_hi:[1,0]
	v_add_u32_e32 v68, 0x80, v149
	v_mad_i64_i32 v[68:69], s[18:19], v68, s11, v[144:145]
	v_pk_mul_f32 v[70:71], v[62:63], v[154:155] op_sel_hi:[1,0]
	v_pk_mul_f32 v[62:63], v[60:61], v[154:155] op_sel_hi:[1,0]
	v_lshl_add_u64 v[68:69], v[68:69], 0, v[146:147]
	v_cvt_pk_bf16_f32 v60, v64, v65
	v_cvt_pk_bf16_f32 v61, v66, v67
	v_cvt_pk_bf16_f32 v62, v62, v63
	v_cvt_pk_bf16_f32 v63, v70, v71
	global_store_dwordx4 v[68:69], v[60:63], off
	v_pk_mul_f32 v[52:53], v[52:53], v[154:155] op_sel_hi:[1,0]
	v_pk_mul_f32 v[34:35], v[34:35], v[142:143] op_sel_hi:[1,0]
	v_pk_mul_f32 v[60:61], v[46:47], v[154:155] op_sel_hi:[1,0]
	v_pk_mul_f32 v[46:47], v[44:45], v[154:155] op_sel_hi:[1,0]
	v_cvt_pk_bf16_f32 v44, v52, v53
	v_cvt_pk_bf16_f32 v45, v54, v55
	v_cvt_pk_bf16_f32 v46, v46, v47
	v_cvt_pk_bf16_f32 v47, v60, v61
	global_store_dwordx4 v[68:69], v[44:47], off offset:256
	v_mov_b32_e32 v54, v155
	v_pk_mul_f32 v[50:51], v[50:51], v[54:55] op_sel_hi:[1,0]
	v_add_u32_e32 v44, 0x90, v149
	v_mad_i64_i32 v[44:45], s[18:19], v44, s11, v[144:145]
	v_lshl_add_u64 v[52:53], v[44:45], 0, v[146:147]
	v_pk_mul_f32 v[46:47], v[58:59], v[54:55] op_sel_hi:[1,0]
	v_pk_mul_f32 v[44:45], v[56:57], v[54:55] op_sel_hi:[1,0]
	v_pk_mul_f32 v[48:49], v[48:49], v[54:55] op_sel_hi:[1,0]
	v_cvt_pk_bf16_f32 v44, v44, v45
	v_cvt_pk_bf16_f32 v45, v46, v47
	v_cvt_pk_bf16_f32 v46, v48, v49
	v_cvt_pk_bf16_f32 v47, v50, v51
	global_store_dwordx4 v[52:53], v[44:47], off
	v_pk_mul_f32 v[38:39], v[38:39], v[54:55] op_sel_hi:[1,0]
	v_pk_mul_f32 v[36:37], v[36:37], v[54:55] op_sel_hi:[1,0]
	v_pk_mul_f32 v[44:45], v[30:31], v[54:55] op_sel_hi:[1,0]
	v_pk_mul_f32 v[30:31], v[28:29], v[54:55] op_sel_hi:[1,0]
	v_cvt_pk_bf16_f32 v28, v36, v37
	v_cvt_pk_bf16_f32 v29, v38, v39
	v_cvt_pk_bf16_f32 v30, v30, v31
	v_cvt_pk_bf16_f32 v31, v44, v45
	global_store_dwordx4 v[52:53], v[28:31], off offset:256
	v_pk_mul_f32 v[32:33], v[32:33], v[142:143] op_sel_hi:[1,0]
	v_pk_mul_f32 v[22:23], v[22:23], v[142:143] op_sel_hi:[1,0]
	v_add_u32_e32 v28, 0xa0, v149
	v_mad_i64_i32 v[28:29], s[18:19], v28, s11, v[144:145]
	v_lshl_add_u64 v[36:37], v[28:29], 0, v[146:147]
	v_pk_mul_f32 v[30:31], v[42:43], v[142:143] op_sel_hi:[1,0]
	v_pk_mul_f32 v[28:29], v[40:41], v[142:143] op_sel_hi:[1,0]
	v_pk_mul_f32 v[20:21], v[20:21], v[142:143] op_sel_hi:[1,0]
	v_cvt_pk_bf16_f32 v28, v28, v29
	v_cvt_pk_bf16_f32 v29, v30, v31
	v_cvt_pk_bf16_f32 v30, v32, v33
	v_cvt_pk_bf16_f32 v31, v34, v35
	global_store_dwordx4 v[36:37], v[28:31], off
	s_and_b64 vcc, exec, s[40:41]
	s_mov_b32 s47, s0
	v_pk_mul_f32 v[28:29], v[14:15], v[142:143] op_sel_hi:[1,0]
	v_pk_mul_f32 v[14:15], v[12:13], v[142:143] op_sel_hi:[1,0]
	v_cvt_pk_bf16_f32 v12, v20, v21
	v_cvt_pk_bf16_f32 v13, v22, v23
	v_cvt_pk_bf16_f32 v14, v14, v15
	v_cvt_pk_bf16_f32 v15, v28, v29
	global_store_dwordx4 v[36:37], v[12:15], off offset:256
	v_mov_b32_e32 v22, v143
	v_pk_mul_f32 v[18:19], v[18:19], v[22:23] op_sel_hi:[1,0]
	v_add_u32_e32 v12, 0xb0, v149
	v_mad_i64_i32 v[12:13], s[18:19], v12, s11, v[144:145]
	v_lshl_add_u64 v[20:21], v[12:13], 0, v[146:147]
	v_pk_mul_f32 v[14:15], v[26:27], v[22:23] op_sel_hi:[1,0]
	v_pk_mul_f32 v[12:13], v[24:25], v[22:23] op_sel_hi:[1,0]
	v_pk_mul_f32 v[16:17], v[16:17], v[22:23] op_sel_hi:[1,0]
	v_cvt_pk_bf16_f32 v12, v12, v13
	v_cvt_pk_bf16_f32 v13, v14, v15
	v_cvt_pk_bf16_f32 v14, v16, v17
	v_cvt_pk_bf16_f32 v15, v18, v19
	global_store_dwordx4 v[20:21], v[12:15], off
	v_pk_mul_f32 v[10:11], v[10:11], v[22:23] op_sel_hi:[1,0]
	v_pk_mul_f32 v[8:9], v[8:9], v[22:23] op_sel_hi:[1,0]
	v_pk_mul_f32 v[12:13], v[6:7], v[22:23] op_sel_hi:[1,0]
	v_pk_mul_f32 v[6:7], v[4:5], v[22:23] op_sel_hi:[1,0]
	v_cvt_pk_bf16_f32 v4, v8, v9
	v_cvt_pk_bf16_f32 v5, v10, v11
	v_cvt_pk_bf16_f32 v6, v6, v7
	v_cvt_pk_bf16_f32 v7, v12, v13
	s_mov_b32 s46, s4
	s_mov_b64 s[20:21], s[14:15]
	s_mov_b64 s[18:19], s[6:7]
	s_mov_b32 s48, s45
	global_store_dwordx4 v[20:21], v[4:7], off offset:256
	s_cmpk_lt_u32 s2, 0x100
	s_cbranch_scc1 .Lalign_b_1094
	s_barrier
	s_setprio 1

; #define PG8_STAGE(bufoff, gbase, voff) do { _Pragma("unroll") for (int _i = 0; _i < 2; ++_i) \
;         __builtin_amdgcn_global_load_lds((const unsigned*)((const char*)(gbase) + (voff)[_i]), (LAS unsigned*)(lds + (bufoff) + ldsw + _i * 8192), 16, 0, 0); } while (0)
; #define PG8_LDA(dst, b, h) do { _Pragma("unroll") for (int m = 0; m < 4; ++m) _Pragma("unroll") for (int k = 0; k < 2; ++k) dst[m][k] = *(const LAS bf16x8*)(lds + PG8_SA(b, h) + aoff + m * 2048 + k * 1024); } while (0)
; #define PG8_LDB(dst, b, h) do { _Pragma("unroll") for (int n = 0; n < 2; ++n) _Pragma("unroll") for (int k = 0; k < 2; ++k) dst[n][k] = *(const LAS bf16x8*)(lds + PG8_SB(b, h) + boff + n * 2048 + k * 1024); } while (0)
; #define PG8_WAIT_V(n) asm volatile("s_waitcnt vmcnt(" #n ")" ::: "memory")
; #define PG8_WAIT_L(n) asm volatile("s_waitcnt lgkmcnt(" #n ")" ::: "memory")
; #define PG8_BAR __builtin_amdgcn_s_barrier()
; #define PG8_SCHED __builtin_amdgcn_sched_barrier(0)
; template <class Epi, class Sched>
; __device__ __forceinline__ void gemm_phase(LAS unsigned char* lds, const Gemm g, const Sched& S, const Epi& E) {
;     ...
;         const char* nA = has_next ? (const char*)g.A + (size_t)nxt.pm * tstepA : cA; const char* nB = has_next ? (const char*)g.Bt + (size_t)nxt.pn * tstepB : cB;
;         for (int t = 0; t < nt; t += 2) {
;             const bool last = (t == nt - 2);
;             const char* a1 = cA + (size_t)(t + 1) * kstep;
;             const char* a2 = last ? nA : cA + (size_t)(t + 2) * kstep; const char* b2 = last ? nB : cB + (size_t)(t + 2) * kstep;
;             const char* a3 = a2 + kstep; const char* b3 = b2 + kstep;
;             if (last && has_next) S.a_ready(nxt);
;             PG8_LDB(B0, 0, 0); PG8_SCHED; PG8_LDA(At, 0, 0); PG8_STAGE(PG8_SA(1, 1), a1 + hstepA, voffA);
;             PG8_WAIT_L(8); PG8_BAR; PG8_WAIT_L(0); PG8_MMA(0, 0, At, B0); PG8_BAR; PG8_SCHED;
;             PG8_LDB(B1, 0, 1); PG8_STAGE(PG8_SB(0, 0), b2, voffB);
;             PG8_BAR; PG8_WAIT_L(0); PG8_MMA(0, 1, At, B1); PG8_BAR;
;             PG8_LDA(At, 0, 1); PG8_STAGE(PG8_SA(0, 0), a2, voffA);
;             PG8_BAR; PG8_WAIT_L(0); PG8_MMA(1, 0, At, B0); PG8_BAR; PG8_SCHED;
;             PG8_STAGE(PG8_SB(0, 1), b2 + hstepB, voffB);
;             PG8_WAIT_V(6); PG8_BAR; PG8_MMA(1, 1, At, B1); PG8_BAR;
.LBB0_1395:
	v_mov_b64_e32 v[4:5], 0x400
	s_ashr_i32 s15, s14, 31
	v_cmp_lt_i64_e32 vcc, s[4:5], v[4:5]
	s_lshl_b64 s[4:5], s[14:15], 20
	v_readlane_b32 s48, v252, 0
	v_readlane_b32 s49, v252, 1
	s_add_u32 s4, s48, s4
	s_addc_u32 s5, s49, s5
	s_and_b64 s[18:19], vcc, exec
	s_cselect_b32 s15, s5, s7
	s_cselect_b32 s47, s4, s6
	s_ashr_i32 s1, s0, 31
	s_lshl_b64 s[18:19], s[0:1], 20
	s_add_u32 s18, s28, s18
	s_addc_u32 s19, s29, s19
	s_and_b64 s[24:25], vcc, exec
	s_cselect_b32 s1, s19, s21
	s_cselect_b32 s48, s18, s20
	s_add_u32 s6, s6, 0x80080
	s_addc_u32 s7, s7, 0
	v_readlane_b32 s50, v252, 2
	v_readlane_b32 s51, v252, 3
	s_add_u32 s49, s20, 0x100
	s_addc_u32 s50, s21, 0
	s_mov_b32 s51, -2
	s_add_u32 s20, s6, 0xfff80080
	s_addc_u32 s21, s7, -1
	s_add_i32 s52, 0, 0x10000
	v_add_u32_e32 v144, s52, v1
	ds_read_b128 v[132:135], v144
	ds_read_b128 v[136:139], v144 offset:1024
	ds_read_b128 v[140:143], v144 offset:2048
	ds_read_b128 v[144:147], v144 offset:3072
	s_cmp_eq_u32 s51, 28
	s_cselect_b32 s25, s15, s21
	s_cselect_b32 s24, s47, s20
	s_cselect_b32 s21, s1, s50
	s_cselect_b32 s20, s48, s49
	ds_read_b128 v[148:151], v224
	ds_read_b128 v[152:155], v224 offset:1024
	ds_read_b128 v[156:159], v224 offset:2048
	ds_read_b128 v[160:163], v224 offset:3072
	ds_read_b128 v[164:167], v224 offset:4096
	ds_read_b128 v[168:171], v224 offset:5120
	ds_read_b128 v[172:175], v224 offset:6144
	ds_read_b128 v[176:179], v224 offset:7168
	s_add_i32 s54, 0, 0x14000
	v_add_u32_e32 v202, s54, v1
	ds_read_b128 v[180:183], v202
	ds_read_b128 v[184:187], v202 offset:1024
	ds_read_b128 v[188:191], v202 offset:2048
	ds_read_b128 v[202:205], v202 offset:3072
	s_add_i32 m0, s31, 0xc000
	s_nop 0
	global_load_lds_dwordx4 v198, s[6:7]
	s_add_i32 m0, s31, 0xe000
	s_nop 0
	global_load_lds_dwordx4 v200, s[6:7]
	s_waitcnt lgkmcnt(0)
	s_barrier
	v_mfma_f32_16x16x32_bf16 v[128:131], v[132:135], v[148:151], 0
	v_mfma_f32_16x16x32_bf16 v[124:127], v[140:143], v[148:151], 0
	v_mfma_f32_16x16x32_bf16 v[112:115], v[132:135], v[156:159], 0
	v_mfma_f32_16x16x32_bf16 v[108:111], v[140:143], v[156:159], 0
	v_mfma_f32_16x16x32_bf16 v[100:103], v[132:135], v[164:167], 0
	v_mfma_f32_16x16x32_bf16 v[92:95], v[140:143], v[164:167], 0
	v_mfma_f32_16x16x32_bf16 v[84:87], v[132:135], v[172:175], 0
	v_mfma_f32_16x16x32_bf16 v[76:79], v[140:143], v[172:175], 0
	v_mfma_f32_16x16x32_bf16 v[128:131], v[136:139], v[152:155], v[128:131]
	v_mfma_f32_16x16x32_bf16 v[124:127], v[144:147], v[152:155], v[124:127]
	v_mfma_f32_16x16x32_bf16 v[112:115], v[136:139], v[160:163], v[112:115]
	v_mfma_f32_16x16x32_bf16 v[108:111], v[144:147], v[160:163], v[108:111]
	v_mfma_f32_16x16x32_bf16 v[100:103], v[136:139], v[168:171], v[100:103]
	v_mfma_f32_16x16x32_bf16 v[92:95], v[144:147], v[168:171], v[92:95]
	v_mfma_f32_16x16x32_bf16 v[84:87], v[136:139], v[176:179], v[84:87]
	v_mfma_f32_16x16x32_bf16 v[76:79], v[144:147], v[176:179], v[76:79]
	v_mfma_f32_16x16x32_bf16 v[120:123], v[180:183], v[148:151], 0
	v_mfma_f32_16x16x32_bf16 v[116:119], v[188:191], v[148:151], 0
	v_mfma_f32_16x16x32_bf16 v[104:107], v[180:183], v[156:159], 0
	v_mfma_f32_16x16x32_bf16 v[96:99], v[188:191], v[156:159], 0
	v_mfma_f32_16x16x32_bf16 v[88:91], v[180:183], v[164:167], 0
	v_mfma_f32_16x16x32_bf16 v[80:83], v[188:191], v[164:167], 0
	v_mfma_f32_16x16x32_bf16 v[72:75], v[180:183], v[172:175], 0
	v_mfma_f32_16x16x32_bf16 v[68:71], v[188:191], v[172:175], 0
	v_mfma_f32_16x16x32_bf16 v[120:123], v[184:187], v[152:155], v[120:123]
	v_mfma_f32_16x16x32_bf16 v[116:119], v[202:205], v[152:155], v[116:119]
	v_mfma_f32_16x16x32_bf16 v[104:107], v[184:187], v[160:163], v[104:107]
	v_mfma_f32_16x16x32_bf16 v[96:99], v[202:205], v[160:163], v[96:99]
	v_mfma_f32_16x16x32_bf16 v[88:91], v[184:187], v[168:171], v[88:91]
	v_mfma_f32_16x16x32_bf16 v[80:83], v[202:205], v[168:171], v[80:83]
	v_mfma_f32_16x16x32_bf16 v[72:75], v[184:187], v[176:179], v[72:75]
	v_mfma_f32_16x16x32_bf16 v[68:71], v[202:205], v[176:179], v[68:71]
	s_barrier
	ds_read_b128 v[148:151], v224 offset:16384
	ds_read_b128 v[152:155], v224 offset:17408
	ds_read_b128 v[156:159], v224 offset:18432
	ds_read_b128 v[160:163], v224 offset:19456
	ds_read_b128 v[164:167], v224 offset:20480
	ds_read_b128 v[168:171], v224 offset:21504
	ds_read_b128 v[172:175], v224 offset:22528
	ds_read_b128 v[176:179], v224 offset:23552
	s_add_i32 s52, s52, s30
	v_lshl_add_u64 v[206:207], s[20:21], 0, v[2:3]
	s_mov_b32 m0, s52
	s_nop 0
	global_load_lds_dwordx4 v[206:207], off
	v_lshl_add_u64 v[208:209], s[20:21], 0, v[192:193]
	s_add_i32 m0, s52, 0x2000
	s_nop 0
	global_load_lds_dwordx4 v[208:209], off
	s_mov_b32 m0, s31
	v_lshl_add_u64 v[210:211], s[24:25], 0, v[196:197]
	global_load_lds_dwordx4 v[210:211], off
	v_lshl_add_u64 v[212:213], s[24:25], 0, v[194:195]
	s_mov_b32 m0, s35
	s_nop 0
	global_load_lds_dwordx4 v[212:213], off
	s_add_u32 s52, s20, 0x80000
	s_addc_u32 s53, s21, 0
	s_add_i32 s54, s54, s30
	s_mov_b32 m0, s54
	s_nop 0
	global_load_lds_dwordx4 v2, s[52:53]
	s_add_i32 m0, s54, 0x2000
	s_nop 0
	global_load_lds_dwordx4 v192, s[52:53]
	s_waitcnt lgkmcnt(0)
	s_waitcnt vmcnt(6)
	s_barrier
; #define PG8_STAGE(bufoff, gbase, voff) do { _Pragma("unroll") for (int _i = 0; _i < 2; ++_i) \
;         __builtin_amdgcn_global_load_lds((const unsigned*)((const char*)(gbase) + (voff)[_i]), (LAS unsigned*)(lds + (bufoff) + ldsw + _i * 8192), 16, 0, 0); } while (0)
; #define PG8_LDA(dst, b, h) do { _Pragma("unroll") for (int m = 0; m < 4; ++m) _Pragma("unroll") for (int k = 0; k < 2; ++k) dst[m][k] = *(const LAS bf16x8*)(lds + PG8_SA(b, h) + aoff + m * 2048 + k * 1024); } while (0)
; #define PG8_LDB(dst, b, h) do { _Pragma("unroll") for (int n = 0; n < 2; ++n) _Pragma("unroll") for (int k = 0; k < 2; ++k) dst[n][k] = *(const LAS bf16x8*)(lds + PG8_SB(b, h) + boff + n * 2048 + k * 1024); } while (0)
; #define PG8_WAIT_V(n) asm volatile("s_waitcnt vmcnt(" #n ")" ::: "memory")
; #define PG8_WAIT_L(n) asm volatile("s_waitcnt lgkmcnt(" #n ")" ::: "memory")
; #define PG8_BAR __builtin_amdgcn_s_barrier()
; #define PG8_SCHED __builtin_amdgcn_sched_barrier(0)
; template <class Epi, class Sched>
; __device__ __forceinline__ void gemm_phase(LAS unsigned char* lds, const Gemm g, const Sched& S, const Epi& E) {
;     ...
;             PG8_LDB(B0, 0, 0); PG8_SCHED; PG8_LDA(At, 0, 0); PG8_STAGE(PG8_SA(1, 1), a1 + hstepA, voffA);
;             PG8_WAIT_L(8); PG8_BAR; PG8_WAIT_L(0); PG8_MMA(0, 0, At, B0); PG8_BAR; PG8_SCHED;
;             PG8_LDB(B1, 0, 1); PG8_STAGE(PG8_SB(0, 0), b2, voffB);
;             PG8_BAR; PG8_WAIT_L(0); PG8_MMA(0, 1, At, B1); PG8_BAR;
;             PG8_LDA(At, 0, 1); PG8_STAGE(PG8_SA(0, 0), a2, voffA);
;             PG8_BAR; PG8_WAIT_L(0); PG8_MMA(1, 0, At, B0); PG8_BAR; PG8_SCHED;
;             PG8_STAGE(PG8_SB(0, 1), b2 + hstepB, voffB);
;             PG8_WAIT_V(6); PG8_BAR; PG8_MMA(1, 1, At, B1); PG8_BAR;
;             PG8_LDB(B0, 1, 0); PG8_SCHED; PG8_LDA(At, 1, 0); PG8_STAGE(PG8_SA(0, 1), a2 + hstepA, voffA);
;             PG8_WAIT_L(8); PG8_BAR; PG8_WAIT_L(0); PG8_MMA(0, 0, At, B0); PG8_BAR; PG8_SCHED;
;             PG8_LDB(B1, 1, 1); PG8_STAGE(PG8_SB(1, 0), b3, voffB);
;             PG8_BAR; PG8_WAIT_L(0); PG8_MMA(0, 1, At, B1); PG8_BAR;
;             PG8_LDA(At, 1, 1); PG8_STAGE(PG8_SA(1, 0), a3, voffA);
;             PG8_BAR; PG8_WAIT_L(0); PG8_MMA(1, 0, At, B0); PG8_BAR; PG8_SCHED;
;             PG8_STAGE(PG8_SB(1, 1), b3 + hstepB, voffB);
;             PG8_WAIT_V(6); PG8_BAR; PG8_MMA(1, 1, At, B1); PG8_BAR;
	v_mfma_f32_16x16x32_bf16 v[64:67], v[132:135], v[148:151], 0
	v_mfma_f32_16x16x32_bf16 v[60:63], v[140:143], v[148:151], 0
	v_mfma_f32_16x16x32_bf16 v[52:55], v[132:135], v[156:159], 0
	v_mfma_f32_16x16x32_bf16 v[44:47], v[140:143], v[156:159], 0
	v_mfma_f32_16x16x32_bf16 v[36:39], v[132:135], v[164:167], 0
	v_mfma_f32_16x16x32_bf16 v[28:31], v[140:143], v[164:167], 0
	v_mfma_f32_16x16x32_bf16 v[20:23], v[132:135], v[172:175], 0
	v_mfma_f32_16x16x32_bf16 v[12:15], v[140:143], v[172:175], 0
	v_mfma_f32_16x16x32_bf16 v[64:67], v[136:139], v[152:155], v[64:67]
	v_mfma_f32_16x16x32_bf16 v[60:63], v[144:147], v[152:155], v[60:63]
	v_mfma_f32_16x16x32_bf16 v[52:55], v[136:139], v[160:163], v[52:55]
	v_mfma_f32_16x16x32_bf16 v[44:47], v[144:147], v[160:163], v[44:47]
	v_mfma_f32_16x16x32_bf16 v[36:39], v[136:139], v[168:171], v[36:39]
	v_mfma_f32_16x16x32_bf16 v[28:31], v[144:147], v[168:171], v[28:31]
	v_mfma_f32_16x16x32_bf16 v[20:23], v[136:139], v[176:179], v[20:23]
	v_mfma_f32_16x16x32_bf16 v[12:15], v[144:147], v[176:179], v[12:15]
	v_mfma_f32_16x16x32_bf16 v[56:59], v[180:183], v[148:151], 0
	v_mfma_f32_16x16x32_bf16 v[48:51], v[188:191], v[148:151], 0
	v_mfma_f32_16x16x32_bf16 v[40:43], v[180:183], v[156:159], 0
	v_mfma_f32_16x16x32_bf16 v[32:35], v[188:191], v[156:159], 0
	v_mfma_f32_16x16x32_bf16 v[24:27], v[180:183], v[164:167], 0
	v_mfma_f32_16x16x32_bf16 v[16:19], v[188:191], v[164:167], 0
	v_mfma_f32_16x16x32_bf16 v[8:11], v[180:183], v[172:175], 0
	v_mfma_f32_16x16x32_bf16 v[4:7], v[188:191], v[172:175], 0
	v_mfma_f32_16x16x32_bf16 v[56:59], v[184:187], v[152:155], v[56:59]
	v_mfma_f32_16x16x32_bf16 v[48:51], v[202:205], v[152:155], v[48:51]
	v_mfma_f32_16x16x32_bf16 v[40:43], v[184:187], v[160:163], v[40:43]
	v_mfma_f32_16x16x32_bf16 v[32:35], v[202:205], v[160:163], v[32:35]
	v_mfma_f32_16x16x32_bf16 v[24:27], v[184:187], v[168:171], v[24:27]
	v_mfma_f32_16x16x32_bf16 v[16:19], v[202:205], v[168:171], v[16:19]
	v_mfma_f32_16x16x32_bf16 v[8:11], v[184:187], v[176:179], v[8:11]
	v_mfma_f32_16x16x32_bf16 v[4:7], v[202:205], v[176:179], v[4:7]
	s_barrier
	s_add_i32 s52, 0, 0x18000
	v_add_u32_e32 v144, s52, v1
	ds_read_b128 v[132:135], v144
	ds_read_b128 v[136:139], v144 offset:1024
	ds_read_b128 v[140:143], v144 offset:2048
	ds_read_b128 v[144:147], v144 offset:3072
	s_add_u32 s24, s24, 0x80000
	s_addc_u32 s25, s25, 0
	ds_read_b128 v[148:151], v224 offset:32768
	ds_read_b128 v[152:155], v224 offset:33792
	ds_read_b128 v[156:159], v224 offset:34816
	ds_read_b128 v[160:163], v224 offset:35840
	ds_read_b128 v[164:167], v224 offset:36864
	ds_read_b128 v[168:171], v224 offset:37888
	ds_read_b128 v[172:175], v224 offset:38912
	ds_read_b128 v[176:179], v224 offset:39936
	s_mov_b32 m0, s36
	s_nop 0
	global_load_lds_dwordx4 v196, s[24:25]
	s_mov_b32 m0, s37
	s_nop 0
	global_load_lds_dwordx4 v194, s[24:25]
	s_add_i32 s24, 0, 0x1c000
	v_add_u32_e32 v202, s24, v1
	ds_read_b128 v[180:183], v202
	ds_read_b128 v[184:187], v202 offset:1024
	ds_read_b128 v[188:191], v202 offset:2048
	ds_read_b128 v[202:205], v202 offset:3072
	s_waitcnt lgkmcnt(0)
	s_barrier
	v_mfma_f32_16x16x32_bf16 v[128:131], v[132:135], v[148:151], v[128:131]
	v_mfma_f32_16x16x32_bf16 v[124:127], v[140:143], v[148:151], v[124:127]
	v_mfma_f32_16x16x32_bf16 v[112:115], v[132:135], v[156:159], v[112:115]
	v_mfma_f32_16x16x32_bf16 v[108:111], v[140:143], v[156:159], v[108:111]
	v_mfma_f32_16x16x32_bf16 v[100:103], v[132:135], v[164:167], v[100:103]
	v_mfma_f32_16x16x32_bf16 v[92:95], v[140:143], v[164:167], v[92:95]
	v_mfma_f32_16x16x32_bf16 v[84:87], v[132:135], v[172:175], v[84:87]
	v_mfma_f32_16x16x32_bf16 v[76:79], v[140:143], v[172:175], v[76:79]
	v_mfma_f32_16x16x32_bf16 v[128:131], v[136:139], v[152:155], v[128:131]
	v_mfma_f32_16x16x32_bf16 v[124:127], v[144:147], v[152:155], v[124:127]
	v_mfma_f32_16x16x32_bf16 v[112:115], v[136:139], v[160:163], v[112:115]
	v_mfma_f32_16x16x32_bf16 v[108:111], v[144:147], v[160:163], v[108:111]
	v_mfma_f32_16x16x32_bf16 v[100:103], v[136:139], v[168:171], v[100:103]
	v_mfma_f32_16x16x32_bf16 v[92:95], v[144:147], v[168:171], v[92:95]
	v_mfma_f32_16x16x32_bf16 v[84:87], v[136:139], v[176:179], v[84:87]
	v_mfma_f32_16x16x32_bf16 v[76:79], v[144:147], v[176:179], v[76:79]
	v_mfma_f32_16x16x32_bf16 v[120:123], v[180:183], v[148:151], v[120:123]
	v_mfma_f32_16x16x32_bf16 v[116:119], v[188:191], v[148:151], v[116:119]
	v_mfma_f32_16x16x32_bf16 v[104:107], v[180:183], v[156:159], v[104:107]
	v_mfma_f32_16x16x32_bf16 v[96:99], v[188:191], v[156:159], v[96:99]
	v_mfma_f32_16x16x32_bf16 v[88:91], v[180:183], v[164:167], v[88:91]
	v_mfma_f32_16x16x32_bf16 v[80:83], v[188:191], v[164:167], v[80:83]
	v_mfma_f32_16x16x32_bf16 v[72:75], v[180:183], v[172:175], v[72:75]
	v_mfma_f32_16x16x32_bf16 v[68:71], v[188:191], v[172:175], v[68:71]
	v_mfma_f32_16x16x32_bf16 v[120:123], v[184:187], v[152:155], v[120:123]
	v_mfma_f32_16x16x32_bf16 v[116:119], v[202:205], v[152:155], v[116:119]
	v_mfma_f32_16x16x32_bf16 v[104:107], v[184:187], v[160:163], v[104:107]
	v_mfma_f32_16x16x32_bf16 v[96:99], v[202:205], v[160:163], v[96:99]
	v_mfma_f32_16x16x32_bf16 v[88:91], v[184:187], v[168:171], v[88:91]
	v_mfma_f32_16x16x32_bf16 v[80:83], v[202:205], v[168:171], v[80:83]
	v_mfma_f32_16x16x32_bf16 v[72:75], v[184:187], v[176:179], v[72:75]
	v_mfma_f32_16x16x32_bf16 v[68:71], v[202:205], v[176:179], v[68:71]
	s_barrier
; #define PG8_STAGE(bufoff, gbase, voff) do { _Pragma("unroll") for (int _i = 0; _i < 2; ++_i) \
;         __builtin_amdgcn_global_load_lds((const unsigned*)((const char*)(gbase) + (voff)[_i]), (LAS unsigned*)(lds + (bufoff) + ldsw + _i * 8192), 16, 0, 0); } while (0)
; #define PG8_LDA(dst, b, h) do { _Pragma("unroll") for (int m = 0; m < 4; ++m) _Pragma("unroll") for (int k = 0; k < 2; ++k) dst[m][k] = *(const LAS bf16x8*)(lds + PG8_SA(b, h) + aoff + m * 2048 + k * 1024); } while (0)
; #define PG8_LDB(dst, b, h) do { _Pragma("unroll") for (int n = 0; n < 2; ++n) _Pragma("unroll") for (int k = 0; k < 2; ++k) dst[n][k] = *(const LAS bf16x8*)(lds + PG8_SB(b, h) + boff + n * 2048 + k * 1024); } while (0)
; #define PG8_MMA(ai, bj, At, Bt) do { __builtin_amdgcn_s_setprio(1); _Pragma("unroll") for (int m = 0; m < 4; ++m) _Pragma("unroll") for (int n = 0; n < 2; ++n) _Pragma("unroll") for (int k = 0; k < 2; ++k) \
;         acc[ai][bj][m][n] = __builtin_amdgcn_mfma_f32_16x16x32_bf16(Bt[n][k], At[m][k], acc[ai][bj][m][n], 0, 0, 0); __builtin_amdgcn_s_setprio(0); } while (0)
; #define PG8_WAIT_V(n) asm volatile("s_waitcnt vmcnt(" #n ")" ::: "memory")
; #define PG8_WAIT_L(n) asm volatile("s_waitcnt lgkmcnt(" #n ")" ::: "memory")
; #define PG8_BAR __builtin_amdgcn_s_barrier()
; #define PG8_SCHED __builtin_amdgcn_sched_barrier(0)
; template <class Epi, class Sched>
; __device__ __forceinline__ void gemm_phase(LAS unsigned char* lds, const Gemm g, const Sched& S, const Epi& E) {
;     ...
;             PG8_LDB(B0, 0, 0); PG8_SCHED; PG8_LDA(At, 0, 0); PG8_STAGE(PG8_SA(1, 1), a1 + hstepA, voffA);
;             PG8_WAIT_L(8); PG8_BAR; PG8_WAIT_L(0); PG8_MMA(0, 0, At, B0); PG8_BAR; PG8_SCHED;
;     ...
;             PG8_LDB(B0, 1, 0); PG8_SCHED; PG8_LDA(At, 1, 0); PG8_STAGE(PG8_SA(0, 1), a2 + hstepA, voffA);
;             PG8_WAIT_L(8); PG8_BAR; PG8_WAIT_L(0); PG8_MMA(0, 0, At, B0); PG8_BAR; PG8_SCHED;
;             PG8_LDB(B1, 1, 1); PG8_STAGE(PG8_SB(1, 0), b3, voffB);
;             PG8_BAR; PG8_WAIT_L(0); PG8_MMA(0, 1, At, B1); PG8_BAR;
;             PG8_LDA(At, 1, 1); PG8_STAGE(PG8_SA(1, 0), a3, voffA);
;             PG8_BAR; PG8_WAIT_L(0); PG8_MMA(1, 0, At, B0); PG8_BAR; PG8_SCHED;
;             PG8_STAGE(PG8_SB(1, 1), b3 + hstepB, voffB);
;             PG8_WAIT_V(6); PG8_BAR; PG8_MMA(1, 1, At, B1); PG8_BAR;
	ds_read_b128 v[148:151], v224 offset:49152
	ds_read_b128 v[152:155], v224 offset:50176
	ds_read_b128 v[156:159], v224 offset:51200
	ds_read_b128 v[160:163], v224 offset:52224
	ds_read_b128 v[164:167], v224 offset:53248
	ds_read_b128 v[168:171], v224 offset:54272
	ds_read_b128 v[172:175], v224 offset:55296
	ds_read_b128 v[176:179], v224 offset:56320
	s_add_i32 s25, s52, s30
	v_lshl_add_u64 v[206:207], v[206:207], 0, s[8:9]
	s_mov_b32 m0, s25
	s_nop 0
	global_load_lds_dwordx4 v[206:207], off
	v_lshl_add_u64 v[206:207], v[208:209], 0, s[8:9]
	s_add_i32 m0, s25, 0x2000
	s_nop 0
	global_load_lds_dwordx4 v[206:207], off
	s_mov_b32 m0, s42
	v_lshl_add_u64 v[206:207], v[210:211], 0, s[8:9]
	global_load_lds_dwordx4 v[206:207], off
	v_lshl_add_u64 v[206:207], v[212:213], 0, s[8:9]
	s_mov_b32 m0, s43
	s_nop 0
	global_load_lds_dwordx4 v[206:207], off
	s_add_u32 s20, s20, 0x80080
	s_addc_u32 s21, s21, 0
	s_add_i32 s24, s24, s30
	s_mov_b32 m0, s24
	s_nop 0
	global_load_lds_dwordx4 v2, s[20:21]
	s_add_i32 m0, s24, 0x2000
	s_nop 0
	global_load_lds_dwordx4 v192, s[20:21]
	s_add_i32 s51, s51, 2
	s_add_u32 s6, s6, 0x100
	s_addc_u32 s7, s7, 0
	s_add_u32 s49, s49, 0x100
	s_addc_u32 s50, s50, 0
	s_cmp_gt_u32 s51, 29
	s_waitcnt lgkmcnt(0)
	s_waitcnt vmcnt(6)
	s_barrier
	v_mfma_f32_16x16x32_bf16 v[64:67], v[132:135], v[148:151], v[64:67]
	v_mfma_f32_16x16x32_bf16 v[60:63], v[140:143], v[148:151], v[60:63]
	v_mfma_f32_16x16x32_bf16 v[52:55], v[132:135], v[156:159], v[52:55]
	v_mfma_f32_16x16x32_bf16 v[44:47], v[140:143], v[156:159], v[44:47]
	v_mfma_f32_16x16x32_bf16 v[36:39], v[132:135], v[164:167], v[36:39]
	v_mfma_f32_16x16x32_bf16 v[28:31], v[140:143], v[164:167], v[28:31]
	v_mfma_f32_16x16x32_bf16 v[20:23], v[132:135], v[172:175], v[20:23]
	v_mfma_f32_16x16x32_bf16 v[12:15], v[140:143], v[172:175], v[12:15]
	v_mfma_f32_16x16x32_bf16 v[64:67], v[136:139], v[152:155], v[64:67]
	v_mfma_f32_16x16x32_bf16 v[60:63], v[144:147], v[152:155], v[60:63]
	v_mfma_f32_16x16x32_bf16 v[52:55], v[136:139], v[160:163], v[52:55]
	v_mfma_f32_16x16x32_bf16 v[44:47], v[144:147], v[160:163], v[44:47]
	v_mfma_f32_16x16x32_bf16 v[36:39], v[136:139], v[168:171], v[36:39]
	v_mfma_f32_16x16x32_bf16 v[28:31], v[144:147], v[168:171], v[28:31]
	v_mfma_f32_16x16x32_bf16 v[20:23], v[136:139], v[176:179], v[20:23]
	v_mfma_f32_16x16x32_bf16 v[12:15], v[144:147], v[176:179], v[12:15]
	v_mfma_f32_16x16x32_bf16 v[56:59], v[180:183], v[148:151], v[56:59]
	v_mfma_f32_16x16x32_bf16 v[48:51], v[188:191], v[148:151], v[48:51]
	v_mfma_f32_16x16x32_bf16 v[40:43], v[180:183], v[156:159], v[40:43]
	v_mfma_f32_16x16x32_bf16 v[32:35], v[188:191], v[156:159], v[32:35]
	v_mfma_f32_16x16x32_bf16 v[24:27], v[180:183], v[164:167], v[24:27]
	v_mfma_f32_16x16x32_bf16 v[16:19], v[188:191], v[164:167], v[16:19]
	v_mfma_f32_16x16x32_bf16 v[8:11], v[180:183], v[172:175], v[8:11]
	v_mfma_f32_16x16x32_bf16 v[4:7], v[188:191], v[172:175], v[4:7]
	v_mfma_f32_16x16x32_bf16 v[56:59], v[184:187], v[152:155], v[56:59]
	v_mfma_f32_16x16x32_bf16 v[48:51], v[202:205], v[152:155], v[48:51]
	v_mfma_f32_16x16x32_bf16 v[40:43], v[184:187], v[160:163], v[40:43]
	v_mfma_f32_16x16x32_bf16 v[32:35], v[202:205], v[160:163], v[32:35]
	v_mfma_f32_16x16x32_bf16 v[24:27], v[184:187], v[168:171], v[24:27]
	v_mfma_f32_16x16x32_bf16 v[16:19], v[202:205], v[168:171], v[16:19]
	v_mfma_f32_16x16x32_bf16 v[8:11], v[184:187], v[176:179], v[8:11]
	v_mfma_f32_16x16x32_bf16 v[4:7], v[202:205], v[176:179], v[4:7]
	s_barrier
	s_setprio 0
.LBB0_1396:
	s_add_u32 s20, s6, 0xfff80080
	s_addc_u32 s21, s7, -1
	s_add_i32 s52, 0, 0x10000
	v_add_u32_e32 v144, s52, v1
	ds_read_b128 v[132:135], v144
	ds_read_b128 v[136:139], v144 offset:1024
	ds_read_b128 v[140:143], v144 offset:2048
	ds_read_b128 v[144:147], v144 offset:3072
	s_cmp_eq_u32 s51, 28
	s_cselect_b32 s25, s15, s21
	s_cselect_b32 s24, s47, s20
	s_cselect_b32 s21, s1, s50
	s_cselect_b32 s20, s48, s49
	ds_read_b128 v[148:151], v224
	ds_read_b128 v[152:155], v224 offset:1024
	ds_read_b128 v[156:159], v224 offset:2048
	ds_read_b128 v[160:163], v224 offset:3072
	ds_read_b128 v[164:167], v224 offset:4096
	ds_read_b128 v[168:171], v224 offset:5120
	ds_read_b128 v[172:175], v224 offset:6144
	ds_read_b128 v[176:179], v224 offset:7168
	s_add_i32 s54, 0, 0x14000
	v_add_u32_e32 v202, s54, v1
	ds_read_b128 v[180:183], v202
	ds_read_b128 v[184:187], v202 offset:1024
	ds_read_b128 v[188:191], v202 offset:2048
	ds_read_b128 v[202:205], v202 offset:3072
	s_add_i32 m0, s31, 0xc000
	s_nop 0
	global_load_lds_dwordx4 v198, s[6:7]
	s_add_i32 m0, s31, 0xe000
	s_nop 0
	global_load_lds_dwordx4 v200, s[6:7]
	s_waitcnt lgkmcnt(0)
	s_barrier
; #define PG8_STAGE(bufoff, gbase, voff) do { _Pragma("unroll") for (int _i = 0; _i < 2; ++_i) \
;         __builtin_amdgcn_global_load_lds((const unsigned*)((const char*)(gbase) + (voff)[_i]), (LAS unsigned*)(lds + (bufoff) + ldsw + _i * 8192), 16, 0, 0); } while (0)
; #define PG8_LDA(dst, b, h) do { _Pragma("unroll") for (int m = 0; m < 4; ++m) _Pragma("unroll") for (int k = 0; k < 2; ++k) dst[m][k] = *(const LAS bf16x8*)(lds + PG8_SA(b, h) + aoff + m * 2048 + k * 1024); } while (0)
; #define PG8_LDB(dst, b, h) do { _Pragma("unroll") for (int n = 0; n < 2; ++n) _Pragma("unroll") for (int k = 0; k < 2; ++k) dst[n][k] = *(const LAS bf16x8*)(lds + PG8_SB(b, h) + boff + n * 2048 + k * 1024); } while (0)
; #define PG8_MMA(ai, bj, At, Bt) do { __builtin_amdgcn_s_setprio(1); _Pragma("unroll") for (int m = 0; m < 4; ++m) _Pragma("unroll") for (int n = 0; n < 2; ++n) _Pragma("unroll") for (int k = 0; k < 2; ++k) \
;         acc[ai][bj][m][n] = __builtin_amdgcn_mfma_f32_16x16x32_bf16(Bt[n][k], At[m][k], acc[ai][bj][m][n], 0, 0, 0); __builtin_amdgcn_s_setprio(0); } while (0)
; #define PG8_WAIT_V(n) asm volatile("s_waitcnt vmcnt(" #n ")" ::: "memory")
; #define PG8_WAIT_L(n) asm volatile("s_waitcnt lgkmcnt(" #n ")" ::: "memory")
; #define PG8_BAR __builtin_amdgcn_s_barrier()
; #define PG8_SCHED __builtin_amdgcn_sched_barrier(0)
; template <class Epi, class Sched>
; __device__ __forceinline__ void gemm_phase(LAS unsigned char* lds, const Gemm g, const Sched& S, const Epi& E) {
;     ...
;             PG8_WAIT_L(8); PG8_BAR; PG8_WAIT_L(0); PG8_MMA(0, 0, At, B0); PG8_BAR; PG8_SCHED;
;             PG8_LDB(B1, 0, 1); PG8_STAGE(PG8_SB(0, 0), b2, voffB);
;             PG8_BAR; PG8_WAIT_L(0); PG8_MMA(0, 1, At, B1); PG8_BAR;
;             PG8_LDA(At, 0, 1); PG8_STAGE(PG8_SA(0, 0), a2, voffA);
;             PG8_BAR; PG8_WAIT_L(0); PG8_MMA(1, 0, At, B0); PG8_BAR; PG8_SCHED;
;             PG8_STAGE(PG8_SB(0, 1), b2 + hstepB, voffB);
;             PG8_WAIT_V(6); PG8_BAR; PG8_MMA(1, 1, At, B1); PG8_BAR;
;             PG8_LDB(B0, 1, 0); PG8_SCHED; PG8_LDA(At, 1, 0); PG8_STAGE(PG8_SA(0, 1), a2 + hstepA, voffA);
;             PG8_WAIT_L(8); PG8_BAR; PG8_WAIT_L(0); PG8_MMA(0, 0, At, B0); PG8_BAR; PG8_SCHED;
	v_mfma_f32_16x16x32_bf16 v[128:131], v[132:135], v[148:151], v[128:131]
	v_mfma_f32_16x16x32_bf16 v[124:127], v[140:143], v[148:151], v[124:127]
	v_mfma_f32_16x16x32_bf16 v[112:115], v[132:135], v[156:159], v[112:115]
	v_mfma_f32_16x16x32_bf16 v[108:111], v[140:143], v[156:159], v[108:111]
	v_mfma_f32_16x16x32_bf16 v[100:103], v[132:135], v[164:167], v[100:103]
	v_mfma_f32_16x16x32_bf16 v[92:95], v[140:143], v[164:167], v[92:95]
	v_mfma_f32_16x16x32_bf16 v[84:87], v[132:135], v[172:175], v[84:87]
	v_mfma_f32_16x16x32_bf16 v[76:79], v[140:143], v[172:175], v[76:79]
	v_mfma_f32_16x16x32_bf16 v[128:131], v[136:139], v[152:155], v[128:131]
	v_mfma_f32_16x16x32_bf16 v[124:127], v[144:147], v[152:155], v[124:127]
	v_mfma_f32_16x16x32_bf16 v[112:115], v[136:139], v[160:163], v[112:115]
	v_mfma_f32_16x16x32_bf16 v[108:111], v[144:147], v[160:163], v[108:111]
	v_mfma_f32_16x16x32_bf16 v[100:103], v[136:139], v[168:171], v[100:103]
	v_mfma_f32_16x16x32_bf16 v[92:95], v[144:147], v[168:171], v[92:95]
	v_mfma_f32_16x16x32_bf16 v[84:87], v[136:139], v[176:179], v[84:87]
	v_mfma_f32_16x16x32_bf16 v[76:79], v[144:147], v[176:179], v[76:79]
	v_mfma_f32_16x16x32_bf16 v[120:123], v[180:183], v[148:151], v[120:123]
	v_mfma_f32_16x16x32_bf16 v[116:119], v[188:191], v[148:151], v[116:119]
	v_mfma_f32_16x16x32_bf16 v[104:107], v[180:183], v[156:159], v[104:107]
	v_mfma_f32_16x16x32_bf16 v[96:99], v[188:191], v[156:159], v[96:99]
	v_mfma_f32_16x16x32_bf16 v[88:91], v[180:183], v[164:167], v[88:91]
	v_mfma_f32_16x16x32_bf16 v[80:83], v[188:191], v[164:167], v[80:83]
	v_mfma_f32_16x16x32_bf16 v[72:75], v[180:183], v[172:175], v[72:75]
	v_mfma_f32_16x16x32_bf16 v[68:71], v[188:191], v[172:175], v[68:71]
	v_mfma_f32_16x16x32_bf16 v[120:123], v[184:187], v[152:155], v[120:123]
	v_mfma_f32_16x16x32_bf16 v[116:119], v[202:205], v[152:155], v[116:119]
	v_mfma_f32_16x16x32_bf16 v[104:107], v[184:187], v[160:163], v[104:107]
	v_mfma_f32_16x16x32_bf16 v[96:99], v[202:205], v[160:163], v[96:99]
	v_mfma_f32_16x16x32_bf16 v[88:91], v[184:187], v[168:171], v[88:91]
	v_mfma_f32_16x16x32_bf16 v[80:83], v[202:205], v[168:171], v[80:83]
	v_mfma_f32_16x16x32_bf16 v[72:75], v[184:187], v[176:179], v[72:75]
	v_mfma_f32_16x16x32_bf16 v[68:71], v[202:205], v[176:179], v[68:71]
	s_barrier
	ds_read_b128 v[148:151], v224 offset:16384
	ds_read_b128 v[152:155], v224 offset:17408
	ds_read_b128 v[156:159], v224 offset:18432
	ds_read_b128 v[160:163], v224 offset:19456
	ds_read_b128 v[164:167], v224 offset:20480
	ds_read_b128 v[168:171], v224 offset:21504
	ds_read_b128 v[172:175], v224 offset:22528
	ds_read_b128 v[176:179], v224 offset:23552
	s_add_i32 s52, s52, s30
	v_lshl_add_u64 v[206:207], s[20:21], 0, v[2:3]
	s_mov_b32 m0, s52
	s_nop 0
	global_load_lds_dwordx4 v[206:207], off
	v_lshl_add_u64 v[208:209], s[20:21], 0, v[192:193]
	s_add_i32 m0, s52, 0x2000
	s_nop 0
	global_load_lds_dwordx4 v[208:209], off
	s_mov_b32 m0, s31
	v_lshl_add_u64 v[210:211], s[24:25], 0, v[196:197]
	global_load_lds_dwordx4 v[210:211], off
	v_lshl_add_u64 v[212:213], s[24:25], 0, v[194:195]
	s_mov_b32 m0, s35
	s_nop 0
	global_load_lds_dwordx4 v[212:213], off
	s_add_u32 s52, s20, 0x80000
	s_addc_u32 s53, s21, 0
	s_add_i32 s54, s54, s30
	s_mov_b32 m0, s54
	s_nop 0
	global_load_lds_dwordx4 v2, s[52:53]
	s_add_i32 m0, s54, 0x2000
	s_nop 0
	global_load_lds_dwordx4 v192, s[52:53]
	s_waitcnt lgkmcnt(0)
	s_waitcnt vmcnt(6)
	s_barrier
	v_mfma_f32_16x16x32_bf16 v[64:67], v[132:135], v[148:151], v[64:67]
	v_mfma_f32_16x16x32_bf16 v[60:63], v[140:143], v[148:151], v[60:63]
	v_mfma_f32_16x16x32_bf16 v[52:55], v[132:135], v[156:159], v[52:55]
	v_mfma_f32_16x16x32_bf16 v[44:47], v[140:143], v[156:159], v[44:47]
	v_mfma_f32_16x16x32_bf16 v[36:39], v[132:135], v[164:167], v[36:39]
	v_mfma_f32_16x16x32_bf16 v[28:31], v[140:143], v[164:167], v[28:31]
	v_mfma_f32_16x16x32_bf16 v[20:23], v[132:135], v[172:175], v[20:23]
	v_mfma_f32_16x16x32_bf16 v[12:15], v[140:143], v[172:175], v[12:15]
	v_mfma_f32_16x16x32_bf16 v[64:67], v[136:139], v[152:155], v[64:67]
	v_mfma_f32_16x16x32_bf16 v[60:63], v[144:147], v[152:155], v[60:63]
	v_mfma_f32_16x16x32_bf16 v[52:55], v[136:139], v[160:163], v[52:55]
	v_mfma_f32_16x16x32_bf16 v[44:47], v[144:147], v[160:163], v[44:47]
	v_mfma_f32_16x16x32_bf16 v[36:39], v[136:139], v[168:171], v[36:39]
	v_mfma_f32_16x16x32_bf16 v[28:31], v[144:147], v[168:171], v[28:31]
	v_mfma_f32_16x16x32_bf16 v[20:23], v[136:139], v[176:179], v[20:23]
	v_mfma_f32_16x16x32_bf16 v[12:15], v[144:147], v[176:179], v[12:15]
	v_mfma_f32_16x16x32_bf16 v[56:59], v[180:183], v[148:151], v[56:59]
	v_mfma_f32_16x16x32_bf16 v[48:51], v[188:191], v[148:151], v[48:51]
	v_mfma_f32_16x16x32_bf16 v[40:43], v[180:183], v[156:159], v[40:43]
	v_mfma_f32_16x16x32_bf16 v[32:35], v[188:191], v[156:159], v[32:35]
	v_mfma_f32_16x16x32_bf16 v[24:27], v[180:183], v[164:167], v[24:27]
	v_mfma_f32_16x16x32_bf16 v[16:19], v[188:191], v[164:167], v[16:19]
	v_mfma_f32_16x16x32_bf16 v[8:11], v[180:183], v[172:175], v[8:11]
	v_mfma_f32_16x16x32_bf16 v[4:7], v[188:191], v[172:175], v[4:7]
	v_mfma_f32_16x16x32_bf16 v[56:59], v[184:187], v[152:155], v[56:59]
	v_mfma_f32_16x16x32_bf16 v[48:51], v[202:205], v[152:155], v[48:51]
	v_mfma_f32_16x16x32_bf16 v[40:43], v[184:187], v[160:163], v[40:43]
	v_mfma_f32_16x16x32_bf16 v[32:35], v[202:205], v[160:163], v[32:35]
	v_mfma_f32_16x16x32_bf16 v[24:27], v[184:187], v[168:171], v[24:27]
	v_mfma_f32_16x16x32_bf16 v[16:19], v[202:205], v[168:171], v[16:19]
	v_mfma_f32_16x16x32_bf16 v[8:11], v[184:187], v[176:179], v[8:11]
	v_mfma_f32_16x16x32_bf16 v[4:7], v[202:205], v[176:179], v[4:7]
	s_barrier
; #define PG8_STAGE(bufoff, gbase, voff) do { _Pragma("unroll") for (int _i = 0; _i < 2; ++_i) \
;         __builtin_amdgcn_global_load_lds((const unsigned*)((const char*)(gbase) + (voff)[_i]), (LAS unsigned*)(lds + (bufoff) + ldsw + _i * 8192), 16, 0, 0); } while (0)
; #define PG8_LDA(dst, b, h) do { _Pragma("unroll") for (int m = 0; m < 4; ++m) _Pragma("unroll") for (int k = 0; k < 2; ++k) dst[m][k] = *(const LAS bf16x8*)(lds + PG8_SA(b, h) + aoff + m * 2048 + k * 1024); } while (0)
; #define PG8_LDB(dst, b, h) do { _Pragma("unroll") for (int n = 0; n < 2; ++n) _Pragma("unroll") for (int k = 0; k < 2; ++k) dst[n][k] = *(const LAS bf16x8*)(lds + PG8_SB(b, h) + boff + n * 2048 + k * 1024); } while (0)
; #define PG8_MMA(ai, bj, At, Bt) do { __builtin_amdgcn_s_setprio(1); _Pragma("unroll") for (int m = 0; m < 4; ++m) _Pragma("unroll") for (int n = 0; n < 2; ++n) _Pragma("unroll") for (int k = 0; k < 2; ++k) \
;         acc[ai][bj][m][n] = __builtin_amdgcn_mfma_f32_16x16x32_bf16(Bt[n][k], At[m][k], acc[ai][bj][m][n], 0, 0, 0); __builtin_amdgcn_s_setprio(0); } while (0)
; #define PG8_WAIT_V(n) asm volatile("s_waitcnt vmcnt(" #n ")" ::: "memory")
; #define PG8_WAIT_L(n) asm volatile("s_waitcnt lgkmcnt(" #n ")" ::: "memory")
; #define PG8_BAR __builtin_amdgcn_s_barrier()
; #define PG8_SCHED __builtin_amdgcn_sched_barrier(0)
; template <class Epi, class Sched>
; __device__ __forceinline__ void gemm_phase(LAS unsigned char* lds, const Gemm g, const Sched& S, const Epi& E) {
;     ...
;             PG8_LDB(B1, 1, 1); PG8_STAGE(PG8_SB(1, 0), b3, voffB);
;             PG8_BAR; PG8_WAIT_L(0); PG8_MMA(0, 1, At, B1); PG8_BAR;
;             PG8_LDA(At, 1, 1); PG8_STAGE(PG8_SA(1, 0), a3, voffA);
;             PG8_BAR; PG8_WAIT_L(0); PG8_MMA(1, 0, At, B0); PG8_BAR; PG8_SCHED;
;             PG8_STAGE(PG8_SB(1, 1), b3 + hstepB, voffB);
;             PG8_WAIT_V(6); PG8_BAR; PG8_MMA(1, 1, At, B1); PG8_BAR;
;         }
;         E(acc, cur, wr, wc, ui, fq);
	s_add_i32 s52, 0, 0x18000
	v_add_u32_e32 v144, s52, v1
	ds_read_b128 v[132:135], v144
	ds_read_b128 v[136:139], v144 offset:1024
	ds_read_b128 v[140:143], v144 offset:2048
	ds_read_b128 v[144:147], v144 offset:3072
	s_add_u32 s24, s24, 0x80000
	s_addc_u32 s25, s25, 0
	ds_read_b128 v[148:151], v224 offset:32768
	ds_read_b128 v[152:155], v224 offset:33792
	ds_read_b128 v[156:159], v224 offset:34816
	ds_read_b128 v[160:163], v224 offset:35840
	ds_read_b128 v[164:167], v224 offset:36864
	ds_read_b128 v[168:171], v224 offset:37888
	ds_read_b128 v[172:175], v224 offset:38912
	ds_read_b128 v[176:179], v224 offset:39936
	s_mov_b32 m0, s36
	s_nop 0
	global_load_lds_dwordx4 v196, s[24:25]
	s_mov_b32 m0, s37
	s_nop 0
	global_load_lds_dwordx4 v194, s[24:25]
	s_add_i32 s24, 0, 0x1c000
	v_add_u32_e32 v202, s24, v1
	ds_read_b128 v[180:183], v202
	ds_read_b128 v[184:187], v202 offset:1024
	ds_read_b128 v[188:191], v202 offset:2048
	ds_read_b128 v[202:205], v202 offset:3072
	s_waitcnt lgkmcnt(0)
	s_barrier
	v_mfma_f32_16x16x32_bf16 v[128:131], v[132:135], v[148:151], v[128:131]
	v_mfma_f32_16x16x32_bf16 v[124:127], v[140:143], v[148:151], v[124:127]
	v_mfma_f32_16x16x32_bf16 v[112:115], v[132:135], v[156:159], v[112:115]
	v_mfma_f32_16x16x32_bf16 v[108:111], v[140:143], v[156:159], v[108:111]
	v_mfma_f32_16x16x32_bf16 v[100:103], v[132:135], v[164:167], v[100:103]
	v_mfma_f32_16x16x32_bf16 v[92:95], v[140:143], v[164:167], v[92:95]
	v_mfma_f32_16x16x32_bf16 v[84:87], v[132:135], v[172:175], v[84:87]
	v_mfma_f32_16x16x32_bf16 v[76:79], v[140:143], v[172:175], v[76:79]
	v_mfma_f32_16x16x32_bf16 v[128:131], v[136:139], v[152:155], v[128:131]
	v_mfma_f32_16x16x32_bf16 v[124:127], v[144:147], v[152:155], v[124:127]
	v_mfma_f32_16x16x32_bf16 v[112:115], v[136:139], v[160:163], v[112:115]
	v_mfma_f32_16x16x32_bf16 v[108:111], v[144:147], v[160:163], v[108:111]
	v_mfma_f32_16x16x32_bf16 v[100:103], v[136:139], v[168:171], v[100:103]
	v_mfma_f32_16x16x32_bf16 v[92:95], v[144:147], v[168:171], v[92:95]
	v_mfma_f32_16x16x32_bf16 v[84:87], v[136:139], v[176:179], v[84:87]
	v_mfma_f32_16x16x32_bf16 v[76:79], v[144:147], v[176:179], v[76:79]
	v_mfma_f32_16x16x32_bf16 v[120:123], v[180:183], v[148:151], v[120:123]
	v_mfma_f32_16x16x32_bf16 v[116:119], v[188:191], v[148:151], v[116:119]
	v_mfma_f32_16x16x32_bf16 v[104:107], v[180:183], v[156:159], v[104:107]
	v_mfma_f32_16x16x32_bf16 v[96:99], v[188:191], v[156:159], v[96:99]
	v_mfma_f32_16x16x32_bf16 v[88:91], v[180:183], v[164:167], v[88:91]
	v_mfma_f32_16x16x32_bf16 v[80:83], v[188:191], v[164:167], v[80:83]
	v_mfma_f32_16x16x32_bf16 v[72:75], v[180:183], v[172:175], v[72:75]
	v_mfma_f32_16x16x32_bf16 v[68:71], v[188:191], v[172:175], v[68:71]
	v_mfma_f32_16x16x32_bf16 v[120:123], v[184:187], v[152:155], v[120:123]
	v_mfma_f32_16x16x32_bf16 v[116:119], v[202:205], v[152:155], v[116:119]
	v_mfma_f32_16x16x32_bf16 v[104:107], v[184:187], v[160:163], v[104:107]
	v_mfma_f32_16x16x32_bf16 v[96:99], v[202:205], v[160:163], v[96:99]
	v_mfma_f32_16x16x32_bf16 v[88:91], v[184:187], v[168:171], v[88:91]
	v_mfma_f32_16x16x32_bf16 v[80:83], v[202:205], v[168:171], v[80:83]
	v_mfma_f32_16x16x32_bf16 v[72:75], v[184:187], v[176:179], v[72:75]
	v_mfma_f32_16x16x32_bf16 v[68:71], v[202:205], v[176:179], v[68:71]
	s_barrier
	ds_read_b128 v[148:151], v224 offset:49152
	ds_read_b128 v[152:155], v224 offset:50176
	ds_read_b128 v[156:159], v224 offset:51200
	ds_read_b128 v[160:163], v224 offset:52224
	ds_read_b128 v[164:167], v224 offset:53248
	ds_read_b128 v[168:171], v224 offset:54272
	ds_read_b128 v[172:175], v224 offset:55296
	ds_read_b128 v[176:179], v224 offset:56320
	s_add_i32 s25, s52, s30
	v_lshl_add_u64 v[206:207], v[206:207], 0, s[8:9]
	s_mov_b32 m0, s25
	s_nop 0
	global_load_lds_dwordx4 v[206:207], off
	v_lshl_add_u64 v[206:207], v[208:209], 0, s[8:9]
	s_add_i32 m0, s25, 0x2000
	s_nop 0
	global_load_lds_dwordx4 v[206:207], off
	s_mov_b32 m0, s42
	v_lshl_add_u64 v[206:207], v[210:211], 0, s[8:9]
	global_load_lds_dwordx4 v[206:207], off
	v_lshl_add_u64 v[206:207], v[212:213], 0, s[8:9]
	s_mov_b32 m0, s43
	s_nop 0
	global_load_lds_dwordx4 v[206:207], off
	s_add_u32 s20, s20, 0x80080
	s_addc_u32 s21, s21, 0
	s_add_i32 s24, s24, s30
	s_mov_b32 m0, s24
	s_nop 0
	global_load_lds_dwordx4 v2, s[20:21]
	s_add_i32 m0, s24, 0x2000
	s_nop 0
	global_load_lds_dwordx4 v192, s[20:21]
	s_add_i32 s51, s51, 2
	s_add_u32 s6, s6, 0x100
	s_addc_u32 s7, s7, 0
	s_add_u32 s49, s49, 0x100
	s_addc_u32 s50, s50, 0
	s_cmp_gt_u32 s51, 29
	s_waitcnt lgkmcnt(0)
	s_waitcnt vmcnt(6)
	s_barrier
	v_mfma_f32_16x16x32_bf16 v[64:67], v[132:135], v[148:151], v[64:67]
	v_mfma_f32_16x16x32_bf16 v[60:63], v[140:143], v[148:151], v[60:63]
	v_mfma_f32_16x16x32_bf16 v[52:55], v[132:135], v[156:159], v[52:55]
	v_mfma_f32_16x16x32_bf16 v[44:47], v[140:143], v[156:159], v[44:47]
	v_mfma_f32_16x16x32_bf16 v[36:39], v[132:135], v[164:167], v[36:39]
	v_mfma_f32_16x16x32_bf16 v[28:31], v[140:143], v[164:167], v[28:31]
	v_mfma_f32_16x16x32_bf16 v[20:23], v[132:135], v[172:175], v[20:23]
	v_mfma_f32_16x16x32_bf16 v[12:15], v[140:143], v[172:175], v[12:15]
	v_mfma_f32_16x16x32_bf16 v[64:67], v[136:139], v[152:155], v[64:67]
	v_mfma_f32_16x16x32_bf16 v[60:63], v[144:147], v[152:155], v[60:63]
	v_mfma_f32_16x16x32_bf16 v[52:55], v[136:139], v[160:163], v[52:55]
	v_mfma_f32_16x16x32_bf16 v[44:47], v[144:147], v[160:163], v[44:47]
	v_mfma_f32_16x16x32_bf16 v[36:39], v[136:139], v[168:171], v[36:39]
	v_mfma_f32_16x16x32_bf16 v[28:31], v[144:147], v[168:171], v[28:31]
	v_mfma_f32_16x16x32_bf16 v[20:23], v[136:139], v[176:179], v[20:23]
	v_mfma_f32_16x16x32_bf16 v[12:15], v[144:147], v[176:179], v[12:15]
	v_mfma_f32_16x16x32_bf16 v[56:59], v[180:183], v[148:151], v[56:59]
	v_mfma_f32_16x16x32_bf16 v[48:51], v[188:191], v[148:151], v[48:51]
	v_mfma_f32_16x16x32_bf16 v[40:43], v[180:183], v[156:159], v[40:43]
	v_mfma_f32_16x16x32_bf16 v[32:35], v[188:191], v[156:159], v[32:35]
	v_mfma_f32_16x16x32_bf16 v[24:27], v[180:183], v[164:167], v[24:27]
	v_mfma_f32_16x16x32_bf16 v[16:19], v[188:191], v[164:167], v[16:19]
	v_mfma_f32_16x16x32_bf16 v[8:11], v[180:183], v[172:175], v[8:11]
	v_mfma_f32_16x16x32_bf16 v[4:7], v[188:191], v[172:175], v[4:7]
	v_mfma_f32_16x16x32_bf16 v[56:59], v[184:187], v[152:155], v[56:59]
	v_mfma_f32_16x16x32_bf16 v[48:51], v[202:205], v[152:155], v[48:51]
	v_mfma_f32_16x16x32_bf16 v[40:43], v[184:187], v[160:163], v[40:43]
	v_mfma_f32_16x16x32_bf16 v[32:35], v[202:205], v[160:163], v[32:35]
	v_mfma_f32_16x16x32_bf16 v[24:27], v[184:187], v[168:171], v[24:27]
	v_mfma_f32_16x16x32_bf16 v[16:19], v[202:205], v[168:171], v[16:19]
	v_mfma_f32_16x16x32_bf16 v[8:11], v[184:187], v[176:179], v[8:11]
	v_mfma_f32_16x16x32_bf16 v[4:7], v[202:205], v[176:179], v[4:7]
	s_barrier
	s_cbranch_scc0 .LBB0_1396
	s_cmpk_gt_u32 s2, 0xff
	s_cbranch_scc1 .Lalign_a_1396
	s_barrier
; __device__ __forceinline__ unsigned cvt_pk_bf16(float lo, float hi) { const f32x2 v = {lo, hi}; const bf16v2_ r = __builtin_convertvector(v, bf16v2_); return __builtin_bit_cast(unsigned, r); }
; __device__ __forceinline__ float bflo(unsigned w) { return __uint_as_float(w << 16); }
; __device__ __forceinline__ float bfhi(unsigned w) { return __uint_as_float(w & 0xffff0000u); }
; __device__ __forceinline__ int opaque_tid() { int t = threadIdx.x; asm volatile("" : "+v"(t)); return t; }
;     __device__ __forceinline__ void operator()(const f32x4 (&acc)[2][2][4][2], const Unit& u, int wr, int wc, int, int) const {
;         const int ol_ = opaque_tid() & 63, fr = ol_ & 15, fq = ol_ >> 4;
;         const int row0 = u.pm * BM + wr * 64 + fr, col0 = u.pn * BM + wc * 32 + 8 * fq;
;         u32x4 cin[2][4][2];
; #pragma unroll
;         for (int ai = 0; ai < 2; ++ai)
; #pragma unroll
;             for (int m = 0; m < 4; ++m)
; #pragma unroll
;                 for (int bj = 0; bj < 2; ++bj) cin[ai][m][bj] = *(const u32x4*)(C + (size_t)(row0 + ai * HALF + m * 16) * ldc + col0 + bj * HALF);
; #pragma unroll
;         for (int ai = 0; ai < 2; ++ai)
; #pragma unroll
;             for (int m = 0; m < 4; ++m)
; #pragma unroll
;                 for (int bj = 0; bj < 2; ++bj) { const u32x4 c = cin[ai][m][bj]; const f32x4 v0 = acc[ai][bj][m][0], v1 = acc[ai][bj][m][1];
;                     u32x4 w; w.x = cvt_pk_bf16(bflo(c.x) + v0[0], bfhi(c.x) + v0[1]); w.y = cvt_pk_bf16(bflo(c.y) + v0[2], bfhi(c.y) + v0[3]);
.Lalign_a_1396:
	v_mov_b32_e32 v133, v0
	s_lshl_b32 s1, s46, 8
	s_add_i32 s1, s1, s38
	v_and_or_b32 v132, v133, 15, s1
	s_lshl_b32 s1, s45, 8
	v_lshrrev_b32_e32 v133, 1, v133
	v_and_or_b32 v133, v133, 24, s1
	v_or_b32_e32 v134, s39, v133
	v_ashrrev_i32_e32 v135, 31, v134
	v_lshlrev_b64 v[202:203], 1, v[134:135]
	v_ashrrev_i32_e32 v133, 31, v132
	v_lshl_add_u64 v[134:135], s[88:89], 0, v[202:203]
	v_lshlrev_b64 v[216:217], 12, v[132:133]
	v_lshl_add_u64 v[136:137], v[134:135], 0, v[216:217]
	global_load_dwordx4 v[226:229], v[136:137], off
	global_load_dwordx4 v[188:191], v[136:137], off offset:256
	v_or_b32_e32 v136, 16, v132
	v_ashrrev_i32_e32 v137, 31, v136
	v_lshlrev_b64 v[222:223], 12, v[136:137]
	v_lshl_add_u64 v[136:137], v[134:135], 0, v[222:223]
	global_load_dwordx4 v[184:187], v[136:137], off
	global_load_dwordx4 v[180:183], v[136:137], off offset:256
	v_or_b32_e32 v136, 32, v132
	v_ashrrev_i32_e32 v137, 31, v136
	v_lshlrev_b64 v[220:221], 12, v[136:137]
	v_lshl_add_u64 v[136:137], v[134:135], 0, v[220:221]
	global_load_dwordx4 v[176:179], v[136:137], off
	global_load_dwordx4 v[168:171], v[136:137], off offset:256
	v_or_b32_e32 v132, 48, v132
	v_ashrrev_i32_e32 v133, 31, v132
	v_lshlrev_b64 v[212:213], 12, v[132:133]
	v_lshl_add_u64 v[132:133], v[134:135], 0, v[212:213]
	global_load_dwordx4 v[172:175], v[132:133], off
	global_load_dwordx4 v[164:167], v[132:133], off offset:256
	s_mov_b64 s[6:7], 0x80000
	v_lshl_add_u64 v[210:211], v[216:217], 0, s[6:7]
	v_lshl_add_u64 v[132:133], v[134:135], 0, v[210:211]
	global_load_dwordx4 v[160:163], v[132:133], off
	global_load_dwordx4 v[156:159], v[132:133], off offset:256
	s_mov_b64 s[6:7], 0x90000
	v_lshl_add_u64 v[208:209], v[216:217], 0, s[6:7]
	v_lshl_add_u64 v[132:133], v[134:135], 0, v[208:209]
	global_load_dwordx4 v[152:155], v[132:133], off
	global_load_dwordx4 v[148:151], v[132:133], off offset:256
	s_mov_b64 s[6:7], 0xa0000
	v_lshl_add_u64 v[206:207], v[216:217], 0, s[6:7]
	v_lshl_add_u64 v[132:133], v[134:135], 0, v[206:207]
	global_load_dwordx4 v[144:147], v[132:133], off
	global_load_dwordx4 v[140:143], v[132:133], off offset:256
	s_mov_b64 s[6:7], 0xb0000
	v_lshl_add_u64 v[204:205], v[216:217], 0, s[6:7]
	v_lshl_add_u64 v[132:133], v[134:135], 0, v[204:205]
	global_load_dwordx4 v[136:139], v[132:133], off
	s_nop 0
	global_load_dwordx4 v[132:135], v[132:133], off offset:256
	s_and_b64 vcc, exec, s[40:41]
	s_mov_b32 s45, s0
	s_mov_b32 s46, s14
	s_mov_b64 s[20:21], s[18:19]
	s_mov_b64 s[6:7], s[4:5]
	s_waitcnt vmcnt(15)
	v_lshlrev_b32_e32 v218, 16, v226
	v_and_b32_e32 v219, 0xffff0000, v226
	v_pk_add_f32 v[128:129], v[128:129], v[218:219]
	v_lshlrev_b32_e32 v218, 16, v227
	v_and_b32_e32 v219, 0xffff0000, v227
	v_pk_add_f32 v[130:131], v[130:131], v[218:219]
	v_cvt_pk_bf16_f32 v128, v128, v129
	v_cvt_pk_bf16_f32 v129, v130, v131
	v_lshlrev_b32_e32 v130, 16, v228
	v_and_b32_e32 v131, 0xffff0000, v228
	v_pk_add_f32 v[124:125], v[124:125], v[130:131]
	s_nop 0
	v_cvt_pk_bf16_f32 v130, v124, v125
	v_lshlrev_b32_e32 v124, 16, v229
	v_and_b32_e32 v125, 0xffff0000, v229
	v_pk_add_f32 v[124:125], v[126:127], v[124:125]
	s_waitcnt vmcnt(14)
	v_lshlrev_b32_e32 v126, 16, v188
	v_and_b32_e32 v127, 0xffff0000, v188
	v_pk_add_f32 v[120:121], v[120:121], v[126:127]
	v_lshlrev_b32_e32 v126, 16, v189
	v_and_b32_e32 v127, 0xffff0000, v189
	v_pk_add_f32 v[122:123], v[122:123], v[126:127]
	v_cvt_pk_bf16_f32 v120, v120, v121
	v_cvt_pk_bf16_f32 v121, v122, v123
	v_lshlrev_b32_e32 v122, 16, v190
	v_and_b32_e32 v123, 0xffff0000, v190
	v_pk_add_f32 v[116:117], v[116:117], v[122:123]
	v_cvt_pk_bf16_f32 v131, v124, v125
	v_cvt_pk_bf16_f32 v122, v116, v117
	v_lshlrev_b32_e32 v116, 16, v191
	v_and_b32_e32 v117, 0xffff0000, v191
	v_pk_add_f32 v[116:117], v[118:119], v[116:117]
	v_lshl_add_u64 v[124:125], s[88:89], 0, v[216:217]
	v_cvt_pk_bf16_f32 v123, v116, v117
	s_waitcnt vmcnt(13)
	v_lshlrev_b32_e32 v116, 16, v184
	v_and_b32_e32 v117, 0xffff0000, v184
	v_pk_add_f32 v[112:113], v[112:113], v[116:117]
	v_lshlrev_b32_e32 v116, 16, v185
	v_and_b32_e32 v117, 0xffff0000, v185
	v_pk_add_f32 v[114:115], v[114:115], v[116:117]
	v_cvt_pk_bf16_f32 v112, v112, v113
	v_cvt_pk_bf16_f32 v113, v114, v115
	v_lshlrev_b32_e32 v114, 16, v186
	v_and_b32_e32 v115, 0xffff0000, v186
	v_pk_add_f32 v[108:109], v[108:109], v[114:115]
	v_lshl_add_u64 v[124:125], v[124:125], 0, v[202:203]
	v_cvt_pk_bf16_f32 v114, v108, v109
	v_lshlrev_b32_e32 v108, 16, v187
	v_and_b32_e32 v109, 0xffff0000, v187
	v_pk_add_f32 v[108:109], v[110:111], v[108:109]
	s_waitcnt vmcnt(12)
	v_lshlrev_b32_e32 v110, 16, v180
	v_and_b32_e32 v111, 0xffff0000, v180
	v_pk_add_f32 v[104:105], v[104:105], v[110:111]
	v_lshlrev_b32_e32 v110, 16, v181
	v_and_b32_e32 v111, 0xffff0000, v181
	v_pk_add_f32 v[106:107], v[106:107], v[110:111]
	v_cvt_pk_bf16_f32 v104, v104, v105
	v_cvt_pk_bf16_f32 v105, v106, v107
	v_lshlrev_b32_e32 v106, 16, v182
	v_and_b32_e32 v107, 0xffff0000, v182
	v_pk_add_f32 v[96:97], v[96:97], v[106:107]
	v_cvt_pk_bf16_f32 v115, v108, v109
	v_cvt_pk_bf16_f32 v106, v96, v97
	v_lshlrev_b32_e32 v96, 16, v183
	v_and_b32_e32 v97, 0xffff0000, v183
	v_pk_add_f32 v[96:97], v[98:99], v[96:97]
	s_waitcnt vmcnt(11)
	v_lshlrev_b32_e32 v98, 16, v177
	v_cvt_pk_bf16_f32 v107, v96, v97
	v_lshlrev_b32_e32 v96, 16, v176
	v_and_b32_e32 v97, 0xffff0000, v176
	v_and_b32_e32 v99, 0xffff0000, v177
	v_pk_add_f32 v[96:97], v[100:101], v[96:97]
	v_pk_add_f32 v[98:99], v[102:103], v[98:99]
	v_cvt_pk_bf16_f32 v96, v96, v97
	v_cvt_pk_bf16_f32 v97, v98, v99
	v_lshlrev_b32_e32 v98, 16, v178
	v_and_b32_e32 v99, 0xffff0000, v178
	v_pk_add_f32 v[92:93], v[92:93], v[98:99]
	v_lshl_add_u64 v[108:109], s[88:89], 0, v[222:223]
	v_cvt_pk_bf16_f32 v98, v92, v93
	v_lshlrev_b32_e32 v92, 16, v179
	v_and_b32_e32 v93, 0xffff0000, v179
	v_pk_add_f32 v[92:93], v[94:95], v[92:93]
	s_waitcnt vmcnt(10)
; __device__ __forceinline__ unsigned cvt_pk_bf16(float lo, float hi) { const f32x2 v = {lo, hi}; const bf16v2_ r = __builtin_convertvector(v, bf16v2_); return __builtin_bit_cast(unsigned, r); }
; __device__ __forceinline__ float bflo(unsigned w) { return __uint_as_float(w << 16); }
; __device__ __forceinline__ float bfhi(unsigned w) { return __uint_as_float(w & 0xffff0000u); }
;     __device__ __forceinline__ void operator()(const f32x4 (&acc)[2][2][4][2], const Unit& u, int wr, int wc, int, int) const {
;     ...
;                 for (int bj = 0; bj < 2; ++bj) { const u32x4 c = cin[ai][m][bj]; const f32x4 v0 = acc[ai][bj][m][0], v1 = acc[ai][bj][m][1];
;                     u32x4 w; w.x = cvt_pk_bf16(bflo(c.x) + v0[0], bfhi(c.x) + v0[1]); w.y = cvt_pk_bf16(bflo(c.y) + v0[2], bfhi(c.y) + v0[3]);
;                     w.z = cvt_pk_bf16(bflo(c.z) + v1[0], bfhi(c.z) + v1[1]); w.w = cvt_pk_bf16(bflo(c.w) + v1[2], bfhi(c.w) + v1[3]);
;                     *(u32x4*)(C + (size_t)(row0 + ai * HALF + m * 16) * ldc + col0 + bj * HALF) = w; }
	v_lshlrev_b32_e32 v94, 16, v168
	v_and_b32_e32 v95, 0xffff0000, v168
	v_pk_add_f32 v[88:89], v[88:89], v[94:95]
	v_lshlrev_b32_e32 v94, 16, v169
	v_and_b32_e32 v95, 0xffff0000, v169
	v_pk_add_f32 v[90:91], v[90:91], v[94:95]
	v_cvt_pk_bf16_f32 v88, v88, v89
	v_cvt_pk_bf16_f32 v89, v90, v91
	v_lshlrev_b32_e32 v90, 16, v170
	v_and_b32_e32 v91, 0xffff0000, v170
	v_pk_add_f32 v[80:81], v[80:81], v[90:91]
	v_cvt_pk_bf16_f32 v99, v92, v93
	v_cvt_pk_bf16_f32 v90, v80, v81
	v_lshlrev_b32_e32 v80, 16, v171
	v_and_b32_e32 v81, 0xffff0000, v171
	v_pk_add_f32 v[80:81], v[82:83], v[80:81]
	s_waitcnt vmcnt(9)
	v_lshlrev_b32_e32 v82, 16, v173
	v_cvt_pk_bf16_f32 v91, v80, v81
	v_lshlrev_b32_e32 v80, 16, v172
	v_and_b32_e32 v81, 0xffff0000, v172
	v_and_b32_e32 v83, 0xffff0000, v173
	v_pk_add_f32 v[80:81], v[84:85], v[80:81]
	v_pk_add_f32 v[82:83], v[86:87], v[82:83]
	v_cvt_pk_bf16_f32 v80, v80, v81
	v_cvt_pk_bf16_f32 v81, v82, v83
	v_lshlrev_b32_e32 v82, 16, v174
	v_and_b32_e32 v83, 0xffff0000, v174
	v_pk_add_f32 v[76:77], v[76:77], v[82:83]
	v_lshl_add_u64 v[92:93], s[88:89], 0, v[220:221]
	v_cvt_pk_bf16_f32 v82, v76, v77
	v_lshlrev_b32_e32 v76, 16, v175
	v_and_b32_e32 v77, 0xffff0000, v175
	v_pk_add_f32 v[76:77], v[78:79], v[76:77]
	s_waitcnt vmcnt(8)
	v_lshlrev_b32_e32 v78, 16, v164
	v_and_b32_e32 v79, 0xffff0000, v164
	v_pk_add_f32 v[72:73], v[72:73], v[78:79]
	v_lshlrev_b32_e32 v78, 16, v165
	v_and_b32_e32 v79, 0xffff0000, v165
	v_pk_add_f32 v[74:75], v[74:75], v[78:79]
	v_cvt_pk_bf16_f32 v72, v72, v73
	v_cvt_pk_bf16_f32 v73, v74, v75
	v_lshlrev_b32_e32 v74, 16, v166
	v_and_b32_e32 v75, 0xffff0000, v166
	v_pk_add_f32 v[68:69], v[68:69], v[74:75]
	v_cvt_pk_bf16_f32 v83, v76, v77
	v_cvt_pk_bf16_f32 v74, v68, v69
	v_lshlrev_b32_e32 v68, 16, v167
	v_and_b32_e32 v69, 0xffff0000, v167
	v_pk_add_f32 v[68:69], v[70:71], v[68:69]
	v_lshl_add_u64 v[76:77], s[88:89], 0, v[212:213]
	v_cvt_pk_bf16_f32 v75, v68, v69
	s_waitcnt vmcnt(7)
	v_lshlrev_b32_e32 v68, 16, v160
	v_and_b32_e32 v69, 0xffff0000, v160
	v_pk_add_f32 v[64:65], v[64:65], v[68:69]
	v_lshlrev_b32_e32 v68, 16, v161
	v_and_b32_e32 v69, 0xffff0000, v161
	v_pk_add_f32 v[66:67], v[66:67], v[68:69]
	v_cvt_pk_bf16_f32 v64, v64, v65
	v_cvt_pk_bf16_f32 v65, v66, v67
	v_lshlrev_b32_e32 v66, 16, v162
	v_and_b32_e32 v67, 0xffff0000, v162
	v_pk_add_f32 v[60:61], v[60:61], v[66:67]
	v_lshl_add_u64 v[108:109], v[108:109], 0, v[202:203]
	v_cvt_pk_bf16_f32 v66, v60, v61
	v_lshlrev_b32_e32 v60, 16, v163
	v_and_b32_e32 v61, 0xffff0000, v163
	v_pk_add_f32 v[60:61], v[62:63], v[60:61]
	s_waitcnt vmcnt(6)
	v_lshlrev_b32_e32 v62, 16, v156
	v_and_b32_e32 v63, 0xffff0000, v156
	v_pk_add_f32 v[56:57], v[56:57], v[62:63]
	v_lshlrev_b32_e32 v62, 16, v157
	v_and_b32_e32 v63, 0xffff0000, v157
	v_pk_add_f32 v[58:59], v[58:59], v[62:63]
	v_cvt_pk_bf16_f32 v56, v56, v57
	v_cvt_pk_bf16_f32 v57, v58, v59
	v_lshlrev_b32_e32 v58, 16, v158
	v_and_b32_e32 v59, 0xffff0000, v158
	v_pk_add_f32 v[48:49], v[48:49], v[58:59]
	v_cvt_pk_bf16_f32 v67, v60, v61
	v_cvt_pk_bf16_f32 v58, v48, v49
	v_lshlrev_b32_e32 v48, 16, v159
	v_and_b32_e32 v49, 0xffff0000, v159
	v_pk_add_f32 v[48:49], v[50:51], v[48:49]
	s_waitcnt vmcnt(5)
	v_lshlrev_b32_e32 v50, 16, v153
	v_cvt_pk_bf16_f32 v59, v48, v49
	v_lshlrev_b32_e32 v48, 16, v152
	v_and_b32_e32 v49, 0xffff0000, v152
	v_and_b32_e32 v51, 0xffff0000, v153
	v_pk_add_f32 v[48:49], v[52:53], v[48:49]
	v_pk_add_f32 v[50:51], v[54:55], v[50:51]
	v_cvt_pk_bf16_f32 v48, v48, v49
	v_cvt_pk_bf16_f32 v49, v50, v51
	v_lshlrev_b32_e32 v50, 16, v154
	v_and_b32_e32 v51, 0xffff0000, v154
	v_pk_add_f32 v[44:45], v[44:45], v[50:51]
	v_lshl_add_u64 v[60:61], s[88:89], 0, v[210:211]
	v_cvt_pk_bf16_f32 v50, v44, v45
	v_lshlrev_b32_e32 v44, 16, v155
	v_and_b32_e32 v45, 0xffff0000, v155
	v_pk_add_f32 v[44:45], v[46:47], v[44:45]
	s_waitcnt vmcnt(4)
; __device__ __forceinline__ unsigned cvt_pk_bf16(float lo, float hi) { const f32x2 v = {lo, hi}; const bf16v2_ r = __builtin_convertvector(v, bf16v2_); return __builtin_bit_cast(unsigned, r); }
; __device__ __forceinline__ float bflo(unsigned w) { return __uint_as_float(w << 16); }
; __device__ __forceinline__ float bfhi(unsigned w) { return __uint_as_float(w & 0xffff0000u); }
;     __device__ __forceinline__ void operator()(const f32x4 (&acc)[2][2][4][2], const Unit& u, int wr, int wc, int, int) const {
;     ...
;                 for (int bj = 0; bj < 2; ++bj) { const u32x4 c = cin[ai][m][bj]; const f32x4 v0 = acc[ai][bj][m][0], v1 = acc[ai][bj][m][1];
;                     u32x4 w; w.x = cvt_pk_bf16(bflo(c.x) + v0[0], bfhi(c.x) + v0[1]); w.y = cvt_pk_bf16(bflo(c.y) + v0[2], bfhi(c.y) + v0[3]);
;                     w.z = cvt_pk_bf16(bflo(c.z) + v1[0], bfhi(c.z) + v1[1]); w.w = cvt_pk_bf16(bflo(c.w) + v1[2], bfhi(c.w) + v1[3]);
;                     *(u32x4*)(C + (size_t)(row0 + ai * HALF + m * 16) * ldc + col0 + bj * HALF) = w; }
	v_lshlrev_b32_e32 v46, 16, v148
	v_and_b32_e32 v47, 0xffff0000, v148
	v_pk_add_f32 v[40:41], v[40:41], v[46:47]
	v_lshlrev_b32_e32 v46, 16, v149
	v_and_b32_e32 v47, 0xffff0000, v149
	v_pk_add_f32 v[42:43], v[42:43], v[46:47]
	v_cvt_pk_bf16_f32 v40, v40, v41
	v_cvt_pk_bf16_f32 v41, v42, v43
	v_lshlrev_b32_e32 v42, 16, v150
	v_and_b32_e32 v43, 0xffff0000, v150
	v_pk_add_f32 v[32:33], v[32:33], v[42:43]
	v_cvt_pk_bf16_f32 v51, v44, v45
	v_cvt_pk_bf16_f32 v42, v32, v33
	v_lshlrev_b32_e32 v32, 16, v151
	v_and_b32_e32 v33, 0xffff0000, v151
	v_pk_add_f32 v[32:33], v[34:35], v[32:33]
	s_waitcnt vmcnt(3)
	v_lshlrev_b32_e32 v34, 16, v145
	v_cvt_pk_bf16_f32 v43, v32, v33
	v_lshlrev_b32_e32 v32, 16, v144
	v_and_b32_e32 v33, 0xffff0000, v144
	v_and_b32_e32 v35, 0xffff0000, v145
	v_pk_add_f32 v[32:33], v[36:37], v[32:33]
	v_pk_add_f32 v[34:35], v[38:39], v[34:35]
	v_cvt_pk_bf16_f32 v32, v32, v33
	v_cvt_pk_bf16_f32 v33, v34, v35
	v_lshlrev_b32_e32 v34, 16, v146
	v_and_b32_e32 v35, 0xffff0000, v146
	v_pk_add_f32 v[28:29], v[28:29], v[34:35]
	v_lshl_add_u64 v[44:45], s[88:89], 0, v[208:209]
	v_cvt_pk_bf16_f32 v34, v28, v29
	v_lshlrev_b32_e32 v28, 16, v147
	v_and_b32_e32 v29, 0xffff0000, v147
	v_pk_add_f32 v[28:29], v[30:31], v[28:29]
	s_waitcnt vmcnt(2)
	v_lshlrev_b32_e32 v30, 16, v140
	v_and_b32_e32 v31, 0xffff0000, v140
	v_pk_add_f32 v[24:25], v[24:25], v[30:31]
	v_lshlrev_b32_e32 v30, 16, v141
	v_and_b32_e32 v31, 0xffff0000, v141
	v_pk_add_f32 v[26:27], v[26:27], v[30:31]
	v_cvt_pk_bf16_f32 v24, v24, v25
	v_cvt_pk_bf16_f32 v25, v26, v27
	v_lshlrev_b32_e32 v26, 16, v142
	v_and_b32_e32 v27, 0xffff0000, v142
	v_pk_add_f32 v[16:17], v[16:17], v[26:27]
	v_cvt_pk_bf16_f32 v35, v28, v29
	v_cvt_pk_bf16_f32 v26, v16, v17
	v_lshlrev_b32_e32 v16, 16, v143
	v_and_b32_e32 v17, 0xffff0000, v143
	v_pk_add_f32 v[16:17], v[18:19], v[16:17]
	s_waitcnt vmcnt(1)
	v_lshlrev_b32_e32 v18, 16, v137
	v_cvt_pk_bf16_f32 v27, v16, v17
	v_lshlrev_b32_e32 v16, 16, v136
	v_and_b32_e32 v17, 0xffff0000, v136
	v_and_b32_e32 v19, 0xffff0000, v137
	v_pk_add_f32 v[16:17], v[20:21], v[16:17]
	v_pk_add_f32 v[18:19], v[22:23], v[18:19]
	v_cvt_pk_bf16_f32 v16, v16, v17
	v_cvt_pk_bf16_f32 v17, v18, v19
	v_lshlrev_b32_e32 v18, 16, v138
	v_and_b32_e32 v19, 0xffff0000, v138
	v_pk_add_f32 v[12:13], v[12:13], v[18:19]
	v_lshl_add_u64 v[28:29], s[88:89], 0, v[206:207]
	v_cvt_pk_bf16_f32 v18, v12, v13
	v_lshlrev_b32_e32 v12, 16, v139
	v_and_b32_e32 v13, 0xffff0000, v139
	v_pk_add_f32 v[12:13], v[14:15], v[12:13]
	s_waitcnt vmcnt(0)
	v_lshlrev_b32_e32 v14, 16, v132
	v_and_b32_e32 v15, 0xffff0000, v132
	v_pk_add_f32 v[8:9], v[8:9], v[14:15]
	v_lshlrev_b32_e32 v14, 16, v133
	v_and_b32_e32 v15, 0xffff0000, v133
	v_pk_add_f32 v[10:11], v[10:11], v[14:15]
	v_cvt_pk_bf16_f32 v8, v8, v9
	v_cvt_pk_bf16_f32 v9, v10, v11
	v_lshlrev_b32_e32 v10, 16, v134
	v_and_b32_e32 v11, 0xffff0000, v134
	v_pk_add_f32 v[4:5], v[4:5], v[10:11]
	v_cvt_pk_bf16_f32 v19, v12, v13
	v_cvt_pk_bf16_f32 v10, v4, v5
	v_lshlrev_b32_e32 v4, 16, v135
	v_and_b32_e32 v5, 0xffff0000, v135
	v_lshl_add_u64 v[12:13], s[88:89], 0, v[204:205]
	v_pk_add_f32 v[4:5], v[6:7], v[4:5]
	v_lshl_add_u64 v[92:93], v[92:93], 0, v[202:203]
	v_lshl_add_u64 v[76:77], v[76:77], 0, v[202:203]
	v_lshl_add_u64 v[60:61], v[60:61], 0, v[202:203]
	v_lshl_add_u64 v[44:45], v[44:45], 0, v[202:203]
	v_lshl_add_u64 v[28:29], v[28:29], 0, v[202:203]
	v_lshl_add_u64 v[12:13], v[12:13], 0, v[202:203]
	v_cvt_pk_bf16_f32 v11, v4, v5
	global_store_dwordx4 v[124:125], v[128:131], off
	global_store_dwordx4 v[124:125], v[120:123], off offset:256
	global_store_dwordx4 v[108:109], v[112:115], off
	global_store_dwordx4 v[108:109], v[104:107], off offset:256
	global_store_dwordx4 v[92:93], v[96:99], off
	global_store_dwordx4 v[92:93], v[88:91], off offset:256
	global_store_dwordx4 v[76:77], v[80:83], off
	global_store_dwordx4 v[76:77], v[72:75], off offset:256
	global_store_dwordx4 v[60:61], v[64:67], off
	global_store_dwordx4 v[60:61], v[56:59], off offset:256
	global_store_dwordx4 v[44:45], v[48:51], off
	global_store_dwordx4 v[44:45], v[40:43], off offset:256
	global_store_dwordx4 v[28:29], v[32:35], off
	global_store_dwordx4 v[28:29], v[24:27], off offset:256
	global_store_dwordx4 v[12:13], v[16:19], off
	global_store_dwordx4 v[12:13], v[8:11], off offset:256
	s_cmpk_lt_u32 s2, 0x100
	s_cbranch_scc1 .Lalign_b_1396
	s_barrier
	s_setprio 1

;     __device__ __forceinline__ void operator()(f32x4 (&acc)[2][2][4][2], const Unit& u, int wr, int wc, int ui, int) const {
;     ...
;         if (wr == 1 && fr >= 14) { float* t = tail + ((size_t)u.pm * 2 + (fr - 14)) * FF + col; *(f32x4*)t = acc[1][1][3][0]; *(f32x4*)(t + 4) = acc[1][1][3][1]; }
;         if (wr == 0 && fr < 2) { float* hg = headg + ((size_t)u.pm * 2 + fr) * FF + col; *(f32x4*)hg = acc[0][1][0][0]; *(f32x4*)(hg + 4) = acc[0][1][0][1];
;                                  float* hu = headu + ((size_t)u.pm * 2 + fr) * FF + col; *(f32x4*)hu = acc[0][0][0][0]; *(f32x4*)(hu + 4) = acc[0][0][0][1]; }
.LBB0_1520:
	s_or_b64 exec, exec, s[4:5]
	s_andn2_b64 vcc, exec, s[44:45]
	s_cbranch_vccnz .Lalign_b_1526
	s_barrier
	s_setprio 1

; #define PG8_STAGE(bufoff, gbase, voff) do { _Pragma("unroll") for (int _i = 0; _i < 2; ++_i) \
;         __builtin_amdgcn_global_load_lds((const unsigned*)((const char*)(gbase) + (voff)[_i]), (LAS unsigned*)(lds + (bufoff) + ldsw + _i * 8192), 16, 0, 0); } while (0)
; #define PG8_LDA(dst, b, h) do { _Pragma("unroll") for (int m = 0; m < 4; ++m) _Pragma("unroll") for (int k = 0; k < 2; ++k) dst[m][k] = *(const LAS bf16x8*)(lds + PG8_SA(b, h) + aoff + m * 2048 + k * 1024); } while (0)
; #define PG8_LDB(dst, b, h) do { _Pragma("unroll") for (int n = 0; n < 2; ++n) _Pragma("unroll") for (int k = 0; k < 2; ++k) dst[n][k] = *(const LAS bf16x8*)(lds + PG8_SB(b, h) + boff + n * 2048 + k * 1024); } while (0)
; #define PG8_WAIT_V(n) asm volatile("s_waitcnt vmcnt(" #n ")" ::: "memory")
; #define PG8_WAIT_L(n) asm volatile("s_waitcnt lgkmcnt(" #n ")" ::: "memory")
; #define PG8_BAR __builtin_amdgcn_s_barrier()
; #define PG8_SCHED __builtin_amdgcn_sched_barrier(0)
; template <class Epi, class Sched>
; __device__ __forceinline__ void gemm_phase(LAS unsigned char* lds, const Gemm g, const Sched& S, const Epi& E) {
;     ...
;         const char* nA = has_next ? (const char*)g.A + (size_t)nxt.pm * tstepA : cA; const char* nB = has_next ? (const char*)g.Bt + (size_t)nxt.pn * tstepB : cB;
;         for (int t = 0; t < nt; t += 2) {
;             const bool last = (t == nt - 2);
;             const char* a1 = cA + (size_t)(t + 1) * kstep;
;             const char* a2 = last ? nA : cA + (size_t)(t + 2) * kstep; const char* b2 = last ? nB : cB + (size_t)(t + 2) * kstep;
;             const char* a3 = a2 + kstep; const char* b3 = b2 + kstep;
;             if (last && has_next) S.a_ready(nxt);
;             PG8_LDB(B0, 0, 0); PG8_SCHED; PG8_LDA(At, 0, 0); PG8_STAGE(PG8_SA(1, 1), a1 + hstepA, voffA);
;             PG8_WAIT_L(8); PG8_BAR; PG8_WAIT_L(0); PG8_MMA(0, 0, At, B0); PG8_BAR; PG8_SCHED;
;             PG8_LDB(B1, 0, 1); PG8_STAGE(PG8_SB(0, 0), b2, voffB);
;             PG8_BAR; PG8_WAIT_L(0); PG8_MMA(0, 1, At, B1); PG8_BAR;
;             PG8_LDA(At, 0, 1); PG8_STAGE(PG8_SA(0, 0), a2, voffA);
;             PG8_BAR; PG8_WAIT_L(0); PG8_MMA(1, 0, At, B0); PG8_BAR; PG8_SCHED;
;             PG8_STAGE(PG8_SB(0, 1), b2 + hstepB, voffB);
;             PG8_WAIT_V(6); PG8_BAR; PG8_MMA(1, 1, At, B1); PG8_BAR;
.LBB0_1525:
	v_mov_b64_e32 v[4:5], 0x1600
	s_ashr_i32 s57, s56, 31
	v_cmp_lt_i64_e32 vcc, s[14:15], v[4:5]
	s_lshl_b64 s[14:15], s[56:57], 20
	s_add_u32 s58, s88, s14
	s_addc_u32 s59, s89, s15
	s_and_b64 s[14:15], vcc, exec
	s_cselect_b32 s57, s59, s5
	s_cselect_b32 s67, s58, s4
	s_ashr_i32 s55, s54, 31
	s_lshl_b64 s[14:15], s[54:55], 20
	s_add_u32 s60, s2, s14
	s_addc_u32 s61, s18, s15
	s_and_b64 s[14:15], vcc, exec
	s_cselect_b32 s55, s61, s7
	s_cselect_b32 s68, s60, s6
	s_add_u32 s4, s4, 0x80080
	s_addc_u32 s5, s5, 0
	s_add_u32 s69, s6, 0x100
	s_addc_u32 s70, s7, 0
	s_mov_b32 s71, -2
	s_add_u32 s6, s4, 0xfff80080
	s_addc_u32 s7, s5, -1
	s_add_i32 s72, 0, 0x10000
	v_add_u32_e32 v2, s72, v1
	ds_read_b128 v[132:135], v2
	ds_read_b128 v[136:139], v2 offset:1024
	ds_read_b128 v[140:143], v2 offset:2048
	ds_read_b128 v[144:147], v2 offset:3072
	s_cmp_eq_u32 s71, 28
	s_cselect_b32 s15, s57, s7
	s_cselect_b32 s14, s67, s6
	s_cselect_b32 s7, s55, s70
	s_cselect_b32 s6, s68, s69
	ds_read_b128 v[148:151], v207
	ds_read_b128 v[152:155], v207 offset:1024
	ds_read_b128 v[156:159], v207 offset:2048
	ds_read_b128 v[160:163], v207 offset:3072
	ds_read_b128 v[164:167], v207 offset:4096
	ds_read_b128 v[168:171], v207 offset:5120
	ds_read_b128 v[186:189], v207 offset:6144
	ds_read_b128 v[190:193], v207 offset:7168
	s_add_i32 s74, 0, 0x14000
	v_add_u32_e32 v2, s74, v1
	ds_read_b128 v[194:197], v2
	ds_read_b128 v[198:201], v2 offset:1024
	ds_read_b128 v[202:205], v2 offset:2048
	ds_read_b128 v[208:211], v2 offset:3072
	s_add_i32 m0, s20, 0xc000
	s_nop 0
	global_load_lds_dwordx4 v182, s[4:5]
	s_add_i32 m0, s20, 0xe000
	s_nop 0
	global_load_lds_dwordx4 v184, s[4:5]
	s_waitcnt lgkmcnt(0)
	s_barrier
	v_mfma_f32_16x16x32_bf16 v[68:71], v[132:135], v[148:151], 0
	v_mfma_f32_16x16x32_bf16 v[72:75], v[140:143], v[148:151], 0
	v_mfma_f32_16x16x32_bf16 v[120:123], v[132:135], v[156:159], 0
	v_mfma_f32_16x16x32_bf16 v[116:119], v[140:143], v[156:159], 0
	v_mfma_f32_16x16x32_bf16 v[112:115], v[132:135], v[164:167], 0
	v_mfma_f32_16x16x32_bf16 v[108:111], v[140:143], v[164:167], 0
	v_mfma_f32_16x16x32_bf16 v[104:107], v[132:135], v[186:189], 0
	v_mfma_f32_16x16x32_bf16 v[100:103], v[140:143], v[186:189], 0
	v_mfma_f32_16x16x32_bf16 v[68:71], v[136:139], v[152:155], v[68:71]
	v_mfma_f32_16x16x32_bf16 v[72:75], v[144:147], v[152:155], v[72:75]
	v_mfma_f32_16x16x32_bf16 v[120:123], v[136:139], v[160:163], v[120:123]
	v_mfma_f32_16x16x32_bf16 v[116:119], v[144:147], v[160:163], v[116:119]
	v_mfma_f32_16x16x32_bf16 v[112:115], v[136:139], v[168:171], v[112:115]
	v_mfma_f32_16x16x32_bf16 v[108:111], v[144:147], v[168:171], v[108:111]
	v_mfma_f32_16x16x32_bf16 v[104:107], v[136:139], v[190:193], v[104:107]
	v_mfma_f32_16x16x32_bf16 v[100:103], v[144:147], v[190:193], v[100:103]
	v_mfma_f32_16x16x32_bf16 v[76:79], v[194:197], v[148:151], 0
	v_mfma_f32_16x16x32_bf16 v[80:83], v[202:205], v[148:151], 0
	v_mfma_f32_16x16x32_bf16 v[96:99], v[194:197], v[156:159], 0
	v_mfma_f32_16x16x32_bf16 v[92:95], v[202:205], v[156:159], 0
	v_mfma_f32_16x16x32_bf16 v[88:91], v[194:197], v[164:167], 0
	v_mfma_f32_16x16x32_bf16 v[84:87], v[202:205], v[164:167], 0
	v_mfma_f32_16x16x32_bf16 v[128:131], v[194:197], v[186:189], 0
	v_mfma_f32_16x16x32_bf16 v[124:127], v[202:205], v[186:189], 0
	v_mfma_f32_16x16x32_bf16 v[76:79], v[198:201], v[152:155], v[76:79]
	v_mfma_f32_16x16x32_bf16 v[80:83], v[208:211], v[152:155], v[80:83]
	v_mfma_f32_16x16x32_bf16 v[96:99], v[198:201], v[160:163], v[96:99]
	v_mfma_f32_16x16x32_bf16 v[92:95], v[208:211], v[160:163], v[92:95]
	v_mfma_f32_16x16x32_bf16 v[88:91], v[198:201], v[168:171], v[88:91]
	v_mfma_f32_16x16x32_bf16 v[84:87], v[208:211], v[168:171], v[84:87]
	v_mfma_f32_16x16x32_bf16 v[128:131], v[198:201], v[190:193], v[128:131]
	v_mfma_f32_16x16x32_bf16 v[124:127], v[208:211], v[190:193], v[124:127]
	s_barrier
	ds_read_b128 v[148:151], v207 offset:16384
	ds_read_b128 v[152:155], v207 offset:17408
	ds_read_b128 v[156:159], v207 offset:18432
	ds_read_b128 v[160:163], v207 offset:19456
	ds_read_b128 v[164:167], v207 offset:20480
	ds_read_b128 v[168:171], v207 offset:21504
	ds_read_b128 v[186:189], v207 offset:22528
	ds_read_b128 v[190:193], v207 offset:23552
	s_add_i32 s72, s72, s19
	v_lshl_add_u64 v[172:173], s[6:7], 0, v[178:179]
	s_mov_b32 m0, s72
	s_nop 0
	global_load_lds_dwordx4 v[172:173], off
	v_lshl_add_u64 v[212:213], s[6:7], 0, v[174:175]
	s_add_i32 m0, s72, 0x2000
	s_nop 0
	global_load_lds_dwordx4 v[212:213], off
	s_mov_b32 m0, s20
	v_lshl_add_u64 v[216:217], s[14:15], 0, v[180:181]
	global_load_lds_dwordx4 v[216:217], off
	v_lshl_add_u64 v[218:219], s[14:15], 0, v[176:177]
	s_mov_b32 m0, s21
	s_nop 0
	global_load_lds_dwordx4 v[218:219], off
	s_add_u32 s72, s6, 0x80000
	s_addc_u32 s73, s7, 0
	s_add_i32 s74, s74, s19
	s_mov_b32 m0, s74
	s_nop 0
	global_load_lds_dwordx4 v178, s[72:73]
	s_add_i32 m0, s74, 0x2000
	s_nop 0
	global_load_lds_dwordx4 v174, s[72:73]
	s_waitcnt lgkmcnt(0)
	s_waitcnt vmcnt(6)
	s_barrier
; #define PG8_STAGE(bufoff, gbase, voff) do { _Pragma("unroll") for (int _i = 0; _i < 2; ++_i) \
;         __builtin_amdgcn_global_load_lds((const unsigned*)((const char*)(gbase) + (voff)[_i]), (LAS unsigned*)(lds + (bufoff) + ldsw + _i * 8192), 16, 0, 0); } while (0)
; #define PG8_LDA(dst, b, h) do { _Pragma("unroll") for (int m = 0; m < 4; ++m) _Pragma("unroll") for (int k = 0; k < 2; ++k) dst[m][k] = *(const LAS bf16x8*)(lds + PG8_SA(b, h) + aoff + m * 2048 + k * 1024); } while (0)
; #define PG8_LDB(dst, b, h) do { _Pragma("unroll") for (int n = 0; n < 2; ++n) _Pragma("unroll") for (int k = 0; k < 2; ++k) dst[n][k] = *(const LAS bf16x8*)(lds + PG8_SB(b, h) + boff + n * 2048 + k * 1024); } while (0)
; #define PG8_WAIT_V(n) asm volatile("s_waitcnt vmcnt(" #n ")" ::: "memory")
; #define PG8_WAIT_L(n) asm volatile("s_waitcnt lgkmcnt(" #n ")" ::: "memory")
; #define PG8_BAR __builtin_amdgcn_s_barrier()
; #define PG8_SCHED __builtin_amdgcn_sched_barrier(0)
; template <class Epi, class Sched>
; __device__ __forceinline__ void gemm_phase(LAS unsigned char* lds, const Gemm g, const Sched& S, const Epi& E) {
;     ...
;             PG8_LDB(B0, 0, 0); PG8_SCHED; PG8_LDA(At, 0, 0); PG8_STAGE(PG8_SA(1, 1), a1 + hstepA, voffA);
;             PG8_WAIT_L(8); PG8_BAR; PG8_WAIT_L(0); PG8_MMA(0, 0, At, B0); PG8_BAR; PG8_SCHED;
;             PG8_LDB(B1, 0, 1); PG8_STAGE(PG8_SB(0, 0), b2, voffB);
;             PG8_BAR; PG8_WAIT_L(0); PG8_MMA(0, 1, At, B1); PG8_BAR;
;             PG8_LDA(At, 0, 1); PG8_STAGE(PG8_SA(0, 0), a2, voffA);
;             PG8_BAR; PG8_WAIT_L(0); PG8_MMA(1, 0, At, B0); PG8_BAR; PG8_SCHED;
;             PG8_STAGE(PG8_SB(0, 1), b2 + hstepB, voffB);
;             PG8_WAIT_V(6); PG8_BAR; PG8_MMA(1, 1, At, B1); PG8_BAR;
;             PG8_LDB(B0, 1, 0); PG8_SCHED; PG8_LDA(At, 1, 0); PG8_STAGE(PG8_SA(0, 1), a2 + hstepA, voffA);
;             PG8_WAIT_L(8); PG8_BAR; PG8_WAIT_L(0); PG8_MMA(0, 0, At, B0); PG8_BAR; PG8_SCHED;
;             PG8_LDB(B1, 1, 1); PG8_STAGE(PG8_SB(1, 0), b3, voffB);
;             PG8_BAR; PG8_WAIT_L(0); PG8_MMA(0, 1, At, B1); PG8_BAR;
;             PG8_LDA(At, 1, 1); PG8_STAGE(PG8_SA(1, 0), a3, voffA);
;             PG8_BAR; PG8_WAIT_L(0); PG8_MMA(1, 0, At, B0); PG8_BAR; PG8_SCHED;
;             PG8_STAGE(PG8_SB(1, 1), b3 + hstepB, voffB);
;             PG8_WAIT_V(6); PG8_BAR; PG8_MMA(1, 1, At, B1); PG8_BAR;
	v_mfma_f32_16x16x32_bf16 v[56:59], v[132:135], v[148:151], 0
	v_mfma_f32_16x16x32_bf16 v[52:55], v[140:143], v[148:151], 0
	v_mfma_f32_16x16x32_bf16 v[48:51], v[132:135], v[156:159], 0
	v_mfma_f32_16x16x32_bf16 v[44:47], v[140:143], v[156:159], 0
	v_mfma_f32_16x16x32_bf16 v[40:43], v[132:135], v[164:167], 0
	v_mfma_f32_16x16x32_bf16 v[36:39], v[140:143], v[164:167], 0
	v_mfma_f32_16x16x32_bf16 v[32:35], v[132:135], v[186:189], 0
	v_mfma_f32_16x16x32_bf16 v[28:31], v[140:143], v[186:189], 0
	v_mfma_f32_16x16x32_bf16 v[56:59], v[136:139], v[152:155], v[56:59]
	v_mfma_f32_16x16x32_bf16 v[52:55], v[144:147], v[152:155], v[52:55]
	v_mfma_f32_16x16x32_bf16 v[48:51], v[136:139], v[160:163], v[48:51]
	v_mfma_f32_16x16x32_bf16 v[44:47], v[144:147], v[160:163], v[44:47]
	v_mfma_f32_16x16x32_bf16 v[40:43], v[136:139], v[168:171], v[40:43]
	v_mfma_f32_16x16x32_bf16 v[36:39], v[144:147], v[168:171], v[36:39]
	v_mfma_f32_16x16x32_bf16 v[32:35], v[136:139], v[190:193], v[32:35]
	v_mfma_f32_16x16x32_bf16 v[28:31], v[144:147], v[190:193], v[28:31]
	v_mfma_f32_16x16x32_bf16 v[24:27], v[194:197], v[148:151], 0
	v_mfma_f32_16x16x32_bf16 v[20:23], v[202:205], v[148:151], 0
	v_mfma_f32_16x16x32_bf16 v[16:19], v[194:197], v[156:159], 0
	v_mfma_f32_16x16x32_bf16 v[12:15], v[202:205], v[156:159], 0
	v_mfma_f32_16x16x32_bf16 v[8:11], v[194:197], v[164:167], 0
	v_mfma_f32_16x16x32_bf16 v[4:7], v[202:205], v[164:167], 0
	v_mfma_f32_16x16x32_bf16 v[60:63], v[194:197], v[186:189], 0
	v_mfma_f32_16x16x32_bf16 v[64:67], v[202:205], v[186:189], 0
	v_mfma_f32_16x16x32_bf16 v[24:27], v[198:201], v[152:155], v[24:27]
	v_mfma_f32_16x16x32_bf16 v[20:23], v[208:211], v[152:155], v[20:23]
	v_mfma_f32_16x16x32_bf16 v[16:19], v[198:201], v[160:163], v[16:19]
	v_mfma_f32_16x16x32_bf16 v[12:15], v[208:211], v[160:163], v[12:15]
	v_mfma_f32_16x16x32_bf16 v[8:11], v[198:201], v[168:171], v[8:11]
	v_mfma_f32_16x16x32_bf16 v[4:7], v[208:211], v[168:171], v[4:7]
	v_mfma_f32_16x16x32_bf16 v[60:63], v[198:201], v[190:193], v[60:63]
	v_mfma_f32_16x16x32_bf16 v[64:67], v[208:211], v[190:193], v[64:67]
	s_barrier
	s_add_i32 s72, 0, 0x18000
	v_add_u32_e32 v2, s72, v1
	ds_read_b128 v[132:135], v2
	ds_read_b128 v[136:139], v2 offset:1024
	ds_read_b128 v[140:143], v2 offset:2048
	ds_read_b128 v[144:147], v2 offset:3072
	s_add_u32 s14, s14, 0x80000
	s_addc_u32 s15, s15, 0
	ds_read_b128 v[148:151], v207 offset:32768
	ds_read_b128 v[152:155], v207 offset:33792
	ds_read_b128 v[156:159], v207 offset:34816
	ds_read_b128 v[160:163], v207 offset:35840
	ds_read_b128 v[164:167], v207 offset:36864
	ds_read_b128 v[168:171], v207 offset:37888
	ds_read_b128 v[186:189], v207 offset:38912
	ds_read_b128 v[190:193], v207 offset:39936
	s_mov_b32 m0, s24
	s_nop 0
	global_load_lds_dwordx4 v180, s[14:15]
	s_mov_b32 m0, s25
	s_nop 0
	global_load_lds_dwordx4 v176, s[14:15]
	s_add_i32 s14, 0, 0x1c000
	v_add_u32_e32 v2, s14, v1
	ds_read_b128 v[194:197], v2
	ds_read_b128 v[198:201], v2 offset:1024
	ds_read_b128 v[202:205], v2 offset:2048
	ds_read_b128 v[208:211], v2 offset:3072
	s_waitcnt lgkmcnt(0)
	s_barrier
	v_mfma_f32_16x16x32_bf16 v[68:71], v[132:135], v[148:151], v[68:71]
	v_mfma_f32_16x16x32_bf16 v[72:75], v[140:143], v[148:151], v[72:75]
	v_mfma_f32_16x16x32_bf16 v[120:123], v[132:135], v[156:159], v[120:123]
	v_mfma_f32_16x16x32_bf16 v[116:119], v[140:143], v[156:159], v[116:119]
	v_mfma_f32_16x16x32_bf16 v[112:115], v[132:135], v[164:167], v[112:115]
	v_mfma_f32_16x16x32_bf16 v[108:111], v[140:143], v[164:167], v[108:111]
	v_mfma_f32_16x16x32_bf16 v[104:107], v[132:135], v[186:189], v[104:107]
	v_mfma_f32_16x16x32_bf16 v[100:103], v[140:143], v[186:189], v[100:103]
	v_mfma_f32_16x16x32_bf16 v[68:71], v[136:139], v[152:155], v[68:71]
	v_mfma_f32_16x16x32_bf16 v[72:75], v[144:147], v[152:155], v[72:75]
	v_mfma_f32_16x16x32_bf16 v[120:123], v[136:139], v[160:163], v[120:123]
	v_mfma_f32_16x16x32_bf16 v[116:119], v[144:147], v[160:163], v[116:119]
	v_mfma_f32_16x16x32_bf16 v[112:115], v[136:139], v[168:171], v[112:115]
	v_mfma_f32_16x16x32_bf16 v[108:111], v[144:147], v[168:171], v[108:111]
	v_mfma_f32_16x16x32_bf16 v[104:107], v[136:139], v[190:193], v[104:107]
	v_mfma_f32_16x16x32_bf16 v[100:103], v[144:147], v[190:193], v[100:103]
	v_mfma_f32_16x16x32_bf16 v[76:79], v[194:197], v[148:151], v[76:79]
	v_mfma_f32_16x16x32_bf16 v[80:83], v[202:205], v[148:151], v[80:83]
	v_mfma_f32_16x16x32_bf16 v[96:99], v[194:197], v[156:159], v[96:99]
	v_mfma_f32_16x16x32_bf16 v[92:95], v[202:205], v[156:159], v[92:95]
	v_mfma_f32_16x16x32_bf16 v[88:91], v[194:197], v[164:167], v[88:91]
	v_mfma_f32_16x16x32_bf16 v[84:87], v[202:205], v[164:167], v[84:87]
	v_mfma_f32_16x16x32_bf16 v[128:131], v[194:197], v[186:189], v[128:131]
	v_mfma_f32_16x16x32_bf16 v[124:127], v[202:205], v[186:189], v[124:127]
	v_mfma_f32_16x16x32_bf16 v[76:79], v[198:201], v[152:155], v[76:79]
	v_mfma_f32_16x16x32_bf16 v[80:83], v[208:211], v[152:155], v[80:83]
	v_mfma_f32_16x16x32_bf16 v[96:99], v[198:201], v[160:163], v[96:99]
	v_mfma_f32_16x16x32_bf16 v[92:95], v[208:211], v[160:163], v[92:95]
	v_mfma_f32_16x16x32_bf16 v[88:91], v[198:201], v[168:171], v[88:91]
	v_mfma_f32_16x16x32_bf16 v[84:87], v[208:211], v[168:171], v[84:87]
	v_mfma_f32_16x16x32_bf16 v[128:131], v[198:201], v[190:193], v[128:131]
	v_mfma_f32_16x16x32_bf16 v[124:127], v[208:211], v[190:193], v[124:127]
	s_barrier
; #define PG8_STAGE(bufoff, gbase, voff) do { _Pragma("unroll") for (int _i = 0; _i < 2; ++_i) \
;         __builtin_amdgcn_global_load_lds((const unsigned*)((const char*)(gbase) + (voff)[_i]), (LAS unsigned*)(lds + (bufoff) + ldsw + _i * 8192), 16, 0, 0); } while (0)
; #define PG8_LDA(dst, b, h) do { _Pragma("unroll") for (int m = 0; m < 4; ++m) _Pragma("unroll") for (int k = 0; k < 2; ++k) dst[m][k] = *(const LAS bf16x8*)(lds + PG8_SA(b, h) + aoff + m * 2048 + k * 1024); } while (0)
; #define PG8_LDB(dst, b, h) do { _Pragma("unroll") for (int n = 0; n < 2; ++n) _Pragma("unroll") for (int k = 0; k < 2; ++k) dst[n][k] = *(const LAS bf16x8*)(lds + PG8_SB(b, h) + boff + n * 2048 + k * 1024); } while (0)
; #define PG8_MMA(ai, bj, At, Bt) do { __builtin_amdgcn_s_setprio(1); _Pragma("unroll") for (int m = 0; m < 4; ++m) _Pragma("unroll") for (int n = 0; n < 2; ++n) _Pragma("unroll") for (int k = 0; k < 2; ++k) \
;         acc[ai][bj][m][n] = __builtin_amdgcn_mfma_f32_16x16x32_bf16(Bt[n][k], At[m][k], acc[ai][bj][m][n], 0, 0, 0); __builtin_amdgcn_s_setprio(0); } while (0)
; #define PG8_WAIT_V(n) asm volatile("s_waitcnt vmcnt(" #n ")" ::: "memory")
; #define PG8_WAIT_L(n) asm volatile("s_waitcnt lgkmcnt(" #n ")" ::: "memory")
; #define PG8_BAR __builtin_amdgcn_s_barrier()
; #define PG8_SCHED __builtin_amdgcn_sched_barrier(0)
; template <class Epi, class Sched>
; __device__ __forceinline__ void gemm_phase(LAS unsigned char* lds, const Gemm g, const Sched& S, const Epi& E) {
;     ...
;             PG8_LDB(B0, 0, 0); PG8_SCHED; PG8_LDA(At, 0, 0); PG8_STAGE(PG8_SA(1, 1), a1 + hstepA, voffA);
;             PG8_WAIT_L(8); PG8_BAR; PG8_WAIT_L(0); PG8_MMA(0, 0, At, B0); PG8_BAR; PG8_SCHED;
;     ...
;             PG8_LDB(B0, 1, 0); PG8_SCHED; PG8_LDA(At, 1, 0); PG8_STAGE(PG8_SA(0, 1), a2 + hstepA, voffA);
;             PG8_WAIT_L(8); PG8_BAR; PG8_WAIT_L(0); PG8_MMA(0, 0, At, B0); PG8_BAR; PG8_SCHED;
;             PG8_LDB(B1, 1, 1); PG8_STAGE(PG8_SB(1, 0), b3, voffB);
;             PG8_BAR; PG8_WAIT_L(0); PG8_MMA(0, 1, At, B1); PG8_BAR;
;             PG8_LDA(At, 1, 1); PG8_STAGE(PG8_SA(1, 0), a3, voffA);
;             PG8_BAR; PG8_WAIT_L(0); PG8_MMA(1, 0, At, B0); PG8_BAR; PG8_SCHED;
;             PG8_STAGE(PG8_SB(1, 1), b3 + hstepB, voffB);
;             PG8_WAIT_V(6); PG8_BAR; PG8_MMA(1, 1, At, B1); PG8_BAR;
	ds_read_b128 v[148:151], v207 offset:49152
	ds_read_b128 v[152:155], v207 offset:50176
	ds_read_b128 v[156:159], v207 offset:51200
	ds_read_b128 v[160:163], v207 offset:52224
	ds_read_b128 v[164:167], v207 offset:53248
	ds_read_b128 v[168:171], v207 offset:54272
	ds_read_b128 v[186:189], v207 offset:55296
	ds_read_b128 v[190:193], v207 offset:56320
	s_add_i32 s15, s72, s19
	v_lshl_add_u64 v[172:173], v[172:173], 0, s[8:9]
	s_mov_b32 m0, s15
	s_nop 0
	global_load_lds_dwordx4 v[172:173], off
	v_lshl_add_u64 v[172:173], v[212:213], 0, s[8:9]
	s_add_i32 m0, s15, 0x2000
	s_nop 0
	global_load_lds_dwordx4 v[172:173], off
	s_mov_b32 m0, s30
	v_lshl_add_u64 v[172:173], v[216:217], 0, s[8:9]
	global_load_lds_dwordx4 v[172:173], off
	v_lshl_add_u64 v[172:173], v[218:219], 0, s[8:9]
	s_mov_b32 m0, s31
	s_nop 0
	global_load_lds_dwordx4 v[172:173], off
	s_add_u32 s6, s6, 0x80080
	s_addc_u32 s7, s7, 0
	s_add_i32 s14, s14, s19
	s_mov_b32 m0, s14
	s_nop 0
	global_load_lds_dwordx4 v178, s[6:7]
	s_add_i32 m0, s14, 0x2000
	s_nop 0
	global_load_lds_dwordx4 v174, s[6:7]
	s_add_i32 s71, s71, 2
	s_add_u32 s4, s4, 0x100
	s_addc_u32 s5, s5, 0
	s_add_u32 s69, s69, 0x100
	s_addc_u32 s70, s70, 0
	s_cmp_gt_u32 s71, 29
	s_waitcnt lgkmcnt(0)
	s_waitcnt vmcnt(6)
	s_barrier
	v_mfma_f32_16x16x32_bf16 v[56:59], v[132:135], v[148:151], v[56:59]
	v_mfma_f32_16x16x32_bf16 v[52:55], v[140:143], v[148:151], v[52:55]
	v_mfma_f32_16x16x32_bf16 v[48:51], v[132:135], v[156:159], v[48:51]
	v_mfma_f32_16x16x32_bf16 v[44:47], v[140:143], v[156:159], v[44:47]
	v_mfma_f32_16x16x32_bf16 v[40:43], v[132:135], v[164:167], v[40:43]
	v_mfma_f32_16x16x32_bf16 v[36:39], v[140:143], v[164:167], v[36:39]
	v_mfma_f32_16x16x32_bf16 v[32:35], v[132:135], v[186:189], v[32:35]
	v_mfma_f32_16x16x32_bf16 v[28:31], v[140:143], v[186:189], v[28:31]
	v_mfma_f32_16x16x32_bf16 v[56:59], v[136:139], v[152:155], v[56:59]
	v_mfma_f32_16x16x32_bf16 v[52:55], v[144:147], v[152:155], v[52:55]
	v_mfma_f32_16x16x32_bf16 v[48:51], v[136:139], v[160:163], v[48:51]
	v_mfma_f32_16x16x32_bf16 v[44:47], v[144:147], v[160:163], v[44:47]
	v_mfma_f32_16x16x32_bf16 v[40:43], v[136:139], v[168:171], v[40:43]
	v_mfma_f32_16x16x32_bf16 v[36:39], v[144:147], v[168:171], v[36:39]
	v_mfma_f32_16x16x32_bf16 v[32:35], v[136:139], v[190:193], v[32:35]
	v_mfma_f32_16x16x32_bf16 v[28:31], v[144:147], v[190:193], v[28:31]
	v_mfma_f32_16x16x32_bf16 v[24:27], v[194:197], v[148:151], v[24:27]
	v_mfma_f32_16x16x32_bf16 v[20:23], v[202:205], v[148:151], v[20:23]
	v_mfma_f32_16x16x32_bf16 v[16:19], v[194:197], v[156:159], v[16:19]
	v_mfma_f32_16x16x32_bf16 v[12:15], v[202:205], v[156:159], v[12:15]
	v_mfma_f32_16x16x32_bf16 v[8:11], v[194:197], v[164:167], v[8:11]
	v_mfma_f32_16x16x32_bf16 v[4:7], v[202:205], v[164:167], v[4:7]
	v_mfma_f32_16x16x32_bf16 v[60:63], v[194:197], v[186:189], v[60:63]
	v_mfma_f32_16x16x32_bf16 v[64:67], v[202:205], v[186:189], v[64:67]
	v_mfma_f32_16x16x32_bf16 v[24:27], v[198:201], v[152:155], v[24:27]
	v_mfma_f32_16x16x32_bf16 v[20:23], v[208:211], v[152:155], v[20:23]
	v_mfma_f32_16x16x32_bf16 v[16:19], v[198:201], v[160:163], v[16:19]
	v_mfma_f32_16x16x32_bf16 v[12:15], v[208:211], v[160:163], v[12:15]
	v_mfma_f32_16x16x32_bf16 v[8:11], v[198:201], v[168:171], v[8:11]
	v_mfma_f32_16x16x32_bf16 v[4:7], v[208:211], v[168:171], v[4:7]
	v_mfma_f32_16x16x32_bf16 v[60:63], v[198:201], v[190:193], v[60:63]
	v_mfma_f32_16x16x32_bf16 v[64:67], v[208:211], v[190:193], v[64:67]
	s_barrier
	s_setprio 0
.LBB0_1526:
	s_add_u32 s6, s4, 0xfff80080
	s_addc_u32 s7, s5, -1
	s_add_i32 s72, 0, 0x10000
	v_add_u32_e32 v2, s72, v1
	ds_read_b128 v[132:135], v2
	ds_read_b128 v[136:139], v2 offset:1024
	ds_read_b128 v[140:143], v2 offset:2048
	ds_read_b128 v[144:147], v2 offset:3072
	s_cmp_eq_u32 s71, 28
	s_cselect_b32 s15, s57, s7
	s_cselect_b32 s14, s67, s6
	s_cselect_b32 s7, s55, s70
	s_cselect_b32 s6, s68, s69
	ds_read_b128 v[148:151], v207
	ds_read_b128 v[152:155], v207 offset:1024
	ds_read_b128 v[156:159], v207 offset:2048
	ds_read_b128 v[160:163], v207 offset:3072
	ds_read_b128 v[164:167], v207 offset:4096
	ds_read_b128 v[168:171], v207 offset:5120
	ds_read_b128 v[186:189], v207 offset:6144
	ds_read_b128 v[190:193], v207 offset:7168
	s_add_i32 s74, 0, 0x14000
	v_add_u32_e32 v2, s74, v1
	ds_read_b128 v[194:197], v2
	ds_read_b128 v[198:201], v2 offset:1024
	ds_read_b128 v[202:205], v2 offset:2048
	ds_read_b128 v[208:211], v2 offset:3072
	s_add_i32 m0, s20, 0xc000
	s_nop 0
	global_load_lds_dwordx4 v182, s[4:5]
	s_add_i32 m0, s20, 0xe000
	s_nop 0
	global_load_lds_dwordx4 v184, s[4:5]
	s_waitcnt lgkmcnt(0)
	s_barrier
; #define PG8_STAGE(bufoff, gbase, voff) do { _Pragma("unroll") for (int _i = 0; _i < 2; ++_i) \
;         __builtin_amdgcn_global_load_lds((const unsigned*)((const char*)(gbase) + (voff)[_i]), (LAS unsigned*)(lds + (bufoff) + ldsw + _i * 8192), 16, 0, 0); } while (0)
; #define PG8_LDA(dst, b, h) do { _Pragma("unroll") for (int m = 0; m < 4; ++m) _Pragma("unroll") for (int k = 0; k < 2; ++k) dst[m][k] = *(const LAS bf16x8*)(lds + PG8_SA(b, h) + aoff + m * 2048 + k * 1024); } while (0)
; #define PG8_LDB(dst, b, h) do { _Pragma("unroll") for (int n = 0; n < 2; ++n) _Pragma("unroll") for (int k = 0; k < 2; ++k) dst[n][k] = *(const LAS bf16x8*)(lds + PG8_SB(b, h) + boff + n * 2048 + k * 1024); } while (0)
; #define PG8_MMA(ai, bj, At, Bt) do { __builtin_amdgcn_s_setprio(1); _Pragma("unroll") for (int m = 0; m < 4; ++m) _Pragma("unroll") for (int n = 0; n < 2; ++n) _Pragma("unroll") for (int k = 0; k < 2; ++k) \
;         acc[ai][bj][m][n] = __builtin_amdgcn_mfma_f32_16x16x32_bf16(Bt[n][k], At[m][k], acc[ai][bj][m][n], 0, 0, 0); __builtin_amdgcn_s_setprio(0); } while (0)
; #define PG8_WAIT_V(n) asm volatile("s_waitcnt vmcnt(" #n ")" ::: "memory")
; #define PG8_WAIT_L(n) asm volatile("s_waitcnt lgkmcnt(" #n ")" ::: "memory")
; #define PG8_BAR __builtin_amdgcn_s_barrier()
; #define PG8_SCHED __builtin_amdgcn_sched_barrier(0)
; template <class Epi, class Sched>
; __device__ __forceinline__ void gemm_phase(LAS unsigned char* lds, const Gemm g, const Sched& S, const Epi& E) {
;     ...
;             PG8_WAIT_L(8); PG8_BAR; PG8_WAIT_L(0); PG8_MMA(0, 0, At, B0); PG8_BAR; PG8_SCHED;
;             PG8_LDB(B1, 0, 1); PG8_STAGE(PG8_SB(0, 0), b2, voffB);
;             PG8_BAR; PG8_WAIT_L(0); PG8_MMA(0, 1, At, B1); PG8_BAR;
;             PG8_LDA(At, 0, 1); PG8_STAGE(PG8_SA(0, 0), a2, voffA);
;             PG8_BAR; PG8_WAIT_L(0); PG8_MMA(1, 0, At, B0); PG8_BAR; PG8_SCHED;
;             PG8_STAGE(PG8_SB(0, 1), b2 + hstepB, voffB);
;             PG8_WAIT_V(6); PG8_BAR; PG8_MMA(1, 1, At, B1); PG8_BAR;
;             PG8_LDB(B0, 1, 0); PG8_SCHED; PG8_LDA(At, 1, 0); PG8_STAGE(PG8_SA(0, 1), a2 + hstepA, voffA);
;             PG8_WAIT_L(8); PG8_BAR; PG8_WAIT_L(0); PG8_MMA(0, 0, At, B0); PG8_BAR; PG8_SCHED;
	v_mfma_f32_16x16x32_bf16 v[68:71], v[132:135], v[148:151], v[68:71]
	v_mfma_f32_16x16x32_bf16 v[72:75], v[140:143], v[148:151], v[72:75]
	v_mfma_f32_16x16x32_bf16 v[120:123], v[132:135], v[156:159], v[120:123]
	v_mfma_f32_16x16x32_bf16 v[116:119], v[140:143], v[156:159], v[116:119]
	v_mfma_f32_16x16x32_bf16 v[112:115], v[132:135], v[164:167], v[112:115]
	v_mfma_f32_16x16x32_bf16 v[108:111], v[140:143], v[164:167], v[108:111]
	v_mfma_f32_16x16x32_bf16 v[104:107], v[132:135], v[186:189], v[104:107]
	v_mfma_f32_16x16x32_bf16 v[100:103], v[140:143], v[186:189], v[100:103]
	v_mfma_f32_16x16x32_bf16 v[68:71], v[136:139], v[152:155], v[68:71]
	v_mfma_f32_16x16x32_bf16 v[72:75], v[144:147], v[152:155], v[72:75]
	v_mfma_f32_16x16x32_bf16 v[120:123], v[136:139], v[160:163], v[120:123]
	v_mfma_f32_16x16x32_bf16 v[116:119], v[144:147], v[160:163], v[116:119]
	v_mfma_f32_16x16x32_bf16 v[112:115], v[136:139], v[168:171], v[112:115]
	v_mfma_f32_16x16x32_bf16 v[108:111], v[144:147], v[168:171], v[108:111]
	v_mfma_f32_16x16x32_bf16 v[104:107], v[136:139], v[190:193], v[104:107]
	v_mfma_f32_16x16x32_bf16 v[100:103], v[144:147], v[190:193], v[100:103]
	v_mfma_f32_16x16x32_bf16 v[76:79], v[194:197], v[148:151], v[76:79]
	v_mfma_f32_16x16x32_bf16 v[80:83], v[202:205], v[148:151], v[80:83]
	v_mfma_f32_16x16x32_bf16 v[96:99], v[194:197], v[156:159], v[96:99]
	v_mfma_f32_16x16x32_bf16 v[92:95], v[202:205], v[156:159], v[92:95]
	v_mfma_f32_16x16x32_bf16 v[88:91], v[194:197], v[164:167], v[88:91]
	v_mfma_f32_16x16x32_bf16 v[84:87], v[202:205], v[164:167], v[84:87]
	v_mfma_f32_16x16x32_bf16 v[128:131], v[194:197], v[186:189], v[128:131]
	v_mfma_f32_16x16x32_bf16 v[124:127], v[202:205], v[186:189], v[124:127]
	v_mfma_f32_16x16x32_bf16 v[76:79], v[198:201], v[152:155], v[76:79]
	v_mfma_f32_16x16x32_bf16 v[80:83], v[208:211], v[152:155], v[80:83]
	v_mfma_f32_16x16x32_bf16 v[96:99], v[198:201], v[160:163], v[96:99]
	v_mfma_f32_16x16x32_bf16 v[92:95], v[208:211], v[160:163], v[92:95]
	v_mfma_f32_16x16x32_bf16 v[88:91], v[198:201], v[168:171], v[88:91]
	v_mfma_f32_16x16x32_bf16 v[84:87], v[208:211], v[168:171], v[84:87]
	v_mfma_f32_16x16x32_bf16 v[128:131], v[198:201], v[190:193], v[128:131]
	v_mfma_f32_16x16x32_bf16 v[124:127], v[208:211], v[190:193], v[124:127]
	s_barrier
	ds_read_b128 v[148:151], v207 offset:16384
	ds_read_b128 v[152:155], v207 offset:17408
	ds_read_b128 v[156:159], v207 offset:18432
	ds_read_b128 v[160:163], v207 offset:19456
	ds_read_b128 v[164:167], v207 offset:20480
	ds_read_b128 v[168:171], v207 offset:21504
	ds_read_b128 v[186:189], v207 offset:22528
	ds_read_b128 v[190:193], v207 offset:23552
	s_add_i32 s72, s72, s19
	v_lshl_add_u64 v[172:173], s[6:7], 0, v[178:179]
	s_mov_b32 m0, s72
	s_nop 0
	global_load_lds_dwordx4 v[172:173], off
	v_lshl_add_u64 v[212:213], s[6:7], 0, v[174:175]
	s_add_i32 m0, s72, 0x2000
	s_nop 0
	global_load_lds_dwordx4 v[212:213], off
	s_mov_b32 m0, s20
	v_lshl_add_u64 v[216:217], s[14:15], 0, v[180:181]
	global_load_lds_dwordx4 v[216:217], off
	v_lshl_add_u64 v[218:219], s[14:15], 0, v[176:177]
	s_mov_b32 m0, s21
	s_nop 0
	global_load_lds_dwordx4 v[218:219], off
	s_add_u32 s72, s6, 0x80000
	s_addc_u32 s73, s7, 0
	s_add_i32 s74, s74, s19
	s_mov_b32 m0, s74
	s_nop 0
	global_load_lds_dwordx4 v178, s[72:73]
	s_add_i32 m0, s74, 0x2000
	s_nop 0
	global_load_lds_dwordx4 v174, s[72:73]
	s_waitcnt lgkmcnt(0)
	s_waitcnt vmcnt(6)
	s_barrier
	v_mfma_f32_16x16x32_bf16 v[56:59], v[132:135], v[148:151], v[56:59]
	v_mfma_f32_16x16x32_bf16 v[52:55], v[140:143], v[148:151], v[52:55]
	v_mfma_f32_16x16x32_bf16 v[48:51], v[132:135], v[156:159], v[48:51]
	v_mfma_f32_16x16x32_bf16 v[44:47], v[140:143], v[156:159], v[44:47]
	v_mfma_f32_16x16x32_bf16 v[40:43], v[132:135], v[164:167], v[40:43]
	v_mfma_f32_16x16x32_bf16 v[36:39], v[140:143], v[164:167], v[36:39]
	v_mfma_f32_16x16x32_bf16 v[32:35], v[132:135], v[186:189], v[32:35]
	v_mfma_f32_16x16x32_bf16 v[28:31], v[140:143], v[186:189], v[28:31]
	v_mfma_f32_16x16x32_bf16 v[56:59], v[136:139], v[152:155], v[56:59]
	v_mfma_f32_16x16x32_bf16 v[52:55], v[144:147], v[152:155], v[52:55]
	v_mfma_f32_16x16x32_bf16 v[48:51], v[136:139], v[160:163], v[48:51]
	v_mfma_f32_16x16x32_bf16 v[44:47], v[144:147], v[160:163], v[44:47]
	v_mfma_f32_16x16x32_bf16 v[40:43], v[136:139], v[168:171], v[40:43]
	v_mfma_f32_16x16x32_bf16 v[36:39], v[144:147], v[168:171], v[36:39]
	v_mfma_f32_16x16x32_bf16 v[32:35], v[136:139], v[190:193], v[32:35]
	v_mfma_f32_16x16x32_bf16 v[28:31], v[144:147], v[190:193], v[28:31]
	v_mfma_f32_16x16x32_bf16 v[24:27], v[194:197], v[148:151], v[24:27]
	v_mfma_f32_16x16x32_bf16 v[20:23], v[202:205], v[148:151], v[20:23]
	v_mfma_f32_16x16x32_bf16 v[16:19], v[194:197], v[156:159], v[16:19]
	v_mfma_f32_16x16x32_bf16 v[12:15], v[202:205], v[156:159], v[12:15]
	v_mfma_f32_16x16x32_bf16 v[8:11], v[194:197], v[164:167], v[8:11]
	v_mfma_f32_16x16x32_bf16 v[4:7], v[202:205], v[164:167], v[4:7]
	v_mfma_f32_16x16x32_bf16 v[60:63], v[194:197], v[186:189], v[60:63]
	v_mfma_f32_16x16x32_bf16 v[64:67], v[202:205], v[186:189], v[64:67]
	v_mfma_f32_16x16x32_bf16 v[24:27], v[198:201], v[152:155], v[24:27]
	v_mfma_f32_16x16x32_bf16 v[20:23], v[208:211], v[152:155], v[20:23]
	v_mfma_f32_16x16x32_bf16 v[16:19], v[198:201], v[160:163], v[16:19]
	v_mfma_f32_16x16x32_bf16 v[12:15], v[208:211], v[160:163], v[12:15]
	v_mfma_f32_16x16x32_bf16 v[8:11], v[198:201], v[168:171], v[8:11]
	v_mfma_f32_16x16x32_bf16 v[4:7], v[208:211], v[168:171], v[4:7]
	v_mfma_f32_16x16x32_bf16 v[60:63], v[198:201], v[190:193], v[60:63]
	v_mfma_f32_16x16x32_bf16 v[64:67], v[208:211], v[190:193], v[64:67]
	s_barrier
; #define PG8_STAGE(bufoff, gbase, voff) do { _Pragma("unroll") for (int _i = 0; _i < 2; ++_i) \
;         __builtin_amdgcn_global_load_lds((const unsigned*)((const char*)(gbase) + (voff)[_i]), (LAS unsigned*)(lds + (bufoff) + ldsw + _i * 8192), 16, 0, 0); } while (0)
; #define PG8_LDA(dst, b, h) do { _Pragma("unroll") for (int m = 0; m < 4; ++m) _Pragma("unroll") for (int k = 0; k < 2; ++k) dst[m][k] = *(const LAS bf16x8*)(lds + PG8_SA(b, h) + aoff + m * 2048 + k * 1024); } while (0)
; #define PG8_LDB(dst, b, h) do { _Pragma("unroll") for (int n = 0; n < 2; ++n) _Pragma("unroll") for (int k = 0; k < 2; ++k) dst[n][k] = *(const LAS bf16x8*)(lds + PG8_SB(b, h) + boff + n * 2048 + k * 1024); } while (0)
; #define PG8_MMA(ai, bj, At, Bt) do { __builtin_amdgcn_s_setprio(1); _Pragma("unroll") for (int m = 0; m < 4; ++m) _Pragma("unroll") for (int n = 0; n < 2; ++n) _Pragma("unroll") for (int k = 0; k < 2; ++k) \
;         acc[ai][bj][m][n] = __builtin_amdgcn_mfma_f32_16x16x32_bf16(Bt[n][k], At[m][k], acc[ai][bj][m][n], 0, 0, 0); __builtin_amdgcn_s_setprio(0); } while (0)
; #define PG8_WAIT_V(n) asm volatile("s_waitcnt vmcnt(" #n ")" ::: "memory")
; #define PG8_WAIT_L(n) asm volatile("s_waitcnt lgkmcnt(" #n ")" ::: "memory")
; #define PG8_BAR __builtin_amdgcn_s_barrier()
; #define PG8_SCHED __builtin_amdgcn_sched_barrier(0)
; template <class Epi, class Sched>
; __device__ __forceinline__ void gemm_phase(LAS unsigned char* lds, const Gemm g, const Sched& S, const Epi& E) {
;     ...
;             PG8_LDB(B1, 1, 1); PG8_STAGE(PG8_SB(1, 0), b3, voffB);
;             PG8_BAR; PG8_WAIT_L(0); PG8_MMA(0, 1, At, B1); PG8_BAR;
;             PG8_LDA(At, 1, 1); PG8_STAGE(PG8_SA(1, 0), a3, voffA);
;             PG8_BAR; PG8_WAIT_L(0); PG8_MMA(1, 0, At, B0); PG8_BAR; PG8_SCHED;
;             PG8_STAGE(PG8_SB(1, 1), b3 + hstepB, voffB);
;             PG8_WAIT_V(6); PG8_BAR; PG8_MMA(1, 1, At, B1); PG8_BAR;
;         }
;         E(acc, cur, wr, wc, ui, fq);
	s_add_i32 s72, 0, 0x18000
	v_add_u32_e32 v2, s72, v1
	ds_read_b128 v[132:135], v2
	ds_read_b128 v[136:139], v2 offset:1024
	ds_read_b128 v[140:143], v2 offset:2048
	ds_read_b128 v[144:147], v2 offset:3072
	s_add_u32 s14, s14, 0x80000
	s_addc_u32 s15, s15, 0
	ds_read_b128 v[148:151], v207 offset:32768
	ds_read_b128 v[152:155], v207 offset:33792
	ds_read_b128 v[156:159], v207 offset:34816
	ds_read_b128 v[160:163], v207 offset:35840
	ds_read_b128 v[164:167], v207 offset:36864
	ds_read_b128 v[168:171], v207 offset:37888
	ds_read_b128 v[186:189], v207 offset:38912
	ds_read_b128 v[190:193], v207 offset:39936
	s_mov_b32 m0, s24
	s_nop 0
	global_load_lds_dwordx4 v180, s[14:15]
	s_mov_b32 m0, s25
	s_nop 0
	global_load_lds_dwordx4 v176, s[14:15]
	s_add_i32 s14, 0, 0x1c000
	v_add_u32_e32 v2, s14, v1
	ds_read_b128 v[194:197], v2
	ds_read_b128 v[198:201], v2 offset:1024
	ds_read_b128 v[202:205], v2 offset:2048
	ds_read_b128 v[208:211], v2 offset:3072
	s_waitcnt lgkmcnt(0)
	s_barrier
	v_mfma_f32_16x16x32_bf16 v[68:71], v[132:135], v[148:151], v[68:71]
	v_mfma_f32_16x16x32_bf16 v[72:75], v[140:143], v[148:151], v[72:75]
	v_mfma_f32_16x16x32_bf16 v[120:123], v[132:135], v[156:159], v[120:123]
	v_mfma_f32_16x16x32_bf16 v[116:119], v[140:143], v[156:159], v[116:119]
	v_mfma_f32_16x16x32_bf16 v[112:115], v[132:135], v[164:167], v[112:115]
	v_mfma_f32_16x16x32_bf16 v[108:111], v[140:143], v[164:167], v[108:111]
	v_mfma_f32_16x16x32_bf16 v[104:107], v[132:135], v[186:189], v[104:107]
	v_mfma_f32_16x16x32_bf16 v[100:103], v[140:143], v[186:189], v[100:103]
	v_mfma_f32_16x16x32_bf16 v[68:71], v[136:139], v[152:155], v[68:71]
	v_mfma_f32_16x16x32_bf16 v[72:75], v[144:147], v[152:155], v[72:75]
	v_mfma_f32_16x16x32_bf16 v[120:123], v[136:139], v[160:163], v[120:123]
	v_mfma_f32_16x16x32_bf16 v[116:119], v[144:147], v[160:163], v[116:119]
	v_mfma_f32_16x16x32_bf16 v[112:115], v[136:139], v[168:171], v[112:115]
	v_mfma_f32_16x16x32_bf16 v[108:111], v[144:147], v[168:171], v[108:111]
	v_mfma_f32_16x16x32_bf16 v[104:107], v[136:139], v[190:193], v[104:107]
	v_mfma_f32_16x16x32_bf16 v[100:103], v[144:147], v[190:193], v[100:103]
	v_mfma_f32_16x16x32_bf16 v[76:79], v[194:197], v[148:151], v[76:79]
	v_mfma_f32_16x16x32_bf16 v[80:83], v[202:205], v[148:151], v[80:83]
	v_mfma_f32_16x16x32_bf16 v[96:99], v[194:197], v[156:159], v[96:99]
	v_mfma_f32_16x16x32_bf16 v[92:95], v[202:205], v[156:159], v[92:95]
	v_mfma_f32_16x16x32_bf16 v[88:91], v[194:197], v[164:167], v[88:91]
	v_mfma_f32_16x16x32_bf16 v[84:87], v[202:205], v[164:167], v[84:87]
	v_mfma_f32_16x16x32_bf16 v[128:131], v[194:197], v[186:189], v[128:131]
	v_mfma_f32_16x16x32_bf16 v[124:127], v[202:205], v[186:189], v[124:127]
	v_mfma_f32_16x16x32_bf16 v[76:79], v[198:201], v[152:155], v[76:79]
	v_mfma_f32_16x16x32_bf16 v[80:83], v[208:211], v[152:155], v[80:83]
	v_mfma_f32_16x16x32_bf16 v[96:99], v[198:201], v[160:163], v[96:99]
	v_mfma_f32_16x16x32_bf16 v[92:95], v[208:211], v[160:163], v[92:95]
	v_mfma_f32_16x16x32_bf16 v[88:91], v[198:201], v[168:171], v[88:91]
	v_mfma_f32_16x16x32_bf16 v[84:87], v[208:211], v[168:171], v[84:87]
	v_mfma_f32_16x16x32_bf16 v[128:131], v[198:201], v[190:193], v[128:131]
	v_mfma_f32_16x16x32_bf16 v[124:127], v[208:211], v[190:193], v[124:127]
	s_barrier
	ds_read_b128 v[148:151], v207 offset:49152
	ds_read_b128 v[152:155], v207 offset:50176
	ds_read_b128 v[156:159], v207 offset:51200
	ds_read_b128 v[160:163], v207 offset:52224
	ds_read_b128 v[164:167], v207 offset:53248
	ds_read_b128 v[168:171], v207 offset:54272
	ds_read_b128 v[186:189], v207 offset:55296
	ds_read_b128 v[190:193], v207 offset:56320
	s_add_i32 s15, s72, s19
	v_lshl_add_u64 v[172:173], v[172:173], 0, s[8:9]
	s_mov_b32 m0, s15
	s_nop 0
	global_load_lds_dwordx4 v[172:173], off
	v_lshl_add_u64 v[172:173], v[212:213], 0, s[8:9]
	s_add_i32 m0, s15, 0x2000
	s_nop 0
	global_load_lds_dwordx4 v[172:173], off
	s_mov_b32 m0, s30
	v_lshl_add_u64 v[172:173], v[216:217], 0, s[8:9]
	global_load_lds_dwordx4 v[172:173], off
	v_lshl_add_u64 v[172:173], v[218:219], 0, s[8:9]
	s_mov_b32 m0, s31
	s_nop 0
	global_load_lds_dwordx4 v[172:173], off
	s_add_u32 s6, s6, 0x80080
	s_addc_u32 s7, s7, 0
	s_add_i32 s14, s14, s19
	s_mov_b32 m0, s14
	s_nop 0
	global_load_lds_dwordx4 v178, s[6:7]
	s_add_i32 m0, s14, 0x2000
	s_nop 0
	global_load_lds_dwordx4 v174, s[6:7]
	s_add_i32 s71, s71, 2
	s_add_u32 s4, s4, 0x100
	s_addc_u32 s5, s5, 0
	s_add_u32 s69, s69, 0x100
	s_addc_u32 s70, s70, 0
	s_cmp_gt_u32 s71, 29
	s_waitcnt lgkmcnt(0)
	s_waitcnt vmcnt(6)
	s_barrier
	v_mfma_f32_16x16x32_bf16 v[56:59], v[132:135], v[148:151], v[56:59]
	v_mfma_f32_16x16x32_bf16 v[52:55], v[140:143], v[148:151], v[52:55]
	v_mfma_f32_16x16x32_bf16 v[48:51], v[132:135], v[156:159], v[48:51]
	v_mfma_f32_16x16x32_bf16 v[44:47], v[140:143], v[156:159], v[44:47]
	v_mfma_f32_16x16x32_bf16 v[40:43], v[132:135], v[164:167], v[40:43]
	v_mfma_f32_16x16x32_bf16 v[36:39], v[140:143], v[164:167], v[36:39]
	v_mfma_f32_16x16x32_bf16 v[32:35], v[132:135], v[186:189], v[32:35]
	v_mfma_f32_16x16x32_bf16 v[28:31], v[140:143], v[186:189], v[28:31]
	v_mfma_f32_16x16x32_bf16 v[56:59], v[136:139], v[152:155], v[56:59]
	v_mfma_f32_16x16x32_bf16 v[52:55], v[144:147], v[152:155], v[52:55]
	v_mfma_f32_16x16x32_bf16 v[48:51], v[136:139], v[160:163], v[48:51]
	v_mfma_f32_16x16x32_bf16 v[44:47], v[144:147], v[160:163], v[44:47]
	v_mfma_f32_16x16x32_bf16 v[40:43], v[136:139], v[168:171], v[40:43]
	v_mfma_f32_16x16x32_bf16 v[36:39], v[144:147], v[168:171], v[36:39]
	v_mfma_f32_16x16x32_bf16 v[32:35], v[136:139], v[190:193], v[32:35]
	v_mfma_f32_16x16x32_bf16 v[28:31], v[144:147], v[190:193], v[28:31]
	v_mfma_f32_16x16x32_bf16 v[24:27], v[194:197], v[148:151], v[24:27]
	v_mfma_f32_16x16x32_bf16 v[20:23], v[202:205], v[148:151], v[20:23]
	v_mfma_f32_16x16x32_bf16 v[16:19], v[194:197], v[156:159], v[16:19]
	v_mfma_f32_16x16x32_bf16 v[12:15], v[202:205], v[156:159], v[12:15]
	v_mfma_f32_16x16x32_bf16 v[8:11], v[194:197], v[164:167], v[8:11]
	v_mfma_f32_16x16x32_bf16 v[4:7], v[202:205], v[164:167], v[4:7]
	v_mfma_f32_16x16x32_bf16 v[60:63], v[194:197], v[186:189], v[60:63]
	v_mfma_f32_16x16x32_bf16 v[64:67], v[202:205], v[186:189], v[64:67]
	v_mfma_f32_16x16x32_bf16 v[24:27], v[198:201], v[152:155], v[24:27]
	v_mfma_f32_16x16x32_bf16 v[20:23], v[208:211], v[152:155], v[20:23]
	v_mfma_f32_16x16x32_bf16 v[16:19], v[198:201], v[160:163], v[16:19]
	v_mfma_f32_16x16x32_bf16 v[12:15], v[208:211], v[160:163], v[12:15]
	v_mfma_f32_16x16x32_bf16 v[8:11], v[198:201], v[168:171], v[8:11]
	v_mfma_f32_16x16x32_bf16 v[4:7], v[208:211], v[168:171], v[4:7]
	v_mfma_f32_16x16x32_bf16 v[60:63], v[198:201], v[190:193], v[60:63]
	v_mfma_f32_16x16x32_bf16 v[64:67], v[208:211], v[190:193], v[64:67]
	s_barrier
	s_cbranch_scc0 .LBB0_1526
	s_andn2_b64 vcc, exec, s[46:47]
	s_cbranch_vccnz .Lalign_a_1526
	s_barrier

; #define PG8_STAGE(bufoff, gbase, voff) do { _Pragma("unroll") for (int _i = 0; _i < 2; ++_i) \
;         __builtin_amdgcn_global_load_lds((const unsigned*)((const char*)(gbase) + (voff)[_i]), (LAS unsigned*)(lds + (bufoff) + ldsw + _i * 8192), 16, 0, 0); } while (0)
; #define PG8_LDA(dst, b, h) do { _Pragma("unroll") for (int m = 0; m < 4; ++m) _Pragma("unroll") for (int k = 0; k < 2; ++k) dst[m][k] = *(const LAS bf16x8*)(lds + PG8_SA(b, h) + aoff + m * 2048 + k * 1024); } while (0)
; #define PG8_LDB(dst, b, h) do { _Pragma("unroll") for (int n = 0; n < 2; ++n) _Pragma("unroll") for (int k = 0; k < 2; ++k) dst[n][k] = *(const LAS bf16x8*)(lds + PG8_SB(b, h) + boff + n * 2048 + k * 1024); } while (0)
; #define PG8_WAIT_V(n) asm volatile("s_waitcnt vmcnt(" #n ")" ::: "memory")
; #define PG8_WAIT_L(n) asm volatile("s_waitcnt lgkmcnt(" #n ")" ::: "memory")
; #define PG8_BAR __builtin_amdgcn_s_barrier()
; #define PG8_SCHED __builtin_amdgcn_sched_barrier(0)
; template <class Epi, class Sched>
; __device__ __forceinline__ void gemm_phase(LAS unsigned char* lds, const Gemm g, const Sched& S, const Epi& E) {
;     ...
;         const char* nA = has_next ? (const char*)g.A + (size_t)nxt.pm * tstepA : cA; const char* nB = has_next ? (const char*)g.Bt + (size_t)nxt.pn * tstepB : cB;
;         for (int t = 0; t < nt; t += 2) {
;             const bool last = (t == nt - 2);
;             const char* a1 = cA + (size_t)(t + 1) * kstep;
;             const char* a2 = last ? nA : cA + (size_t)(t + 2) * kstep; const char* b2 = last ? nB : cB + (size_t)(t + 2) * kstep;
;             const char* a3 = a2 + kstep; const char* b3 = b2 + kstep;
;             if (last && has_next) S.a_ready(nxt);
;             PG8_LDB(B0, 0, 0); PG8_SCHED; PG8_LDA(At, 0, 0); PG8_STAGE(PG8_SA(1, 1), a1 + hstepA, voffA);
;             PG8_WAIT_L(8); PG8_BAR; PG8_WAIT_L(0); PG8_MMA(0, 0, At, B0); PG8_BAR; PG8_SCHED;
;             PG8_LDB(B1, 0, 1); PG8_STAGE(PG8_SB(0, 0), b2, voffB);
;             PG8_BAR; PG8_WAIT_L(0); PG8_MMA(0, 1, At, B1); PG8_BAR;
;             PG8_LDA(At, 0, 1); PG8_STAGE(PG8_SA(0, 0), a2, voffA);
;             PG8_BAR; PG8_WAIT_L(0); PG8_MMA(1, 0, At, B0); PG8_BAR; PG8_SCHED;
;             PG8_STAGE(PG8_SB(0, 1), b2 + hstepB, voffB);
;             PG8_WAIT_V(6); PG8_BAR; PG8_MMA(1, 1, At, B1); PG8_BAR;
.LBB0_1665:
	s_add_u32 s42, s14, 0x100
	s_addc_u32 s43, s15, 0
	s_mov_b32 s44, -2
	s_add_u32 s14, s6, 0x100
	s_addc_u32 s15, s7, 0
	s_add_i32 s45, 0, 0x10000
	v_add_u32_e32 v144, s45, v1
	ds_read_b128 v[132:135], v144
	ds_read_b128 v[136:139], v144 offset:1024
	ds_read_b128 v[140:143], v144 offset:2048
	ds_read_b128 v[144:147], v144 offset:3072
	s_cmpk_eq_i32 s44, 0x54
	s_cselect_b32 s21, s1, s15
	s_cselect_b32 s20, s0, s14
	s_cselect_b32 s19, s5, s43
	s_cselect_b32 s18, s4, s42
	ds_read_b128 v[148:151], v224
	ds_read_b128 v[152:155], v224 offset:1024
	ds_read_b128 v[156:159], v224 offset:2048
	ds_read_b128 v[160:163], v224 offset:3072
	ds_read_b128 v[164:167], v224 offset:4096
	ds_read_b128 v[168:171], v224 offset:5120
	ds_read_b128 v[172:175], v224 offset:6144
	ds_read_b128 v[176:179], v224 offset:7168
	s_add_i32 s51, 0, 0x14000
	v_add_u32_e32 v202, s51, v1
	ds_read_b128 v[180:183], v202
	ds_read_b128 v[184:187], v202 offset:1024
	ds_read_b128 v[188:191], v202 offset:2048
	ds_read_b128 v[202:205], v202 offset:3072
	s_add_i32 m0, s29, 0xc000
	s_nop 0
	global_load_lds_dwordx4 v198, s[6:7]
	s_add_i32 m0, s29, 0xe000
	s_nop 0
	global_load_lds_dwordx4 v200, s[6:7]
	s_waitcnt lgkmcnt(0)
	s_barrier
	v_mfma_f32_16x16x32_bf16 v[128:131], v[132:135], v[148:151], 0
	v_mfma_f32_16x16x32_bf16 v[124:127], v[140:143], v[148:151], 0
	v_mfma_f32_16x16x32_bf16 v[112:115], v[132:135], v[156:159], 0
	v_mfma_f32_16x16x32_bf16 v[108:111], v[140:143], v[156:159], 0
	v_mfma_f32_16x16x32_bf16 v[100:103], v[132:135], v[164:167], 0
	v_mfma_f32_16x16x32_bf16 v[92:95], v[140:143], v[164:167], 0
	v_mfma_f32_16x16x32_bf16 v[84:87], v[132:135], v[172:175], 0
	v_mfma_f32_16x16x32_bf16 v[76:79], v[140:143], v[172:175], 0
	v_mfma_f32_16x16x32_bf16 v[128:131], v[136:139], v[152:155], v[128:131]
	v_mfma_f32_16x16x32_bf16 v[124:127], v[144:147], v[152:155], v[124:127]
	v_mfma_f32_16x16x32_bf16 v[112:115], v[136:139], v[160:163], v[112:115]
	v_mfma_f32_16x16x32_bf16 v[108:111], v[144:147], v[160:163], v[108:111]
	v_mfma_f32_16x16x32_bf16 v[100:103], v[136:139], v[168:171], v[100:103]
	v_mfma_f32_16x16x32_bf16 v[92:95], v[144:147], v[168:171], v[92:95]
	v_mfma_f32_16x16x32_bf16 v[84:87], v[136:139], v[176:179], v[84:87]
	v_mfma_f32_16x16x32_bf16 v[76:79], v[144:147], v[176:179], v[76:79]
	v_mfma_f32_16x16x32_bf16 v[120:123], v[180:183], v[148:151], 0
	v_mfma_f32_16x16x32_bf16 v[116:119], v[188:191], v[148:151], 0
	v_mfma_f32_16x16x32_bf16 v[104:107], v[180:183], v[156:159], 0
	v_mfma_f32_16x16x32_bf16 v[96:99], v[188:191], v[156:159], 0
	v_mfma_f32_16x16x32_bf16 v[88:91], v[180:183], v[164:167], 0
	v_mfma_f32_16x16x32_bf16 v[80:83], v[188:191], v[164:167], 0
	v_mfma_f32_16x16x32_bf16 v[72:75], v[180:183], v[172:175], 0
	v_mfma_f32_16x16x32_bf16 v[68:71], v[188:191], v[172:175], 0
	v_mfma_f32_16x16x32_bf16 v[120:123], v[184:187], v[152:155], v[120:123]
	v_mfma_f32_16x16x32_bf16 v[116:119], v[202:205], v[152:155], v[116:119]
	v_mfma_f32_16x16x32_bf16 v[104:107], v[184:187], v[160:163], v[104:107]
	v_mfma_f32_16x16x32_bf16 v[96:99], v[202:205], v[160:163], v[96:99]
	v_mfma_f32_16x16x32_bf16 v[88:91], v[184:187], v[168:171], v[88:91]
	v_mfma_f32_16x16x32_bf16 v[80:83], v[202:205], v[168:171], v[80:83]
	v_mfma_f32_16x16x32_bf16 v[72:75], v[184:187], v[176:179], v[72:75]
	v_mfma_f32_16x16x32_bf16 v[68:71], v[202:205], v[176:179], v[68:71]
	s_barrier
	ds_read_b128 v[148:151], v224 offset:16384
	ds_read_b128 v[152:155], v224 offset:17408
	ds_read_b128 v[156:159], v224 offset:18432
	ds_read_b128 v[160:163], v224 offset:19456
	ds_read_b128 v[164:167], v224 offset:20480
	ds_read_b128 v[168:171], v224 offset:21504
	ds_read_b128 v[172:175], v224 offset:22528
	ds_read_b128 v[176:179], v224 offset:23552
	s_add_i32 s6, s45, s28
	v_lshl_add_u64 v[206:207], s[18:19], 0, v[2:3]
	s_mov_b32 m0, s6
	s_nop 0
	global_load_lds_dwordx4 v[206:207], off
	v_lshl_add_u64 v[208:209], s[18:19], 0, v[192:193]
	s_add_i32 m0, s6, 0x2000
	s_nop 0
	global_load_lds_dwordx4 v[208:209], off
	s_mov_b32 m0, s29
	v_lshl_add_u64 v[210:211], s[20:21], 0, v[196:197]
	global_load_lds_dwordx4 v[210:211], off
	v_lshl_add_u64 v[212:213], s[20:21], 0, v[194:195]
	s_mov_b32 m0, s30
	s_nop 0
	global_load_lds_dwordx4 v[212:213], off
	s_add_u32 s6, s18, 0x160000
	s_addc_u32 s7, s19, 0
	s_add_i32 s45, s51, s28
	s_mov_b32 m0, s45
	s_nop 0
	global_load_lds_dwordx4 v2, s[6:7]
	s_add_i32 m0, s45, 0x2000
	s_nop 0
	global_load_lds_dwordx4 v192, s[6:7]
	s_waitcnt lgkmcnt(0)
	s_waitcnt vmcnt(6)
	s_barrier
	v_mfma_f32_16x16x32_bf16 v[64:67], v[132:135], v[148:151], 0
	v_mfma_f32_16x16x32_bf16 v[60:63], v[140:143], v[148:151], 0
	v_mfma_f32_16x16x32_bf16 v[52:55], v[132:135], v[156:159], 0
	v_mfma_f32_16x16x32_bf16 v[44:47], v[140:143], v[156:159], 0
	v_mfma_f32_16x16x32_bf16 v[36:39], v[132:135], v[164:167], 0
	v_mfma_f32_16x16x32_bf16 v[28:31], v[140:143], v[164:167], 0
	v_mfma_f32_16x16x32_bf16 v[20:23], v[132:135], v[172:175], 0
	v_mfma_f32_16x16x32_bf16 v[12:15], v[140:143], v[172:175], 0
	v_mfma_f32_16x16x32_bf16 v[64:67], v[136:139], v[152:155], v[64:67]
	v_mfma_f32_16x16x32_bf16 v[60:63], v[144:147], v[152:155], v[60:63]
	v_mfma_f32_16x16x32_bf16 v[52:55], v[136:139], v[160:163], v[52:55]
	v_mfma_f32_16x16x32_bf16 v[44:47], v[144:147], v[160:163], v[44:47]
	v_mfma_f32_16x16x32_bf16 v[36:39], v[136:139], v[168:171], v[36:39]
	v_mfma_f32_16x16x32_bf16 v[28:31], v[144:147], v[168:171], v[28:31]
	v_mfma_f32_16x16x32_bf16 v[20:23], v[136:139], v[176:179], v[20:23]
	v_mfma_f32_16x16x32_bf16 v[12:15], v[144:147], v[176:179], v[12:15]
	v_mfma_f32_16x16x32_bf16 v[56:59], v[180:183], v[148:151], 0
	v_mfma_f32_16x16x32_bf16 v[48:51], v[188:191], v[148:151], 0
	v_mfma_f32_16x16x32_bf16 v[40:43], v[180:183], v[156:159], 0
	v_mfma_f32_16x16x32_bf16 v[32:35], v[188:191], v[156:159], 0
	v_mfma_f32_16x16x32_bf16 v[24:27], v[180:183], v[164:167], 0
	v_mfma_f32_16x16x32_bf16 v[16:19], v[188:191], v[164:167], 0
	v_mfma_f32_16x16x32_bf16 v[8:11], v[180:183], v[172:175], 0
	v_mfma_f32_16x16x32_bf16 v[4:7], v[188:191], v[172:175], 0
	v_mfma_f32_16x16x32_bf16 v[56:59], v[184:187], v[152:155], v[56:59]
	v_mfma_f32_16x16x32_bf16 v[48:51], v[202:205], v[152:155], v[48:51]
	v_mfma_f32_16x16x32_bf16 v[40:43], v[184:187], v[160:163], v[40:43]
	v_mfma_f32_16x16x32_bf16 v[32:35], v[202:205], v[160:163], v[32:35]
	v_mfma_f32_16x16x32_bf16 v[24:27], v[184:187], v[168:171], v[24:27]
	v_mfma_f32_16x16x32_bf16 v[16:19], v[202:205], v[168:171], v[16:19]
	v_mfma_f32_16x16x32_bf16 v[8:11], v[184:187], v[176:179], v[8:11]
	v_mfma_f32_16x16x32_bf16 v[4:7], v[202:205], v[176:179], v[4:7]
	s_barrier
; #define PG8_STAGE(bufoff, gbase, voff) do { _Pragma("unroll") for (int _i = 0; _i < 2; ++_i) \
;         __builtin_amdgcn_global_load_lds((const unsigned*)((const char*)(gbase) + (voff)[_i]), (LAS unsigned*)(lds + (bufoff) + ldsw + _i * 8192), 16, 0, 0); } while (0)
; #define PG8_LDA(dst, b, h) do { _Pragma("unroll") for (int m = 0; m < 4; ++m) _Pragma("unroll") for (int k = 0; k < 2; ++k) dst[m][k] = *(const LAS bf16x8*)(lds + PG8_SA(b, h) + aoff + m * 2048 + k * 1024); } while (0)
; #define PG8_LDB(dst, b, h) do { _Pragma("unroll") for (int n = 0; n < 2; ++n) _Pragma("unroll") for (int k = 0; k < 2; ++k) dst[n][k] = *(const LAS bf16x8*)(lds + PG8_SB(b, h) + boff + n * 2048 + k * 1024); } while (0)
; #define PG8_MMA(ai, bj, At, Bt) do { __builtin_amdgcn_s_setprio(1); _Pragma("unroll") for (int m = 0; m < 4; ++m) _Pragma("unroll") for (int n = 0; n < 2; ++n) _Pragma("unroll") for (int k = 0; k < 2; ++k) \
;         acc[ai][bj][m][n] = __builtin_amdgcn_mfma_f32_16x16x32_bf16(Bt[n][k], At[m][k], acc[ai][bj][m][n], 0, 0, 0); __builtin_amdgcn_s_setprio(0); } while (0)
; #define PG8_WAIT_V(n) asm volatile("s_waitcnt vmcnt(" #n ")" ::: "memory")
; #define PG8_WAIT_L(n) asm volatile("s_waitcnt lgkmcnt(" #n ")" ::: "memory")
; #define PG8_BAR __builtin_amdgcn_s_barrier()
; #define PG8_SCHED __builtin_amdgcn_sched_barrier(0)
; template <class Epi, class Sched>
; __device__ __forceinline__ void gemm_phase(LAS unsigned char* lds, const Gemm g, const Sched& S, const Epi& E) {
;     ...
;             PG8_LDB(B0, 1, 0); PG8_SCHED; PG8_LDA(At, 1, 0); PG8_STAGE(PG8_SA(0, 1), a2 + hstepA, voffA);
;             PG8_WAIT_L(8); PG8_BAR; PG8_WAIT_L(0); PG8_MMA(0, 0, At, B0); PG8_BAR; PG8_SCHED;
;             PG8_LDB(B1, 1, 1); PG8_STAGE(PG8_SB(1, 0), b3, voffB);
;             PG8_BAR; PG8_WAIT_L(0); PG8_MMA(0, 1, At, B1); PG8_BAR;
;             PG8_LDA(At, 1, 1); PG8_STAGE(PG8_SA(1, 0), a3, voffA);
;             PG8_BAR; PG8_WAIT_L(0); PG8_MMA(1, 0, At, B0); PG8_BAR; PG8_SCHED;
;             PG8_STAGE(PG8_SB(1, 1), b3 + hstepB, voffB);
;             PG8_WAIT_V(6); PG8_BAR; PG8_MMA(1, 1, At, B1); PG8_BAR;
	s_add_i32 s45, 0, 0x18000
	v_add_u32_e32 v144, s45, v1
	ds_read_b128 v[132:135], v144
	ds_read_b128 v[136:139], v144 offset:1024
	ds_read_b128 v[140:143], v144 offset:2048
	ds_read_b128 v[144:147], v144 offset:3072
	s_add_u32 s6, s20, 0x160000
	s_addc_u32 s7, s21, 0
	ds_read_b128 v[148:151], v224 offset:32768
	ds_read_b128 v[152:155], v224 offset:33792
	ds_read_b128 v[156:159], v224 offset:34816
	ds_read_b128 v[160:163], v224 offset:35840
	ds_read_b128 v[164:167], v224 offset:36864
	ds_read_b128 v[168:171], v224 offset:37888
	ds_read_b128 v[172:175], v224 offset:38912
	ds_read_b128 v[176:179], v224 offset:39936
	s_mov_b32 m0, s31
	s_nop 0
	global_load_lds_dwordx4 v196, s[6:7]
	s_mov_b32 m0, s35
	s_nop 0
	global_load_lds_dwordx4 v194, s[6:7]
	s_add_i32 s20, 0, 0x1c000
	v_add_u32_e32 v202, s20, v1
	ds_read_b128 v[180:183], v202
	ds_read_b128 v[184:187], v202 offset:1024
	ds_read_b128 v[188:191], v202 offset:2048
	ds_read_b128 v[202:205], v202 offset:3072
	s_waitcnt lgkmcnt(0)
	s_barrier
	v_mfma_f32_16x16x32_bf16 v[128:131], v[132:135], v[148:151], v[128:131]
	v_mfma_f32_16x16x32_bf16 v[124:127], v[140:143], v[148:151], v[124:127]
	v_mfma_f32_16x16x32_bf16 v[112:115], v[132:135], v[156:159], v[112:115]
	v_mfma_f32_16x16x32_bf16 v[108:111], v[140:143], v[156:159], v[108:111]
	v_mfma_f32_16x16x32_bf16 v[100:103], v[132:135], v[164:167], v[100:103]
	v_mfma_f32_16x16x32_bf16 v[92:95], v[140:143], v[164:167], v[92:95]
	v_mfma_f32_16x16x32_bf16 v[84:87], v[132:135], v[172:175], v[84:87]
	v_mfma_f32_16x16x32_bf16 v[76:79], v[140:143], v[172:175], v[76:79]
	v_mfma_f32_16x16x32_bf16 v[128:131], v[136:139], v[152:155], v[128:131]
	v_mfma_f32_16x16x32_bf16 v[124:127], v[144:147], v[152:155], v[124:127]
	v_mfma_f32_16x16x32_bf16 v[112:115], v[136:139], v[160:163], v[112:115]
	v_mfma_f32_16x16x32_bf16 v[108:111], v[144:147], v[160:163], v[108:111]
	v_mfma_f32_16x16x32_bf16 v[100:103], v[136:139], v[168:171], v[100:103]
	v_mfma_f32_16x16x32_bf16 v[92:95], v[144:147], v[168:171], v[92:95]
	v_mfma_f32_16x16x32_bf16 v[84:87], v[136:139], v[176:179], v[84:87]
	v_mfma_f32_16x16x32_bf16 v[76:79], v[144:147], v[176:179], v[76:79]
	v_mfma_f32_16x16x32_bf16 v[120:123], v[180:183], v[148:151], v[120:123]
	v_mfma_f32_16x16x32_bf16 v[116:119], v[188:191], v[148:151], v[116:119]
	v_mfma_f32_16x16x32_bf16 v[104:107], v[180:183], v[156:159], v[104:107]
	v_mfma_f32_16x16x32_bf16 v[96:99], v[188:191], v[156:159], v[96:99]
	v_mfma_f32_16x16x32_bf16 v[88:91], v[180:183], v[164:167], v[88:91]
	v_mfma_f32_16x16x32_bf16 v[80:83], v[188:191], v[164:167], v[80:83]
	v_mfma_f32_16x16x32_bf16 v[72:75], v[180:183], v[172:175], v[72:75]
	v_mfma_f32_16x16x32_bf16 v[68:71], v[188:191], v[172:175], v[68:71]
	v_mfma_f32_16x16x32_bf16 v[120:123], v[184:187], v[152:155], v[120:123]
	v_mfma_f32_16x16x32_bf16 v[116:119], v[202:205], v[152:155], v[116:119]
	v_mfma_f32_16x16x32_bf16 v[104:107], v[184:187], v[160:163], v[104:107]
	v_mfma_f32_16x16x32_bf16 v[96:99], v[202:205], v[160:163], v[96:99]
	v_mfma_f32_16x16x32_bf16 v[88:91], v[184:187], v[168:171], v[88:91]
	v_mfma_f32_16x16x32_bf16 v[80:83], v[202:205], v[168:171], v[80:83]
	v_mfma_f32_16x16x32_bf16 v[72:75], v[184:187], v[176:179], v[72:75]
	v_mfma_f32_16x16x32_bf16 v[68:71], v[202:205], v[176:179], v[68:71]
	s_barrier
	ds_read_b128 v[148:151], v224 offset:49152
	ds_read_b128 v[152:155], v224 offset:50176
	ds_read_b128 v[156:159], v224 offset:51200
	ds_read_b128 v[160:163], v224 offset:52224
	ds_read_b128 v[164:167], v224 offset:53248
	ds_read_b128 v[168:171], v224 offset:54272
	ds_read_b128 v[172:175], v224 offset:55296
	ds_read_b128 v[176:179], v224 offset:56320
	s_add_i32 s6, s45, s28
	v_lshl_add_u64 v[206:207], v[206:207], 0, s[8:9]
	s_mov_b32 m0, s6
	s_nop 0
	global_load_lds_dwordx4 v[206:207], off
	v_lshl_add_u64 v[206:207], v[208:209], 0, s[8:9]
	s_add_i32 m0, s6, 0x2000
	s_nop 0
	global_load_lds_dwordx4 v[206:207], off
	s_mov_b32 m0, s38
	v_lshl_add_u64 v[206:207], v[210:211], 0, s[8:9]
	global_load_lds_dwordx4 v[206:207], off
	v_lshl_add_u64 v[206:207], v[212:213], 0, s[8:9]
	s_mov_b32 m0, s39
	s_nop 0
	global_load_lds_dwordx4 v[206:207], off
	s_add_u32 s6, s18, 0x160080
	s_addc_u32 s7, s19, 0
	s_add_i32 s18, s20, s28
	s_mov_b32 m0, s18
	s_nop 0
	global_load_lds_dwordx4 v2, s[6:7]
	s_add_i32 m0, s18, 0x2000
	s_nop 0
	global_load_lds_dwordx4 v192, s[6:7]
	s_add_i32 s44, s44, 2
	s_add_u32 s42, s42, 0x100
	s_addc_u32 s43, s43, 0
	s_cmpk_gt_u32 s44, 0x55
	s_mov_b64 s[6:7], s[14:15]
	s_waitcnt lgkmcnt(0)
	s_waitcnt vmcnt(6)
	s_barrier
	v_mfma_f32_16x16x32_bf16 v[64:67], v[132:135], v[148:151], v[64:67]
	v_mfma_f32_16x16x32_bf16 v[60:63], v[140:143], v[148:151], v[60:63]
	v_mfma_f32_16x16x32_bf16 v[52:55], v[132:135], v[156:159], v[52:55]
	v_mfma_f32_16x16x32_bf16 v[44:47], v[140:143], v[156:159], v[44:47]
	v_mfma_f32_16x16x32_bf16 v[36:39], v[132:135], v[164:167], v[36:39]
	v_mfma_f32_16x16x32_bf16 v[28:31], v[140:143], v[164:167], v[28:31]
	v_mfma_f32_16x16x32_bf16 v[20:23], v[132:135], v[172:175], v[20:23]
	v_mfma_f32_16x16x32_bf16 v[12:15], v[140:143], v[172:175], v[12:15]
	v_mfma_f32_16x16x32_bf16 v[64:67], v[136:139], v[152:155], v[64:67]
	v_mfma_f32_16x16x32_bf16 v[60:63], v[144:147], v[152:155], v[60:63]
	v_mfma_f32_16x16x32_bf16 v[52:55], v[136:139], v[160:163], v[52:55]
	v_mfma_f32_16x16x32_bf16 v[44:47], v[144:147], v[160:163], v[44:47]
	v_mfma_f32_16x16x32_bf16 v[36:39], v[136:139], v[168:171], v[36:39]
	v_mfma_f32_16x16x32_bf16 v[28:31], v[144:147], v[168:171], v[28:31]
	v_mfma_f32_16x16x32_bf16 v[20:23], v[136:139], v[176:179], v[20:23]
	v_mfma_f32_16x16x32_bf16 v[12:15], v[144:147], v[176:179], v[12:15]
	v_mfma_f32_16x16x32_bf16 v[56:59], v[180:183], v[148:151], v[56:59]
	v_mfma_f32_16x16x32_bf16 v[48:51], v[188:191], v[148:151], v[48:51]
	v_mfma_f32_16x16x32_bf16 v[40:43], v[180:183], v[156:159], v[40:43]
	v_mfma_f32_16x16x32_bf16 v[32:35], v[188:191], v[156:159], v[32:35]
	v_mfma_f32_16x16x32_bf16 v[24:27], v[180:183], v[164:167], v[24:27]
	v_mfma_f32_16x16x32_bf16 v[16:19], v[188:191], v[164:167], v[16:19]
	v_mfma_f32_16x16x32_bf16 v[8:11], v[180:183], v[172:175], v[8:11]
	v_mfma_f32_16x16x32_bf16 v[4:7], v[188:191], v[172:175], v[4:7]
	v_mfma_f32_16x16x32_bf16 v[56:59], v[184:187], v[152:155], v[56:59]
	v_mfma_f32_16x16x32_bf16 v[48:51], v[202:205], v[152:155], v[48:51]
	v_mfma_f32_16x16x32_bf16 v[40:43], v[184:187], v[160:163], v[40:43]
	v_mfma_f32_16x16x32_bf16 v[32:35], v[202:205], v[160:163], v[32:35]
	v_mfma_f32_16x16x32_bf16 v[24:27], v[184:187], v[168:171], v[24:27]
	v_mfma_f32_16x16x32_bf16 v[16:19], v[202:205], v[168:171], v[16:19]
	v_mfma_f32_16x16x32_bf16 v[8:11], v[184:187], v[176:179], v[8:11]
	v_mfma_f32_16x16x32_bf16 v[4:7], v[202:205], v[176:179], v[4:7]
	s_barrier
	s_setprio 0
; #define PG8_STAGE(bufoff, gbase, voff) do { _Pragma("unroll") for (int _i = 0; _i < 2; ++_i) \
;         __builtin_amdgcn_global_load_lds((const unsigned*)((const char*)(gbase) + (voff)[_i]), (LAS unsigned*)(lds + (bufoff) + ldsw + _i * 8192), 16, 0, 0); } while (0)
; #define PG8_LDA(dst, b, h) do { _Pragma("unroll") for (int m = 0; m < 4; ++m) _Pragma("unroll") for (int k = 0; k < 2; ++k) dst[m][k] = *(const LAS bf16x8*)(lds + PG8_SA(b, h) + aoff + m * 2048 + k * 1024); } while (0)
; #define PG8_WAIT_V(n) asm volatile("s_waitcnt vmcnt(" #n ")" ::: "memory")
; template <class Epi, class Sched>
; __device__ __forceinline__ void gemm_phase(LAS unsigned char* lds, const Gemm g, const Sched& S, const Epi& E) {
;     ...
;         for (int t = 0; t < nt; t += 2) {
;             const bool last = (t == nt - 2);
;             const char* a1 = cA + (size_t)(t + 1) * kstep;
;             const char* a2 = last ? nA : cA + (size_t)(t + 2) * kstep; const char* b2 = last ? nB : cB + (size_t)(t + 2) * kstep;
;             const char* a3 = a2 + kstep; const char* b3 = b2 + kstep;
;             if (last && has_next) S.a_ready(nxt);
;             PG8_LDB(B0, 0, 0); PG8_SCHED; PG8_LDA(At, 0, 0); PG8_STAGE(PG8_SA(1, 1), a1 + hstepA, voffA);
;             PG8_WAIT_L(8); PG8_BAR; PG8_WAIT_L(0); PG8_MMA(0, 0, At, B0); PG8_BAR; PG8_SCHED;
;             PG8_LDB(B1, 0, 1); PG8_STAGE(PG8_SB(0, 0), b2, voffB);
;             PG8_BAR; PG8_WAIT_L(0); PG8_MMA(0, 1, At, B1); PG8_BAR;
;             PG8_LDA(At, 0, 1); PG8_STAGE(PG8_SA(0, 0), a2, voffA);
;             PG8_BAR; PG8_WAIT_L(0); PG8_MMA(1, 0, At, B0); PG8_BAR; PG8_SCHED;
;             PG8_STAGE(PG8_SB(0, 1), b2 + hstepB, voffB);
;             PG8_WAIT_V(6); PG8_BAR; PG8_MMA(1, 1, At, B1); PG8_BAR;
;             PG8_LDB(B0, 1, 0); PG8_SCHED; PG8_LDA(At, 1, 0); PG8_STAGE(PG8_SA(0, 1), a2 + hstepA, voffA);
;             PG8_WAIT_L(8); PG8_BAR; PG8_WAIT_L(0); PG8_MMA(0, 0, At, B0); PG8_BAR; PG8_SCHED;
;             PG8_LDB(B1, 1, 1); PG8_STAGE(PG8_SB(1, 0), b3, voffB);
;             PG8_BAR; PG8_WAIT_L(0); PG8_MMA(0, 1, At, B1); PG8_BAR;
;             PG8_LDA(At, 1, 1); PG8_STAGE(PG8_SA(1, 0), a3, voffA);
;             PG8_BAR; PG8_WAIT_L(0); PG8_MMA(1, 0, At, B0); PG8_BAR; PG8_SCHED;
;             PG8_STAGE(PG8_SB(1, 1), b3 + hstepB, voffB);
;             PG8_WAIT_V(6); PG8_BAR; PG8_MMA(1, 1, At, B1); PG8_BAR;
.LBB0_1666:
	s_add_u32 s14, s6, 0x100
	s_addc_u32 s15, s7, 0
	s_add_i32 s45, 0, 0x10000
	v_add_u32_e32 v144, s45, v1
	ds_read_b128 v[132:135], v144
	ds_read_b128 v[136:139], v144 offset:1024
	ds_read_b128 v[140:143], v144 offset:2048
	ds_read_b128 v[144:147], v144 offset:3072
	s_cmpk_eq_i32 s44, 0x54
	s_cselect_b32 s21, s1, s15
	s_cselect_b32 s20, s0, s14
	s_cselect_b32 s19, s5, s43
	s_cselect_b32 s18, s4, s42
	ds_read_b128 v[148:151], v224
	ds_read_b128 v[152:155], v224 offset:1024
	ds_read_b128 v[156:159], v224 offset:2048
	ds_read_b128 v[160:163], v224 offset:3072
	ds_read_b128 v[164:167], v224 offset:4096
	ds_read_b128 v[168:171], v224 offset:5120
	ds_read_b128 v[172:175], v224 offset:6144
	ds_read_b128 v[176:179], v224 offset:7168
	s_add_i32 s51, 0, 0x14000
	v_add_u32_e32 v202, s51, v1
	ds_read_b128 v[180:183], v202
	ds_read_b128 v[184:187], v202 offset:1024
	ds_read_b128 v[188:191], v202 offset:2048
	ds_read_b128 v[202:205], v202 offset:3072
	s_add_i32 m0, s29, 0xc000
	s_nop 0
	global_load_lds_dwordx4 v198, s[6:7]
	s_add_i32 m0, s29, 0xe000
	s_nop 0
	global_load_lds_dwordx4 v200, s[6:7]
	s_waitcnt lgkmcnt(0)
	s_barrier
	v_mfma_f32_16x16x32_bf16 v[128:131], v[132:135], v[148:151], v[128:131]
	v_mfma_f32_16x16x32_bf16 v[124:127], v[140:143], v[148:151], v[124:127]
	v_mfma_f32_16x16x32_bf16 v[112:115], v[132:135], v[156:159], v[112:115]
	v_mfma_f32_16x16x32_bf16 v[108:111], v[140:143], v[156:159], v[108:111]
	v_mfma_f32_16x16x32_bf16 v[100:103], v[132:135], v[164:167], v[100:103]
	v_mfma_f32_16x16x32_bf16 v[92:95], v[140:143], v[164:167], v[92:95]
	v_mfma_f32_16x16x32_bf16 v[84:87], v[132:135], v[172:175], v[84:87]
	v_mfma_f32_16x16x32_bf16 v[76:79], v[140:143], v[172:175], v[76:79]
	v_mfma_f32_16x16x32_bf16 v[128:131], v[136:139], v[152:155], v[128:131]
	v_mfma_f32_16x16x32_bf16 v[124:127], v[144:147], v[152:155], v[124:127]
	v_mfma_f32_16x16x32_bf16 v[112:115], v[136:139], v[160:163], v[112:115]
	v_mfma_f32_16x16x32_bf16 v[108:111], v[144:147], v[160:163], v[108:111]
	v_mfma_f32_16x16x32_bf16 v[100:103], v[136:139], v[168:171], v[100:103]
	v_mfma_f32_16x16x32_bf16 v[92:95], v[144:147], v[168:171], v[92:95]
	v_mfma_f32_16x16x32_bf16 v[84:87], v[136:139], v[176:179], v[84:87]
	v_mfma_f32_16x16x32_bf16 v[76:79], v[144:147], v[176:179], v[76:79]
	v_mfma_f32_16x16x32_bf16 v[120:123], v[180:183], v[148:151], v[120:123]
	v_mfma_f32_16x16x32_bf16 v[116:119], v[188:191], v[148:151], v[116:119]
	v_mfma_f32_16x16x32_bf16 v[104:107], v[180:183], v[156:159], v[104:107]
	v_mfma_f32_16x16x32_bf16 v[96:99], v[188:191], v[156:159], v[96:99]
	v_mfma_f32_16x16x32_bf16 v[88:91], v[180:183], v[164:167], v[88:91]
	v_mfma_f32_16x16x32_bf16 v[80:83], v[188:191], v[164:167], v[80:83]
	v_mfma_f32_16x16x32_bf16 v[72:75], v[180:183], v[172:175], v[72:75]
	v_mfma_f32_16x16x32_bf16 v[68:71], v[188:191], v[172:175], v[68:71]
	v_mfma_f32_16x16x32_bf16 v[120:123], v[184:187], v[152:155], v[120:123]
	v_mfma_f32_16x16x32_bf16 v[116:119], v[202:205], v[152:155], v[116:119]
	v_mfma_f32_16x16x32_bf16 v[104:107], v[184:187], v[160:163], v[104:107]
	v_mfma_f32_16x16x32_bf16 v[96:99], v[202:205], v[160:163], v[96:99]
	v_mfma_f32_16x16x32_bf16 v[88:91], v[184:187], v[168:171], v[88:91]
	v_mfma_f32_16x16x32_bf16 v[80:83], v[202:205], v[168:171], v[80:83]
	v_mfma_f32_16x16x32_bf16 v[72:75], v[184:187], v[176:179], v[72:75]
	v_mfma_f32_16x16x32_bf16 v[68:71], v[202:205], v[176:179], v[68:71]
	s_barrier
	ds_read_b128 v[148:151], v224 offset:16384
	ds_read_b128 v[152:155], v224 offset:17408
	ds_read_b128 v[156:159], v224 offset:18432
	ds_read_b128 v[160:163], v224 offset:19456
	ds_read_b128 v[164:167], v224 offset:20480
	ds_read_b128 v[168:171], v224 offset:21504
	ds_read_b128 v[172:175], v224 offset:22528
	ds_read_b128 v[176:179], v224 offset:23552
	s_add_i32 s6, s45, s28
	v_lshl_add_u64 v[206:207], s[18:19], 0, v[2:3]
	s_mov_b32 m0, s6
	s_nop 0
	global_load_lds_dwordx4 v[206:207], off
	v_lshl_add_u64 v[208:209], s[18:19], 0, v[192:193]
	s_add_i32 m0, s6, 0x2000
	s_nop 0
	global_load_lds_dwordx4 v[208:209], off
	s_mov_b32 m0, s29
	v_lshl_add_u64 v[210:211], s[20:21], 0, v[196:197]
	global_load_lds_dwordx4 v[210:211], off
	v_lshl_add_u64 v[212:213], s[20:21], 0, v[194:195]
	s_mov_b32 m0, s30
	s_nop 0
	global_load_lds_dwordx4 v[212:213], off
	s_add_u32 s6, s18, 0x160000
	s_addc_u32 s7, s19, 0
	s_add_i32 s45, s51, s28
	s_mov_b32 m0, s45
	s_nop 0
	global_load_lds_dwordx4 v2, s[6:7]
	s_add_i32 m0, s45, 0x2000
	s_nop 0
	global_load_lds_dwordx4 v192, s[6:7]
	s_waitcnt lgkmcnt(0)
	s_waitcnt vmcnt(6)
	s_barrier
; #define PG8_STAGE(bufoff, gbase, voff) do { _Pragma("unroll") for (int _i = 0; _i < 2; ++_i) \
;         __builtin_amdgcn_global_load_lds((const unsigned*)((const char*)(gbase) + (voff)[_i]), (LAS unsigned*)(lds + (bufoff) + ldsw + _i * 8192), 16, 0, 0); } while (0)
; #define PG8_LDA(dst, b, h) do { _Pragma("unroll") for (int m = 0; m < 4; ++m) _Pragma("unroll") for (int k = 0; k < 2; ++k) dst[m][k] = *(const LAS bf16x8*)(lds + PG8_SA(b, h) + aoff + m * 2048 + k * 1024); } while (0)
; #define PG8_LDB(dst, b, h) do { _Pragma("unroll") for (int n = 0; n < 2; ++n) _Pragma("unroll") for (int k = 0; k < 2; ++k) dst[n][k] = *(const LAS bf16x8*)(lds + PG8_SB(b, h) + boff + n * 2048 + k * 1024); } while (0)
; #define PG8_MMA(ai, bj, At, Bt) do { __builtin_amdgcn_s_setprio(1); _Pragma("unroll") for (int m = 0; m < 4; ++m) _Pragma("unroll") for (int n = 0; n < 2; ++n) _Pragma("unroll") for (int k = 0; k < 2; ++k) \
;         acc[ai][bj][m][n] = __builtin_amdgcn_mfma_f32_16x16x32_bf16(Bt[n][k], At[m][k], acc[ai][bj][m][n], 0, 0, 0); __builtin_amdgcn_s_setprio(0); } while (0)
; #define PG8_WAIT_V(n) asm volatile("s_waitcnt vmcnt(" #n ")" ::: "memory")
; #define PG8_WAIT_L(n) asm volatile("s_waitcnt lgkmcnt(" #n ")" ::: "memory")
; #define PG8_BAR __builtin_amdgcn_s_barrier()
; #define PG8_SCHED __builtin_amdgcn_sched_barrier(0)
; template <class Epi, class Sched>
; __device__ __forceinline__ void gemm_phase(LAS unsigned char* lds, const Gemm g, const Sched& S, const Epi& E) {
;     ...
;             PG8_BAR; PG8_WAIT_L(0); PG8_MMA(0, 1, At, B1); PG8_BAR;
;             PG8_LDA(At, 0, 1); PG8_STAGE(PG8_SA(0, 0), a2, voffA);
;             PG8_BAR; PG8_WAIT_L(0); PG8_MMA(1, 0, At, B0); PG8_BAR; PG8_SCHED;
;             PG8_STAGE(PG8_SB(0, 1), b2 + hstepB, voffB);
;             PG8_WAIT_V(6); PG8_BAR; PG8_MMA(1, 1, At, B1); PG8_BAR;
;             PG8_LDB(B0, 1, 0); PG8_SCHED; PG8_LDA(At, 1, 0); PG8_STAGE(PG8_SA(0, 1), a2 + hstepA, voffA);
;             PG8_WAIT_L(8); PG8_BAR; PG8_WAIT_L(0); PG8_MMA(0, 0, At, B0); PG8_BAR; PG8_SCHED;
;             PG8_LDB(B1, 1, 1); PG8_STAGE(PG8_SB(1, 0), b3, voffB);
;             PG8_BAR; PG8_WAIT_L(0); PG8_MMA(0, 1, At, B1); PG8_BAR;
	v_mfma_f32_16x16x32_bf16 v[64:67], v[132:135], v[148:151], v[64:67]
	v_mfma_f32_16x16x32_bf16 v[60:63], v[140:143], v[148:151], v[60:63]
	v_mfma_f32_16x16x32_bf16 v[52:55], v[132:135], v[156:159], v[52:55]
	v_mfma_f32_16x16x32_bf16 v[44:47], v[140:143], v[156:159], v[44:47]
	v_mfma_f32_16x16x32_bf16 v[36:39], v[132:135], v[164:167], v[36:39]
	v_mfma_f32_16x16x32_bf16 v[28:31], v[140:143], v[164:167], v[28:31]
	v_mfma_f32_16x16x32_bf16 v[20:23], v[132:135], v[172:175], v[20:23]
	v_mfma_f32_16x16x32_bf16 v[12:15], v[140:143], v[172:175], v[12:15]
	v_mfma_f32_16x16x32_bf16 v[64:67], v[136:139], v[152:155], v[64:67]
	v_mfma_f32_16x16x32_bf16 v[60:63], v[144:147], v[152:155], v[60:63]
	v_mfma_f32_16x16x32_bf16 v[52:55], v[136:139], v[160:163], v[52:55]
	v_mfma_f32_16x16x32_bf16 v[44:47], v[144:147], v[160:163], v[44:47]
	v_mfma_f32_16x16x32_bf16 v[36:39], v[136:139], v[168:171], v[36:39]
	v_mfma_f32_16x16x32_bf16 v[28:31], v[144:147], v[168:171], v[28:31]
	v_mfma_f32_16x16x32_bf16 v[20:23], v[136:139], v[176:179], v[20:23]
	v_mfma_f32_16x16x32_bf16 v[12:15], v[144:147], v[176:179], v[12:15]
	v_mfma_f32_16x16x32_bf16 v[56:59], v[180:183], v[148:151], v[56:59]
	v_mfma_f32_16x16x32_bf16 v[48:51], v[188:191], v[148:151], v[48:51]
	v_mfma_f32_16x16x32_bf16 v[40:43], v[180:183], v[156:159], v[40:43]
	v_mfma_f32_16x16x32_bf16 v[32:35], v[188:191], v[156:159], v[32:35]
	v_mfma_f32_16x16x32_bf16 v[24:27], v[180:183], v[164:167], v[24:27]
	v_mfma_f32_16x16x32_bf16 v[16:19], v[188:191], v[164:167], v[16:19]
	v_mfma_f32_16x16x32_bf16 v[8:11], v[180:183], v[172:175], v[8:11]
	v_mfma_f32_16x16x32_bf16 v[4:7], v[188:191], v[172:175], v[4:7]
	v_mfma_f32_16x16x32_bf16 v[56:59], v[184:187], v[152:155], v[56:59]
	v_mfma_f32_16x16x32_bf16 v[48:51], v[202:205], v[152:155], v[48:51]
	v_mfma_f32_16x16x32_bf16 v[40:43], v[184:187], v[160:163], v[40:43]
	v_mfma_f32_16x16x32_bf16 v[32:35], v[202:205], v[160:163], v[32:35]
	v_mfma_f32_16x16x32_bf16 v[24:27], v[184:187], v[168:171], v[24:27]
	v_mfma_f32_16x16x32_bf16 v[16:19], v[202:205], v[168:171], v[16:19]
	v_mfma_f32_16x16x32_bf16 v[8:11], v[184:187], v[176:179], v[8:11]
	v_mfma_f32_16x16x32_bf16 v[4:7], v[202:205], v[176:179], v[4:7]
	s_barrier
	s_add_i32 s45, 0, 0x18000
	v_add_u32_e32 v144, s45, v1
	ds_read_b128 v[132:135], v144
	ds_read_b128 v[136:139], v144 offset:1024
	ds_read_b128 v[140:143], v144 offset:2048
	ds_read_b128 v[144:147], v144 offset:3072
	s_add_u32 s6, s20, 0x160000
	s_addc_u32 s7, s21, 0
	ds_read_b128 v[148:151], v224 offset:32768
	ds_read_b128 v[152:155], v224 offset:33792
	ds_read_b128 v[156:159], v224 offset:34816
	ds_read_b128 v[160:163], v224 offset:35840
	ds_read_b128 v[164:167], v224 offset:36864
	ds_read_b128 v[168:171], v224 offset:37888
	ds_read_b128 v[172:175], v224 offset:38912
	ds_read_b128 v[176:179], v224 offset:39936
	s_mov_b32 m0, s31
	s_nop 0
	global_load_lds_dwordx4 v196, s[6:7]
	s_mov_b32 m0, s35
	s_nop 0
	global_load_lds_dwordx4 v194, s[6:7]
	s_add_i32 s20, 0, 0x1c000
	v_add_u32_e32 v202, s20, v1
	ds_read_b128 v[180:183], v202
	ds_read_b128 v[184:187], v202 offset:1024
	ds_read_b128 v[188:191], v202 offset:2048
	ds_read_b128 v[202:205], v202 offset:3072
	s_waitcnt lgkmcnt(0)
	s_barrier
	v_mfma_f32_16x16x32_bf16 v[128:131], v[132:135], v[148:151], v[128:131]
	v_mfma_f32_16x16x32_bf16 v[124:127], v[140:143], v[148:151], v[124:127]
	v_mfma_f32_16x16x32_bf16 v[112:115], v[132:135], v[156:159], v[112:115]
	v_mfma_f32_16x16x32_bf16 v[108:111], v[140:143], v[156:159], v[108:111]
	v_mfma_f32_16x16x32_bf16 v[100:103], v[132:135], v[164:167], v[100:103]
	v_mfma_f32_16x16x32_bf16 v[92:95], v[140:143], v[164:167], v[92:95]
	v_mfma_f32_16x16x32_bf16 v[84:87], v[132:135], v[172:175], v[84:87]
	v_mfma_f32_16x16x32_bf16 v[76:79], v[140:143], v[172:175], v[76:79]
	v_mfma_f32_16x16x32_bf16 v[128:131], v[136:139], v[152:155], v[128:131]
	v_mfma_f32_16x16x32_bf16 v[124:127], v[144:147], v[152:155], v[124:127]
	v_mfma_f32_16x16x32_bf16 v[112:115], v[136:139], v[160:163], v[112:115]
	v_mfma_f32_16x16x32_bf16 v[108:111], v[144:147], v[160:163], v[108:111]
	v_mfma_f32_16x16x32_bf16 v[100:103], v[136:139], v[168:171], v[100:103]
	v_mfma_f32_16x16x32_bf16 v[92:95], v[144:147], v[168:171], v[92:95]
	v_mfma_f32_16x16x32_bf16 v[84:87], v[136:139], v[176:179], v[84:87]
	v_mfma_f32_16x16x32_bf16 v[76:79], v[144:147], v[176:179], v[76:79]
	v_mfma_f32_16x16x32_bf16 v[120:123], v[180:183], v[148:151], v[120:123]
	v_mfma_f32_16x16x32_bf16 v[116:119], v[188:191], v[148:151], v[116:119]
	v_mfma_f32_16x16x32_bf16 v[104:107], v[180:183], v[156:159], v[104:107]
	v_mfma_f32_16x16x32_bf16 v[96:99], v[188:191], v[156:159], v[96:99]
	v_mfma_f32_16x16x32_bf16 v[88:91], v[180:183], v[164:167], v[88:91]
	v_mfma_f32_16x16x32_bf16 v[80:83], v[188:191], v[164:167], v[80:83]
	v_mfma_f32_16x16x32_bf16 v[72:75], v[180:183], v[172:175], v[72:75]
	v_mfma_f32_16x16x32_bf16 v[68:71], v[188:191], v[172:175], v[68:71]
	v_mfma_f32_16x16x32_bf16 v[120:123], v[184:187], v[152:155], v[120:123]
	v_mfma_f32_16x16x32_bf16 v[116:119], v[202:205], v[152:155], v[116:119]
	v_mfma_f32_16x16x32_bf16 v[104:107], v[184:187], v[160:163], v[104:107]
	v_mfma_f32_16x16x32_bf16 v[96:99], v[202:205], v[160:163], v[96:99]
	v_mfma_f32_16x16x32_bf16 v[88:91], v[184:187], v[168:171], v[88:91]
	v_mfma_f32_16x16x32_bf16 v[80:83], v[202:205], v[168:171], v[80:83]
	v_mfma_f32_16x16x32_bf16 v[72:75], v[184:187], v[176:179], v[72:75]
	v_mfma_f32_16x16x32_bf16 v[68:71], v[202:205], v[176:179], v[68:71]
	s_barrier
; __device__ __forceinline__ int opaque_tid() { int t = threadIdx.x; asm volatile("" : "+v"(t)); return t; }
; #define PG8_STAGE(bufoff, gbase, voff) do { _Pragma("unroll") for (int _i = 0; _i < 2; ++_i) \
;         __builtin_amdgcn_global_load_lds((const unsigned*)((const char*)(gbase) + (voff)[_i]), (LAS unsigned*)(lds + (bufoff) + ldsw + _i * 8192), 16, 0, 0); } while (0)
; #define PG8_LDA(dst, b, h) do { _Pragma("unroll") for (int m = 0; m < 4; ++m) _Pragma("unroll") for (int k = 0; k < 2; ++k) dst[m][k] = *(const LAS bf16x8*)(lds + PG8_SA(b, h) + aoff + m * 2048 + k * 1024); } while (0)
; #define PG8_MMA(ai, bj, At, Bt) do { __builtin_amdgcn_s_setprio(1); _Pragma("unroll") for (int m = 0; m < 4; ++m) _Pragma("unroll") for (int n = 0; n < 2; ++n) _Pragma("unroll") for (int k = 0; k < 2; ++k) \
;         acc[ai][bj][m][n] = __builtin_amdgcn_mfma_f32_16x16x32_bf16(Bt[n][k], At[m][k], acc[ai][bj][m][n], 0, 0, 0); __builtin_amdgcn_s_setprio(0); } while (0)
; #define PG8_WAIT_V(n) asm volatile("s_waitcnt vmcnt(" #n ")" ::: "memory")
; #define PG8_WAIT_L(n) asm volatile("s_waitcnt lgkmcnt(" #n ")" ::: "memory")
; #define PG8_BAR __builtin_amdgcn_s_barrier()
; #define PG8_SCHED __builtin_amdgcn_sched_barrier(0)
;     __device__ __forceinline__ void operator()(const f32x4 (&acc)[2][2][4][2], const Unit& u, int wr, int wc, int, int) const {
;         const int ol_ = opaque_tid() & 63, fr = ol_ & 15, fq = ol_ >> 4;
;         const int row0 = u.pm * BM + wr * 64 + fr, col0 = u.pn * BM + wc * 32 + 8 * fq;
;         u32x4 cin[2][4][2];
; #pragma unroll
;         for (int ai = 0; ai < 2; ++ai)
; #pragma unroll
;             for (int m = 0; m < 4; ++m)
; #pragma unroll
;                 for (int bj = 0; bj < 2; ++bj) cin[ai][m][bj] = *(const u32x4*)(C + (size_t)(row0 + ai * HALF + m * 16) * ldc + col0 + bj * HALF);
; template <class Epi, class Sched>
; __device__ __forceinline__ void gemm_phase(LAS unsigned char* lds, const Gemm g, const Sched& S, const Epi& E) {
;     ...
;             PG8_LDA(At, 1, 1); PG8_STAGE(PG8_SA(1, 0), a3, voffA);
;             PG8_BAR; PG8_WAIT_L(0); PG8_MMA(1, 0, At, B0); PG8_BAR; PG8_SCHED;
;             PG8_STAGE(PG8_SB(1, 1), b3 + hstepB, voffB);
;             PG8_WAIT_V(6); PG8_BAR; PG8_MMA(1, 1, At, B1); PG8_BAR;
;         }
;         E(acc, cur, wr, wc, ui, fq);
;         S.done(cur);
;         if (!has_next) break;
	ds_read_b128 v[148:151], v224 offset:49152
	ds_read_b128 v[152:155], v224 offset:50176
	ds_read_b128 v[156:159], v224 offset:51200
	ds_read_b128 v[160:163], v224 offset:52224
	ds_read_b128 v[164:167], v224 offset:53248
	ds_read_b128 v[168:171], v224 offset:54272
	ds_read_b128 v[172:175], v224 offset:55296
	ds_read_b128 v[176:179], v224 offset:56320
	s_add_i32 s6, s45, s28
	v_lshl_add_u64 v[206:207], v[206:207], 0, s[8:9]
	s_mov_b32 m0, s6
	s_nop 0
	global_load_lds_dwordx4 v[206:207], off
	v_lshl_add_u64 v[206:207], v[208:209], 0, s[8:9]
	s_add_i32 m0, s6, 0x2000
	s_nop 0
	global_load_lds_dwordx4 v[206:207], off
	s_mov_b32 m0, s38
	v_lshl_add_u64 v[206:207], v[210:211], 0, s[8:9]
	global_load_lds_dwordx4 v[206:207], off
	v_lshl_add_u64 v[206:207], v[212:213], 0, s[8:9]
	s_mov_b32 m0, s39
	s_nop 0
	global_load_lds_dwordx4 v[206:207], off
	s_add_u32 s6, s18, 0x160080
	s_addc_u32 s7, s19, 0
	s_add_i32 s18, s20, s28
	s_mov_b32 m0, s18
	s_nop 0
	global_load_lds_dwordx4 v2, s[6:7]
	s_add_i32 m0, s18, 0x2000
	s_nop 0
	global_load_lds_dwordx4 v192, s[6:7]
	s_add_i32 s44, s44, 2
	s_add_u32 s42, s42, 0x100
	s_addc_u32 s43, s43, 0
	s_cmpk_gt_u32 s44, 0x55
	s_mov_b64 s[6:7], s[14:15]
	s_waitcnt lgkmcnt(0)
	s_waitcnt vmcnt(6)
	s_barrier
	v_mfma_f32_16x16x32_bf16 v[64:67], v[132:135], v[148:151], v[64:67]
	v_mfma_f32_16x16x32_bf16 v[60:63], v[140:143], v[148:151], v[60:63]
	v_mfma_f32_16x16x32_bf16 v[52:55], v[132:135], v[156:159], v[52:55]
	v_mfma_f32_16x16x32_bf16 v[44:47], v[140:143], v[156:159], v[44:47]
	v_mfma_f32_16x16x32_bf16 v[36:39], v[132:135], v[164:167], v[36:39]
	v_mfma_f32_16x16x32_bf16 v[28:31], v[140:143], v[164:167], v[28:31]
	v_mfma_f32_16x16x32_bf16 v[20:23], v[132:135], v[172:175], v[20:23]
	v_mfma_f32_16x16x32_bf16 v[12:15], v[140:143], v[172:175], v[12:15]
	v_mfma_f32_16x16x32_bf16 v[64:67], v[136:139], v[152:155], v[64:67]
	v_mfma_f32_16x16x32_bf16 v[60:63], v[144:147], v[152:155], v[60:63]
	v_mfma_f32_16x16x32_bf16 v[52:55], v[136:139], v[160:163], v[52:55]
	v_mfma_f32_16x16x32_bf16 v[44:47], v[144:147], v[160:163], v[44:47]
	v_mfma_f32_16x16x32_bf16 v[36:39], v[136:139], v[168:171], v[36:39]
	v_mfma_f32_16x16x32_bf16 v[28:31], v[144:147], v[168:171], v[28:31]
	v_mfma_f32_16x16x32_bf16 v[20:23], v[136:139], v[176:179], v[20:23]
	v_mfma_f32_16x16x32_bf16 v[12:15], v[144:147], v[176:179], v[12:15]
	v_mfma_f32_16x16x32_bf16 v[56:59], v[180:183], v[148:151], v[56:59]
	v_mfma_f32_16x16x32_bf16 v[48:51], v[188:191], v[148:151], v[48:51]
	v_mfma_f32_16x16x32_bf16 v[40:43], v[180:183], v[156:159], v[40:43]
	v_mfma_f32_16x16x32_bf16 v[32:35], v[188:191], v[156:159], v[32:35]
	v_mfma_f32_16x16x32_bf16 v[24:27], v[180:183], v[164:167], v[24:27]
	v_mfma_f32_16x16x32_bf16 v[16:19], v[188:191], v[164:167], v[16:19]
	v_mfma_f32_16x16x32_bf16 v[8:11], v[180:183], v[172:175], v[8:11]
	v_mfma_f32_16x16x32_bf16 v[4:7], v[188:191], v[172:175], v[4:7]
	v_mfma_f32_16x16x32_bf16 v[56:59], v[184:187], v[152:155], v[56:59]
	v_mfma_f32_16x16x32_bf16 v[48:51], v[202:205], v[152:155], v[48:51]
	v_mfma_f32_16x16x32_bf16 v[40:43], v[184:187], v[160:163], v[40:43]
	v_mfma_f32_16x16x32_bf16 v[32:35], v[202:205], v[160:163], v[32:35]
	v_mfma_f32_16x16x32_bf16 v[24:27], v[184:187], v[168:171], v[24:27]
	v_mfma_f32_16x16x32_bf16 v[16:19], v[202:205], v[168:171], v[16:19]
	v_mfma_f32_16x16x32_bf16 v[8:11], v[184:187], v[176:179], v[8:11]
	v_mfma_f32_16x16x32_bf16 v[4:7], v[202:205], v[176:179], v[4:7]
	s_barrier
	s_cbranch_scc0 .LBB0_1666
	s_cmpk_gt_u32 s2, 0xff
	s_cbranch_scc1 .Lalign_a_1666
	s_barrier
.Lalign_a_1666:
	v_mov_b32_e32 v133, v0
	s_lshl_b32 s6, s50, 8
	s_add_i32 s6, s6, s36
	v_and_or_b32 v132, v133, 15, s6
	s_lshl_b32 s6, s49, 8
	v_lshrrev_b32_e32 v133, 1, v133
	v_and_or_b32 v133, v133, 24, s6
	v_or_b32_e32 v134, s37, v133
	v_ashrrev_i32_e32 v135, 31, v134
	v_lshlrev_b64 v[202:203], 1, v[134:135]
	v_ashrrev_i32_e32 v133, 31, v132
	v_lshl_add_u64 v[134:135], s[88:89], 0, v[202:203]
	v_lshlrev_b64 v[226:227], 12, v[132:133]
	v_lshl_add_u64 v[136:137], v[134:135], 0, v[226:227]
	global_load_dwordx4 v[216:219], v[136:137], off
	global_load_dwordx4 v[188:191], v[136:137], off offset:256
	v_or_b32_e32 v136, 16, v132
	v_ashrrev_i32_e32 v137, 31, v136
	v_lshlrev_b64 v[222:223], 12, v[136:137]
	v_lshl_add_u64 v[136:137], v[134:135], 0, v[222:223]
	global_load_dwordx4 v[184:187], v[136:137], off
	global_load_dwordx4 v[180:183], v[136:137], off offset:256
	v_or_b32_e32 v136, 32, v132
	v_ashrrev_i32_e32 v137, 31, v136
	v_lshlrev_b64 v[220:221], 12, v[136:137]
	v_lshl_add_u64 v[136:137], v[134:135], 0, v[220:221]
	global_load_dwordx4 v[176:179], v[136:137], off
	global_load_dwordx4 v[168:171], v[136:137], off offset:256
	v_or_b32_e32 v132, 48, v132
	v_ashrrev_i32_e32 v133, 31, v132
	v_lshlrev_b64 v[212:213], 12, v[132:133]
	v_lshl_add_u64 v[132:133], v[134:135], 0, v[212:213]
	global_load_dwordx4 v[172:175], v[132:133], off
	global_load_dwordx4 v[164:167], v[132:133], off offset:256
	s_mov_b64 s[6:7], 0x80000
	v_lshl_add_u64 v[210:211], v[226:227], 0, s[6:7]
	v_lshl_add_u64 v[132:133], v[134:135], 0, v[210:211]
	global_load_dwordx4 v[160:163], v[132:133], off
	global_load_dwordx4 v[156:159], v[132:133], off offset:256
	s_mov_b64 s[6:7], 0x90000
	v_lshl_add_u64 v[208:209], v[226:227], 0, s[6:7]
	v_lshl_add_u64 v[132:133], v[134:135], 0, v[208:209]
	global_load_dwordx4 v[152:155], v[132:133], off
	global_load_dwordx4 v[148:151], v[132:133], off offset:256
	s_mov_b64 s[6:7], 0xa0000
	v_lshl_add_u64 v[206:207], v[226:227], 0, s[6:7]
	v_lshl_add_u64 v[132:133], v[134:135], 0, v[206:207]
	global_load_dwordx4 v[144:147], v[132:133], off
	global_load_dwordx4 v[140:143], v[132:133], off offset:256
	s_mov_b64 s[6:7], 0xb0000
	v_lshl_add_u64 v[204:205], v[226:227], 0, s[6:7]
	v_lshl_add_u64 v[132:133], v[134:135], 0, v[204:205]
	global_load_dwordx4 v[136:139], v[132:133], off
	s_nop 0
	global_load_dwordx4 v[132:135], v[132:133], off offset:256
	s_and_b64 vcc, exec, s[40:41]
	s_mov_b32 s49, s47
	s_mov_b32 s50, s48
	s_mov_b64 s[14:15], s[4:5]
	s_mov_b64 s[6:7], s[0:1]
	s_waitcnt vmcnt(15)
; __device__ __forceinline__ unsigned cvt_pk_bf16(float lo, float hi) { const f32x2 v = {lo, hi}; const bf16v2_ r = __builtin_convertvector(v, bf16v2_); return __builtin_bit_cast(unsigned, r); }
; __device__ __forceinline__ float bflo(unsigned w) { return __uint_as_float(w << 16); }
; __device__ __forceinline__ float bfhi(unsigned w) { return __uint_as_float(w & 0xffff0000u); }
;     __device__ __forceinline__ void operator()(const f32x4 (&acc)[2][2][4][2], const Unit& u, int wr, int wc, int, int) const {
;     ...
; #pragma unroll
;         for (int ai = 0; ai < 2; ++ai)
; #pragma unroll
;             for (int m = 0; m < 4; ++m)
; #pragma unroll
;                 for (int bj = 0; bj < 2; ++bj) { const u32x4 c = cin[ai][m][bj]; const f32x4 v0 = acc[ai][bj][m][0], v1 = acc[ai][bj][m][1];
;                     u32x4 w; w.x = cvt_pk_bf16(bflo(c.x) + v0[0], bfhi(c.x) + v0[1]); w.y = cvt_pk_bf16(bflo(c.y) + v0[2], bfhi(c.y) + v0[3]);
;                     w.z = cvt_pk_bf16(bflo(c.z) + v1[0], bfhi(c.z) + v1[1]); w.w = cvt_pk_bf16(bflo(c.w) + v1[2], bfhi(c.w) + v1[3]);
;                     *(u32x4*)(C + (size_t)(row0 + ai * HALF + m * 16) * ldc + col0 + bj * HALF) = w; }
	v_lshlrev_b32_e32 v228, 16, v216
	v_and_b32_e32 v229, 0xffff0000, v216
	v_lshlrev_b32_e32 v216, 16, v217
	v_and_b32_e32 v217, 0xffff0000, v217
	v_pk_add_f32 v[128:129], v[128:129], v[228:229]
	v_pk_add_f32 v[130:131], v[130:131], v[216:217]
	v_cvt_pk_bf16_f32 v128, v128, v129
	v_cvt_pk_bf16_f32 v129, v130, v131
	v_lshlrev_b32_e32 v130, 16, v218
	v_and_b32_e32 v131, 0xffff0000, v218
	v_pk_add_f32 v[124:125], v[124:125], v[130:131]
	s_nop 0
	v_cvt_pk_bf16_f32 v130, v124, v125
	v_lshlrev_b32_e32 v124, 16, v219
	v_and_b32_e32 v125, 0xffff0000, v219
	v_pk_add_f32 v[124:125], v[126:127], v[124:125]
	s_waitcnt vmcnt(14)
	v_lshlrev_b32_e32 v126, 16, v188
	v_and_b32_e32 v127, 0xffff0000, v188
	v_pk_add_f32 v[120:121], v[120:121], v[126:127]
	v_lshlrev_b32_e32 v126, 16, v189
	v_and_b32_e32 v127, 0xffff0000, v189
	v_pk_add_f32 v[122:123], v[122:123], v[126:127]
	v_cvt_pk_bf16_f32 v120, v120, v121
	v_cvt_pk_bf16_f32 v121, v122, v123
	v_lshlrev_b32_e32 v122, 16, v190
	v_and_b32_e32 v123, 0xffff0000, v190
	v_pk_add_f32 v[116:117], v[116:117], v[122:123]
	v_cvt_pk_bf16_f32 v131, v124, v125
	v_cvt_pk_bf16_f32 v122, v116, v117
	v_lshlrev_b32_e32 v116, 16, v191
	v_and_b32_e32 v117, 0xffff0000, v191
	v_pk_add_f32 v[116:117], v[118:119], v[116:117]
	v_lshl_add_u64 v[124:125], s[88:89], 0, v[226:227]
	v_cvt_pk_bf16_f32 v123, v116, v117
	s_waitcnt vmcnt(13)
	v_lshlrev_b32_e32 v116, 16, v184
	v_and_b32_e32 v117, 0xffff0000, v184
	v_pk_add_f32 v[112:113], v[112:113], v[116:117]
	v_lshlrev_b32_e32 v116, 16, v185
	v_and_b32_e32 v117, 0xffff0000, v185
	v_pk_add_f32 v[114:115], v[114:115], v[116:117]
	v_cvt_pk_bf16_f32 v112, v112, v113
	v_cvt_pk_bf16_f32 v113, v114, v115
	v_lshlrev_b32_e32 v114, 16, v186
	v_and_b32_e32 v115, 0xffff0000, v186
	v_pk_add_f32 v[108:109], v[108:109], v[114:115]
	v_lshl_add_u64 v[124:125], v[124:125], 0, v[202:203]
	v_cvt_pk_bf16_f32 v114, v108, v109
	v_lshlrev_b32_e32 v108, 16, v187
	v_and_b32_e32 v109, 0xffff0000, v187
	v_pk_add_f32 v[108:109], v[110:111], v[108:109]
	s_waitcnt vmcnt(12)
	v_lshlrev_b32_e32 v110, 16, v180
	v_and_b32_e32 v111, 0xffff0000, v180
	v_pk_add_f32 v[104:105], v[104:105], v[110:111]
	v_lshlrev_b32_e32 v110, 16, v181
	v_and_b32_e32 v111, 0xffff0000, v181
	v_pk_add_f32 v[106:107], v[106:107], v[110:111]
	v_cvt_pk_bf16_f32 v104, v104, v105
	v_cvt_pk_bf16_f32 v105, v106, v107
	v_lshlrev_b32_e32 v106, 16, v182
	v_and_b32_e32 v107, 0xffff0000, v182
	v_pk_add_f32 v[96:97], v[96:97], v[106:107]
	v_cvt_pk_bf16_f32 v115, v108, v109
	v_cvt_pk_bf16_f32 v106, v96, v97
	v_lshlrev_b32_e32 v96, 16, v183
	v_and_b32_e32 v97, 0xffff0000, v183
	v_pk_add_f32 v[96:97], v[98:99], v[96:97]
	s_waitcnt vmcnt(11)
	v_lshlrev_b32_e32 v98, 16, v177
	v_cvt_pk_bf16_f32 v107, v96, v97
	v_lshlrev_b32_e32 v96, 16, v176
	v_and_b32_e32 v97, 0xffff0000, v176
	v_and_b32_e32 v99, 0xffff0000, v177
	v_pk_add_f32 v[96:97], v[100:101], v[96:97]
	v_pk_add_f32 v[98:99], v[102:103], v[98:99]
	v_cvt_pk_bf16_f32 v96, v96, v97
	v_cvt_pk_bf16_f32 v97, v98, v99
	v_lshlrev_b32_e32 v98, 16, v178
	v_and_b32_e32 v99, 0xffff0000, v178
	v_pk_add_f32 v[92:93], v[92:93], v[98:99]
	v_lshl_add_u64 v[108:109], s[88:89], 0, v[222:223]
	v_cvt_pk_bf16_f32 v98, v92, v93
	v_lshlrev_b32_e32 v92, 16, v179
	v_and_b32_e32 v93, 0xffff0000, v179
	v_pk_add_f32 v[92:93], v[94:95], v[92:93]
	s_waitcnt vmcnt(10)
	v_lshlrev_b32_e32 v94, 16, v168
	v_and_b32_e32 v95, 0xffff0000, v168
	v_pk_add_f32 v[88:89], v[88:89], v[94:95]
	v_lshlrev_b32_e32 v94, 16, v169
	v_and_b32_e32 v95, 0xffff0000, v169
	v_pk_add_f32 v[90:91], v[90:91], v[94:95]
	v_cvt_pk_bf16_f32 v88, v88, v89
	v_cvt_pk_bf16_f32 v89, v90, v91
	v_lshlrev_b32_e32 v90, 16, v170
	v_and_b32_e32 v91, 0xffff0000, v170
	v_pk_add_f32 v[80:81], v[80:81], v[90:91]
	v_cvt_pk_bf16_f32 v99, v92, v93
	v_cvt_pk_bf16_f32 v90, v80, v81
	v_lshlrev_b32_e32 v80, 16, v171
	v_and_b32_e32 v81, 0xffff0000, v171
	v_pk_add_f32 v[80:81], v[82:83], v[80:81]
	s_waitcnt vmcnt(9)
	v_lshlrev_b32_e32 v82, 16, v173
	v_cvt_pk_bf16_f32 v91, v80, v81
	v_lshlrev_b32_e32 v80, 16, v172
	v_and_b32_e32 v81, 0xffff0000, v172
	v_and_b32_e32 v83, 0xffff0000, v173
	v_pk_add_f32 v[80:81], v[84:85], v[80:81]
	v_pk_add_f32 v[82:83], v[86:87], v[82:83]
	v_cvt_pk_bf16_f32 v80, v80, v81
	v_cvt_pk_bf16_f32 v81, v82, v83
	v_lshlrev_b32_e32 v82, 16, v174
	v_and_b32_e32 v83, 0xffff0000, v174
	v_pk_add_f32 v[76:77], v[76:77], v[82:83]
	v_lshl_add_u64 v[92:93], s[88:89], 0, v[220:221]
	v_cvt_pk_bf16_f32 v82, v76, v77
	v_lshlrev_b32_e32 v76, 16, v175
	v_and_b32_e32 v77, 0xffff0000, v175
	v_pk_add_f32 v[76:77], v[78:79], v[76:77]
	s_waitcnt vmcnt(8)
	v_lshlrev_b32_e32 v78, 16, v164
	v_and_b32_e32 v79, 0xffff0000, v164
	v_pk_add_f32 v[72:73], v[72:73], v[78:79]
	v_lshlrev_b32_e32 v78, 16, v165
	v_and_b32_e32 v79, 0xffff0000, v165
	v_pk_add_f32 v[74:75], v[74:75], v[78:79]
	v_cvt_pk_bf16_f32 v72, v72, v73
	v_cvt_pk_bf16_f32 v73, v74, v75
	v_lshlrev_b32_e32 v74, 16, v166
	v_and_b32_e32 v75, 0xffff0000, v166
	v_pk_add_f32 v[68:69], v[68:69], v[74:75]
	v_cvt_pk_bf16_f32 v83, v76, v77
	v_cvt_pk_bf16_f32 v74, v68, v69
	v_lshlrev_b32_e32 v68, 16, v167
	v_and_b32_e32 v69, 0xffff0000, v167
	v_pk_add_f32 v[68:69], v[70:71], v[68:69]
	v_lshl_add_u64 v[76:77], s[88:89], 0, v[212:213]
	v_cvt_pk_bf16_f32 v75, v68, v69
	s_waitcnt vmcnt(7)
	v_lshlrev_b32_e32 v68, 16, v160
	v_and_b32_e32 v69, 0xffff0000, v160
	v_pk_add_f32 v[64:65], v[64:65], v[68:69]
	v_lshlrev_b32_e32 v68, 16, v161
	v_and_b32_e32 v69, 0xffff0000, v161
	v_pk_add_f32 v[66:67], v[66:67], v[68:69]
	v_cvt_pk_bf16_f32 v64, v64, v65
	v_cvt_pk_bf16_f32 v65, v66, v67
	v_lshlrev_b32_e32 v66, 16, v162
	v_and_b32_e32 v67, 0xffff0000, v162
	v_pk_add_f32 v[60:61], v[60:61], v[66:67]
	v_lshl_add_u64 v[108:109], v[108:109], 0, v[202:203]
	v_cvt_pk_bf16_f32 v66, v60, v61
	v_lshlrev_b32_e32 v60, 16, v163
	v_and_b32_e32 v61, 0xffff0000, v163
	v_pk_add_f32 v[60:61], v[62:63], v[60:61]
	s_waitcnt vmcnt(6)
; __device__ __forceinline__ unsigned cvt_pk_bf16(float lo, float hi) { const f32x2 v = {lo, hi}; const bf16v2_ r = __builtin_convertvector(v, bf16v2_); return __builtin_bit_cast(unsigned, r); }
; __device__ __forceinline__ float bflo(unsigned w) { return __uint_as_float(w << 16); }
; __device__ __forceinline__ float bfhi(unsigned w) { return __uint_as_float(w & 0xffff0000u); }
; #define PG8_WAIT_V(n) asm volatile("s_waitcnt vmcnt(" #n ")" ::: "memory")
; #define PG8_BAR __builtin_amdgcn_s_barrier()
;     __device__ __forceinline__ void operator()(const f32x4 (&acc)[2][2][4][2], const Unit& u, int wr, int wc, int, int) const {
;     ...
; #pragma unroll
;         for (int ai = 0; ai < 2; ++ai)
; #pragma unroll
;             for (int m = 0; m < 4; ++m)
; #pragma unroll
;                 for (int bj = 0; bj < 2; ++bj) { const u32x4 c = cin[ai][m][bj]; const f32x4 v0 = acc[ai][bj][m][0], v1 = acc[ai][bj][m][1];
;                     u32x4 w; w.x = cvt_pk_bf16(bflo(c.x) + v0[0], bfhi(c.x) + v0[1]); w.y = cvt_pk_bf16(bflo(c.y) + v0[2], bfhi(c.y) + v0[3]);
;                     w.z = cvt_pk_bf16(bflo(c.z) + v1[0], bfhi(c.z) + v1[1]); w.w = cvt_pk_bf16(bflo(c.w) + v1[2], bfhi(c.w) + v1[3]);
;                     *(u32x4*)(C + (size_t)(row0 + ai * HALF + m * 16) * ldc + col0 + bj * HALF) = w; }
; template <class Epi, class Sched>
; __device__ __forceinline__ void gemm_phase(LAS unsigned char* lds, const Gemm g, const Sched& S, const Epi& E) {
;     ...
;     PG8_WAIT_V(0);
;     if (wr == 0) PG8_BAR;
;     PG8_BAR;
	v_lshlrev_b32_e32 v62, 16, v156
	v_and_b32_e32 v63, 0xffff0000, v156
	v_pk_add_f32 v[56:57], v[56:57], v[62:63]
	v_lshlrev_b32_e32 v62, 16, v157
	v_and_b32_e32 v63, 0xffff0000, v157
	v_pk_add_f32 v[58:59], v[58:59], v[62:63]
	v_cvt_pk_bf16_f32 v56, v56, v57
	v_cvt_pk_bf16_f32 v57, v58, v59
	v_lshlrev_b32_e32 v58, 16, v158
	v_and_b32_e32 v59, 0xffff0000, v158
	v_pk_add_f32 v[48:49], v[48:49], v[58:59]
	v_cvt_pk_bf16_f32 v67, v60, v61
	v_cvt_pk_bf16_f32 v58, v48, v49
	v_lshlrev_b32_e32 v48, 16, v159
	v_and_b32_e32 v49, 0xffff0000, v159
	v_pk_add_f32 v[48:49], v[50:51], v[48:49]
	s_waitcnt vmcnt(5)
	v_lshlrev_b32_e32 v50, 16, v153
	v_cvt_pk_bf16_f32 v59, v48, v49
	v_lshlrev_b32_e32 v48, 16, v152
	v_and_b32_e32 v49, 0xffff0000, v152
	v_and_b32_e32 v51, 0xffff0000, v153
	v_pk_add_f32 v[48:49], v[52:53], v[48:49]
	v_pk_add_f32 v[50:51], v[54:55], v[50:51]
	v_cvt_pk_bf16_f32 v48, v48, v49
	v_cvt_pk_bf16_f32 v49, v50, v51
	v_lshlrev_b32_e32 v50, 16, v154
	v_and_b32_e32 v51, 0xffff0000, v154
	v_pk_add_f32 v[44:45], v[44:45], v[50:51]
	v_lshl_add_u64 v[60:61], s[88:89], 0, v[210:211]
	v_cvt_pk_bf16_f32 v50, v44, v45
	v_lshlrev_b32_e32 v44, 16, v155
	v_and_b32_e32 v45, 0xffff0000, v155
	v_pk_add_f32 v[44:45], v[46:47], v[44:45]
	s_waitcnt vmcnt(4)
	v_lshlrev_b32_e32 v46, 16, v148
	v_and_b32_e32 v47, 0xffff0000, v148
	v_pk_add_f32 v[40:41], v[40:41], v[46:47]
	v_lshlrev_b32_e32 v46, 16, v149
	v_and_b32_e32 v47, 0xffff0000, v149
	v_pk_add_f32 v[42:43], v[42:43], v[46:47]
	v_cvt_pk_bf16_f32 v40, v40, v41
	v_cvt_pk_bf16_f32 v41, v42, v43
	v_lshlrev_b32_e32 v42, 16, v150
	v_and_b32_e32 v43, 0xffff0000, v150
	v_pk_add_f32 v[32:33], v[32:33], v[42:43]
	v_cvt_pk_bf16_f32 v51, v44, v45
	v_cvt_pk_bf16_f32 v42, v32, v33
	v_lshlrev_b32_e32 v32, 16, v151
	v_and_b32_e32 v33, 0xffff0000, v151
	v_pk_add_f32 v[32:33], v[34:35], v[32:33]
	s_waitcnt vmcnt(3)
	v_lshlrev_b32_e32 v34, 16, v145
	v_cvt_pk_bf16_f32 v43, v32, v33
	v_lshlrev_b32_e32 v32, 16, v144
	v_and_b32_e32 v33, 0xffff0000, v144
	v_and_b32_e32 v35, 0xffff0000, v145
	v_pk_add_f32 v[32:33], v[36:37], v[32:33]
	v_pk_add_f32 v[34:35], v[38:39], v[34:35]
	v_cvt_pk_bf16_f32 v32, v32, v33
	v_cvt_pk_bf16_f32 v33, v34, v35
	v_lshlrev_b32_e32 v34, 16, v146
	v_and_b32_e32 v35, 0xffff0000, v146
	v_pk_add_f32 v[28:29], v[28:29], v[34:35]
	v_lshl_add_u64 v[44:45], s[88:89], 0, v[208:209]
	v_cvt_pk_bf16_f32 v34, v28, v29
	v_lshlrev_b32_e32 v28, 16, v147
	v_and_b32_e32 v29, 0xffff0000, v147
	v_pk_add_f32 v[28:29], v[30:31], v[28:29]
	s_waitcnt vmcnt(2)
	v_lshlrev_b32_e32 v30, 16, v140
	v_and_b32_e32 v31, 0xffff0000, v140
	v_pk_add_f32 v[24:25], v[24:25], v[30:31]
	v_lshlrev_b32_e32 v30, 16, v141
	v_and_b32_e32 v31, 0xffff0000, v141
	v_pk_add_f32 v[26:27], v[26:27], v[30:31]
	v_cvt_pk_bf16_f32 v24, v24, v25
	v_cvt_pk_bf16_f32 v25, v26, v27
	v_lshlrev_b32_e32 v26, 16, v142
	v_and_b32_e32 v27, 0xffff0000, v142
	v_pk_add_f32 v[16:17], v[16:17], v[26:27]
	v_cvt_pk_bf16_f32 v35, v28, v29
	v_cvt_pk_bf16_f32 v26, v16, v17
	v_lshlrev_b32_e32 v16, 16, v143
	v_and_b32_e32 v17, 0xffff0000, v143
	v_pk_add_f32 v[16:17], v[18:19], v[16:17]
	s_waitcnt vmcnt(1)
	v_lshlrev_b32_e32 v18, 16, v137
	v_cvt_pk_bf16_f32 v27, v16, v17
	v_lshlrev_b32_e32 v16, 16, v136
	v_and_b32_e32 v17, 0xffff0000, v136
	v_and_b32_e32 v19, 0xffff0000, v137
	v_pk_add_f32 v[16:17], v[20:21], v[16:17]
	v_pk_add_f32 v[18:19], v[22:23], v[18:19]
	v_cvt_pk_bf16_f32 v16, v16, v17
	v_cvt_pk_bf16_f32 v17, v18, v19
	v_lshlrev_b32_e32 v18, 16, v138
	v_and_b32_e32 v19, 0xffff0000, v138
	v_pk_add_f32 v[12:13], v[12:13], v[18:19]
	v_lshl_add_u64 v[28:29], s[88:89], 0, v[206:207]
	v_cvt_pk_bf16_f32 v18, v12, v13
	v_lshlrev_b32_e32 v12, 16, v139
	v_and_b32_e32 v13, 0xffff0000, v139
	v_pk_add_f32 v[12:13], v[14:15], v[12:13]
	s_waitcnt vmcnt(0)
	v_lshlrev_b32_e32 v14, 16, v132
	v_and_b32_e32 v15, 0xffff0000, v132
	v_pk_add_f32 v[8:9], v[8:9], v[14:15]
	v_lshlrev_b32_e32 v14, 16, v133
	v_and_b32_e32 v15, 0xffff0000, v133
	v_pk_add_f32 v[10:11], v[10:11], v[14:15]
	v_cvt_pk_bf16_f32 v8, v8, v9
	v_cvt_pk_bf16_f32 v9, v10, v11
	v_lshlrev_b32_e32 v10, 16, v134
	v_and_b32_e32 v11, 0xffff0000, v134
	v_pk_add_f32 v[4:5], v[4:5], v[10:11]
	v_cvt_pk_bf16_f32 v19, v12, v13
	v_cvt_pk_bf16_f32 v10, v4, v5
	v_lshlrev_b32_e32 v4, 16, v135
	v_and_b32_e32 v5, 0xffff0000, v135
	v_lshl_add_u64 v[12:13], s[88:89], 0, v[204:205]
	v_pk_add_f32 v[4:5], v[6:7], v[4:5]
	v_lshl_add_u64 v[92:93], v[92:93], 0, v[202:203]
	v_lshl_add_u64 v[76:77], v[76:77], 0, v[202:203]
	v_lshl_add_u64 v[60:61], v[60:61], 0, v[202:203]
	v_lshl_add_u64 v[44:45], v[44:45], 0, v[202:203]
	v_lshl_add_u64 v[28:29], v[28:29], 0, v[202:203]
	v_lshl_add_u64 v[12:13], v[12:13], 0, v[202:203]
	v_cvt_pk_bf16_f32 v11, v4, v5
	global_store_dwordx4 v[124:125], v[128:131], off
	global_store_dwordx4 v[124:125], v[120:123], off offset:256
	global_store_dwordx4 v[108:109], v[112:115], off
	global_store_dwordx4 v[108:109], v[104:107], off offset:256
	global_store_dwordx4 v[92:93], v[96:99], off
	global_store_dwordx4 v[92:93], v[88:91], off offset:256
	global_store_dwordx4 v[76:77], v[80:83], off
	global_store_dwordx4 v[76:77], v[72:75], off offset:256
	global_store_dwordx4 v[60:61], v[64:67], off
	global_store_dwordx4 v[60:61], v[56:59], off offset:256
	global_store_dwordx4 v[44:45], v[48:51], off
	global_store_dwordx4 v[44:45], v[40:43], off offset:256
	global_store_dwordx4 v[28:29], v[32:35], off
	global_store_dwordx4 v[28:29], v[24:27], off offset:256
	global_store_dwordx4 v[12:13], v[16:19], off
	global_store_dwordx4 v[12:13], v[8:11], off offset:256
	s_cmpk_lt_u32 s2, 0x100
	s_cbranch_scc1 .Lalign_b_1666
	s_barrier
	s_setprio 1
